# GEMM K-loops: no setprio, no dup wait, ds_reads hoisted to the top of each load section (ahead of stage-load address setup)
# speedup vs baseline: 1.0161x; 1.0161x over previous
; #define PG8_STAGE(bufoff, gbase, voff) do { _Pragma("unroll") for (int _i = 0; _i < 2; ++_i) \
;         __builtin_amdgcn_global_load_lds((const unsigned*)((const char*)(gbase) + (voff)[_i]), (PG8_LAS unsigned*)(lds + (bufoff) + ldsw + _i * 8192), 16, 0, 0); } while (0)
; #define PG8_LDA(dst, b, h) do { _Pragma("unroll") for (int m = 0; m < 4; ++m) _Pragma("unroll") for (int k = 0; k < 2; ++k) dst[m][k] = *(const PG8_LAS bf16x8*)(lds + PG8_SA(b, h) + aoff + m * 2048 + k * 1024); } while (0)
; #define PG8_LDB(dst, b, h) do { _Pragma("unroll") for (int n = 0; n < 2; ++n) _Pragma("unroll") for (int k = 0; k < 2; ++k) dst[n][k] = *(const PG8_LAS bf16x8*)(lds + PG8_SB(b, h) + boff + n * 2048 + k * 1024); } while (0)
; #define PG8_MMA(ai, bj, At, Bt) do { __builtin_amdgcn_s_setprio(1); _Pragma("unroll") for (int m = 0; m < 4; ++m) _Pragma("unroll") for (int n = 0; n < 2; ++n) _Pragma("unroll") for (int k = 0; k < 2; ++k) \
;         acc[ai][bj][m][n] = __builtin_amdgcn_mfma_f32_16x16x32_bf16(Bt[n][k], At[m][k], acc[ai][bj][m][n], 0, 0, 0); __builtin_amdgcn_s_setprio(0); } while (0)
; #define PG8_WAIT_L(n) asm volatile("s_waitcnt lgkmcnt(" #n ")" ::: "memory")
; #define PG8_BAR __builtin_amdgcn_s_barrier()
; #define PG8_SCHED __builtin_amdgcn_sched_barrier(0)
; template <class Epi, class Sched>
; __device__ __forceinline__ void gemm_phase(PG8_LAS unsigned char* lds, const Gemm g, const Sched& S, const Epi& E) {
;     ...
;             const bool last = (t == nt - 2);
;             const char* a1 = cA + (size_t)(t + 1) * kstep;
;             const char* a2 = last ? nA : cA + (size_t)(t + 2) * kstep; const char* b2 = last ? nB : cB + (size_t)(t + 2) * kstep;
;             const char* a3 = a2 + kstep; const char* b3 = b2 + kstep;
;             if (last && has_next) S.a_ready(nxt);
;             PG8_LDB(B0, 0, 0); PG8_SCHED; PG8_LDA(At, 0, 0); PG8_STAGE(PG8_SA(1, 1), a1 + hstep, voffA);
;             PG8_WAIT_L(8); PG8_BAR; PG8_WAIT_L(0); PG8_MMA(0, 0, At, B0); PG8_BAR; PG8_SCHED;
;             PG8_LDB(B1, 0, 1); PG8_STAGE(PG8_SB(0, 0), b2, voffB);
;             PG8_BAR; PG8_WAIT_L(0); PG8_MMA(0, 1, At, B1); PG8_BAR;
;             PG8_LDA(At, 0, 1); PG8_STAGE(PG8_SA(0, 0), a2, voffA);
;             PG8_BAR; PG8_WAIT_L(0); PG8_MMA(1, 0, At, B0); PG8_BAR; PG8_SCHED;
.LBB0_195:
	ds_read_b128 v[144:147], v151
	ds_read_b128 v[156:159], v151 offset:1024
	ds_read_b128 v[160:163], v151 offset:2048
	ds_read_b128 v[166:169], v151 offset:3072
	ds_read_b128 v[170:173], v153
	ds_read_b128 v[182:185], v153 offset:1024
	ds_read_b128 v[190:193], v153 offset:2048
	ds_read_b128 v[194:197], v153 offset:3072
	ds_read_b128 v[198:201], v153 offset:4096
	ds_read_b128 v[202:205], v153 offset:5120
	ds_read_b128 v[206:209], v153 offset:6144
	ds_read_b128 v[210:213], v153 offset:7168
	s_add_u32 s30, s28, 0xfffc0080
	s_addc_u32 s31, s29, -1
	s_cmp_eq_u32 s58, 12
	s_cselect_b32 s35, s17, s31
	s_cselect_b32 s34, s54, s30
	s_cselect_b32 s31, s15, s57
	s_cselect_b32 s30, s55, s56
	v_lshl_add_u64 v[174:175], s[28:29], 0, v[136:137]
	s_add_i32 m0, s27, 0xc000
	s_nop 0
	global_load_lds_dwordx4 v[174:175], off
	v_lshl_add_u64 v[174:175], s[28:29], 0, v[138:139]
	s_add_i32 m0, s27, 0xe000
	s_nop 0
	global_load_lds_dwordx4 v[174:175], off
	s_waitcnt lgkmcnt(8)
	s_barrier
	s_waitcnt lgkmcnt(0)
	v_mfma_f32_16x16x32_bf16 v[124:127], v[144:147], v[170:173], v[124:127]
	v_mfma_f32_16x16x32_bf16 v[120:123], v[160:163], v[170:173], v[120:123]
	v_mfma_f32_16x16x32_bf16 v[108:111], v[144:147], v[190:193], v[108:111]
	v_mfma_f32_16x16x32_bf16 v[104:107], v[160:163], v[190:193], v[104:107]
	v_mfma_f32_16x16x32_bf16 v[92:95], v[144:147], v[198:201], v[92:95]
	v_mfma_f32_16x16x32_bf16 v[88:91], v[160:163], v[198:201], v[88:91]
	v_mfma_f32_16x16x32_bf16 v[76:79], v[144:147], v[206:209], v[76:79]
	v_mfma_f32_16x16x32_bf16 v[72:75], v[160:163], v[206:209], v[72:75]
	v_mfma_f32_16x16x32_bf16 v[124:127], v[156:159], v[182:185], v[124:127]
	v_mfma_f32_16x16x32_bf16 v[120:123], v[166:169], v[182:185], v[120:123]
	v_mfma_f32_16x16x32_bf16 v[108:111], v[156:159], v[194:197], v[108:111]
	v_mfma_f32_16x16x32_bf16 v[104:107], v[166:169], v[194:197], v[104:107]
	v_mfma_f32_16x16x32_bf16 v[92:95], v[156:159], v[202:205], v[92:95]
	v_mfma_f32_16x16x32_bf16 v[88:91], v[166:169], v[202:205], v[88:91]
	v_mfma_f32_16x16x32_bf16 v[76:79], v[156:159], v[210:213], v[76:79]
	v_mfma_f32_16x16x32_bf16 v[72:75], v[166:169], v[210:213], v[72:75]
	s_barrier
	ds_read_b128 v[214:217], v154
	ds_read_b128 v[218:221], v154 offset:1024
	ds_read_b128 v[222:225], v154 offset:2048
	ds_read_b128 v[226:229], v154 offset:3072
	s_add_i32 s59, s50, s40
	v_lshl_add_u64 v[174:175], s[30:31], 0, v[132:133]
	s_mov_b32 m0, s59
	s_nop 0
	global_load_lds_dwordx4 v[174:175], off
	v_lshl_add_u64 v[178:179], s[30:31], 0, v[128:129]
	s_add_i32 m0, s59, 0x2000
	s_nop 0
	global_load_lds_dwordx4 v[178:179], off
	s_barrier
	s_waitcnt lgkmcnt(0)
	v_mfma_f32_16x16x32_bf16 v[116:119], v[214:217], v[170:173], v[116:119]
	v_mfma_f32_16x16x32_bf16 v[112:115], v[222:225], v[170:173], v[112:115]
	v_mfma_f32_16x16x32_bf16 v[100:103], v[214:217], v[190:193], v[100:103]
	v_mfma_f32_16x16x32_bf16 v[96:99], v[222:225], v[190:193], v[96:99]
	v_mfma_f32_16x16x32_bf16 v[84:87], v[214:217], v[198:201], v[84:87]
	v_mfma_f32_16x16x32_bf16 v[80:83], v[222:225], v[198:201], v[80:83]
	v_mfma_f32_16x16x32_bf16 v[68:71], v[214:217], v[206:209], v[68:71]
	v_mfma_f32_16x16x32_bf16 v[64:67], v[222:225], v[206:209], v[64:67]
	v_mfma_f32_16x16x32_bf16 v[116:119], v[218:221], v[182:185], v[116:119]
	v_mfma_f32_16x16x32_bf16 v[112:115], v[226:229], v[182:185], v[112:115]
	v_mfma_f32_16x16x32_bf16 v[100:103], v[218:221], v[194:197], v[100:103]
	v_mfma_f32_16x16x32_bf16 v[96:99], v[226:229], v[194:197], v[96:99]
	v_mfma_f32_16x16x32_bf16 v[84:87], v[218:221], v[202:205], v[84:87]
	v_mfma_f32_16x16x32_bf16 v[80:83], v[226:229], v[202:205], v[80:83]
	v_mfma_f32_16x16x32_bf16 v[68:71], v[218:221], v[210:213], v[68:71]
	v_mfma_f32_16x16x32_bf16 v[64:67], v[226:229], v[210:213], v[64:67]
	s_mov_b32 m0, s27
	v_lshl_add_u64 v[186:187], s[34:35], 0, v[134:135]
	s_barrier
	ds_read_b128 v[170:173], v153 offset:16384
	ds_read_b128 v[182:185], v153 offset:17408
	ds_read_b128 v[190:193], v153 offset:18432
	ds_read_b128 v[194:197], v153 offset:19456
	ds_read_b128 v[198:201], v153 offset:20480
	ds_read_b128 v[202:205], v153 offset:21504
	ds_read_b128 v[206:209], v153 offset:22528
	ds_read_b128 v[210:213], v153 offset:23552
	global_load_lds_dwordx4 v[186:187], off
	v_lshl_add_u64 v[230:231], s[34:35], 0, v[130:131]
	s_mov_b32 m0, s43
	s_nop 0
	global_load_lds_dwordx4 v[230:231], off
	s_barrier
	s_waitcnt lgkmcnt(0)
	v_mfma_f32_16x16x32_bf16 v[60:63], v[144:147], v[170:173], v[60:63]
	v_mfma_f32_16x16x32_bf16 v[56:59], v[160:163], v[170:173], v[56:59]
	v_mfma_f32_16x16x32_bf16 v[44:47], v[144:147], v[190:193], v[44:47]
	v_mfma_f32_16x16x32_bf16 v[40:43], v[160:163], v[190:193], v[40:43]
	v_mfma_f32_16x16x32_bf16 v[28:31], v[144:147], v[198:201], v[28:31]
	v_mfma_f32_16x16x32_bf16 v[24:27], v[160:163], v[198:201], v[24:27]
	v_mfma_f32_16x16x32_bf16 v[12:15], v[144:147], v[206:209], v[12:15]
	v_mfma_f32_16x16x32_bf16 v[8:11], v[160:163], v[206:209], v[8:11]
	v_mfma_f32_16x16x32_bf16 v[60:63], v[156:159], v[182:185], v[60:63]
	v_mfma_f32_16x16x32_bf16 v[56:59], v[166:169], v[182:185], v[56:59]
	v_mfma_f32_16x16x32_bf16 v[44:47], v[156:159], v[194:197], v[44:47]
	v_mfma_f32_16x16x32_bf16 v[40:43], v[166:169], v[194:197], v[40:43]
	v_mfma_f32_16x16x32_bf16 v[28:31], v[156:159], v[202:205], v[28:31]
	v_mfma_f32_16x16x32_bf16 v[24:27], v[166:169], v[202:205], v[24:27]
	v_mfma_f32_16x16x32_bf16 v[12:15], v[156:159], v[210:213], v[12:15]
	v_mfma_f32_16x16x32_bf16 v[8:11], v[166:169], v[210:213], v[8:11]
	s_barrier
; #define PG8_STAGE(bufoff, gbase, voff) do { _Pragma("unroll") for (int _i = 0; _i < 2; ++_i) \
;         __builtin_amdgcn_global_load_lds((const unsigned*)((const char*)(gbase) + (voff)[_i]), (PG8_LAS unsigned*)(lds + (bufoff) + ldsw + _i * 8192), 16, 0, 0); } while (0)
; #define PG8_LDA(dst, b, h) do { _Pragma("unroll") for (int m = 0; m < 4; ++m) _Pragma("unroll") for (int k = 0; k < 2; ++k) dst[m][k] = *(const PG8_LAS bf16x8*)(lds + PG8_SA(b, h) + aoff + m * 2048 + k * 1024); } while (0)
; #define PG8_LDB(dst, b, h) do { _Pragma("unroll") for (int n = 0; n < 2; ++n) _Pragma("unroll") for (int k = 0; k < 2; ++k) dst[n][k] = *(const PG8_LAS bf16x8*)(lds + PG8_SB(b, h) + boff + n * 2048 + k * 1024); } while (0)
; #define PG8_MMA(ai, bj, At, Bt) do { __builtin_amdgcn_s_setprio(1); _Pragma("unroll") for (int m = 0; m < 4; ++m) _Pragma("unroll") for (int n = 0; n < 2; ++n) _Pragma("unroll") for (int k = 0; k < 2; ++k) \
;         acc[ai][bj][m][n] = __builtin_amdgcn_mfma_f32_16x16x32_bf16(Bt[n][k], At[m][k], acc[ai][bj][m][n], 0, 0, 0); __builtin_amdgcn_s_setprio(0); } while (0)
; #define PG8_WAIT_V(n) asm volatile("s_waitcnt vmcnt(" #n ")" ::: "memory")
; #define PG8_WAIT_L(n) asm volatile("s_waitcnt lgkmcnt(" #n ")" ::: "memory")
; #define PG8_BAR __builtin_amdgcn_s_barrier()
; #define PG8_SCHED __builtin_amdgcn_sched_barrier(0)
; template <class Epi, class Sched>
; __device__ __forceinline__ void gemm_phase(PG8_LAS unsigned char* lds, const Gemm g, const Sched& S, const Epi& E) {
;     ...
;             PG8_STAGE(PG8_SB(0, 1), b2 + hstep, voffB);
;             PG8_WAIT_V(6); PG8_BAR; PG8_MMA(1, 1, At, B1); PG8_BAR;
;             PG8_LDB(B0, 1, 0); PG8_SCHED; PG8_LDA(At, 1, 0); PG8_STAGE(PG8_SA(0, 1), a2 + hstep, voffA);
;             PG8_WAIT_L(8); PG8_BAR; PG8_WAIT_L(0); PG8_MMA(0, 0, At, B0); PG8_BAR; PG8_SCHED;
;             PG8_LDB(B1, 1, 1); PG8_STAGE(PG8_SB(1, 0), b3, voffB);
;             PG8_BAR; PG8_WAIT_L(0); PG8_MMA(0, 1, At, B1); PG8_BAR;
;             PG8_LDA(At, 1, 1); PG8_STAGE(PG8_SA(1, 0), a3, voffA);
	s_add_u32 s60, s30, 0x40000
	s_addc_u32 s61, s31, 0
	s_add_i32 s59, s51, s40
	v_lshl_add_u64 v[144:145], s[60:61], 0, v[132:133]
	s_mov_b32 m0, s59
	s_nop 0
	global_load_lds_dwordx4 v[144:145], off
	v_lshl_add_u64 v[144:145], s[60:61], 0, v[128:129]
	s_add_i32 m0, s59, 0x2000
	s_nop 0
	global_load_lds_dwordx4 v[144:145], off
	s_waitcnt vmcnt(6)
	s_barrier
	v_mfma_f32_16x16x32_bf16 v[52:55], v[214:217], v[170:173], v[52:55]
	v_mfma_f32_16x16x32_bf16 v[48:51], v[222:225], v[170:173], v[48:51]
	v_mfma_f32_16x16x32_bf16 v[36:39], v[214:217], v[190:193], v[36:39]
	v_mfma_f32_16x16x32_bf16 v[32:35], v[222:225], v[190:193], v[32:35]
	v_mfma_f32_16x16x32_bf16 v[20:23], v[214:217], v[198:201], v[20:23]
	v_mfma_f32_16x16x32_bf16 v[16:19], v[222:225], v[198:201], v[16:19]
	v_mfma_f32_16x16x32_bf16 v[4:7], v[214:217], v[206:209], v[4:7]
	v_mfma_f32_16x16x32_bf16 v[0:3], v[222:225], v[206:209], v[0:3]
	v_mfma_f32_16x16x32_bf16 v[52:55], v[218:221], v[182:185], v[52:55]
	v_mfma_f32_16x16x32_bf16 v[48:51], v[226:229], v[182:185], v[48:51]
	v_mfma_f32_16x16x32_bf16 v[36:39], v[218:221], v[194:197], v[36:39]
	v_mfma_f32_16x16x32_bf16 v[32:35], v[226:229], v[194:197], v[32:35]
	v_mfma_f32_16x16x32_bf16 v[20:23], v[218:221], v[202:205], v[20:23]
	v_mfma_f32_16x16x32_bf16 v[16:19], v[226:229], v[202:205], v[16:19]
	v_mfma_f32_16x16x32_bf16 v[4:7], v[218:221], v[210:213], v[4:7]
	v_mfma_f32_16x16x32_bf16 v[0:3], v[226:229], v[210:213], v[0:3]
	s_add_i32 s59, 0, 0x18000
	v_add_u32_e32 v155, s59, v149
	s_barrier
	ds_read_b128 v[144:147], v155
	ds_read_b128 v[156:159], v155 offset:1024
	ds_read_b128 v[160:163], v155 offset:2048
	ds_read_b128 v[166:169], v155 offset:3072
	ds_read_b128 v[170:173], v153 offset:32768
	ds_read_b128 v[182:185], v153 offset:33792
	ds_read_b128 v[190:193], v153 offset:34816
	ds_read_b128 v[194:197], v153 offset:35840
	ds_read_b128 v[198:201], v153 offset:36864
	ds_read_b128 v[202:205], v153 offset:37888
	ds_read_b128 v[206:209], v153 offset:38912
	ds_read_b128 v[210:213], v153 offset:39936
	s_add_u32 s34, s34, 0x40000
	s_addc_u32 s35, s35, 0
	s_mov_b32 m0, s44
	v_lshl_add_u64 v[214:215], s[34:35], 0, v[134:135]
	global_load_lds_dwordx4 v[214:215], off
	v_lshl_add_u64 v[214:215], s[34:35], 0, v[130:131]
	s_mov_b32 m0, s45
	s_nop 0
	global_load_lds_dwordx4 v[214:215], off
	s_waitcnt lgkmcnt(8)
	s_barrier
	s_waitcnt lgkmcnt(0)
	v_mfma_f32_16x16x32_bf16 v[124:127], v[144:147], v[170:173], v[124:127]
	v_mfma_f32_16x16x32_bf16 v[120:123], v[160:163], v[170:173], v[120:123]
	v_mfma_f32_16x16x32_bf16 v[108:111], v[144:147], v[190:193], v[108:111]
	v_mfma_f32_16x16x32_bf16 v[104:107], v[160:163], v[190:193], v[104:107]
	v_mfma_f32_16x16x32_bf16 v[92:95], v[144:147], v[198:201], v[92:95]
	v_mfma_f32_16x16x32_bf16 v[88:91], v[160:163], v[198:201], v[88:91]
	v_mfma_f32_16x16x32_bf16 v[76:79], v[144:147], v[206:209], v[76:79]
	v_mfma_f32_16x16x32_bf16 v[72:75], v[160:163], v[206:209], v[72:75]
	v_mfma_f32_16x16x32_bf16 v[124:127], v[156:159], v[182:185], v[124:127]
	v_mfma_f32_16x16x32_bf16 v[120:123], v[166:169], v[182:185], v[120:123]
	v_mfma_f32_16x16x32_bf16 v[108:111], v[156:159], v[194:197], v[108:111]
	v_mfma_f32_16x16x32_bf16 v[104:107], v[166:169], v[194:197], v[104:107]
	v_mfma_f32_16x16x32_bf16 v[92:95], v[156:159], v[202:205], v[92:95]
	v_mfma_f32_16x16x32_bf16 v[88:91], v[166:169], v[202:205], v[88:91]
	v_mfma_f32_16x16x32_bf16 v[76:79], v[156:159], v[210:213], v[76:79]
	v_mfma_f32_16x16x32_bf16 v[72:75], v[166:169], v[210:213], v[72:75]
	s_barrier
	s_add_i32 s34, 0, 0x1c000
	v_add_u32_e32 v155, s34, v149
	ds_read_b128 v[214:217], v155
	ds_read_b128 v[218:221], v155 offset:1024
	ds_read_b128 v[222:225], v155 offset:2048
	ds_read_b128 v[226:229], v155 offset:3072
	s_add_i32 s35, s59, s40
	v_lshl_add_u64 v[174:175], v[174:175], 0, s[10:11]
	s_mov_b32 m0, s35
	s_nop 0
	global_load_lds_dwordx4 v[174:175], off
	v_lshl_add_u64 v[174:175], v[178:179], 0, s[10:11]
	s_add_i32 m0, s35, 0x2000
	s_nop 0
	global_load_lds_dwordx4 v[174:175], off
	s_barrier
	s_waitcnt lgkmcnt(0)
	v_mfma_f32_16x16x32_bf16 v[116:119], v[214:217], v[170:173], v[116:119]
	v_mfma_f32_16x16x32_bf16 v[112:115], v[222:225], v[170:173], v[112:115]
	v_mfma_f32_16x16x32_bf16 v[100:103], v[214:217], v[190:193], v[100:103]
	v_mfma_f32_16x16x32_bf16 v[96:99], v[222:225], v[190:193], v[96:99]
	v_mfma_f32_16x16x32_bf16 v[84:87], v[214:217], v[198:201], v[84:87]
	v_mfma_f32_16x16x32_bf16 v[80:83], v[222:225], v[198:201], v[80:83]
	v_mfma_f32_16x16x32_bf16 v[68:71], v[214:217], v[206:209], v[68:71]
	v_mfma_f32_16x16x32_bf16 v[64:67], v[222:225], v[206:209], v[64:67]
	v_mfma_f32_16x16x32_bf16 v[116:119], v[218:221], v[182:185], v[116:119]
	v_mfma_f32_16x16x32_bf16 v[112:115], v[226:229], v[182:185], v[112:115]
	v_mfma_f32_16x16x32_bf16 v[100:103], v[218:221], v[194:197], v[100:103]
	v_mfma_f32_16x16x32_bf16 v[96:99], v[226:229], v[194:197], v[96:99]
	v_mfma_f32_16x16x32_bf16 v[84:87], v[218:221], v[202:205], v[84:87]
	v_mfma_f32_16x16x32_bf16 v[80:83], v[226:229], v[202:205], v[80:83]
	v_mfma_f32_16x16x32_bf16 v[68:71], v[218:221], v[210:213], v[68:71]
	v_mfma_f32_16x16x32_bf16 v[64:67], v[226:229], v[210:213], v[64:67]
	s_mov_b32 m0, s47
	v_lshl_add_u64 v[174:175], v[186:187], 0, s[10:11]
	s_barrier
	ds_read_b128 v[170:173], v153 offset:49152
	ds_read_b128 v[182:185], v153 offset:50176
	ds_read_b128 v[190:193], v153 offset:51200
	ds_read_b128 v[194:197], v153 offset:52224
	ds_read_b128 v[198:201], v153 offset:53248
	ds_read_b128 v[202:205], v153 offset:54272
	ds_read_b128 v[206:209], v153 offset:55296
	ds_read_b128 v[210:213], v153 offset:56320
	global_load_lds_dwordx4 v[174:175], off
	v_lshl_add_u64 v[174:175], v[230:231], 0, s[10:11]
	s_mov_b32 m0, s48
	s_nop 0
	global_load_lds_dwordx4 v[174:175], off
	s_barrier
; __device__ __forceinline__ unsigned cvt_pk_bf16(float lo, float hi) { unsigned r; asm volatile("v_cvt_pk_bf16_f32 %0, %1, %2" : "=v"(r) : "v"(lo), "v"(hi)); return r; }
; #define PG8_STAGE(bufoff, gbase, voff) do { _Pragma("unroll") for (int _i = 0; _i < 2; ++_i) \
;         __builtin_amdgcn_global_load_lds((const unsigned*)((const char*)(gbase) + (voff)[_i]), (PG8_LAS unsigned*)(lds + (bufoff) + ldsw + _i * 8192), 16, 0, 0); } while (0)
; #define PG8_MMA(ai, bj, At, Bt) do { __builtin_amdgcn_s_setprio(1); _Pragma("unroll") for (int m = 0; m < 4; ++m) _Pragma("unroll") for (int n = 0; n < 2; ++n) _Pragma("unroll") for (int k = 0; k < 2; ++k) \
;         acc[ai][bj][m][n] = __builtin_amdgcn_mfma_f32_16x16x32_bf16(Bt[n][k], At[m][k], acc[ai][bj][m][n], 0, 0, 0); __builtin_amdgcn_s_setprio(0); } while (0)
; #define PG8_WAIT_V(n) asm volatile("s_waitcnt vmcnt(" #n ")" ::: "memory")
; #define PG8_WAIT_L(n) asm volatile("s_waitcnt lgkmcnt(" #n ")" ::: "memory")
; #define PG8_BAR __builtin_amdgcn_s_barrier()
; #define PG8_SCHED __builtin_amdgcn_sched_barrier(0)
;     __device__ __forceinline__ void operator()(const f32x4 (&acc)[2][2][4][2], const Unit& u, int wr, int wc, int fr, int fq) const {
;         const int row0 = u.pm * BM + wr * 64 + fr, col0 = u.pn * HALF + wc * 32 + 8 * fq;
; #pragma unroll
;         for (int ai = 0; ai < 2; ++ai)
; #pragma unroll
;             for (int m = 0; m < 4; ++m) { bf16_t* rowp = O + (size_t)(row0 + ai * HALF + m * 16) * ldc + col0;
;                 f32x4 v0, v1;
; #pragma unroll
;                 for (int j = 0; j < 1; ++j) { v0 = acc[ai][0][m][0] * sigmoid4(acc[ai][0][m][0]) * acc[ai][1][m][0]; v1 = acc[ai][0][m][1] * sigmoid4(acc[ai][0][m][1]) * acc[ai][1][m][1]; }
;                 u32x4 w; w.x = cvt_pk_bf16(v0[0], v0[1]); w.y = cvt_pk_bf16(v0[2], v0[3]); w.z = cvt_pk_bf16(v1[0], v1[1]); w.w = cvt_pk_bf16(v1[2], v1[3]);
;                 *(u32x4*)rowp = w; }
; template <class Epi, class Sched>
; __device__ __forceinline__ void gemm_phase(PG8_LAS unsigned char* lds, const Gemm g, const Sched& S, const Epi& E) {
;     ...
;             PG8_BAR; PG8_WAIT_L(0); PG8_MMA(1, 0, At, B0); PG8_BAR; PG8_SCHED;
;             PG8_STAGE(PG8_SB(1, 1), b3 + hstep, voffB);
;             PG8_WAIT_V(6); PG8_BAR; PG8_MMA(1, 1, At, B1); PG8_BAR;
	s_waitcnt lgkmcnt(0)
	v_mfma_f32_16x16x32_bf16 v[60:63], v[144:147], v[170:173], v[60:63]
	v_mfma_f32_16x16x32_bf16 v[56:59], v[160:163], v[170:173], v[56:59]
	v_mfma_f32_16x16x32_bf16 v[44:47], v[144:147], v[190:193], v[44:47]
	v_mfma_f32_16x16x32_bf16 v[40:43], v[160:163], v[190:193], v[40:43]
	v_mfma_f32_16x16x32_bf16 v[28:31], v[144:147], v[198:201], v[28:31]
	v_mfma_f32_16x16x32_bf16 v[24:27], v[160:163], v[198:201], v[24:27]
	v_mfma_f32_16x16x32_bf16 v[12:15], v[144:147], v[206:209], v[12:15]
	v_mfma_f32_16x16x32_bf16 v[8:11], v[160:163], v[206:209], v[8:11]
	v_mfma_f32_16x16x32_bf16 v[60:63], v[156:159], v[182:185], v[60:63]
	v_mfma_f32_16x16x32_bf16 v[56:59], v[166:169], v[182:185], v[56:59]
	v_mfma_f32_16x16x32_bf16 v[44:47], v[156:159], v[194:197], v[44:47]
	v_mfma_f32_16x16x32_bf16 v[40:43], v[166:169], v[194:197], v[40:43]
	v_mfma_f32_16x16x32_bf16 v[28:31], v[156:159], v[202:205], v[28:31]
	v_mfma_f32_16x16x32_bf16 v[24:27], v[166:169], v[202:205], v[24:27]
	v_mfma_f32_16x16x32_bf16 v[12:15], v[156:159], v[210:213], v[12:15]
	v_mfma_f32_16x16x32_bf16 v[8:11], v[166:169], v[210:213], v[8:11]
	s_barrier
	s_add_u32 s30, s30, 0x40080
	s_addc_u32 s31, s31, 0
	s_add_i32 s34, s34, s40
	v_lshl_add_u64 v[144:145], s[30:31], 0, v[132:133]
	s_mov_b32 m0, s34
	s_nop 0
	global_load_lds_dwordx4 v[144:145], off
	v_lshl_add_u64 v[144:145], s[30:31], 0, v[128:129]
	s_add_i32 m0, s34, 0x2000
	s_nop 0
	global_load_lds_dwordx4 v[144:145], off
	s_waitcnt vmcnt(6)
	s_barrier
	v_mfma_f32_16x16x32_bf16 v[52:55], v[214:217], v[170:173], v[52:55]
	v_mfma_f32_16x16x32_bf16 v[48:51], v[222:225], v[170:173], v[48:51]
	v_mfma_f32_16x16x32_bf16 v[36:39], v[214:217], v[190:193], v[36:39]
	v_mfma_f32_16x16x32_bf16 v[32:35], v[222:225], v[190:193], v[32:35]
	v_mfma_f32_16x16x32_bf16 v[20:23], v[214:217], v[198:201], v[20:23]
	v_mfma_f32_16x16x32_bf16 v[16:19], v[222:225], v[198:201], v[16:19]
	v_mfma_f32_16x16x32_bf16 v[4:7], v[214:217], v[206:209], v[4:7]
	v_mfma_f32_16x16x32_bf16 v[0:3], v[222:225], v[206:209], v[0:3]
	v_mfma_f32_16x16x32_bf16 v[52:55], v[218:221], v[182:185], v[52:55]
	v_mfma_f32_16x16x32_bf16 v[48:51], v[226:229], v[182:185], v[48:51]
	v_mfma_f32_16x16x32_bf16 v[36:39], v[218:221], v[194:197], v[36:39]
	v_mfma_f32_16x16x32_bf16 v[32:35], v[226:229], v[194:197], v[32:35]
	v_mfma_f32_16x16x32_bf16 v[20:23], v[218:221], v[202:205], v[20:23]
	v_mfma_f32_16x16x32_bf16 v[16:19], v[226:229], v[202:205], v[16:19]
	v_mfma_f32_16x16x32_bf16 v[4:7], v[218:221], v[210:213], v[4:7]
	v_mfma_f32_16x16x32_bf16 v[0:3], v[226:229], v[210:213], v[0:3]
	s_add_i32 s58, s58, 2
	s_add_u32 s28, s28, 0x100
	s_addc_u32 s29, s29, 0
	s_add_u32 s56, s56, 0x100
	s_addc_u32 s57, s57, 0
	s_cmp_gt_u32 s58, 13
	s_barrier
	s_cbranch_scc0 .LBB0_195
	v_max_f32_e32 v144, v124, v124
	v_max_f32_e32 v144, 0xc1a00000, v144
	v_mul_f32_e32 v144, 0xbfb8aa3b, v144
	v_exp_f32_e32 v157, v144
	v_max_f32_e32 v144, v125, v125
	v_max_f32_e32 v144, 0xc1a00000, v144
	v_mul_f32_e32 v144, 0xbfb8aa3b, v144
	v_exp_f32_e32 v156, v144
	v_max_f32_e32 v144, v126, v126
	v_max_f32_e32 v144, 0xc1a00000, v144
	v_mul_f32_e32 v144, 0xbfb8aa3b, v144
	v_exp_f32_e32 v159, v144
	v_max_f32_e32 v144, v127, v127
	v_max_f32_e32 v144, 0xc1a00000, v144
	v_mul_f32_e32 v144, 0xbfb8aa3b, v144
	v_exp_f32_e32 v158, v144
	v_pk_add_f32 v[156:157], v[156:157], 1.0 op_sel_hi:[1,0]
	v_lshl_or_b32 v146, s53, 7, v150
	v_mov_b32_e32 v160, v157
	v_pk_add_f32 v[158:159], v[158:159], 1.0 op_sel_hi:[1,0]
	v_mov_b32_e32 v162, v156
	v_mov_b32_e32 v161, v159
	v_mov_b32_e32 v163, v158
	v_pk_mul_f32 v[160:161], v[160:161], v[162:163]
	v_lshl_add_u32 v155, s26, 8, v148
	v_mul_f32_e32 v162, v160, v161
	v_rcp_f32_e32 v166, v162
	v_ashrrev_i32_e32 v147, 31, v146
	v_mov_b64_e32 v[144:145], s[4:5]
	v_mad_i64_i32 v[162:163], s[28:29], v155, s52, v[144:145]
	v_mul_f32_e32 v160, v160, v166
	v_mul_f32_e32 v164, v161, v166
	v_pk_mul_f32 v[158:159], v[158:159], v[160:161] op_sel_hi:[1,0]
	v_max_f32_e32 v160, v120, v120
	v_max_f32_e32 v166, v122, v122
	v_max_f32_e32 v160, 0xc1a00000, v160
	v_max_f32_e32 v166, 0xc1a00000, v166
	v_mul_f32_e32 v160, 0xbfb8aa3b, v160
	v_mul_f32_e32 v166, 0xbfb8aa3b, v166
	v_exp_f32_e32 v161, v160
	v_max_f32_e32 v160, v121, v121
	v_exp_f32_e32 v167, v166
	v_max_f32_e32 v166, v123, v123
	v_max_f32_e32 v160, 0xc1a00000, v160
	v_max_f32_e32 v166, 0xc1a00000, v166
	v_mul_f32_e32 v160, 0xbfb8aa3b, v160
	v_mul_f32_e32 v166, 0xbfb8aa3b, v166
	v_exp_f32_e32 v160, v160
	v_exp_f32_e32 v166, v166
	v_pk_mul_f32 v[156:157], v[156:157], v[164:165] op_sel_hi:[1,0]
	v_pk_mul_f32 v[126:127], v[126:127], v[158:159]
	v_pk_mul_f32 v[124:125], v[124:125], v[156:157]
	v_pk_add_f32 v[156:157], v[160:161], 1.0 op_sel_hi:[1,0]
	v_pk_add_f32 v[160:161], v[166:167], 1.0 op_sel_hi:[1,0]
	v_mov_b32_e32 v166, v157
	v_mov_b32_e32 v167, v161
	v_mov_b32_e32 v168, v156
	v_mov_b32_e32 v169, v160
	v_pk_mul_f32 v[166:167], v[166:167], v[168:169]
	v_pk_mul_f32 v[118:119], v[126:127], v[118:119]
	v_mul_f32_e32 v164, v166, v167
	v_rcp_f32_e32 v164, v164
	v_pk_mul_f32 v[116:117], v[124:125], v[116:117]
	v_lshlrev_b64 v[146:147], 1, v[146:147]
	v_lshl_add_u64 v[162:163], v[162:163], 0, v[146:147]
	v_mul_f32_e32 v124, v167, v164
	v_mul_f32_e32 v126, v166, v164
	v_pk_mul_f32 v[126:127], v[160:161], v[126:127] op_sel_hi:[1,0]
	v_pk_mul_f32 v[124:125], v[156:157], v[124:125] op_sel_hi:[1,0]
	v_pk_mul_f32 v[122:123], v[122:123], v[126:127]
	v_pk_mul_f32 v[120:121], v[120:121], v[124:125]
	v_pk_mul_f32 v[122:123], v[122:123], v[114:115]
	v_pk_mul_f32 v[114:115], v[120:121], v[112:113]
	v_cvt_pk_bf16_f32 v112, v116, v117
	v_cvt_pk_bf16_f32 v113, v118, v119
; __device__ __forceinline__ unsigned cvt_pk_bf16(float lo, float hi) { unsigned r; asm volatile("v_cvt_pk_bf16_f32 %0, %1, %2" : "=v"(r) : "v"(lo), "v"(hi)); return r; }
; __device__ __forceinline__ f32x4 sigmoid4(f32x4 x) {
;     f32x4 d;
; #pragma unroll
;     for (int j = 0; j < 4; ++j) d[j] = 1.0f + __expf(-fmaxf(x[j], -20.0f));
;     const float p01 = d[0] * d[1], p23 = d[2] * d[3], r = __builtin_amdgcn_rcpf(p01 * p23), r01 = r * p23, r23 = r * p01;
;     return (f32x4){r01 * d[1], r01 * d[0], r23 * d[3], r23 * d[2]};
; }
;     __device__ __forceinline__ void operator()(const f32x4 (&acc)[2][2][4][2], const Unit& u, int wr, int wc, int fr, int fq) const {
;     ...
;         for (int ai = 0; ai < 2; ++ai)
; #pragma unroll
;             for (int m = 0; m < 4; ++m) { bf16_t* rowp = O + (size_t)(row0 + ai * HALF + m * 16) * ldc + col0;
;                 f32x4 v0, v1;
; #pragma unroll
;                 for (int j = 0; j < 1; ++j) { v0 = acc[ai][0][m][0] * sigmoid4(acc[ai][0][m][0]) * acc[ai][1][m][0]; v1 = acc[ai][0][m][1] * sigmoid4(acc[ai][0][m][1]) * acc[ai][1][m][1]; }
;                 u32x4 w; w.x = cvt_pk_bf16(v0[0], v0[1]); w.y = cvt_pk_bf16(v0[2], v0[3]); w.z = cvt_pk_bf16(v1[0], v1[1]); w.w = cvt_pk_bf16(v1[2], v1[3]);
;                 *(u32x4*)rowp = w; }
	v_max_f32_e32 v116, v108, v108
	v_max_f32_e32 v118, v110, v110
	v_max_f32_e32 v116, 0xc1a00000, v116
	v_max_f32_e32 v118, 0xc1a00000, v118
	v_mul_f32_e32 v116, 0xbfb8aa3b, v116
	v_mul_f32_e32 v118, 0xbfb8aa3b, v118
	v_exp_f32_e32 v117, v116
	v_max_f32_e32 v116, v109, v109
	v_exp_f32_e32 v119, v118
	v_max_f32_e32 v118, v111, v111
	v_max_f32_e32 v116, 0xc1a00000, v116
	v_max_f32_e32 v118, 0xc1a00000, v118
	v_mul_f32_e32 v116, 0xbfb8aa3b, v116
	v_mul_f32_e32 v118, 0xbfb8aa3b, v118
	v_exp_f32_e32 v116, v116
	v_exp_f32_e32 v118, v118
	v_cvt_pk_bf16_f32 v114, v114, v115
	v_cvt_pk_bf16_f32 v115, v122, v123
	global_store_dwordx4 v[162:163], v[112:115], off
	v_or_b32_e32 v120, 16, v155
	s_and_b64 vcc, exec, s[2:3]
	v_pk_add_f32 v[112:113], v[116:117], 1.0 op_sel_hi:[1,0]
	v_pk_add_f32 v[114:115], v[118:119], 1.0 op_sel_hi:[1,0]
	v_mov_b32_e32 v116, v113
	v_mov_b32_e32 v117, v115
	v_mov_b32_e32 v118, v112
	v_mov_b32_e32 v119, v114
	v_pk_mul_f32 v[116:117], v[116:117], v[118:119]
	s_mov_b32 s53, s14
	v_mul_f32_e32 v118, v116, v117
	v_rcp_f32_e32 v121, v118
	v_mad_i64_i32 v[118:119], s[28:29], v120, s52, v[144:145]
	v_lshl_add_u64 v[118:119], v[118:119], 0, v[146:147]
	v_mul_f32_e32 v116, v116, v121
	v_mul_f32_e32 v120, v117, v121
	v_pk_mul_f32 v[114:115], v[114:115], v[116:117] op_sel_hi:[1,0]
	v_max_f32_e32 v116, v104, v104
	v_max_f32_e32 v121, v106, v106
	v_max_f32_e32 v116, 0xc1a00000, v116
	v_max_f32_e32 v121, 0xc1a00000, v121
	v_mul_f32_e32 v116, 0xbfb8aa3b, v116
	v_mul_f32_e32 v121, 0xbfb8aa3b, v121
	v_exp_f32_e32 v117, v116
	v_max_f32_e32 v116, v105, v105
	v_exp_f32_e32 v123, v121
	v_max_f32_e32 v121, v107, v107
	v_max_f32_e32 v116, 0xc1a00000, v116
	v_max_f32_e32 v121, 0xc1a00000, v121
	v_mul_f32_e32 v116, 0xbfb8aa3b, v116
	v_mul_f32_e32 v121, 0xbfb8aa3b, v121
	v_exp_f32_e32 v116, v116
	v_exp_f32_e32 v122, v121
	v_pk_mul_f32 v[112:113], v[112:113], v[120:121] op_sel_hi:[1,0]
	v_pk_mul_f32 v[110:111], v[110:111], v[114:115]
	v_pk_mul_f32 v[108:109], v[108:109], v[112:113]
	v_pk_add_f32 v[112:113], v[116:117], 1.0 op_sel_hi:[1,0]
	v_pk_add_f32 v[116:117], v[122:123], 1.0 op_sel_hi:[1,0]
	v_mov_b32_e32 v120, v113
	v_mov_b32_e32 v121, v117
	v_mov_b32_e32 v122, v112
	v_mov_b32_e32 v123, v116
	v_pk_mul_f32 v[120:121], v[120:121], v[122:123]
	v_pk_mul_f32 v[102:103], v[110:111], v[102:103]
	v_mul_f32_e32 v122, v120, v121
	v_rcp_f32_e32 v122, v122
	v_pk_mul_f32 v[100:101], v[108:109], v[100:101]
	s_mov_b32 s26, s16
	s_mov_b64 s[30:31], s[24:25]
	v_mul_f32_e32 v108, v121, v122
	v_mul_f32_e32 v110, v120, v122
	v_pk_mul_f32 v[110:111], v[116:117], v[110:111] op_sel_hi:[1,0]
	v_pk_mul_f32 v[108:109], v[112:113], v[108:109] op_sel_hi:[1,0]
	v_pk_mul_f32 v[106:107], v[106:107], v[110:111]
	v_pk_mul_f32 v[104:105], v[104:105], v[108:109]
	v_pk_mul_f32 v[106:107], v[106:107], v[98:99]
	v_pk_mul_f32 v[98:99], v[104:105], v[96:97]
	v_cvt_pk_bf16_f32 v96, v100, v101
	v_cvt_pk_bf16_f32 v97, v102, v103
	v_max_f32_e32 v100, v92, v92
	v_max_f32_e32 v102, v94, v94
	v_max_f32_e32 v100, 0xc1a00000, v100
	v_max_f32_e32 v102, 0xc1a00000, v102
	v_mul_f32_e32 v100, 0xbfb8aa3b, v100
	v_mul_f32_e32 v102, 0xbfb8aa3b, v102
	v_exp_f32_e32 v101, v100
	v_max_f32_e32 v100, v93, v93
	v_exp_f32_e32 v103, v102
	v_max_f32_e32 v102, v95, v95
	v_max_f32_e32 v100, 0xc1a00000, v100
	v_max_f32_e32 v102, 0xc1a00000, v102
	v_mul_f32_e32 v100, 0xbfb8aa3b, v100
	v_mul_f32_e32 v102, 0xbfb8aa3b, v102
	v_exp_f32_e32 v100, v100
	v_exp_f32_e32 v102, v102
	v_cvt_pk_bf16_f32 v98, v98, v99
	v_cvt_pk_bf16_f32 v99, v106, v107
	global_store_dwordx4 v[118:119], v[96:99], off
	v_or_b32_e32 v104, 32, v155
	s_nop 0
	v_pk_add_f32 v[96:97], v[100:101], 1.0 op_sel_hi:[1,0]
	v_pk_add_f32 v[98:99], v[102:103], 1.0 op_sel_hi:[1,0]
	v_mov_b32_e32 v100, v97
	v_mov_b32_e32 v101, v99
	v_mov_b32_e32 v102, v96
	v_mov_b32_e32 v103, v98
	v_pk_mul_f32 v[100:101], v[100:101], v[102:103]
	s_nop 0
	v_mul_f32_e32 v102, v100, v101
	v_rcp_f32_e32 v105, v102
	v_mad_i64_i32 v[102:103], s[28:29], v104, s52, v[144:145]
	v_lshl_add_u64 v[102:103], v[102:103], 0, v[146:147]
	v_mul_f32_e32 v100, v100, v105
	v_mul_f32_e32 v104, v101, v105
	v_pk_mul_f32 v[98:99], v[98:99], v[100:101] op_sel_hi:[1,0]
	v_max_f32_e32 v100, v88, v88
	v_max_f32_e32 v105, v90, v90
	v_max_f32_e32 v100, 0xc1a00000, v100
	v_max_f32_e32 v105, 0xc1a00000, v105
	v_mul_f32_e32 v100, 0xbfb8aa3b, v100
	v_mul_f32_e32 v105, 0xbfb8aa3b, v105
	v_exp_f32_e32 v101, v100
	v_max_f32_e32 v100, v89, v89
	v_exp_f32_e32 v107, v105
	v_max_f32_e32 v105, v91, v91
	v_max_f32_e32 v100, 0xc1a00000, v100
	v_max_f32_e32 v105, 0xc1a00000, v105
	v_mul_f32_e32 v100, 0xbfb8aa3b, v100
	v_mul_f32_e32 v105, 0xbfb8aa3b, v105
	v_exp_f32_e32 v100, v100
	v_exp_f32_e32 v106, v105
	v_pk_mul_f32 v[96:97], v[96:97], v[104:105] op_sel_hi:[1,0]
	v_pk_mul_f32 v[94:95], v[94:95], v[98:99]
	v_pk_mul_f32 v[92:93], v[92:93], v[96:97]
	v_pk_add_f32 v[96:97], v[100:101], 1.0 op_sel_hi:[1,0]
	v_pk_add_f32 v[100:101], v[106:107], 1.0 op_sel_hi:[1,0]
	v_mov_b32_e32 v104, v97
	v_mov_b32_e32 v105, v101
	v_mov_b32_e32 v106, v96
	v_mov_b32_e32 v107, v100
	v_pk_mul_f32 v[104:105], v[104:105], v[106:107]
	v_pk_mul_f32 v[86:87], v[94:95], v[86:87]
	v_mul_f32_e32 v106, v104, v105
	v_rcp_f32_e32 v106, v106
	v_pk_mul_f32 v[84:85], v[92:93], v[84:85]
	v_mul_f32_e32 v92, v105, v106
	v_mul_f32_e32 v94, v104, v106
	v_pk_mul_f32 v[94:95], v[100:101], v[94:95] op_sel_hi:[1,0]
	v_pk_mul_f32 v[92:93], v[96:97], v[92:93] op_sel_hi:[1,0]
	v_pk_mul_f32 v[90:91], v[90:91], v[94:95]
	v_pk_mul_f32 v[88:89], v[88:89], v[92:93]
	v_pk_mul_f32 v[90:91], v[90:91], v[82:83]
	v_pk_mul_f32 v[82:83], v[88:89], v[80:81]
	v_cvt_pk_bf16_f32 v80, v84, v85
; __device__ __forceinline__ unsigned cvt_pk_bf16(float lo, float hi) { unsigned r; asm volatile("v_cvt_pk_bf16_f32 %0, %1, %2" : "=v"(r) : "v"(lo), "v"(hi)); return r; }
; __device__ __forceinline__ f32x4 sigmoid4(f32x4 x) {
;     f32x4 d;
; #pragma unroll
;     for (int j = 0; j < 4; ++j) d[j] = 1.0f + __expf(-fmaxf(x[j], -20.0f));
;     const float p01 = d[0] * d[1], p23 = d[2] * d[3], r = __builtin_amdgcn_rcpf(p01 * p23), r01 = r * p23, r23 = r * p01;
;     return (f32x4){r01 * d[1], r01 * d[0], r23 * d[3], r23 * d[2]};
; }
;     __device__ __forceinline__ void operator()(const f32x4 (&acc)[2][2][4][2], const Unit& u, int wr, int wc, int fr, int fq) const {
;     ...
;         for (int ai = 0; ai < 2; ++ai)
; #pragma unroll
;             for (int m = 0; m < 4; ++m) { bf16_t* rowp = O + (size_t)(row0 + ai * HALF + m * 16) * ldc + col0;
;                 f32x4 v0, v1;
; #pragma unroll
;                 for (int j = 0; j < 1; ++j) { v0 = acc[ai][0][m][0] * sigmoid4(acc[ai][0][m][0]) * acc[ai][1][m][0]; v1 = acc[ai][0][m][1] * sigmoid4(acc[ai][0][m][1]) * acc[ai][1][m][1]; }
;                 u32x4 w; w.x = cvt_pk_bf16(v0[0], v0[1]); w.y = cvt_pk_bf16(v0[2], v0[3]); w.z = cvt_pk_bf16(v1[0], v1[1]); w.w = cvt_pk_bf16(v1[2], v1[3]);
;                 *(u32x4*)rowp = w; }
	v_cvt_pk_bf16_f32 v81, v86, v87
	v_max_f32_e32 v84, v76, v76
	v_max_f32_e32 v86, v78, v78
	v_max_f32_e32 v84, 0xc1a00000, v84
	v_max_f32_e32 v86, 0xc1a00000, v86
	v_mul_f32_e32 v84, 0xbfb8aa3b, v84
	v_mul_f32_e32 v86, 0xbfb8aa3b, v86
	v_exp_f32_e32 v85, v84
	v_max_f32_e32 v84, v77, v77
	v_exp_f32_e32 v87, v86
	v_max_f32_e32 v86, v79, v79
	v_max_f32_e32 v84, 0xc1a00000, v84
	v_max_f32_e32 v86, 0xc1a00000, v86
	v_mul_f32_e32 v84, 0xbfb8aa3b, v84
	v_mul_f32_e32 v86, 0xbfb8aa3b, v86
	v_exp_f32_e32 v84, v84
	v_exp_f32_e32 v86, v86
	v_cvt_pk_bf16_f32 v82, v82, v83
	v_cvt_pk_bf16_f32 v83, v90, v91
	global_store_dwordx4 v[102:103], v[80:83], off
	v_or_b32_e32 v88, 48, v155
	s_nop 0
	v_pk_add_f32 v[80:81], v[84:85], 1.0 op_sel_hi:[1,0]
	v_pk_add_f32 v[82:83], v[86:87], 1.0 op_sel_hi:[1,0]
	v_mov_b32_e32 v84, v81
	v_mov_b32_e32 v85, v83
	v_mov_b32_e32 v86, v80
	v_mov_b32_e32 v87, v82
	v_pk_mul_f32 v[84:85], v[84:85], v[86:87]
	s_nop 0
	v_mul_f32_e32 v86, v84, v85
	v_rcp_f32_e32 v89, v86
	v_mad_i64_i32 v[86:87], s[28:29], v88, s52, v[144:145]
	v_lshl_add_u64 v[86:87], v[86:87], 0, v[146:147]
	v_mul_f32_e32 v84, v84, v89
	v_mul_f32_e32 v88, v85, v89
	v_pk_mul_f32 v[82:83], v[82:83], v[84:85] op_sel_hi:[1,0]
	v_max_f32_e32 v84, v72, v72
	v_max_f32_e32 v89, v74, v74
	v_max_f32_e32 v84, 0xc1a00000, v84
	v_max_f32_e32 v89, 0xc1a00000, v89
	v_mul_f32_e32 v84, 0xbfb8aa3b, v84
	v_mul_f32_e32 v89, 0xbfb8aa3b, v89
	v_exp_f32_e32 v85, v84
	v_max_f32_e32 v84, v73, v73
	v_exp_f32_e32 v91, v89
	v_max_f32_e32 v89, v75, v75
	v_max_f32_e32 v84, 0xc1a00000, v84
	v_max_f32_e32 v89, 0xc1a00000, v89
	v_mul_f32_e32 v84, 0xbfb8aa3b, v84
	v_mul_f32_e32 v89, 0xbfb8aa3b, v89
	v_exp_f32_e32 v84, v84
	v_exp_f32_e32 v90, v89
	v_pk_mul_f32 v[80:81], v[80:81], v[88:89] op_sel_hi:[1,0]
	v_pk_mul_f32 v[78:79], v[78:79], v[82:83]
	v_pk_mul_f32 v[76:77], v[76:77], v[80:81]
	v_pk_add_f32 v[80:81], v[84:85], 1.0 op_sel_hi:[1,0]
	v_pk_add_f32 v[84:85], v[90:91], 1.0 op_sel_hi:[1,0]
	v_mov_b32_e32 v88, v81
	v_mov_b32_e32 v89, v85
	v_mov_b32_e32 v90, v80
	v_mov_b32_e32 v91, v84
	v_pk_mul_f32 v[88:89], v[88:89], v[90:91]
	v_pk_mul_f32 v[70:71], v[78:79], v[70:71]
	v_mul_f32_e32 v90, v88, v89
	v_rcp_f32_e32 v90, v90
	v_pk_mul_f32 v[68:69], v[76:77], v[68:69]
	v_mul_f32_e32 v76, v89, v90
	v_mul_f32_e32 v78, v88, v90
	v_pk_mul_f32 v[78:79], v[84:85], v[78:79] op_sel_hi:[1,0]
	v_pk_mul_f32 v[76:77], v[80:81], v[76:77] op_sel_hi:[1,0]
	v_pk_mul_f32 v[74:75], v[74:75], v[78:79]
	v_pk_mul_f32 v[72:73], v[72:73], v[76:77]
	v_pk_mul_f32 v[74:75], v[74:75], v[66:67]
	v_pk_mul_f32 v[66:67], v[72:73], v[64:65]
	v_cvt_pk_bf16_f32 v64, v68, v69
	v_cvt_pk_bf16_f32 v65, v70, v71
	v_max_f32_e32 v68, v60, v60
	v_max_f32_e32 v70, v62, v62
	v_max_f32_e32 v68, 0xc1a00000, v68
	v_max_f32_e32 v70, 0xc1a00000, v70
	v_mul_f32_e32 v68, 0xbfb8aa3b, v68
	v_mul_f32_e32 v70, 0xbfb8aa3b, v70
	v_exp_f32_e32 v69, v68
	v_max_f32_e32 v68, v61, v61
	v_exp_f32_e32 v71, v70
	v_max_f32_e32 v70, v63, v63
	v_max_f32_e32 v68, 0xc1a00000, v68
	v_max_f32_e32 v70, 0xc1a00000, v70
	v_mul_f32_e32 v68, 0xbfb8aa3b, v68
	v_mul_f32_e32 v70, 0xbfb8aa3b, v70
	v_exp_f32_e32 v68, v68
	v_exp_f32_e32 v70, v70
	v_cvt_pk_bf16_f32 v66, v66, v67
	v_cvt_pk_bf16_f32 v67, v74, v75
	global_store_dwordx4 v[86:87], v[64:67], off
	v_add_u32_e32 v72, 0x80, v155
	s_nop 0
	v_pk_add_f32 v[64:65], v[68:69], 1.0 op_sel_hi:[1,0]
	v_pk_add_f32 v[66:67], v[70:71], 1.0 op_sel_hi:[1,0]
	v_mov_b32_e32 v68, v65
	v_mov_b32_e32 v69, v67
	v_mov_b32_e32 v70, v64
	v_mov_b32_e32 v71, v66
	v_pk_mul_f32 v[68:69], v[68:69], v[70:71]
	s_nop 0
	v_mul_f32_e32 v70, v68, v69
	v_rcp_f32_e32 v73, v70
	v_mad_i64_i32 v[70:71], s[28:29], v72, s52, v[144:145]
	v_lshl_add_u64 v[70:71], v[70:71], 0, v[146:147]
	v_mul_f32_e32 v68, v68, v73
	v_mul_f32_e32 v72, v69, v73
	v_pk_mul_f32 v[66:67], v[66:67], v[68:69] op_sel_hi:[1,0]
	v_max_f32_e32 v68, v56, v56
	v_max_f32_e32 v73, v58, v58
	v_max_f32_e32 v68, 0xc1a00000, v68
	v_max_f32_e32 v73, 0xc1a00000, v73
	v_mul_f32_e32 v68, 0xbfb8aa3b, v68
	v_mul_f32_e32 v73, 0xbfb8aa3b, v73
	v_exp_f32_e32 v69, v68
	v_max_f32_e32 v68, v57, v57
	v_exp_f32_e32 v75, v73
	v_max_f32_e32 v73, v59, v59
	v_max_f32_e32 v68, 0xc1a00000, v68
	v_max_f32_e32 v73, 0xc1a00000, v73
	v_mul_f32_e32 v68, 0xbfb8aa3b, v68
	v_mul_f32_e32 v73, 0xbfb8aa3b, v73
	v_exp_f32_e32 v68, v68
	v_exp_f32_e32 v74, v73
	v_pk_mul_f32 v[64:65], v[64:65], v[72:73] op_sel_hi:[1,0]
	v_pk_mul_f32 v[62:63], v[62:63], v[66:67]
	v_pk_mul_f32 v[60:61], v[60:61], v[64:65]
	v_pk_add_f32 v[64:65], v[68:69], 1.0 op_sel_hi:[1,0]
	v_pk_add_f32 v[68:69], v[74:75], 1.0 op_sel_hi:[1,0]
	v_mov_b32_e32 v72, v65
	v_mov_b32_e32 v73, v69
	v_mov_b32_e32 v74, v64
	v_mov_b32_e32 v75, v68
	v_pk_mul_f32 v[72:73], v[72:73], v[74:75]
	v_pk_mul_f32 v[54:55], v[62:63], v[54:55]
	v_mul_f32_e32 v74, v72, v73
	v_rcp_f32_e32 v74, v74
	v_pk_mul_f32 v[52:53], v[60:61], v[52:53]
	v_mul_f32_e32 v60, v73, v74
	v_mul_f32_e32 v62, v72, v74
	v_pk_mul_f32 v[62:63], v[68:69], v[62:63] op_sel_hi:[1,0]
	v_pk_mul_f32 v[60:61], v[64:65], v[60:61] op_sel_hi:[1,0]
	v_pk_mul_f32 v[58:59], v[58:59], v[62:63]
	v_pk_mul_f32 v[56:57], v[56:57], v[60:61]
	v_pk_mul_f32 v[58:59], v[58:59], v[50:51]
	v_pk_mul_f32 v[50:51], v[56:57], v[48:49]
	v_cvt_pk_bf16_f32 v48, v52, v53
	v_cvt_pk_bf16_f32 v49, v54, v55
	v_max_f32_e32 v52, v44, v44
	v_max_f32_e32 v54, v46, v46
	v_max_f32_e32 v52, 0xc1a00000, v52
	v_max_f32_e32 v54, 0xc1a00000, v54
	v_mul_f32_e32 v52, 0xbfb8aa3b, v52
	v_mul_f32_e32 v54, 0xbfb8aa3b, v54
	v_exp_f32_e32 v53, v52
	v_max_f32_e32 v52, v45, v45
	v_exp_f32_e32 v55, v54
	v_max_f32_e32 v54, v47, v47
	v_max_f32_e32 v52, 0xc1a00000, v52
; __device__ __forceinline__ unsigned cvt_pk_bf16(float lo, float hi) { unsigned r; asm volatile("v_cvt_pk_bf16_f32 %0, %1, %2" : "=v"(r) : "v"(lo), "v"(hi)); return r; }
; __device__ __forceinline__ f32x4 sigmoid4(f32x4 x) {
;     f32x4 d;
; #pragma unroll
;     for (int j = 0; j < 4; ++j) d[j] = 1.0f + __expf(-fmaxf(x[j], -20.0f));
;     const float p01 = d[0] * d[1], p23 = d[2] * d[3], r = __builtin_amdgcn_rcpf(p01 * p23), r01 = r * p23, r23 = r * p01;
;     return (f32x4){r01 * d[1], r01 * d[0], r23 * d[3], r23 * d[2]};
; }
;     __device__ __forceinline__ void operator()(const f32x4 (&acc)[2][2][4][2], const Unit& u, int wr, int wc, int fr, int fq) const {
;     ...
;         for (int ai = 0; ai < 2; ++ai)
; #pragma unroll
;             for (int m = 0; m < 4; ++m) { bf16_t* rowp = O + (size_t)(row0 + ai * HALF + m * 16) * ldc + col0;
;                 f32x4 v0, v1;
; #pragma unroll
;                 for (int j = 0; j < 1; ++j) { v0 = acc[ai][0][m][0] * sigmoid4(acc[ai][0][m][0]) * acc[ai][1][m][0]; v1 = acc[ai][0][m][1] * sigmoid4(acc[ai][0][m][1]) * acc[ai][1][m][1]; }
;                 u32x4 w; w.x = cvt_pk_bf16(v0[0], v0[1]); w.y = cvt_pk_bf16(v0[2], v0[3]); w.z = cvt_pk_bf16(v1[0], v1[1]); w.w = cvt_pk_bf16(v1[2], v1[3]);
;                 *(u32x4*)rowp = w; }
	v_max_f32_e32 v54, 0xc1a00000, v54
	v_mul_f32_e32 v52, 0xbfb8aa3b, v52
	v_mul_f32_e32 v54, 0xbfb8aa3b, v54
	v_exp_f32_e32 v52, v52
	v_exp_f32_e32 v54, v54
	v_cvt_pk_bf16_f32 v50, v50, v51
	v_cvt_pk_bf16_f32 v51, v58, v59
	global_store_dwordx4 v[70:71], v[48:51], off
	v_add_u32_e32 v56, 0x90, v155
	s_nop 0
	v_pk_add_f32 v[48:49], v[52:53], 1.0 op_sel_hi:[1,0]
	v_pk_add_f32 v[50:51], v[54:55], 1.0 op_sel_hi:[1,0]
	v_mov_b32_e32 v52, v49
	v_mov_b32_e32 v53, v51
	v_mov_b32_e32 v54, v48
	v_mov_b32_e32 v55, v50
	v_pk_mul_f32 v[52:53], v[52:53], v[54:55]
	s_nop 0
	v_mul_f32_e32 v54, v52, v53
	v_rcp_f32_e32 v57, v54
	v_mad_i64_i32 v[54:55], s[28:29], v56, s52, v[144:145]
	v_lshl_add_u64 v[54:55], v[54:55], 0, v[146:147]
	v_mul_f32_e32 v52, v52, v57
	v_mul_f32_e32 v56, v53, v57
	v_pk_mul_f32 v[50:51], v[50:51], v[52:53] op_sel_hi:[1,0]
	v_max_f32_e32 v52, v40, v40
	v_max_f32_e32 v57, v42, v42
	v_max_f32_e32 v52, 0xc1a00000, v52
	v_max_f32_e32 v57, 0xc1a00000, v57
	v_mul_f32_e32 v52, 0xbfb8aa3b, v52
	v_mul_f32_e32 v57, 0xbfb8aa3b, v57
	v_exp_f32_e32 v53, v52
	v_max_f32_e32 v52, v41, v41
	v_exp_f32_e32 v59, v57
	v_max_f32_e32 v57, v43, v43
	v_max_f32_e32 v52, 0xc1a00000, v52
	v_max_f32_e32 v57, 0xc1a00000, v57
	v_mul_f32_e32 v52, 0xbfb8aa3b, v52
	v_mul_f32_e32 v57, 0xbfb8aa3b, v57
	v_exp_f32_e32 v52, v52
	v_exp_f32_e32 v58, v57
	v_pk_mul_f32 v[48:49], v[48:49], v[56:57] op_sel_hi:[1,0]
	v_pk_mul_f32 v[46:47], v[46:47], v[50:51]
	v_pk_mul_f32 v[44:45], v[44:45], v[48:49]
	v_pk_add_f32 v[48:49], v[52:53], 1.0 op_sel_hi:[1,0]
	v_pk_add_f32 v[52:53], v[58:59], 1.0 op_sel_hi:[1,0]
	v_mov_b32_e32 v56, v49
	v_mov_b32_e32 v57, v53
	v_mov_b32_e32 v58, v48
	v_mov_b32_e32 v59, v52
	v_pk_mul_f32 v[56:57], v[56:57], v[58:59]
	v_pk_mul_f32 v[38:39], v[46:47], v[38:39]
	v_mul_f32_e32 v58, v56, v57
	v_rcp_f32_e32 v58, v58
	v_pk_mul_f32 v[36:37], v[44:45], v[36:37]
	v_mul_f32_e32 v44, v57, v58
	v_mul_f32_e32 v46, v56, v58
	v_pk_mul_f32 v[46:47], v[52:53], v[46:47] op_sel_hi:[1,0]
	v_pk_mul_f32 v[44:45], v[48:49], v[44:45] op_sel_hi:[1,0]
	v_pk_mul_f32 v[42:43], v[42:43], v[46:47]
	v_pk_mul_f32 v[40:41], v[40:41], v[44:45]
	v_pk_mul_f32 v[42:43], v[42:43], v[34:35]
	v_pk_mul_f32 v[34:35], v[40:41], v[32:33]
	v_cvt_pk_bf16_f32 v32, v36, v37
	v_cvt_pk_bf16_f32 v33, v38, v39
	v_max_f32_e32 v36, v28, v28
	v_max_f32_e32 v38, v30, v30
	v_max_f32_e32 v36, 0xc1a00000, v36
	v_max_f32_e32 v38, 0xc1a00000, v38
	v_mul_f32_e32 v36, 0xbfb8aa3b, v36
	v_mul_f32_e32 v38, 0xbfb8aa3b, v38
	v_exp_f32_e32 v37, v36
	v_max_f32_e32 v36, v29, v29
	v_exp_f32_e32 v39, v38
	v_max_f32_e32 v38, v31, v31
	v_max_f32_e32 v36, 0xc1a00000, v36
	v_max_f32_e32 v38, 0xc1a00000, v38
	v_mul_f32_e32 v36, 0xbfb8aa3b, v36
	v_mul_f32_e32 v38, 0xbfb8aa3b, v38
	v_exp_f32_e32 v36, v36
	v_exp_f32_e32 v38, v38
	v_cvt_pk_bf16_f32 v34, v34, v35
	v_cvt_pk_bf16_f32 v35, v42, v43
	global_store_dwordx4 v[54:55], v[32:35], off
	v_add_u32_e32 v40, 0xa0, v155
	s_nop 0
	v_pk_add_f32 v[32:33], v[36:37], 1.0 op_sel_hi:[1,0]
	v_pk_add_f32 v[34:35], v[38:39], 1.0 op_sel_hi:[1,0]
	v_mov_b32_e32 v36, v33
	v_mov_b32_e32 v37, v35
	v_mov_b32_e32 v38, v32
	v_mov_b32_e32 v39, v34
	v_pk_mul_f32 v[36:37], v[36:37], v[38:39]
	s_nop 0
	v_mul_f32_e32 v38, v36, v37
	v_rcp_f32_e32 v41, v38
	v_mad_i64_i32 v[38:39], s[28:29], v40, s52, v[144:145]
	v_lshl_add_u64 v[38:39], v[38:39], 0, v[146:147]
	v_mul_f32_e32 v36, v36, v41
	v_mul_f32_e32 v40, v37, v41
	v_pk_mul_f32 v[34:35], v[34:35], v[36:37] op_sel_hi:[1,0]
	v_max_f32_e32 v36, v24, v24
	v_max_f32_e32 v41, v26, v26
	v_max_f32_e32 v36, 0xc1a00000, v36
	v_max_f32_e32 v41, 0xc1a00000, v41
	v_mul_f32_e32 v36, 0xbfb8aa3b, v36
	v_mul_f32_e32 v41, 0xbfb8aa3b, v41
	v_exp_f32_e32 v37, v36
	v_max_f32_e32 v36, v25, v25
	v_exp_f32_e32 v43, v41
	v_max_f32_e32 v41, v27, v27
	v_max_f32_e32 v36, 0xc1a00000, v36
	v_max_f32_e32 v41, 0xc1a00000, v41
	v_mul_f32_e32 v36, 0xbfb8aa3b, v36
; __device__ __forceinline__ unsigned cvt_pk_bf16(float lo, float hi) { unsigned r; asm volatile("v_cvt_pk_bf16_f32 %0, %1, %2" : "=v"(r) : "v"(lo), "v"(hi)); return r; }
; __device__ __forceinline__ f32x4 sigmoid4(f32x4 x) {
;     f32x4 d;
; #pragma unroll
;     for (int j = 0; j < 4; ++j) d[j] = 1.0f + __expf(-fmaxf(x[j], -20.0f));
;     const float p01 = d[0] * d[1], p23 = d[2] * d[3], r = __builtin_amdgcn_rcpf(p01 * p23), r01 = r * p23, r23 = r * p01;
;     return (f32x4){r01 * d[1], r01 * d[0], r23 * d[3], r23 * d[2]};
; }
;     __device__ __forceinline__ void operator()(const f32x4 (&acc)[2][2][4][2], const Unit& u, int wr, int wc, int fr, int fq) const {
;     ...
;         for (int ai = 0; ai < 2; ++ai)
; #pragma unroll
;             for (int m = 0; m < 4; ++m) { bf16_t* rowp = O + (size_t)(row0 + ai * HALF + m * 16) * ldc + col0;
;                 f32x4 v0, v1;
; #pragma unroll
;                 for (int j = 0; j < 1; ++j) { v0 = acc[ai][0][m][0] * sigmoid4(acc[ai][0][m][0]) * acc[ai][1][m][0]; v1 = acc[ai][0][m][1] * sigmoid4(acc[ai][0][m][1]) * acc[ai][1][m][1]; }
;                 u32x4 w; w.x = cvt_pk_bf16(v0[0], v0[1]); w.y = cvt_pk_bf16(v0[2], v0[3]); w.z = cvt_pk_bf16(v1[0], v1[1]); w.w = cvt_pk_bf16(v1[2], v1[3]);
;                 *(u32x4*)rowp = w; }
	v_mul_f32_e32 v41, 0xbfb8aa3b, v41
	v_exp_f32_e32 v36, v36
	v_exp_f32_e32 v42, v41
	v_pk_mul_f32 v[32:33], v[32:33], v[40:41] op_sel_hi:[1,0]
	v_pk_mul_f32 v[30:31], v[30:31], v[34:35]
	v_pk_mul_f32 v[28:29], v[28:29], v[32:33]
	v_pk_add_f32 v[32:33], v[36:37], 1.0 op_sel_hi:[1,0]
	v_pk_add_f32 v[36:37], v[42:43], 1.0 op_sel_hi:[1,0]
	v_mov_b32_e32 v40, v33
	v_mov_b32_e32 v41, v37
	v_mov_b32_e32 v42, v32
	v_mov_b32_e32 v43, v36
	v_pk_mul_f32 v[40:41], v[40:41], v[42:43]
	v_pk_mul_f32 v[22:23], v[30:31], v[22:23]
	v_mul_f32_e32 v42, v40, v41
	v_rcp_f32_e32 v42, v42
	v_pk_mul_f32 v[20:21], v[28:29], v[20:21]
	v_mul_f32_e32 v28, v41, v42
	v_mul_f32_e32 v30, v40, v42
	v_pk_mul_f32 v[30:31], v[36:37], v[30:31] op_sel_hi:[1,0]
	v_pk_mul_f32 v[28:29], v[32:33], v[28:29] op_sel_hi:[1,0]
	v_pk_mul_f32 v[26:27], v[26:27], v[30:31]
	v_pk_mul_f32 v[24:25], v[24:25], v[28:29]
	v_pk_mul_f32 v[26:27], v[26:27], v[18:19]
	v_pk_mul_f32 v[18:19], v[24:25], v[16:17]
	v_cvt_pk_bf16_f32 v16, v20, v21
	v_cvt_pk_bf16_f32 v17, v22, v23
	v_max_f32_e32 v20, v12, v12
	v_max_f32_e32 v22, v14, v14
	v_max_f32_e32 v20, 0xc1a00000, v20
	v_max_f32_e32 v22, 0xc1a00000, v22
	v_mul_f32_e32 v20, 0xbfb8aa3b, v20
	v_mul_f32_e32 v22, 0xbfb8aa3b, v22
	v_exp_f32_e32 v21, v20
	v_max_f32_e32 v20, v13, v13
	v_exp_f32_e32 v23, v22
	v_max_f32_e32 v22, v15, v15
	v_max_f32_e32 v20, 0xc1a00000, v20
	v_max_f32_e32 v22, 0xc1a00000, v22
	v_mul_f32_e32 v20, 0xbfb8aa3b, v20
	v_mul_f32_e32 v22, 0xbfb8aa3b, v22
	v_exp_f32_e32 v20, v20
	v_exp_f32_e32 v22, v22
	v_cvt_pk_bf16_f32 v18, v18, v19
	v_cvt_pk_bf16_f32 v19, v26, v27
	global_store_dwordx4 v[38:39], v[16:19], off
	v_add_u32_e32 v24, 0xb0, v155
	s_nop 0
	v_pk_add_f32 v[16:17], v[20:21], 1.0 op_sel_hi:[1,0]
	v_pk_add_f32 v[18:19], v[22:23], 1.0 op_sel_hi:[1,0]
	v_mov_b32_e32 v20, v17
	v_mov_b32_e32 v21, v19
	v_mov_b32_e32 v22, v16
	v_mov_b32_e32 v23, v18
	v_pk_mul_f32 v[20:21], v[20:21], v[22:23]
	s_nop 0
	v_mul_f32_e32 v22, v20, v21
	v_rcp_f32_e32 v25, v22
	v_mad_i64_i32 v[22:23], s[28:29], v24, s52, v[144:145]
	v_lshl_add_u64 v[22:23], v[22:23], 0, v[146:147]
	v_mul_f32_e32 v20, v20, v25
	v_mul_f32_e32 v24, v21, v25
	v_pk_mul_f32 v[18:19], v[18:19], v[20:21] op_sel_hi:[1,0]
	v_max_f32_e32 v20, v8, v8
	v_max_f32_e32 v25, v10, v10
	v_max_f32_e32 v20, 0xc1a00000, v20
	v_max_f32_e32 v25, 0xc1a00000, v25
	v_mul_f32_e32 v20, 0xbfb8aa3b, v20
	v_mul_f32_e32 v25, 0xbfb8aa3b, v25
	v_exp_f32_e32 v21, v20
	v_max_f32_e32 v20, v9, v9
	v_exp_f32_e32 v27, v25
	v_max_f32_e32 v25, v11, v11
	v_max_f32_e32 v20, 0xc1a00000, v20
	v_max_f32_e32 v25, 0xc1a00000, v25
	v_mul_f32_e32 v20, 0xbfb8aa3b, v20
	v_mul_f32_e32 v25, 0xbfb8aa3b, v25
	v_exp_f32_e32 v20, v20
	v_exp_f32_e32 v26, v25
	v_pk_mul_f32 v[16:17], v[16:17], v[24:25] op_sel_hi:[1,0]
	v_pk_mul_f32 v[14:15], v[14:15], v[18:19]
	v_pk_mul_f32 v[12:13], v[12:13], v[16:17]
	v_pk_add_f32 v[16:17], v[20:21], 1.0 op_sel_hi:[1,0]
	v_pk_add_f32 v[20:21], v[26:27], 1.0 op_sel_hi:[1,0]
	v_mov_b32_e32 v24, v17
	v_mov_b32_e32 v25, v21
	v_mov_b32_e32 v26, v16
	v_mov_b32_e32 v27, v20
	v_pk_mul_f32 v[24:25], v[24:25], v[26:27]
	v_pk_mul_f32 v[6:7], v[14:15], v[6:7]
	v_mul_f32_e32 v26, v24, v25
	v_rcp_f32_e32 v26, v26
	v_pk_mul_f32 v[4:5], v[12:13], v[4:5]
	s_mov_b64 s[28:29], s[18:19]
	v_mul_f32_e32 v12, v25, v26
	v_mul_f32_e32 v14, v24, v26
	v_pk_mul_f32 v[14:15], v[20:21], v[14:15] op_sel_hi:[1,0]
	v_pk_mul_f32 v[12:13], v[16:17], v[12:13] op_sel_hi:[1,0]
	v_pk_mul_f32 v[10:11], v[10:11], v[14:15]
	v_pk_mul_f32 v[8:9], v[8:9], v[12:13]
	v_pk_mul_f32 v[10:11], v[10:11], v[2:3]
	v_pk_mul_f32 v[2:3], v[8:9], v[0:1]
	v_cvt_pk_bf16_f32 v0, v4, v5
	v_cvt_pk_bf16_f32 v1, v6, v7
	s_nop 0
	v_cvt_pk_bf16_f32 v2, v2, v3
	v_cvt_pk_bf16_f32 v3, v10, v11
	global_store_dwordx4 v[22:23], v[0:3], off
	s_cbranch_vccz .LBB0_192
	s_waitcnt vmcnt(0)
	s_cmpk_gt_u32 s37, 0xff
	s_cbranch_scc1 .LBB0_199
	s_barrier

; #define PG8_STAGE(bufoff, gbase, voff) do { _Pragma("unroll") for (int _i = 0; _i < 2; ++_i) \
;         __builtin_amdgcn_global_load_lds((const unsigned*)((const char*)(gbase) + (voff)[_i]), (PG8_LAS unsigned*)(lds + (bufoff) + ldsw + _i * 8192), 16, 0, 0); } while (0)
; #define PG8_LDA(dst, b, h) do { _Pragma("unroll") for (int m = 0; m < 4; ++m) _Pragma("unroll") for (int k = 0; k < 2; ++k) dst[m][k] = *(const PG8_LAS bf16x8*)(lds + PG8_SA(b, h) + aoff + m * 2048 + k * 1024); } while (0)
; #define PG8_LDB(dst, b, h) do { _Pragma("unroll") for (int n = 0; n < 2; ++n) _Pragma("unroll") for (int k = 0; k < 2; ++k) dst[n][k] = *(const PG8_LAS bf16x8*)(lds + PG8_SB(b, h) + boff + n * 2048 + k * 1024); } while (0)
; #define PG8_MMA(ai, bj, At, Bt) do { __builtin_amdgcn_s_setprio(1); _Pragma("unroll") for (int m = 0; m < 4; ++m) _Pragma("unroll") for (int n = 0; n < 2; ++n) _Pragma("unroll") for (int k = 0; k < 2; ++k) \
;         acc[ai][bj][m][n] = __builtin_amdgcn_mfma_f32_16x16x32_bf16(Bt[n][k], At[m][k], acc[ai][bj][m][n], 0, 0, 0); __builtin_amdgcn_s_setprio(0); } while (0)
; #define PG8_WAIT_L(n) asm volatile("s_waitcnt lgkmcnt(" #n ")" ::: "memory")
; #define PG8_BAR __builtin_amdgcn_s_barrier()
; #define PG8_SCHED __builtin_amdgcn_sched_barrier(0)
; template <class Epi, class Sched>
; __device__ __forceinline__ void gemm_phase(PG8_LAS unsigned char* lds, const Gemm g, const Sched& S, const Epi& E) {
;     ...
;             const bool last = (t == nt - 2);
;             const char* a1 = cA + (size_t)(t + 1) * kstep;
;             const char* a2 = last ? nA : cA + (size_t)(t + 2) * kstep; const char* b2 = last ? nB : cB + (size_t)(t + 2) * kstep;
;             const char* a3 = a2 + kstep; const char* b3 = b2 + kstep;
;             if (last && has_next) S.a_ready(nxt);
;             PG8_LDB(B0, 0, 0); PG8_SCHED; PG8_LDA(At, 0, 0); PG8_STAGE(PG8_SA(1, 1), a1 + hstep, voffA);
;             PG8_WAIT_L(8); PG8_BAR; PG8_WAIT_L(0); PG8_MMA(0, 0, At, B0); PG8_BAR; PG8_SCHED;
;             PG8_LDB(B1, 0, 1); PG8_STAGE(PG8_SB(0, 0), b2, voffB);
;             PG8_BAR; PG8_WAIT_L(0); PG8_MMA(0, 1, At, B1); PG8_BAR;
;             PG8_LDA(At, 0, 1); PG8_STAGE(PG8_SA(0, 0), a2, voffA);
;             PG8_BAR; PG8_WAIT_L(0); PG8_MMA(1, 0, At, B0); PG8_BAR; PG8_SCHED;
.LBB0_286:
	ds_read_b128 v[154:157], v149
	ds_read_b128 v[158:161], v149 offset:1024
	ds_read_b128 v[166:169], v149 offset:2048
	ds_read_b128 v[170:173], v149 offset:3072
	ds_read_b128 v[182:185], v150
	ds_read_b128 v[190:193], v150 offset:1024
	ds_read_b128 v[194:197], v150 offset:2048
	ds_read_b128 v[198:201], v150 offset:3072
	ds_read_b128 v[202:205], v150 offset:4096
	ds_read_b128 v[206:209], v150 offset:5120
	ds_read_b128 v[210:213], v150 offset:6144
	ds_read_b128 v[214:217], v150 offset:7168
	s_add_u32 s24, s22, 0x100
	s_addc_u32 s25, s23, 0
	s_cmp_eq_u32 s57, 40
	s_cselect_b32 s29, s1, s25
	s_cselect_b32 s28, s0, s24
	s_cselect_b32 s27, s5, s56
	s_cselect_b32 s26, s4, s55
	v_lshl_add_u64 v[144:145], s[22:23], 0, v[136:137]
	s_add_i32 m0, s38, 0xc000
	s_nop 0
	global_load_lds_dwordx4 v[144:145], off
	v_lshl_add_u64 v[144:145], s[22:23], 0, v[138:139]
	s_add_i32 m0, s38, 0xe000
	s_nop 0
	global_load_lds_dwordx4 v[144:145], off
	s_waitcnt lgkmcnt(8)
	s_barrier
	s_waitcnt lgkmcnt(0)
	v_mfma_f32_16x16x32_bf16 v[124:127], v[154:157], v[182:185], v[124:127]
	v_mfma_f32_16x16x32_bf16 v[120:123], v[166:169], v[182:185], v[120:123]
	v_mfma_f32_16x16x32_bf16 v[108:111], v[154:157], v[194:197], v[108:111]
	v_mfma_f32_16x16x32_bf16 v[104:107], v[166:169], v[194:197], v[104:107]
	v_mfma_f32_16x16x32_bf16 v[92:95], v[154:157], v[202:205], v[92:95]
	v_mfma_f32_16x16x32_bf16 v[88:91], v[166:169], v[202:205], v[88:91]
	v_mfma_f32_16x16x32_bf16 v[76:79], v[154:157], v[210:213], v[76:79]
	v_mfma_f32_16x16x32_bf16 v[72:75], v[166:169], v[210:213], v[72:75]
	v_mfma_f32_16x16x32_bf16 v[124:127], v[158:161], v[190:193], v[124:127]
	v_mfma_f32_16x16x32_bf16 v[120:123], v[170:173], v[190:193], v[120:123]
	v_mfma_f32_16x16x32_bf16 v[108:111], v[158:161], v[198:201], v[108:111]
	v_mfma_f32_16x16x32_bf16 v[104:107], v[170:173], v[198:201], v[104:107]
	v_mfma_f32_16x16x32_bf16 v[92:95], v[158:161], v[206:209], v[92:95]
	v_mfma_f32_16x16x32_bf16 v[88:91], v[170:173], v[206:209], v[88:91]
	v_mfma_f32_16x16x32_bf16 v[76:79], v[158:161], v[214:217], v[76:79]
	v_mfma_f32_16x16x32_bf16 v[72:75], v[170:173], v[214:217], v[72:75]
	s_barrier
	ds_read_b128 v[218:221], v151
	ds_read_b128 v[222:225], v151 offset:1024
	ds_read_b128 v[226:229], v151 offset:2048
	ds_read_b128 v[230:233], v151 offset:3072
	s_add_i32 s22, s46, s37
	v_lshl_add_u64 v[144:145], s[26:27], 0, v[130:131]
	s_mov_b32 m0, s22
	s_nop 0
	global_load_lds_dwordx4 v[144:145], off
	v_lshl_add_u64 v[162:163], s[26:27], 0, v[134:135]
	s_add_i32 m0, s22, 0x2000
	s_nop 0
	global_load_lds_dwordx4 v[162:163], off
	s_barrier
	s_waitcnt lgkmcnt(0)
	v_mfma_f32_16x16x32_bf16 v[116:119], v[218:221], v[182:185], v[116:119]
	v_mfma_f32_16x16x32_bf16 v[112:115], v[226:229], v[182:185], v[112:115]
	v_mfma_f32_16x16x32_bf16 v[100:103], v[218:221], v[194:197], v[100:103]
	v_mfma_f32_16x16x32_bf16 v[96:99], v[226:229], v[194:197], v[96:99]
	v_mfma_f32_16x16x32_bf16 v[84:87], v[218:221], v[202:205], v[84:87]
	v_mfma_f32_16x16x32_bf16 v[80:83], v[226:229], v[202:205], v[80:83]
	v_mfma_f32_16x16x32_bf16 v[68:71], v[218:221], v[210:213], v[68:71]
	v_mfma_f32_16x16x32_bf16 v[64:67], v[226:229], v[210:213], v[64:67]
	v_mfma_f32_16x16x32_bf16 v[116:119], v[222:225], v[190:193], v[116:119]
	v_mfma_f32_16x16x32_bf16 v[112:115], v[230:233], v[190:193], v[112:115]
	v_mfma_f32_16x16x32_bf16 v[100:103], v[222:225], v[198:201], v[100:103]
	v_mfma_f32_16x16x32_bf16 v[96:99], v[230:233], v[198:201], v[96:99]
	v_mfma_f32_16x16x32_bf16 v[84:87], v[222:225], v[206:209], v[84:87]
	v_mfma_f32_16x16x32_bf16 v[80:83], v[230:233], v[206:209], v[80:83]
	v_mfma_f32_16x16x32_bf16 v[68:71], v[222:225], v[214:217], v[68:71]
	v_mfma_f32_16x16x32_bf16 v[64:67], v[230:233], v[214:217], v[64:67]
	s_mov_b32 m0, s38
	v_lshl_add_u64 v[174:175], s[28:29], 0, v[128:129]
	s_barrier
	ds_read_b128 v[182:185], v150 offset:16384
	ds_read_b128 v[190:193], v150 offset:17408
	ds_read_b128 v[194:197], v150 offset:18432
	ds_read_b128 v[198:201], v150 offset:19456
	ds_read_b128 v[202:205], v150 offset:20480
	ds_read_b128 v[206:209], v150 offset:21504
	ds_read_b128 v[210:213], v150 offset:22528
	ds_read_b128 v[214:217], v150 offset:23552
	global_load_lds_dwordx4 v[174:175], off
	v_lshl_add_u64 v[178:179], s[28:29], 0, v[132:133]
	s_mov_b32 m0, s39
	s_nop 0
	global_load_lds_dwordx4 v[178:179], off
	s_barrier
	s_waitcnt lgkmcnt(0)
	v_mfma_f32_16x16x32_bf16 v[60:63], v[154:157], v[182:185], v[60:63]
	v_mfma_f32_16x16x32_bf16 v[56:59], v[166:169], v[182:185], v[56:59]
	v_mfma_f32_16x16x32_bf16 v[48:51], v[154:157], v[194:197], v[48:51]
	v_mfma_f32_16x16x32_bf16 v[40:43], v[166:169], v[194:197], v[40:43]
	v_mfma_f32_16x16x32_bf16 v[32:35], v[154:157], v[202:205], v[32:35]
	v_mfma_f32_16x16x32_bf16 v[24:27], v[166:169], v[202:205], v[24:27]
	v_mfma_f32_16x16x32_bf16 v[16:19], v[154:157], v[210:213], v[16:19]
	v_mfma_f32_16x16x32_bf16 v[8:11], v[166:169], v[210:213], v[8:11]
	v_mfma_f32_16x16x32_bf16 v[60:63], v[158:161], v[190:193], v[60:63]
	v_mfma_f32_16x16x32_bf16 v[56:59], v[170:173], v[190:193], v[56:59]
	v_mfma_f32_16x16x32_bf16 v[48:51], v[158:161], v[198:201], v[48:51]
	v_mfma_f32_16x16x32_bf16 v[40:43], v[170:173], v[198:201], v[40:43]
	v_mfma_f32_16x16x32_bf16 v[32:35], v[158:161], v[206:209], v[32:35]
	v_mfma_f32_16x16x32_bf16 v[24:27], v[170:173], v[206:209], v[24:27]
	v_mfma_f32_16x16x32_bf16 v[16:19], v[158:161], v[214:217], v[16:19]
	v_mfma_f32_16x16x32_bf16 v[8:11], v[170:173], v[214:217], v[8:11]
	s_barrier
; #define PG8_STAGE(bufoff, gbase, voff) do { _Pragma("unroll") for (int _i = 0; _i < 2; ++_i) \
;         __builtin_amdgcn_global_load_lds((const unsigned*)((const char*)(gbase) + (voff)[_i]), (PG8_LAS unsigned*)(lds + (bufoff) + ldsw + _i * 8192), 16, 0, 0); } while (0)
; #define PG8_LDA(dst, b, h) do { _Pragma("unroll") for (int m = 0; m < 4; ++m) _Pragma("unroll") for (int k = 0; k < 2; ++k) dst[m][k] = *(const PG8_LAS bf16x8*)(lds + PG8_SA(b, h) + aoff + m * 2048 + k * 1024); } while (0)
; #define PG8_LDB(dst, b, h) do { _Pragma("unroll") for (int n = 0; n < 2; ++n) _Pragma("unroll") for (int k = 0; k < 2; ++k) dst[n][k] = *(const PG8_LAS bf16x8*)(lds + PG8_SB(b, h) + boff + n * 2048 + k * 1024); } while (0)
; #define PG8_MMA(ai, bj, At, Bt) do { __builtin_amdgcn_s_setprio(1); _Pragma("unroll") for (int m = 0; m < 4; ++m) _Pragma("unroll") for (int n = 0; n < 2; ++n) _Pragma("unroll") for (int k = 0; k < 2; ++k) \
;         acc[ai][bj][m][n] = __builtin_amdgcn_mfma_f32_16x16x32_bf16(Bt[n][k], At[m][k], acc[ai][bj][m][n], 0, 0, 0); __builtin_amdgcn_s_setprio(0); } while (0)
; #define PG8_WAIT_V(n) asm volatile("s_waitcnt vmcnt(" #n ")" ::: "memory")
; #define PG8_WAIT_L(n) asm volatile("s_waitcnt lgkmcnt(" #n ")" ::: "memory")
; #define PG8_BAR __builtin_amdgcn_s_barrier()
; #define PG8_SCHED __builtin_amdgcn_sched_barrier(0)
; template <class Epi, class Sched>
; __device__ __forceinline__ void gemm_phase(PG8_LAS unsigned char* lds, const Gemm g, const Sched& S, const Epi& E) {
;     ...
;             PG8_STAGE(PG8_SB(0, 1), b2 + hstep, voffB);
;             PG8_WAIT_V(6); PG8_BAR; PG8_MMA(1, 1, At, B1); PG8_BAR;
;             PG8_LDB(B0, 1, 0); PG8_SCHED; PG8_LDA(At, 1, 0); PG8_STAGE(PG8_SA(0, 1), a2 + hstep, voffA);
;             PG8_WAIT_L(8); PG8_BAR; PG8_WAIT_L(0); PG8_MMA(0, 0, At, B0); PG8_BAR; PG8_SCHED;
;             PG8_LDB(B1, 1, 1); PG8_STAGE(PG8_SB(1, 0), b3, voffB);
;             PG8_BAR; PG8_WAIT_L(0); PG8_MMA(0, 1, At, B1); PG8_BAR;
;             PG8_LDA(At, 1, 1); PG8_STAGE(PG8_SA(1, 0), a3, voffA);
	s_add_u32 s22, s26, 0xb0000
	s_addc_u32 s23, s27, 0
	s_add_i32 s58, s47, s37
	v_lshl_add_u64 v[154:155], s[22:23], 0, v[130:131]
	s_mov_b32 m0, s58
	s_nop 0
	global_load_lds_dwordx4 v[154:155], off
	v_lshl_add_u64 v[154:155], s[22:23], 0, v[134:135]
	s_add_i32 m0, s58, 0x2000
	s_nop 0
	global_load_lds_dwordx4 v[154:155], off
	s_waitcnt vmcnt(6)
	s_barrier
	v_mfma_f32_16x16x32_bf16 v[52:55], v[218:221], v[182:185], v[52:55]
	v_mfma_f32_16x16x32_bf16 v[44:47], v[226:229], v[182:185], v[44:47]
	v_mfma_f32_16x16x32_bf16 v[36:39], v[218:221], v[194:197], v[36:39]
	v_mfma_f32_16x16x32_bf16 v[28:31], v[226:229], v[194:197], v[28:31]
	v_mfma_f32_16x16x32_bf16 v[20:23], v[218:221], v[202:205], v[20:23]
	v_mfma_f32_16x16x32_bf16 v[12:15], v[226:229], v[202:205], v[12:15]
	v_mfma_f32_16x16x32_bf16 v[4:7], v[218:221], v[210:213], v[4:7]
	v_mfma_f32_16x16x32_bf16 v[0:3], v[226:229], v[210:213], v[0:3]
	v_mfma_f32_16x16x32_bf16 v[52:55], v[222:225], v[190:193], v[52:55]
	v_mfma_f32_16x16x32_bf16 v[44:47], v[230:233], v[190:193], v[44:47]
	v_mfma_f32_16x16x32_bf16 v[36:39], v[222:225], v[198:201], v[36:39]
	v_mfma_f32_16x16x32_bf16 v[28:31], v[230:233], v[198:201], v[28:31]
	v_mfma_f32_16x16x32_bf16 v[20:23], v[222:225], v[206:209], v[20:23]
	v_mfma_f32_16x16x32_bf16 v[12:15], v[230:233], v[206:209], v[12:15]
	v_mfma_f32_16x16x32_bf16 v[4:7], v[222:225], v[214:217], v[4:7]
	v_mfma_f32_16x16x32_bf16 v[0:3], v[230:233], v[214:217], v[0:3]
	s_add_i32 s58, 0, 0x18000
	v_add_u32_e32 v153, s58, v147
	s_barrier
	ds_read_b128 v[154:157], v153
	ds_read_b128 v[158:161], v153 offset:1024
	ds_read_b128 v[166:169], v153 offset:2048
	ds_read_b128 v[170:173], v153 offset:3072
	ds_read_b128 v[182:185], v150 offset:32768
	ds_read_b128 v[190:193], v150 offset:33792
	ds_read_b128 v[194:197], v150 offset:34816
	ds_read_b128 v[198:201], v150 offset:35840
	ds_read_b128 v[202:205], v150 offset:36864
	ds_read_b128 v[206:209], v150 offset:37888
	ds_read_b128 v[210:213], v150 offset:38912
	ds_read_b128 v[214:217], v150 offset:39936
	s_add_u32 s22, s28, 0xb0000
	s_addc_u32 s23, s29, 0
	s_mov_b32 m0, s40
	v_lshl_add_u64 v[186:187], s[22:23], 0, v[128:129]
	global_load_lds_dwordx4 v[186:187], off
	v_lshl_add_u64 v[186:187], s[22:23], 0, v[132:133]
	s_mov_b32 m0, s41
	s_nop 0
	global_load_lds_dwordx4 v[186:187], off
	s_waitcnt lgkmcnt(8)
	s_barrier
	s_waitcnt lgkmcnt(0)
	v_mfma_f32_16x16x32_bf16 v[124:127], v[154:157], v[182:185], v[124:127]
	v_mfma_f32_16x16x32_bf16 v[120:123], v[166:169], v[182:185], v[120:123]
	v_mfma_f32_16x16x32_bf16 v[108:111], v[154:157], v[194:197], v[108:111]
	v_mfma_f32_16x16x32_bf16 v[104:107], v[166:169], v[194:197], v[104:107]
	v_mfma_f32_16x16x32_bf16 v[92:95], v[154:157], v[202:205], v[92:95]
	v_mfma_f32_16x16x32_bf16 v[88:91], v[166:169], v[202:205], v[88:91]
	v_mfma_f32_16x16x32_bf16 v[76:79], v[154:157], v[210:213], v[76:79]
	v_mfma_f32_16x16x32_bf16 v[72:75], v[166:169], v[210:213], v[72:75]
	v_mfma_f32_16x16x32_bf16 v[124:127], v[158:161], v[190:193], v[124:127]
	v_mfma_f32_16x16x32_bf16 v[120:123], v[170:173], v[190:193], v[120:123]
	v_mfma_f32_16x16x32_bf16 v[108:111], v[158:161], v[198:201], v[108:111]
	v_mfma_f32_16x16x32_bf16 v[104:107], v[170:173], v[198:201], v[104:107]
	v_mfma_f32_16x16x32_bf16 v[92:95], v[158:161], v[206:209], v[92:95]
	v_mfma_f32_16x16x32_bf16 v[88:91], v[170:173], v[206:209], v[88:91]
	v_mfma_f32_16x16x32_bf16 v[76:79], v[158:161], v[214:217], v[76:79]
	v_mfma_f32_16x16x32_bf16 v[72:75], v[170:173], v[214:217], v[72:75]
	s_barrier
	s_add_i32 s28, 0, 0x1c000
	v_add_u32_e32 v153, s28, v147
	ds_read_b128 v[218:221], v153
	ds_read_b128 v[222:225], v153 offset:1024
	ds_read_b128 v[226:229], v153 offset:2048
	ds_read_b128 v[230:233], v153 offset:3072
	s_add_i32 s22, s58, s37
	v_lshl_add_u64 v[144:145], v[144:145], 0, s[14:15]
	s_mov_b32 m0, s22
	s_nop 0
	global_load_lds_dwordx4 v[144:145], off
	v_lshl_add_u64 v[144:145], v[162:163], 0, s[14:15]
	s_add_i32 m0, s22, 0x2000
	s_nop 0
	global_load_lds_dwordx4 v[144:145], off
	s_barrier
	s_waitcnt lgkmcnt(0)
	v_mfma_f32_16x16x32_bf16 v[116:119], v[218:221], v[182:185], v[116:119]
	v_mfma_f32_16x16x32_bf16 v[112:115], v[226:229], v[182:185], v[112:115]
	v_mfma_f32_16x16x32_bf16 v[100:103], v[218:221], v[194:197], v[100:103]
	v_mfma_f32_16x16x32_bf16 v[96:99], v[226:229], v[194:197], v[96:99]
	v_mfma_f32_16x16x32_bf16 v[84:87], v[218:221], v[202:205], v[84:87]
	v_mfma_f32_16x16x32_bf16 v[80:83], v[226:229], v[202:205], v[80:83]
	v_mfma_f32_16x16x32_bf16 v[68:71], v[218:221], v[210:213], v[68:71]
	v_mfma_f32_16x16x32_bf16 v[64:67], v[226:229], v[210:213], v[64:67]
	v_mfma_f32_16x16x32_bf16 v[116:119], v[222:225], v[190:193], v[116:119]
	v_mfma_f32_16x16x32_bf16 v[112:115], v[230:233], v[190:193], v[112:115]
	v_mfma_f32_16x16x32_bf16 v[100:103], v[222:225], v[198:201], v[100:103]
	v_mfma_f32_16x16x32_bf16 v[96:99], v[230:233], v[198:201], v[96:99]
	v_mfma_f32_16x16x32_bf16 v[84:87], v[222:225], v[206:209], v[84:87]
	v_mfma_f32_16x16x32_bf16 v[80:83], v[230:233], v[206:209], v[80:83]
	v_mfma_f32_16x16x32_bf16 v[68:71], v[222:225], v[214:217], v[68:71]
	v_mfma_f32_16x16x32_bf16 v[64:67], v[230:233], v[214:217], v[64:67]
	s_mov_b32 m0, s43
	v_lshl_add_u64 v[144:145], v[174:175], 0, s[14:15]
	s_barrier
	ds_read_b128 v[182:185], v150 offset:49152
	ds_read_b128 v[190:193], v150 offset:50176
	ds_read_b128 v[194:197], v150 offset:51200
	ds_read_b128 v[198:201], v150 offset:52224
	ds_read_b128 v[202:205], v150 offset:53248
	ds_read_b128 v[206:209], v150 offset:54272
	ds_read_b128 v[210:213], v150 offset:55296
	ds_read_b128 v[214:217], v150 offset:56320
	global_load_lds_dwordx4 v[144:145], off
	v_lshl_add_u64 v[144:145], v[178:179], 0, s[14:15]
	s_mov_b32 m0, s44
	s_nop 0
	global_load_lds_dwordx4 v[144:145], off
	s_barrier
; __device__ __forceinline__ unsigned cvt_pk_bf16(float lo, float hi) { unsigned r; asm volatile("v_cvt_pk_bf16_f32 %0, %1, %2" : "=v"(r) : "v"(lo), "v"(hi)); return r; }
; __device__ __forceinline__ float flogsig16(float x) { return (fminf(x, 0.f) - __logf(1.0f + __expf(-fabsf(x)))) * 0.0625f; }
; #define PG8_STAGE(bufoff, gbase, voff) do { _Pragma("unroll") for (int _i = 0; _i < 2; ++_i) \
;         __builtin_amdgcn_global_load_lds((const unsigned*)((const char*)(gbase) + (voff)[_i]), (PG8_LAS unsigned*)(lds + (bufoff) + ldsw + _i * 8192), 16, 0, 0); } while (0)
; #define PG8_WAIT_V(n) asm volatile("s_waitcnt vmcnt(" #n ")" ::: "memory")
; #define PG8_WAIT_L(n) asm volatile("s_waitcnt lgkmcnt(" #n ")" ::: "memory")
; #define PG8_BAR __builtin_amdgcn_s_barrier()
; #define PG8_SCHED __builtin_amdgcn_sched_barrier(0)
;     __device__ __forceinline__ void operator()(const f32x4 (&acc)[2][2][4][2], const Unit& u, int wr, int wc, int fr, int fq) const {
;     ...
;             for (int m = 0; m < 4; ++m) { bf16_t* rowp = O + (size_t)(row0 + ai * HALF + m * 16) * ldc + col0;
; #pragma unroll
;                 for (int bj = 0; bj < 2; ++bj) { f32x4 v0 = acc[ai][bj][m][0] + bv[bj][0], v1 = acc[ai][bj][m][1] + bv[bj][1];
;                     if (act == 1) {
; #pragma unroll
;                         for (int j = 0; j < 1; ++j) { v0 = v0 * sigmoid4(v0); v1 = v1 * sigmoid4(v1); } }
;                     else if (act == 2) {
; #pragma unroll
;                         for (int j = 0; j < 1; ++j) { v0 = sigmoid4(v0); v1 = sigmoid4(v1); } }
;                     else if (act == 3) {
; #pragma unroll
;                         for (int j = 0; j < 4; ++j) { v0[j] = flogsig16(v0[j]); v1[j] = flogsig16(v1[j]); } }
;                     u32x4 w; w.x = cvt_pk_bf16(v0[0], v0[1]); w.y = cvt_pk_bf16(v0[2], v0[3]); w.z = cvt_pk_bf16(v1[0], v1[1]); w.w = cvt_pk_bf16(v1[2], v1[3]);
;                     *(u32x4*)(rowp + bj * HALF) = w; } }
; template <class Epi, class Sched>
; __device__ __forceinline__ void gemm_phase(PG8_LAS unsigned char* lds, const Gemm g, const Sched& S, const Epi& E) {
;     ...
;             PG8_BAR; PG8_WAIT_L(0); PG8_MMA(1, 0, At, B0); PG8_BAR; PG8_SCHED;
;             PG8_STAGE(PG8_SB(1, 1), b3 + hstep, voffB);
;             PG8_WAIT_V(6); PG8_BAR; PG8_MMA(1, 1, At, B1); PG8_BAR;
;     ...
;         if constexpr (!Epi::AFTER_DRAIN) { E(acc, cur, wr, wc, fr, fq); S.done(cur); }
	s_waitcnt lgkmcnt(0)
	v_mfma_f32_16x16x32_bf16 v[60:63], v[154:157], v[182:185], v[60:63]
	v_mfma_f32_16x16x32_bf16 v[56:59], v[166:169], v[182:185], v[56:59]
	v_mfma_f32_16x16x32_bf16 v[48:51], v[154:157], v[194:197], v[48:51]
	v_mfma_f32_16x16x32_bf16 v[40:43], v[166:169], v[194:197], v[40:43]
	v_mfma_f32_16x16x32_bf16 v[32:35], v[154:157], v[202:205], v[32:35]
	v_mfma_f32_16x16x32_bf16 v[24:27], v[166:169], v[202:205], v[24:27]
	v_mfma_f32_16x16x32_bf16 v[16:19], v[154:157], v[210:213], v[16:19]
	v_mfma_f32_16x16x32_bf16 v[8:11], v[166:169], v[210:213], v[8:11]
	v_mfma_f32_16x16x32_bf16 v[60:63], v[158:161], v[190:193], v[60:63]
	v_mfma_f32_16x16x32_bf16 v[56:59], v[170:173], v[190:193], v[56:59]
	v_mfma_f32_16x16x32_bf16 v[48:51], v[158:161], v[198:201], v[48:51]
	v_mfma_f32_16x16x32_bf16 v[40:43], v[170:173], v[198:201], v[40:43]
	v_mfma_f32_16x16x32_bf16 v[32:35], v[158:161], v[206:209], v[32:35]
	v_mfma_f32_16x16x32_bf16 v[24:27], v[170:173], v[206:209], v[24:27]
	v_mfma_f32_16x16x32_bf16 v[16:19], v[158:161], v[214:217], v[16:19]
	v_mfma_f32_16x16x32_bf16 v[8:11], v[170:173], v[214:217], v[8:11]
	s_barrier
	s_add_u32 s22, s26, 0xb0080
	s_addc_u32 s23, s27, 0
	s_add_i32 s26, s28, s37
	v_lshl_add_u64 v[144:145], s[22:23], 0, v[130:131]
	s_mov_b32 m0, s26
	s_nop 0
	global_load_lds_dwordx4 v[144:145], off
	v_lshl_add_u64 v[144:145], s[22:23], 0, v[134:135]
	s_add_i32 m0, s26, 0x2000
	s_nop 0
	global_load_lds_dwordx4 v[144:145], off
	s_waitcnt vmcnt(6)
	s_barrier
	v_mfma_f32_16x16x32_bf16 v[52:55], v[218:221], v[182:185], v[52:55]
	v_mfma_f32_16x16x32_bf16 v[44:47], v[226:229], v[182:185], v[44:47]
	v_mfma_f32_16x16x32_bf16 v[36:39], v[218:221], v[194:197], v[36:39]
	v_mfma_f32_16x16x32_bf16 v[28:31], v[226:229], v[194:197], v[28:31]
	v_mfma_f32_16x16x32_bf16 v[20:23], v[218:221], v[202:205], v[20:23]
	v_mfma_f32_16x16x32_bf16 v[12:15], v[226:229], v[202:205], v[12:15]
	v_mfma_f32_16x16x32_bf16 v[4:7], v[218:221], v[210:213], v[4:7]
	v_mfma_f32_16x16x32_bf16 v[0:3], v[226:229], v[210:213], v[0:3]
	v_mfma_f32_16x16x32_bf16 v[52:55], v[222:225], v[190:193], v[52:55]
	v_mfma_f32_16x16x32_bf16 v[44:47], v[230:233], v[190:193], v[44:47]
	v_mfma_f32_16x16x32_bf16 v[36:39], v[222:225], v[198:201], v[36:39]
	v_mfma_f32_16x16x32_bf16 v[28:31], v[230:233], v[198:201], v[28:31]
	v_mfma_f32_16x16x32_bf16 v[20:23], v[222:225], v[206:209], v[20:23]
	v_mfma_f32_16x16x32_bf16 v[12:15], v[230:233], v[206:209], v[12:15]
	v_mfma_f32_16x16x32_bf16 v[4:7], v[222:225], v[214:217], v[4:7]
	v_mfma_f32_16x16x32_bf16 v[0:3], v[230:233], v[214:217], v[0:3]
	s_add_i32 s57, s57, 2
	s_add_u32 s55, s55, 0x100
	s_addc_u32 s56, s56, 0
	s_cmp_gt_u32 s57, 41
	s_mov_b64 s[22:23], s[24:25]
	s_barrier
	s_cbranch_scc0 .LBB0_286
	v_lshl_add_u32 v154, s53, 8, v146
	v_lshl_or_b32 v144, s54, 8, v148
	v_ashrrev_i32_e32 v155, 31, v154
	v_ashrrev_i32_e32 v145, 31, v144
	v_lshlrev_b64 v[156:157], 11, v[154:155]
	v_lshl_add_u64 v[156:157], s[10:11], 0, v[156:157]
	v_lshlrev_b64 v[158:159], 1, v[144:145]
	v_lshl_add_u64 v[144:145], v[156:157], 0, v[158:159]
	v_pk_add_f32 v[126:127], v[126:127], 0 op_sel_hi:[1,0]
	v_pk_add_f32 v[124:125], v[124:125], 0 op_sel_hi:[1,0]
	v_pk_add_f32 v[156:157], v[122:123], 0 op_sel_hi:[1,0]
	v_pk_add_f32 v[122:123], v[120:121], 0 op_sel_hi:[1,0]
	v_cvt_pk_bf16_f32 v120, v124, v125
	v_cvt_pk_bf16_f32 v121, v126, v127
	v_pk_add_f32 v[116:117], v[116:117], 0 op_sel_hi:[1,0]
	v_cvt_pk_bf16_f32 v122, v122, v123
	v_cvt_pk_bf16_f32 v123, v156, v157
	global_store_dwordx4 v[144:145], v[120:123], off
	v_pk_add_f32 v[118:119], v[118:119], 0 op_sel_hi:[1,0]
	v_pk_add_f32 v[110:111], v[110:111], 0 op_sel_hi:[1,0]
	v_pk_add_f32 v[120:121], v[114:115], 0 op_sel_hi:[1,0]
	v_pk_add_f32 v[114:115], v[112:113], 0 op_sel_hi:[1,0]
	v_cvt_pk_bf16_f32 v112, v116, v117
	v_cvt_pk_bf16_f32 v113, v118, v119
	v_pk_add_f32 v[108:109], v[108:109], 0 op_sel_hi:[1,0]
	v_cvt_pk_bf16_f32 v114, v114, v115
	v_cvt_pk_bf16_f32 v115, v120, v121
	global_store_dwordx4 v[144:145], v[112:115], off offset:256
	v_pk_add_f32 v[100:101], v[100:101], 0 op_sel_hi:[1,0]
	v_pk_add_f32 v[102:103], v[102:103], 0 op_sel_hi:[1,0]
	v_or_b32_e32 v112, 16, v154
	v_ashrrev_i32_e32 v113, 31, v112
	v_lshlrev_b64 v[112:113], 11, v[112:113]
	v_lshl_add_u64 v[112:113], s[10:11], 0, v[112:113]
	v_lshl_add_u64 v[112:113], v[112:113], 0, v[158:159]
	v_pk_add_f32 v[114:115], v[106:107], 0 op_sel_hi:[1,0]
	v_pk_add_f32 v[106:107], v[104:105], 0 op_sel_hi:[1,0]
	v_cvt_pk_bf16_f32 v104, v108, v109
	v_cvt_pk_bf16_f32 v105, v110, v111
	v_pk_add_f32 v[94:95], v[94:95], 0 op_sel_hi:[1,0]
	v_cvt_pk_bf16_f32 v106, v106, v107
	v_cvt_pk_bf16_f32 v107, v114, v115
	global_store_dwordx4 v[112:113], v[104:107], off
	v_pk_add_f32 v[92:93], v[92:93], 0 op_sel_hi:[1,0]
	v_pk_add_f32 v[84:85], v[84:85], 0 op_sel_hi:[1,0]
	v_pk_add_f32 v[104:105], v[98:99], 0 op_sel_hi:[1,0]
	v_pk_add_f32 v[98:99], v[96:97], 0 op_sel_hi:[1,0]
	v_cvt_pk_bf16_f32 v96, v100, v101
	v_cvt_pk_bf16_f32 v97, v102, v103
	v_pk_add_f32 v[86:87], v[86:87], 0 op_sel_hi:[1,0]
	v_cvt_pk_bf16_f32 v98, v98, v99
	v_cvt_pk_bf16_f32 v99, v104, v105
	global_store_dwordx4 v[112:113], v[96:99], off offset:256
	v_pk_add_f32 v[78:79], v[78:79], 0 op_sel_hi:[1,0]
	v_pk_add_f32 v[76:77], v[76:77], 0 op_sel_hi:[1,0]
	v_or_b32_e32 v96, 32, v154
	v_ashrrev_i32_e32 v97, 31, v96
	v_lshlrev_b64 v[96:97], 11, v[96:97]
	v_lshl_add_u64 v[96:97], s[10:11], 0, v[96:97]
	v_lshl_add_u64 v[96:97], v[96:97], 0, v[158:159]
; __device__ __forceinline__ unsigned cvt_pk_bf16(float lo, float hi) { unsigned r; asm volatile("v_cvt_pk_bf16_f32 %0, %1, %2" : "=v"(r) : "v"(lo), "v"(hi)); return r; }
; __device__ __forceinline__ float flogsig16(float x) { return (fminf(x, 0.f) - __logf(1.0f + __expf(-fabsf(x)))) * 0.0625f; }
; #define PG8_WAIT_V(n) asm volatile("s_waitcnt vmcnt(" #n ")" ::: "memory")
; #define PG8_BAR __builtin_amdgcn_s_barrier()
;     __device__ __forceinline__ void operator()(const f32x4 (&acc)[2][2][4][2], const Unit& u, int wr, int wc, int fr, int fq) const {
;     ...
;         for (int ai = 0; ai < 2; ++ai)
; #pragma unroll
;             for (int m = 0; m < 4; ++m) { bf16_t* rowp = O + (size_t)(row0 + ai * HALF + m * 16) * ldc + col0;
; #pragma unroll
;                 for (int bj = 0; bj < 2; ++bj) { f32x4 v0 = acc[ai][bj][m][0] + bv[bj][0], v1 = acc[ai][bj][m][1] + bv[bj][1];
;                     if (act == 1) {
; #pragma unroll
;                         for (int j = 0; j < 1; ++j) { v0 = v0 * sigmoid4(v0); v1 = v1 * sigmoid4(v1); } }
;                     else if (act == 2) {
; #pragma unroll
;                         for (int j = 0; j < 1; ++j) { v0 = sigmoid4(v0); v1 = sigmoid4(v1); } }
;                     else if (act == 3) {
; #pragma unroll
;                         for (int j = 0; j < 4; ++j) { v0[j] = flogsig16(v0[j]); v1[j] = flogsig16(v1[j]); } }
;                     u32x4 w; w.x = cvt_pk_bf16(v0[0], v0[1]); w.y = cvt_pk_bf16(v0[2], v0[3]); w.z = cvt_pk_bf16(v1[0], v1[1]); w.w = cvt_pk_bf16(v1[2], v1[3]);
;                     *(u32x4*)(rowp + bj * HALF) = w; } }
; template <class Epi, class Sched>
; __device__ __forceinline__ void gemm_phase(PG8_LAS unsigned char* lds, const Gemm g, const Sched& S, const Epi& E) {
;     ...
;         if (!has_next) break;
;     ...
;     PG8_WAIT_V(0);
;     if (wr == 0) PG8_BAR;
;     PG8_BAR;
	v_pk_add_f32 v[98:99], v[90:91], 0 op_sel_hi:[1,0]
	v_pk_add_f32 v[90:91], v[88:89], 0 op_sel_hi:[1,0]
	v_cvt_pk_bf16_f32 v88, v92, v93
	v_cvt_pk_bf16_f32 v89, v94, v95
	v_pk_add_f32 v[70:71], v[70:71], 0 op_sel_hi:[1,0]
	v_cvt_pk_bf16_f32 v90, v90, v91
	v_cvt_pk_bf16_f32 v91, v98, v99
	global_store_dwordx4 v[96:97], v[88:91], off
	v_pk_add_f32 v[68:69], v[68:69], 0 op_sel_hi:[1,0]
	s_mov_b64 s[22:23], 0x40000
	v_pk_add_f32 v[88:89], v[82:83], 0 op_sel_hi:[1,0]
	v_pk_add_f32 v[82:83], v[80:81], 0 op_sel_hi:[1,0]
	v_cvt_pk_bf16_f32 v80, v84, v85
	v_cvt_pk_bf16_f32 v81, v86, v87
	v_pk_add_f32 v[60:61], v[60:61], 0 op_sel_hi:[1,0]
	v_cvt_pk_bf16_f32 v82, v82, v83
	v_cvt_pk_bf16_f32 v83, v88, v89
	global_store_dwordx4 v[96:97], v[80:83], off offset:256
	v_pk_add_f32 v[62:63], v[62:63], 0 op_sel_hi:[1,0]
	v_pk_add_f32 v[54:55], v[54:55], 0 op_sel_hi:[1,0]
	v_or_b32_e32 v80, 48, v154
	v_ashrrev_i32_e32 v81, 31, v80
	v_lshlrev_b64 v[80:81], 11, v[80:81]
	v_lshl_add_u64 v[80:81], s[10:11], 0, v[80:81]
	v_lshl_add_u64 v[80:81], v[80:81], 0, v[158:159]
	v_pk_add_f32 v[82:83], v[74:75], 0 op_sel_hi:[1,0]
	v_pk_add_f32 v[74:75], v[72:73], 0 op_sel_hi:[1,0]
	v_cvt_pk_bf16_f32 v72, v76, v77
	v_cvt_pk_bf16_f32 v73, v78, v79
	v_pk_add_f32 v[52:53], v[52:53], 0 op_sel_hi:[1,0]
	v_cvt_pk_bf16_f32 v74, v74, v75
	v_cvt_pk_bf16_f32 v75, v82, v83
	global_store_dwordx4 v[80:81], v[72:75], off
	v_pk_add_f32 v[48:49], v[48:49], 0 op_sel_hi:[1,0]
	v_pk_add_f32 v[38:39], v[38:39], 0 op_sel_hi:[1,0]
	v_pk_add_f32 v[72:73], v[66:67], 0 op_sel_hi:[1,0]
	v_pk_add_f32 v[66:67], v[64:65], 0 op_sel_hi:[1,0]
	v_cvt_pk_bf16_f32 v64, v68, v69
	v_cvt_pk_bf16_f32 v65, v70, v71
	v_pk_add_f32 v[36:37], v[36:37], 0 op_sel_hi:[1,0]
	v_cvt_pk_bf16_f32 v66, v66, v67
	v_cvt_pk_bf16_f32 v67, v72, v73
	global_store_dwordx4 v[80:81], v[64:67], off offset:256
	v_pk_add_f32 v[32:33], v[32:33], 0 op_sel_hi:[1,0]
	v_pk_add_f32 v[22:23], v[22:23], 0 op_sel_hi:[1,0]
	v_lshl_add_u64 v[64:65], v[144:145], 0, s[22:23]
	s_mov_b32 s22, 0x40000
	v_pk_add_f32 v[66:67], v[58:59], 0 op_sel_hi:[1,0]
	v_pk_add_f32 v[58:59], v[56:57], 0 op_sel_hi:[1,0]
	v_cvt_pk_bf16_f32 v56, v60, v61
	v_add_co_u32_e32 v60, vcc, s22, v144
	v_cvt_pk_bf16_f32 v57, v62, v63
	v_cvt_pk_bf16_f32 v58, v58, v59
	v_cvt_pk_bf16_f32 v59, v66, v67
	s_mov_b64 s[22:23], 0x48000
	s_nop 0
	v_addc_co_u32_e32 v61, vcc, 0, v145, vcc
	global_store_dwordx4 v[60:61], v[56:59], off
	v_pk_add_f32 v[20:21], v[20:21], 0 op_sel_hi:[1,0]
	v_pk_add_f32 v[16:17], v[16:17], 0 op_sel_hi:[1,0]
	v_pk_add_f32 v[56:57], v[46:47], 0 op_sel_hi:[1,0]
	v_pk_add_f32 v[46:47], v[44:45], 0 op_sel_hi:[1,0]
	v_cvt_pk_bf16_f32 v44, v52, v53
	v_cvt_pk_bf16_f32 v45, v54, v55
	s_mov_b32 s54, s51
	v_cvt_pk_bf16_f32 v46, v46, v47
	v_cvt_pk_bf16_f32 v47, v56, v57
	global_store_dwordx4 v[64:65], v[44:47], off offset:256
	s_mov_b32 s53, s52
	s_mov_b64 s[24:25], s[4:5]
	v_pk_add_f32 v[46:47], v[50:51], 0 op_sel_hi:[1,0]
	v_pk_add_f32 v[50:51], v[42:43], 0 op_sel_hi:[1,0]
	v_pk_add_f32 v[42:43], v[40:41], 0 op_sel_hi:[1,0]
	v_cvt_pk_bf16_f32 v40, v48, v49
	v_cvt_pk_bf16_f32 v41, v46, v47
	v_add_co_u32_e32 v46, vcc, s48, v144
	v_cvt_pk_bf16_f32 v42, v42, v43
	v_cvt_pk_bf16_f32 v43, v50, v51
	v_lshl_add_u64 v[44:45], v[144:145], 0, s[22:23]
	s_nop 0
	v_addc_co_u32_e32 v47, vcc, 0, v145, vcc
	global_store_dwordx4 v[46:47], v[40:43], off
	s_mov_b64 s[22:23], s[0:1]
	v_pk_add_f32 v[6:7], v[6:7], 0 op_sel_hi:[1,0]
	v_pk_add_f32 v[40:41], v[30:31], 0 op_sel_hi:[1,0]
	v_pk_add_f32 v[30:31], v[28:29], 0 op_sel_hi:[1,0]
	v_cvt_pk_bf16_f32 v28, v36, v37
	v_cvt_pk_bf16_f32 v29, v38, v39
	v_pk_add_f32 v[4:5], v[4:5], 0 op_sel_hi:[1,0]
	v_cvt_pk_bf16_f32 v30, v30, v31
	v_cvt_pk_bf16_f32 v31, v40, v41
	global_store_dwordx4 v[44:45], v[28:31], off offset:256
	s_nop 1
	v_pk_add_f32 v[30:31], v[34:35], 0 op_sel_hi:[1,0]
	v_pk_add_f32 v[34:35], v[26:27], 0 op_sel_hi:[1,0]
	v_pk_add_f32 v[26:27], v[24:25], 0 op_sel_hi:[1,0]
	v_cvt_pk_bf16_f32 v24, v32, v33
	v_cvt_pk_bf16_f32 v25, v30, v31
	v_add_co_u32_e32 v30, vcc, s49, v144
	v_cvt_pk_bf16_f32 v26, v26, v27
	v_cvt_pk_bf16_f32 v27, v34, v35
	v_lshl_add_u64 v[28:29], v[144:145], 0, s[16:17]
	s_nop 0
	v_addc_co_u32_e32 v31, vcc, 0, v145, vcc
	global_store_dwordx4 v[30:31], v[24:27], off
	s_nop 1
	v_pk_add_f32 v[24:25], v[14:15], 0 op_sel_hi:[1,0]
	v_pk_add_f32 v[14:15], v[12:13], 0 op_sel_hi:[1,0]
	v_cvt_pk_bf16_f32 v12, v20, v21
	v_cvt_pk_bf16_f32 v13, v22, v23
	s_nop 0
	v_cvt_pk_bf16_f32 v14, v14, v15
	v_cvt_pk_bf16_f32 v15, v24, v25
	global_store_dwordx4 v[28:29], v[12:15], off offset:256
	s_nop 1
	v_pk_add_f32 v[14:15], v[18:19], 0 op_sel_hi:[1,0]
	v_pk_add_f32 v[18:19], v[10:11], 0 op_sel_hi:[1,0]
	v_pk_add_f32 v[10:11], v[8:9], 0 op_sel_hi:[1,0]
	v_cvt_pk_bf16_f32 v8, v16, v17
	v_cvt_pk_bf16_f32 v9, v14, v15
	v_add_co_u32_e32 v14, vcc, s50, v144
	v_lshl_add_u64 v[12:13], v[144:145], 0, s[18:19]
	s_nop 0
	v_addc_co_u32_e32 v15, vcc, 0, v145, vcc
	v_cvt_pk_bf16_f32 v10, v10, v11
	v_cvt_pk_bf16_f32 v11, v18, v19
	global_store_dwordx4 v[14:15], v[8:11], off
	s_and_b64 vcc, exec, s[2:3]
	s_nop 0
	v_pk_add_f32 v[8:9], v[2:3], 0 op_sel_hi:[1,0]
	v_pk_add_f32 v[2:3], v[0:1], 0 op_sel_hi:[1,0]
	v_cvt_pk_bf16_f32 v0, v4, v5
	v_cvt_pk_bf16_f32 v1, v6, v7
	s_nop 0
	v_cvt_pk_bf16_f32 v2, v2, v3
	v_cvt_pk_bf16_f32 v3, v8, v9
	global_store_dwordx4 v[12:13], v[0:3], off offset:256
	s_cbranch_vccz .LBB0_275
	s_waitcnt vmcnt(0)
	s_cmpk_gt_u32 s31, 0xff
	s_cbranch_scc1 .LBB0_290
	s_barrier

; #define PG8_STAGE(bufoff, gbase, voff) do { _Pragma("unroll") for (int _i = 0; _i < 2; ++_i) \
;         __builtin_amdgcn_global_load_lds((const unsigned*)((const char*)(gbase) + (voff)[_i]), (PG8_LAS unsigned*)(lds + (bufoff) + ldsw + _i * 8192), 16, 0, 0); } while (0)
; #define PG8_LDA(dst, b, h) do { _Pragma("unroll") for (int m = 0; m < 4; ++m) _Pragma("unroll") for (int k = 0; k < 2; ++k) dst[m][k] = *(const PG8_LAS bf16x8*)(lds + PG8_SA(b, h) + aoff + m * 2048 + k * 1024); } while (0)
; #define PG8_LDB(dst, b, h) do { _Pragma("unroll") for (int n = 0; n < 2; ++n) _Pragma("unroll") for (int k = 0; k < 2; ++k) dst[n][k] = *(const PG8_LAS bf16x8*)(lds + PG8_SB(b, h) + boff + n * 2048 + k * 1024); } while (0)
; #define PG8_MMA(ai, bj, At, Bt) do { __builtin_amdgcn_s_setprio(1); _Pragma("unroll") for (int m = 0; m < 4; ++m) _Pragma("unroll") for (int n = 0; n < 2; ++n) _Pragma("unroll") for (int k = 0; k < 2; ++k) \
;         acc[ai][bj][m][n] = __builtin_amdgcn_mfma_f32_16x16x32_bf16(Bt[n][k], At[m][k], acc[ai][bj][m][n], 0, 0, 0); __builtin_amdgcn_s_setprio(0); } while (0)
; #define PG8_WAIT_V(n) asm volatile("s_waitcnt vmcnt(" #n ")" ::: "memory")
; #define PG8_WAIT_L(n) asm volatile("s_waitcnt lgkmcnt(" #n ")" ::: "memory")
; #define PG8_BAR __builtin_amdgcn_s_barrier()
; #define PG8_SCHED __builtin_amdgcn_sched_barrier(0)
; template <class Epi, class Sched>
; __device__ __forceinline__ void gemm_phase(PG8_LAS unsigned char* lds, const Gemm g, const Sched& S, const Epi& E) {
;     ...
;             PG8_LDB(B0, 0, 0); PG8_SCHED; PG8_LDA(At, 0, 0); PG8_STAGE(PG8_SA(1, 1), a1 + hstep, voffA);
;             PG8_WAIT_L(8); PG8_BAR; PG8_WAIT_L(0); PG8_MMA(0, 0, At, B0); PG8_BAR; PG8_SCHED;
;             PG8_LDB(B1, 0, 1); PG8_STAGE(PG8_SB(0, 0), b2, voffB);
;             PG8_BAR; PG8_WAIT_L(0); PG8_MMA(0, 1, At, B1); PG8_BAR;
;             PG8_LDA(At, 0, 1); PG8_STAGE(PG8_SA(0, 0), a2, voffA);
;             PG8_BAR; PG8_WAIT_L(0); PG8_MMA(1, 0, At, B0); PG8_BAR; PG8_SCHED;
;             PG8_STAGE(PG8_SB(0, 1), b2 + hstep, voffB);
;             PG8_WAIT_V(6); PG8_BAR; PG8_MMA(1, 1, At, B1); PG8_BAR;
.LBB0_416:
	ds_read_b128 v[24:27], v186
	ds_read_b128 v[28:31], v186 offset:1024
	ds_read_b128 v[40:43], v186 offset:2048
	ds_read_b128 v[44:47], v186 offset:3072
	ds_read_b128 v[144:147], v187
	ds_read_b128 v[148:151], v187 offset:1024
	ds_read_b128 v[182:185], v187 offset:2048
	ds_read_b128 v[192:195], v187 offset:3072
	ds_read_b128 v[196:199], v187 offset:4096
	ds_read_b128 v[200:203], v187 offset:5120
	ds_read_b128 v[204:207], v187 offset:6144
	ds_read_b128 v[208:211], v187 offset:7168
	s_add_u32 s4, s0, 0xfffc0080
	s_addc_u32 s5, s1, -1
	s_cmp_eq_u32 s53, 12
	s_cselect_b32 s29, s7, s5
	s_cselect_b32 s28, s10, s4
	s_cselect_b32 s5, s19, s52
	s_cselect_b32 s4, s21, s51
	v_lshl_add_u64 v[174:175], s[0:1], 0, v[166:167]
	s_add_i32 m0, s27, 0xc000
	s_nop 0
	global_load_lds_dwordx4 v[174:175], off
	v_lshl_add_u64 v[174:175], s[0:1], 0, v[168:169]
	s_add_i32 m0, s27, 0xe000
	s_nop 0
	global_load_lds_dwordx4 v[174:175], off
	s_waitcnt lgkmcnt(8)
	s_barrier
	s_waitcnt lgkmcnt(0)
	v_mfma_f32_16x16x32_bf16 v[140:143], v[24:27], v[144:147], v[140:143]
	v_mfma_f32_16x16x32_bf16 v[136:139], v[40:43], v[144:147], v[136:139]
	v_mfma_f32_16x16x32_bf16 v[124:127], v[24:27], v[182:185], v[124:127]
	v_mfma_f32_16x16x32_bf16 v[120:123], v[40:43], v[182:185], v[120:123]
	v_mfma_f32_16x16x32_bf16 v[108:111], v[24:27], v[196:199], v[108:111]
	v_mfma_f32_16x16x32_bf16 v[104:107], v[40:43], v[196:199], v[104:107]
	v_mfma_f32_16x16x32_bf16 v[92:95], v[24:27], v[204:207], v[92:95]
	v_mfma_f32_16x16x32_bf16 v[88:91], v[40:43], v[204:207], v[88:91]
	v_mfma_f32_16x16x32_bf16 v[140:143], v[28:31], v[148:151], v[140:143]
	v_mfma_f32_16x16x32_bf16 v[136:139], v[44:47], v[148:151], v[136:139]
	v_mfma_f32_16x16x32_bf16 v[124:127], v[28:31], v[192:195], v[124:127]
	v_mfma_f32_16x16x32_bf16 v[120:123], v[44:47], v[192:195], v[120:123]
	v_mfma_f32_16x16x32_bf16 v[108:111], v[28:31], v[200:203], v[108:111]
	v_mfma_f32_16x16x32_bf16 v[104:107], v[44:47], v[200:203], v[104:107]
	v_mfma_f32_16x16x32_bf16 v[92:95], v[28:31], v[208:211], v[92:95]
	v_mfma_f32_16x16x32_bf16 v[88:91], v[44:47], v[208:211], v[88:91]
	s_barrier
	ds_read_b128 v[212:215], v189
	ds_read_b128 v[216:219], v189 offset:1024
	ds_read_b128 v[220:223], v189 offset:2048
	ds_read_b128 v[224:227], v189 offset:3072
	s_add_i32 s54, s43, s35
	v_lshl_add_u64 v[174:175], s[4:5], 0, v[156:157]
	s_mov_b32 m0, s54
	s_nop 0
	global_load_lds_dwordx4 v[174:175], off
	v_lshl_add_u64 v[228:229], s[4:5], 0, v[160:161]
	s_add_i32 m0, s54, 0x2000
	s_nop 0
	global_load_lds_dwordx4 v[228:229], off
	s_barrier
	s_waitcnt lgkmcnt(0)
	v_mfma_f32_16x16x32_bf16 v[132:135], v[212:215], v[144:147], v[132:135]
	v_mfma_f32_16x16x32_bf16 v[128:131], v[220:223], v[144:147], v[128:131]
	v_mfma_f32_16x16x32_bf16 v[116:119], v[212:215], v[182:185], v[116:119]
	v_mfma_f32_16x16x32_bf16 v[112:115], v[220:223], v[182:185], v[112:115]
	v_mfma_f32_16x16x32_bf16 v[100:103], v[212:215], v[196:199], v[100:103]
	v_mfma_f32_16x16x32_bf16 v[96:99], v[220:223], v[196:199], v[96:99]
	v_mfma_f32_16x16x32_bf16 v[84:87], v[212:215], v[204:207], v[84:87]
	v_mfma_f32_16x16x32_bf16 v[80:83], v[220:223], v[204:207], v[80:83]
	v_mfma_f32_16x16x32_bf16 v[132:135], v[216:219], v[148:151], v[132:135]
	v_mfma_f32_16x16x32_bf16 v[128:131], v[224:227], v[148:151], v[128:131]
	v_mfma_f32_16x16x32_bf16 v[116:119], v[216:219], v[192:195], v[116:119]
	v_mfma_f32_16x16x32_bf16 v[112:115], v[224:227], v[192:195], v[112:115]
	v_mfma_f32_16x16x32_bf16 v[100:103], v[216:219], v[200:203], v[100:103]
	v_mfma_f32_16x16x32_bf16 v[96:99], v[224:227], v[200:203], v[96:99]
	v_mfma_f32_16x16x32_bf16 v[84:87], v[216:219], v[208:211], v[84:87]
	v_mfma_f32_16x16x32_bf16 v[80:83], v[224:227], v[208:211], v[80:83]
	s_mov_b32 m0, s27
	v_lshl_add_u64 v[230:231], s[28:29], 0, v[154:155]
	s_barrier
	ds_read_b128 v[144:147], v187 offset:16384
	ds_read_b128 v[148:151], v187 offset:17408
	ds_read_b128 v[182:185], v187 offset:18432
	ds_read_b128 v[192:195], v187 offset:19456
	ds_read_b128 v[196:199], v187 offset:20480
	ds_read_b128 v[200:203], v187 offset:21504
	ds_read_b128 v[204:207], v187 offset:22528
	ds_read_b128 v[208:211], v187 offset:23552
	global_load_lds_dwordx4 v[230:231], off
	v_lshl_add_u64 v[232:233], s[28:29], 0, v[158:159]
	s_mov_b32 m0, s36
	s_nop 0
	global_load_lds_dwordx4 v[232:233], off
	s_barrier
	s_waitcnt lgkmcnt(0)
	v_mfma_f32_16x16x32_bf16 v[76:79], v[24:27], v[144:147], v[76:79]
	v_mfma_f32_16x16x32_bf16 v[72:75], v[40:43], v[144:147], v[72:75]
	v_mfma_f32_16x16x32_bf16 v[60:63], v[24:27], v[182:185], v[60:63]
	v_mfma_f32_16x16x32_bf16 v[56:59], v[40:43], v[182:185], v[56:59]
	v_mfma_f32_16x16x32_bf16 v[36:39], v[24:27], v[196:199], v[36:39]
	v_mfma_f32_16x16x32_bf16 v[32:35], v[40:43], v[196:199], v[32:35]
	v_mfma_f32_16x16x32_bf16 v[12:15], v[24:27], v[204:207], v[12:15]
	v_mfma_f32_16x16x32_bf16 v[8:11], v[40:43], v[204:207], v[8:11]
	v_mfma_f32_16x16x32_bf16 v[76:79], v[28:31], v[148:151], v[76:79]
	v_mfma_f32_16x16x32_bf16 v[72:75], v[44:47], v[148:151], v[72:75]
	v_mfma_f32_16x16x32_bf16 v[60:63], v[28:31], v[192:195], v[60:63]
	v_mfma_f32_16x16x32_bf16 v[56:59], v[44:47], v[192:195], v[56:59]
	v_mfma_f32_16x16x32_bf16 v[36:39], v[28:31], v[200:203], v[36:39]
	v_mfma_f32_16x16x32_bf16 v[32:35], v[44:47], v[200:203], v[32:35]
	v_mfma_f32_16x16x32_bf16 v[12:15], v[28:31], v[208:211], v[12:15]
	v_mfma_f32_16x16x32_bf16 v[8:11], v[44:47], v[208:211], v[8:11]
	s_barrier
	s_add_u32 s54, s4, 0x40000
	s_addc_u32 s55, s5, 0
	s_add_i32 s56, s44, s35
	v_lshl_add_u64 v[24:25], s[54:55], 0, v[156:157]
	s_mov_b32 m0, s56
	s_nop 0
	global_load_lds_dwordx4 v[24:25], off
	v_lshl_add_u64 v[24:25], s[54:55], 0, v[160:161]
	s_add_i32 m0, s56, 0x2000
	s_nop 0
	global_load_lds_dwordx4 v[24:25], off
	s_waitcnt vmcnt(6)
	s_barrier
; #define PG8_STAGE(bufoff, gbase, voff) do { _Pragma("unroll") for (int _i = 0; _i < 2; ++_i) \
;         __builtin_amdgcn_global_load_lds((const unsigned*)((const char*)(gbase) + (voff)[_i]), (PG8_LAS unsigned*)(lds + (bufoff) + ldsw + _i * 8192), 16, 0, 0); } while (0)
; #define PG8_LDA(dst, b, h) do { _Pragma("unroll") for (int m = 0; m < 4; ++m) _Pragma("unroll") for (int k = 0; k < 2; ++k) dst[m][k] = *(const PG8_LAS bf16x8*)(lds + PG8_SA(b, h) + aoff + m * 2048 + k * 1024); } while (0)
; #define PG8_LDB(dst, b, h) do { _Pragma("unroll") for (int n = 0; n < 2; ++n) _Pragma("unroll") for (int k = 0; k < 2; ++k) dst[n][k] = *(const PG8_LAS bf16x8*)(lds + PG8_SB(b, h) + boff + n * 2048 + k * 1024); } while (0)
; #define PG8_MMA(ai, bj, At, Bt) do { __builtin_amdgcn_s_setprio(1); _Pragma("unroll") for (int m = 0; m < 4; ++m) _Pragma("unroll") for (int n = 0; n < 2; ++n) _Pragma("unroll") for (int k = 0; k < 2; ++k) \
;         acc[ai][bj][m][n] = __builtin_amdgcn_mfma_f32_16x16x32_bf16(Bt[n][k], At[m][k], acc[ai][bj][m][n], 0, 0, 0); __builtin_amdgcn_s_setprio(0); } while (0)
; #define PG8_WAIT_V(n) asm volatile("s_waitcnt vmcnt(" #n ")" ::: "memory")
; #define PG8_WAIT_L(n) asm volatile("s_waitcnt lgkmcnt(" #n ")" ::: "memory")
; #define PG8_BAR __builtin_amdgcn_s_barrier()
; #define PG8_SCHED __builtin_amdgcn_sched_barrier(0)
; template <class Epi, class Sched>
; __device__ __forceinline__ void gemm_phase(PG8_LAS unsigned char* lds, const Gemm g, const Sched& S, const Epi& E) {
;     ...
;             PG8_WAIT_V(6); PG8_BAR; PG8_MMA(1, 1, At, B1); PG8_BAR;
;             PG8_LDB(B0, 1, 0); PG8_SCHED; PG8_LDA(At, 1, 0); PG8_STAGE(PG8_SA(0, 1), a2 + hstep, voffA);
;             PG8_WAIT_L(8); PG8_BAR; PG8_WAIT_L(0); PG8_MMA(0, 0, At, B0); PG8_BAR; PG8_SCHED;
;             PG8_LDB(B1, 1, 1); PG8_STAGE(PG8_SB(1, 0), b3, voffB);
;             PG8_BAR; PG8_WAIT_L(0); PG8_MMA(0, 1, At, B1); PG8_BAR;
;             PG8_LDA(At, 1, 1); PG8_STAGE(PG8_SA(1, 0), a3, voffA);
	v_mfma_f32_16x16x32_bf16 v[20:23], v[212:215], v[196:199], v[20:23]
	v_mfma_f32_16x16x32_bf16 v[16:19], v[220:223], v[196:199], v[16:19]
	v_mfma_f32_16x16x32_bf16 v[4:7], v[212:215], v[204:207], v[4:7]
	v_mfma_f32_16x16x32_bf16 v[0:3], v[220:223], v[204:207], v[0:3]
	v_mfma_f32_16x16x32_bf16 v[24:27], v[212:215], v[144:147], v[68:71]
	v_mfma_f32_16x16x32_bf16 v[28:31], v[220:223], v[144:147], v[64:67]
	v_mfma_f32_16x16x32_bf16 v[40:43], v[212:215], v[182:185], v[52:55]
	v_mfma_f32_16x16x32_bf16 v[44:47], v[220:223], v[182:185], v[48:51]
	v_mfma_f32_16x16x32_bf16 v[20:23], v[216:219], v[200:203], v[20:23]
	v_mfma_f32_16x16x32_bf16 v[16:19], v[224:227], v[200:203], v[16:19]
	v_mfma_f32_16x16x32_bf16 v[4:7], v[216:219], v[208:211], v[4:7]
	v_mfma_f32_16x16x32_bf16 v[0:3], v[224:227], v[208:211], v[0:3]
	v_mfma_f32_16x16x32_bf16 v[24:27], v[216:219], v[148:151], v[24:27]
	v_mfma_f32_16x16x32_bf16 v[28:31], v[224:227], v[148:151], v[28:31]
	v_mfma_f32_16x16x32_bf16 v[40:43], v[216:219], v[192:195], v[40:43]
	v_mfma_f32_16x16x32_bf16 v[44:47], v[224:227], v[192:195], v[44:47]
	s_add_i32 s54, 0, 0x18000
	v_add_u32_e32 v68, s54, v179
	s_barrier
	ds_read_b128 v[48:51], v68
	ds_read_b128 v[52:55], v68 offset:1024
	ds_read_b128 v[64:67], v68 offset:2048
	ds_read_b128 v[68:71], v68 offset:3072
	ds_read_b128 v[144:147], v187 offset:32768
	ds_read_b128 v[148:151], v187 offset:33792
	ds_read_b128 v[182:185], v187 offset:34816
	ds_read_b128 v[192:195], v187 offset:35840
	ds_read_b128 v[196:199], v187 offset:36864
	ds_read_b128 v[200:203], v187 offset:37888
	ds_read_b128 v[204:207], v187 offset:38912
	ds_read_b128 v[208:211], v187 offset:39936
	s_add_u32 s28, s28, 0x40000
	s_addc_u32 s29, s29, 0
	s_mov_b32 m0, s37
	v_lshl_add_u64 v[212:213], s[28:29], 0, v[154:155]
	global_load_lds_dwordx4 v[212:213], off
	v_lshl_add_u64 v[212:213], s[28:29], 0, v[158:159]
	s_mov_b32 m0, s38
	s_nop 0
	global_load_lds_dwordx4 v[212:213], off
	s_waitcnt lgkmcnt(8)
	s_barrier
	s_waitcnt lgkmcnt(0)
	v_mfma_f32_16x16x32_bf16 v[140:143], v[48:51], v[144:147], v[140:143]
	v_mfma_f32_16x16x32_bf16 v[136:139], v[64:67], v[144:147], v[136:139]
	v_mfma_f32_16x16x32_bf16 v[124:127], v[48:51], v[182:185], v[124:127]
	v_mfma_f32_16x16x32_bf16 v[120:123], v[64:67], v[182:185], v[120:123]
	v_mfma_f32_16x16x32_bf16 v[108:111], v[48:51], v[196:199], v[108:111]
	v_mfma_f32_16x16x32_bf16 v[104:107], v[64:67], v[196:199], v[104:107]
	v_mfma_f32_16x16x32_bf16 v[92:95], v[48:51], v[204:207], v[92:95]
	v_mfma_f32_16x16x32_bf16 v[88:91], v[64:67], v[204:207], v[88:91]
	v_mfma_f32_16x16x32_bf16 v[140:143], v[52:55], v[148:151], v[140:143]
	v_mfma_f32_16x16x32_bf16 v[136:139], v[68:71], v[148:151], v[136:139]
	v_mfma_f32_16x16x32_bf16 v[124:127], v[52:55], v[192:195], v[124:127]
	v_mfma_f32_16x16x32_bf16 v[120:123], v[68:71], v[192:195], v[120:123]
	v_mfma_f32_16x16x32_bf16 v[108:111], v[52:55], v[200:203], v[108:111]
	v_mfma_f32_16x16x32_bf16 v[104:107], v[68:71], v[200:203], v[104:107]
	v_mfma_f32_16x16x32_bf16 v[92:95], v[52:55], v[208:211], v[92:95]
	v_mfma_f32_16x16x32_bf16 v[88:91], v[68:71], v[208:211], v[88:91]
	s_barrier
	s_add_i32 s28, 0, 0x1c000
	v_add_u32_e32 v162, s28, v179
	ds_read_b128 v[212:215], v162
	ds_read_b128 v[216:219], v162 offset:1024
	ds_read_b128 v[220:223], v162 offset:2048
	ds_read_b128 v[224:227], v162 offset:3072
	s_add_i32 s29, s54, s35
	v_lshl_add_u64 v[174:175], v[174:175], 0, s[14:15]
	s_mov_b32 m0, s29
	s_nop 0
	global_load_lds_dwordx4 v[174:175], off
	v_lshl_add_u64 v[174:175], v[228:229], 0, s[14:15]
	s_add_i32 m0, s29, 0x2000
	s_nop 0
	global_load_lds_dwordx4 v[174:175], off
	s_barrier
	s_waitcnt lgkmcnt(0)
	v_mfma_f32_16x16x32_bf16 v[132:135], v[212:215], v[144:147], v[132:135]
	v_mfma_f32_16x16x32_bf16 v[128:131], v[220:223], v[144:147], v[128:131]
	v_mfma_f32_16x16x32_bf16 v[116:119], v[212:215], v[182:185], v[116:119]
	v_mfma_f32_16x16x32_bf16 v[112:115], v[220:223], v[182:185], v[112:115]
	v_mfma_f32_16x16x32_bf16 v[100:103], v[212:215], v[196:199], v[100:103]
	v_mfma_f32_16x16x32_bf16 v[96:99], v[220:223], v[196:199], v[96:99]
	v_mfma_f32_16x16x32_bf16 v[84:87], v[212:215], v[204:207], v[84:87]
	v_mfma_f32_16x16x32_bf16 v[80:83], v[220:223], v[204:207], v[80:83]
	v_mfma_f32_16x16x32_bf16 v[132:135], v[216:219], v[148:151], v[132:135]
	v_mfma_f32_16x16x32_bf16 v[128:131], v[224:227], v[148:151], v[128:131]
	v_mfma_f32_16x16x32_bf16 v[116:119], v[216:219], v[192:195], v[116:119]
	v_mfma_f32_16x16x32_bf16 v[112:115], v[224:227], v[192:195], v[112:115]
	v_mfma_f32_16x16x32_bf16 v[100:103], v[216:219], v[200:203], v[100:103]
	v_mfma_f32_16x16x32_bf16 v[96:99], v[224:227], v[200:203], v[96:99]
	v_mfma_f32_16x16x32_bf16 v[84:87], v[216:219], v[208:211], v[84:87]
	v_mfma_f32_16x16x32_bf16 v[80:83], v[224:227], v[208:211], v[80:83]
	s_mov_b32 m0, s39
	v_lshl_add_u64 v[174:175], v[230:231], 0, s[14:15]
	s_barrier
; #define PG8_STAGE(bufoff, gbase, voff) do { _Pragma("unroll") for (int _i = 0; _i < 2; ++_i) \
;         __builtin_amdgcn_global_load_lds((const unsigned*)((const char*)(gbase) + (voff)[_i]), (PG8_LAS unsigned*)(lds + (bufoff) + ldsw + _i * 8192), 16, 0, 0); } while (0)
; #define PG8_LDA(dst, b, h) do { _Pragma("unroll") for (int m = 0; m < 4; ++m) _Pragma("unroll") for (int k = 0; k < 2; ++k) dst[m][k] = *(const PG8_LAS bf16x8*)(lds + PG8_SA(b, h) + aoff + m * 2048 + k * 1024); } while (0)
; #define PG8_MMA(ai, bj, At, Bt) do { __builtin_amdgcn_s_setprio(1); _Pragma("unroll") for (int m = 0; m < 4; ++m) _Pragma("unroll") for (int n = 0; n < 2; ++n) _Pragma("unroll") for (int k = 0; k < 2; ++k) \
;         acc[ai][bj][m][n] = __builtin_amdgcn_mfma_f32_16x16x32_bf16(Bt[n][k], At[m][k], acc[ai][bj][m][n], 0, 0, 0); __builtin_amdgcn_s_setprio(0); } while (0)
; #define PG8_WAIT_V(n) asm volatile("s_waitcnt vmcnt(" #n ")" ::: "memory")
; #define PG8_WAIT_L(n) asm volatile("s_waitcnt lgkmcnt(" #n ")" ::: "memory")
; #define PG8_BAR __builtin_amdgcn_s_barrier()
; #define PG8_SCHED __builtin_amdgcn_sched_barrier(0)
;     __device__ __forceinline__ void operator()(const f32x4 (&acc)[2][2][4][2], const Unit& u, int wr, int wc, int fr, int fq) const {
;     ...
;         if (mode == 1) { if (u.pn >= 8 && u.pn < 12) act = 1; else if (u.pn >= 12) { act = 3; bias = (u.pn >= 14) ? bias_b + (u.pn - 14) * 256 : bias_f + (u.pn - 12) * 256; } }
; template <class Epi, class Sched>
; __device__ __forceinline__ void gemm_phase(PG8_LAS unsigned char* lds, const Gemm g, const Sched& S, const Epi& E) {
;     ...
;             PG8_LDA(At, 1, 1); PG8_STAGE(PG8_SA(1, 0), a3, voffA);
;             PG8_BAR; PG8_WAIT_L(0); PG8_MMA(1, 0, At, B0); PG8_BAR; PG8_SCHED;
;             PG8_STAGE(PG8_SB(1, 1), b3 + hstep, voffB);
;             PG8_WAIT_V(6); PG8_BAR; PG8_MMA(1, 1, At, B1); PG8_BAR;
;     ...
;         if constexpr (!Epi::AFTER_DRAIN) { E(acc, cur, wr, wc, fr, fq); S.done(cur); }
	ds_read_b128 v[144:147], v187 offset:49152
	ds_read_b128 v[148:151], v187 offset:50176
	ds_read_b128 v[182:185], v187 offset:51200
	ds_read_b128 v[192:195], v187 offset:52224
	ds_read_b128 v[196:199], v187 offset:53248
	ds_read_b128 v[200:203], v187 offset:54272
	ds_read_b128 v[204:207], v187 offset:55296
	ds_read_b128 v[208:211], v187 offset:56320
	global_load_lds_dwordx4 v[174:175], off
	v_lshl_add_u64 v[174:175], v[232:233], 0, s[14:15]
	s_mov_b32 m0, s40
	s_nop 0
	global_load_lds_dwordx4 v[174:175], off
	s_barrier
	s_waitcnt lgkmcnt(0)
	v_mfma_f32_16x16x32_bf16 v[76:79], v[48:51], v[144:147], v[76:79]
	v_mfma_f32_16x16x32_bf16 v[72:75], v[64:67], v[144:147], v[72:75]
	v_mfma_f32_16x16x32_bf16 v[60:63], v[48:51], v[182:185], v[60:63]
	v_mfma_f32_16x16x32_bf16 v[56:59], v[64:67], v[182:185], v[56:59]
	v_mfma_f32_16x16x32_bf16 v[36:39], v[48:51], v[196:199], v[36:39]
	v_mfma_f32_16x16x32_bf16 v[32:35], v[64:67], v[196:199], v[32:35]
	v_mfma_f32_16x16x32_bf16 v[12:15], v[48:51], v[204:207], v[12:15]
	v_mfma_f32_16x16x32_bf16 v[8:11], v[64:67], v[204:207], v[8:11]
	v_mfma_f32_16x16x32_bf16 v[76:79], v[52:55], v[148:151], v[76:79]
	v_mfma_f32_16x16x32_bf16 v[72:75], v[68:71], v[148:151], v[72:75]
	v_mfma_f32_16x16x32_bf16 v[60:63], v[52:55], v[192:195], v[60:63]
	v_mfma_f32_16x16x32_bf16 v[56:59], v[68:71], v[192:195], v[56:59]
	v_mfma_f32_16x16x32_bf16 v[36:39], v[52:55], v[200:203], v[36:39]
	v_mfma_f32_16x16x32_bf16 v[32:35], v[68:71], v[200:203], v[32:35]
	v_mfma_f32_16x16x32_bf16 v[12:15], v[52:55], v[208:211], v[12:15]
	v_mfma_f32_16x16x32_bf16 v[8:11], v[68:71], v[208:211], v[8:11]
	s_barrier
	s_add_u32 s4, s4, 0x40080
	s_addc_u32 s5, s5, 0
	s_add_i32 s28, s28, s35
	v_lshl_add_u64 v[48:49], s[4:5], 0, v[156:157]
	s_mov_b32 m0, s28
	s_nop 0
	global_load_lds_dwordx4 v[48:49], off
	v_lshl_add_u64 v[48:49], s[4:5], 0, v[160:161]
	s_add_i32 m0, s28, 0x2000
	s_nop 0
	global_load_lds_dwordx4 v[48:49], off
	s_waitcnt vmcnt(6)
	s_barrier
	v_mfma_f32_16x16x32_bf16 v[24:27], v[212:215], v[144:147], v[24:27]
	v_mfma_f32_16x16x32_bf16 v[68:71], v[216:219], v[148:151], v[24:27]
	v_mfma_f32_16x16x32_bf16 v[24:27], v[220:223], v[144:147], v[28:31]
	v_mfma_f32_16x16x32_bf16 v[64:67], v[224:227], v[148:151], v[24:27]
	v_mfma_f32_16x16x32_bf16 v[24:27], v[212:215], v[182:185], v[40:43]
	v_mfma_f32_16x16x32_bf16 v[52:55], v[216:219], v[192:195], v[24:27]
	v_mfma_f32_16x16x32_bf16 v[24:27], v[220:223], v[182:185], v[44:47]
	v_mfma_f32_16x16x32_bf16 v[20:23], v[212:215], v[196:199], v[20:23]
	v_mfma_f32_16x16x32_bf16 v[16:19], v[220:223], v[196:199], v[16:19]
	v_mfma_f32_16x16x32_bf16 v[4:7], v[212:215], v[204:207], v[4:7]
	v_mfma_f32_16x16x32_bf16 v[0:3], v[220:223], v[204:207], v[0:3]
	v_mfma_f32_16x16x32_bf16 v[48:51], v[224:227], v[192:195], v[24:27]
	v_mfma_f32_16x16x32_bf16 v[20:23], v[216:219], v[200:203], v[20:23]
	v_mfma_f32_16x16x32_bf16 v[16:19], v[224:227], v[200:203], v[16:19]
	v_mfma_f32_16x16x32_bf16 v[4:7], v[216:219], v[208:211], v[4:7]
	v_mfma_f32_16x16x32_bf16 v[0:3], v[224:227], v[208:211], v[0:3]
	s_add_i32 s53, s53, 2
	s_add_u32 s0, s0, 0x100
	s_addc_u32 s1, s1, 0
	s_add_u32 s51, s51, 0x100
	s_addc_u32 s52, s52, 0
	s_cmp_gt_u32 s53, 13
	s_barrier
	s_cbranch_scc0 .LBB0_416
	s_cmp_gt_i32 s26, 11
	s_cselect_b64 s[4:5], -1, 0
	s_cmp_lt_i32 s26, 12
	s_mov_b64 s[0:1], 0
	s_cbranch_scc1 .LBB0_422
	s_lshl_b32 s10, s26, 8
	s_cmp_lt_u32 s26, 14
	s_mov_b64 s[28:29], -1
	s_cbranch_scc0 .LBB0_420
	s_lshl_b64 s[0:1], s[10:11], 2
	v_readlane_b32 s52, v245, 0
	v_readlane_b32 s53, v245, 1
	s_add_u32 s0, s52, s0
	s_addc_u32 s1, s53, s1
	s_add_u32 s0, s0, 0xffffd000
	v_readlane_b32 s54, v245, 2
	v_readlane_b32 s55, v245, 3
	v_readlane_b32 s56, v245, 4
	v_readlane_b32 s57, v245, 5
	v_readlane_b32 s58, v245, 6
	v_readlane_b32 s59, v245, 7
	v_readlane_b32 s60, v245, 8
	v_readlane_b32 s61, v245, 9
	v_readlane_b32 s62, v245, 10
	v_readlane_b32 s63, v245, 11
	v_readlane_b32 s64, v245, 12
	v_readlane_b32 s65, v245, 13
	v_readlane_b32 s66, v245, 14
	v_readlane_b32 s67, v245, 15
	s_addc_u32 s1, s1, -1
	s_mov_b64 s[28:29], 0

; #define PG8_STAGE(bufoff, gbase, voff) do { _Pragma("unroll") for (int _i = 0; _i < 2; ++_i) \
;         __builtin_amdgcn_global_load_lds((const unsigned*)((const char*)(gbase) + (voff)[_i]), (PG8_LAS unsigned*)(lds + (bufoff) + ldsw + _i * 8192), 16, 0, 0); } while (0)
; #define PG8_LDA(dst, b, h) do { _Pragma("unroll") for (int m = 0; m < 4; ++m) _Pragma("unroll") for (int k = 0; k < 2; ++k) dst[m][k] = *(const PG8_LAS bf16x8*)(lds + PG8_SA(b, h) + aoff + m * 2048 + k * 1024); } while (0)
; #define PG8_LDB(dst, b, h) do { _Pragma("unroll") for (int n = 0; n < 2; ++n) _Pragma("unroll") for (int k = 0; k < 2; ++k) dst[n][k] = *(const PG8_LAS bf16x8*)(lds + PG8_SB(b, h) + boff + n * 2048 + k * 1024); } while (0)
; #define PG8_MMA(ai, bj, At, Bt) do { __builtin_amdgcn_s_setprio(1); _Pragma("unroll") for (int m = 0; m < 4; ++m) _Pragma("unroll") for (int n = 0; n < 2; ++n) _Pragma("unroll") for (int k = 0; k < 2; ++k) \
;         acc[ai][bj][m][n] = __builtin_amdgcn_mfma_f32_16x16x32_bf16(Bt[n][k], At[m][k], acc[ai][bj][m][n], 0, 0, 0); __builtin_amdgcn_s_setprio(0); } while (0)
; #define PG8_WAIT_L(n) asm volatile("s_waitcnt lgkmcnt(" #n ")" ::: "memory")
; #define PG8_BAR __builtin_amdgcn_s_barrier()
; #define PG8_SCHED __builtin_amdgcn_sched_barrier(0)
; template <class Epi, class Sched>
; __device__ __forceinline__ void gemm_phase(PG8_LAS unsigned char* lds, const Gemm g, const Sched& S, const Epi& E) {
;     ...
;             PG8_LDB(B0, 0, 0); PG8_SCHED; PG8_LDA(At, 0, 0); PG8_STAGE(PG8_SA(1, 1), a1 + hstep, voffA);
;             PG8_WAIT_L(8); PG8_BAR; PG8_WAIT_L(0); PG8_MMA(0, 0, At, B0); PG8_BAR; PG8_SCHED;
;             PG8_LDB(B1, 0, 1); PG8_STAGE(PG8_SB(0, 0), b2, voffB);
;             PG8_BAR; PG8_WAIT_L(0); PG8_MMA(0, 1, At, B1); PG8_BAR;
;             PG8_LDA(At, 0, 1); PG8_STAGE(PG8_SA(0, 0), a2, voffA);
;             PG8_BAR; PG8_WAIT_L(0); PG8_MMA(1, 0, At, B0); PG8_BAR; PG8_SCHED;
.LBB0_724:
	ds_read_b128 v[144:147], v151
	ds_read_b128 v[156:159], v151 offset:1024
	ds_read_b128 v[160:163], v151 offset:2048
	ds_read_b128 v[166:169], v151 offset:3072
	ds_read_b128 v[170:173], v153
	ds_read_b128 v[182:185], v153 offset:1024
	ds_read_b128 v[190:193], v153 offset:2048
	ds_read_b128 v[194:197], v153 offset:3072
	ds_read_b128 v[198:201], v153 offset:4096
	ds_read_b128 v[202:205], v153 offset:5120
	ds_read_b128 v[206:209], v153 offset:6144
	ds_read_b128 v[210:213], v153 offset:7168
	s_add_u32 s20, s18, 0xfffc0080
	s_addc_u32 s21, s19, -1
	s_cmp_eq_u32 s48, 12
	s_cselect_b32 s23, s5, s21
	s_cselect_b32 s22, s11, s20
	s_cselect_b32 s21, s9, s47
	s_cselect_b32 s20, s45, s46
	v_lshl_add_u64 v[174:175], s[18:19], 0, v[136:137]
	s_add_i32 m0, s17, 0xc000
	s_nop 0
	global_load_lds_dwordx4 v[174:175], off
	v_lshl_add_u64 v[174:175], s[18:19], 0, v[138:139]
	s_add_i32 m0, s17, 0xe000
	s_nop 0
	global_load_lds_dwordx4 v[174:175], off
	s_waitcnt lgkmcnt(8)
	s_barrier
	s_waitcnt lgkmcnt(0)
	v_mfma_f32_16x16x32_bf16 v[124:127], v[144:147], v[170:173], v[124:127]
	v_mfma_f32_16x16x32_bf16 v[120:123], v[160:163], v[170:173], v[120:123]
	v_mfma_f32_16x16x32_bf16 v[108:111], v[144:147], v[190:193], v[108:111]
	v_mfma_f32_16x16x32_bf16 v[104:107], v[160:163], v[190:193], v[104:107]
	v_mfma_f32_16x16x32_bf16 v[92:95], v[144:147], v[198:201], v[92:95]
	v_mfma_f32_16x16x32_bf16 v[88:91], v[160:163], v[198:201], v[88:91]
	v_mfma_f32_16x16x32_bf16 v[76:79], v[144:147], v[206:209], v[76:79]
	v_mfma_f32_16x16x32_bf16 v[72:75], v[160:163], v[206:209], v[72:75]
	v_mfma_f32_16x16x32_bf16 v[124:127], v[156:159], v[182:185], v[124:127]
	v_mfma_f32_16x16x32_bf16 v[120:123], v[166:169], v[182:185], v[120:123]
	v_mfma_f32_16x16x32_bf16 v[108:111], v[156:159], v[194:197], v[108:111]
	v_mfma_f32_16x16x32_bf16 v[104:107], v[166:169], v[194:197], v[104:107]
	v_mfma_f32_16x16x32_bf16 v[92:95], v[156:159], v[202:205], v[92:95]
	v_mfma_f32_16x16x32_bf16 v[88:91], v[166:169], v[202:205], v[88:91]
	v_mfma_f32_16x16x32_bf16 v[76:79], v[156:159], v[210:213], v[76:79]
	v_mfma_f32_16x16x32_bf16 v[72:75], v[166:169], v[210:213], v[72:75]
	s_barrier
	ds_read_b128 v[214:217], v154
	ds_read_b128 v[218:221], v154 offset:1024
	ds_read_b128 v[222:225], v154 offset:2048
	ds_read_b128 v[226:229], v154 offset:3072
	s_add_i32 s49, s42, s30
	v_lshl_add_u64 v[174:175], s[20:21], 0, v[130:131]
	s_mov_b32 m0, s49
	s_nop 0
	global_load_lds_dwordx4 v[174:175], off
	v_lshl_add_u64 v[186:187], s[20:21], 0, v[134:135]
	s_add_i32 m0, s49, 0x2000
	s_nop 0
	global_load_lds_dwordx4 v[186:187], off
	s_barrier
	s_waitcnt lgkmcnt(0)
	v_mfma_f32_16x16x32_bf16 v[116:119], v[214:217], v[170:173], v[116:119]
	v_mfma_f32_16x16x32_bf16 v[112:115], v[222:225], v[170:173], v[112:115]
	v_mfma_f32_16x16x32_bf16 v[100:103], v[214:217], v[190:193], v[100:103]
	v_mfma_f32_16x16x32_bf16 v[96:99], v[222:225], v[190:193], v[96:99]
	v_mfma_f32_16x16x32_bf16 v[84:87], v[214:217], v[198:201], v[84:87]
	v_mfma_f32_16x16x32_bf16 v[80:83], v[222:225], v[198:201], v[80:83]
	v_mfma_f32_16x16x32_bf16 v[68:71], v[214:217], v[206:209], v[68:71]
	v_mfma_f32_16x16x32_bf16 v[64:67], v[222:225], v[206:209], v[64:67]
	v_mfma_f32_16x16x32_bf16 v[116:119], v[218:221], v[182:185], v[116:119]
	v_mfma_f32_16x16x32_bf16 v[112:115], v[226:229], v[182:185], v[112:115]
	v_mfma_f32_16x16x32_bf16 v[100:103], v[218:221], v[194:197], v[100:103]
	v_mfma_f32_16x16x32_bf16 v[96:99], v[226:229], v[194:197], v[96:99]
	v_mfma_f32_16x16x32_bf16 v[84:87], v[218:221], v[202:205], v[84:87]
	v_mfma_f32_16x16x32_bf16 v[80:83], v[226:229], v[202:205], v[80:83]
	v_mfma_f32_16x16x32_bf16 v[68:71], v[218:221], v[210:213], v[68:71]
	v_mfma_f32_16x16x32_bf16 v[64:67], v[226:229], v[210:213], v[64:67]
	s_mov_b32 m0, s17
	v_lshl_add_u64 v[230:231], s[22:23], 0, v[128:129]
	s_barrier
	ds_read_b128 v[170:173], v153 offset:16384
	ds_read_b128 v[182:185], v153 offset:17408
	ds_read_b128 v[190:193], v153 offset:18432
	ds_read_b128 v[194:197], v153 offset:19456
	ds_read_b128 v[198:201], v153 offset:20480
	ds_read_b128 v[202:205], v153 offset:21504
	ds_read_b128 v[206:209], v153 offset:22528
	ds_read_b128 v[210:213], v153 offset:23552
	global_load_lds_dwordx4 v[230:231], off
	v_lshl_add_u64 v[232:233], s[22:23], 0, v[132:133]
	s_mov_b32 m0, s31
	s_nop 0
	global_load_lds_dwordx4 v[232:233], off
	s_barrier
	s_waitcnt lgkmcnt(0)
	v_mfma_f32_16x16x32_bf16 v[60:63], v[144:147], v[170:173], v[60:63]
	v_mfma_f32_16x16x32_bf16 v[56:59], v[160:163], v[170:173], v[56:59]
	v_mfma_f32_16x16x32_bf16 v[44:47], v[144:147], v[190:193], v[44:47]
	v_mfma_f32_16x16x32_bf16 v[40:43], v[160:163], v[190:193], v[40:43]
	v_mfma_f32_16x16x32_bf16 v[28:31], v[144:147], v[198:201], v[28:31]
	v_mfma_f32_16x16x32_bf16 v[24:27], v[160:163], v[198:201], v[24:27]
	v_mfma_f32_16x16x32_bf16 v[12:15], v[144:147], v[206:209], v[12:15]
	v_mfma_f32_16x16x32_bf16 v[8:11], v[160:163], v[206:209], v[8:11]
	v_mfma_f32_16x16x32_bf16 v[60:63], v[156:159], v[182:185], v[60:63]
	v_mfma_f32_16x16x32_bf16 v[56:59], v[166:169], v[182:185], v[56:59]
	v_mfma_f32_16x16x32_bf16 v[44:47], v[156:159], v[194:197], v[44:47]
	v_mfma_f32_16x16x32_bf16 v[40:43], v[166:169], v[194:197], v[40:43]
	v_mfma_f32_16x16x32_bf16 v[28:31], v[156:159], v[202:205], v[28:31]
	v_mfma_f32_16x16x32_bf16 v[24:27], v[166:169], v[202:205], v[24:27]
	v_mfma_f32_16x16x32_bf16 v[12:15], v[156:159], v[210:213], v[12:15]
	v_mfma_f32_16x16x32_bf16 v[8:11], v[166:169], v[210:213], v[8:11]
	s_barrier
; #define PG8_STAGE(bufoff, gbase, voff) do { _Pragma("unroll") for (int _i = 0; _i < 2; ++_i) \
;         __builtin_amdgcn_global_load_lds((const unsigned*)((const char*)(gbase) + (voff)[_i]), (PG8_LAS unsigned*)(lds + (bufoff) + ldsw + _i * 8192), 16, 0, 0); } while (0)
; #define PG8_LDA(dst, b, h) do { _Pragma("unroll") for (int m = 0; m < 4; ++m) _Pragma("unroll") for (int k = 0; k < 2; ++k) dst[m][k] = *(const PG8_LAS bf16x8*)(lds + PG8_SA(b, h) + aoff + m * 2048 + k * 1024); } while (0)
; #define PG8_LDB(dst, b, h) do { _Pragma("unroll") for (int n = 0; n < 2; ++n) _Pragma("unroll") for (int k = 0; k < 2; ++k) dst[n][k] = *(const PG8_LAS bf16x8*)(lds + PG8_SB(b, h) + boff + n * 2048 + k * 1024); } while (0)
; #define PG8_MMA(ai, bj, At, Bt) do { __builtin_amdgcn_s_setprio(1); _Pragma("unroll") for (int m = 0; m < 4; ++m) _Pragma("unroll") for (int n = 0; n < 2; ++n) _Pragma("unroll") for (int k = 0; k < 2; ++k) \
;         acc[ai][bj][m][n] = __builtin_amdgcn_mfma_f32_16x16x32_bf16(Bt[n][k], At[m][k], acc[ai][bj][m][n], 0, 0, 0); __builtin_amdgcn_s_setprio(0); } while (0)
; #define PG8_WAIT_V(n) asm volatile("s_waitcnt vmcnt(" #n ")" ::: "memory")
; #define PG8_WAIT_L(n) asm volatile("s_waitcnt lgkmcnt(" #n ")" ::: "memory")
; #define PG8_BAR __builtin_amdgcn_s_barrier()
; #define PG8_SCHED __builtin_amdgcn_sched_barrier(0)
; template <class Epi, class Sched>
; __device__ __forceinline__ void gemm_phase(PG8_LAS unsigned char* lds, const Gemm g, const Sched& S, const Epi& E) {
;     ...
;             PG8_STAGE(PG8_SB(0, 1), b2 + hstep, voffB);
;             PG8_WAIT_V(6); PG8_BAR; PG8_MMA(1, 1, At, B1); PG8_BAR;
;             PG8_LDB(B0, 1, 0); PG8_SCHED; PG8_LDA(At, 1, 0); PG8_STAGE(PG8_SA(0, 1), a2 + hstep, voffA);
;             PG8_WAIT_L(8); PG8_BAR; PG8_WAIT_L(0); PG8_MMA(0, 0, At, B0); PG8_BAR; PG8_SCHED;
;             PG8_LDB(B1, 1, 1); PG8_STAGE(PG8_SB(1, 0), b3, voffB);
;             PG8_BAR; PG8_WAIT_L(0); PG8_MMA(0, 1, At, B1); PG8_BAR;
;             PG8_LDA(At, 1, 1); PG8_STAGE(PG8_SA(1, 0), a3, voffA);
	s_add_u32 s50, s20, 0x40000
	s_addc_u32 s51, s21, 0
	s_add_i32 s49, s43, s30
	v_lshl_add_u64 v[144:145], s[50:51], 0, v[130:131]
	s_mov_b32 m0, s49
	s_nop 0
	global_load_lds_dwordx4 v[144:145], off
	v_lshl_add_u64 v[144:145], s[50:51], 0, v[134:135]
	s_add_i32 m0, s49, 0x2000
	s_nop 0
	global_load_lds_dwordx4 v[144:145], off
	s_waitcnt vmcnt(6)
	s_barrier
	v_mfma_f32_16x16x32_bf16 v[52:55], v[214:217], v[170:173], v[52:55]
	v_mfma_f32_16x16x32_bf16 v[48:51], v[222:225], v[170:173], v[48:51]
	v_mfma_f32_16x16x32_bf16 v[36:39], v[214:217], v[190:193], v[36:39]
	v_mfma_f32_16x16x32_bf16 v[32:35], v[222:225], v[190:193], v[32:35]
	v_mfma_f32_16x16x32_bf16 v[20:23], v[214:217], v[198:201], v[20:23]
	v_mfma_f32_16x16x32_bf16 v[16:19], v[222:225], v[198:201], v[16:19]
	v_mfma_f32_16x16x32_bf16 v[4:7], v[214:217], v[206:209], v[4:7]
	v_mfma_f32_16x16x32_bf16 v[0:3], v[222:225], v[206:209], v[0:3]
	v_mfma_f32_16x16x32_bf16 v[52:55], v[218:221], v[182:185], v[52:55]
	v_mfma_f32_16x16x32_bf16 v[48:51], v[226:229], v[182:185], v[48:51]
	v_mfma_f32_16x16x32_bf16 v[36:39], v[218:221], v[194:197], v[36:39]
	v_mfma_f32_16x16x32_bf16 v[32:35], v[226:229], v[194:197], v[32:35]
	v_mfma_f32_16x16x32_bf16 v[20:23], v[218:221], v[202:205], v[20:23]
	v_mfma_f32_16x16x32_bf16 v[16:19], v[226:229], v[202:205], v[16:19]
	v_mfma_f32_16x16x32_bf16 v[4:7], v[218:221], v[210:213], v[4:7]
	v_mfma_f32_16x16x32_bf16 v[0:3], v[226:229], v[210:213], v[0:3]
	s_add_i32 s49, 0, 0x18000
	v_add_u32_e32 v155, s49, v149
	s_barrier
	ds_read_b128 v[144:147], v155
	ds_read_b128 v[156:159], v155 offset:1024
	ds_read_b128 v[160:163], v155 offset:2048
	ds_read_b128 v[166:169], v155 offset:3072
	ds_read_b128 v[170:173], v153 offset:32768
	ds_read_b128 v[182:185], v153 offset:33792
	ds_read_b128 v[190:193], v153 offset:34816
	ds_read_b128 v[194:197], v153 offset:35840
	ds_read_b128 v[198:201], v153 offset:36864
	ds_read_b128 v[202:205], v153 offset:37888
	ds_read_b128 v[206:209], v153 offset:38912
	ds_read_b128 v[210:213], v153 offset:39936
	s_add_u32 s22, s22, 0x40000
	s_addc_u32 s23, s23, 0
	s_mov_b32 m0, s34
	v_lshl_add_u64 v[214:215], s[22:23], 0, v[128:129]
	global_load_lds_dwordx4 v[214:215], off
	v_lshl_add_u64 v[214:215], s[22:23], 0, v[132:133]
	s_mov_b32 m0, s35
	s_nop 0
	global_load_lds_dwordx4 v[214:215], off
	s_waitcnt lgkmcnt(8)
	s_barrier
	s_waitcnt lgkmcnt(0)
	v_mfma_f32_16x16x32_bf16 v[124:127], v[144:147], v[170:173], v[124:127]
	v_mfma_f32_16x16x32_bf16 v[120:123], v[160:163], v[170:173], v[120:123]
	v_mfma_f32_16x16x32_bf16 v[108:111], v[144:147], v[190:193], v[108:111]
	v_mfma_f32_16x16x32_bf16 v[104:107], v[160:163], v[190:193], v[104:107]
	v_mfma_f32_16x16x32_bf16 v[92:95], v[144:147], v[198:201], v[92:95]
	v_mfma_f32_16x16x32_bf16 v[88:91], v[160:163], v[198:201], v[88:91]
	v_mfma_f32_16x16x32_bf16 v[76:79], v[144:147], v[206:209], v[76:79]
	v_mfma_f32_16x16x32_bf16 v[72:75], v[160:163], v[206:209], v[72:75]
	v_mfma_f32_16x16x32_bf16 v[124:127], v[156:159], v[182:185], v[124:127]
	v_mfma_f32_16x16x32_bf16 v[120:123], v[166:169], v[182:185], v[120:123]
	v_mfma_f32_16x16x32_bf16 v[108:111], v[156:159], v[194:197], v[108:111]
	v_mfma_f32_16x16x32_bf16 v[104:107], v[166:169], v[194:197], v[104:107]
	v_mfma_f32_16x16x32_bf16 v[92:95], v[156:159], v[202:205], v[92:95]
	v_mfma_f32_16x16x32_bf16 v[88:91], v[166:169], v[202:205], v[88:91]
	v_mfma_f32_16x16x32_bf16 v[76:79], v[156:159], v[210:213], v[76:79]
	v_mfma_f32_16x16x32_bf16 v[72:75], v[166:169], v[210:213], v[72:75]
	s_barrier
	s_add_i32 s22, 0, 0x1c000
	v_add_u32_e32 v155, s22, v149
	ds_read_b128 v[214:217], v155
	ds_read_b128 v[218:221], v155 offset:1024
	ds_read_b128 v[222:225], v155 offset:2048
	ds_read_b128 v[226:229], v155 offset:3072
	s_add_i32 s23, s49, s30
	v_lshl_add_u64 v[174:175], v[174:175], 0, s[6:7]
	s_mov_b32 m0, s23
	s_nop 0
	global_load_lds_dwordx4 v[174:175], off
	v_lshl_add_u64 v[174:175], v[186:187], 0, s[6:7]
	s_add_i32 m0, s23, 0x2000
	s_nop 0
	global_load_lds_dwordx4 v[174:175], off
	s_barrier
	s_waitcnt lgkmcnt(0)
	v_mfma_f32_16x16x32_bf16 v[116:119], v[214:217], v[170:173], v[116:119]
	v_mfma_f32_16x16x32_bf16 v[112:115], v[222:225], v[170:173], v[112:115]
	v_mfma_f32_16x16x32_bf16 v[100:103], v[214:217], v[190:193], v[100:103]
	v_mfma_f32_16x16x32_bf16 v[96:99], v[222:225], v[190:193], v[96:99]
	v_mfma_f32_16x16x32_bf16 v[84:87], v[214:217], v[198:201], v[84:87]
	v_mfma_f32_16x16x32_bf16 v[80:83], v[222:225], v[198:201], v[80:83]
	v_mfma_f32_16x16x32_bf16 v[68:71], v[214:217], v[206:209], v[68:71]
	v_mfma_f32_16x16x32_bf16 v[64:67], v[222:225], v[206:209], v[64:67]
	v_mfma_f32_16x16x32_bf16 v[116:119], v[218:221], v[182:185], v[116:119]
	v_mfma_f32_16x16x32_bf16 v[112:115], v[226:229], v[182:185], v[112:115]
	v_mfma_f32_16x16x32_bf16 v[100:103], v[218:221], v[194:197], v[100:103]
	v_mfma_f32_16x16x32_bf16 v[96:99], v[226:229], v[194:197], v[96:99]
	v_mfma_f32_16x16x32_bf16 v[84:87], v[218:221], v[202:205], v[84:87]
	v_mfma_f32_16x16x32_bf16 v[80:83], v[226:229], v[202:205], v[80:83]
	v_mfma_f32_16x16x32_bf16 v[68:71], v[218:221], v[210:213], v[68:71]
	v_mfma_f32_16x16x32_bf16 v[64:67], v[226:229], v[210:213], v[64:67]
	s_mov_b32 m0, s37
	v_lshl_add_u64 v[174:175], v[230:231], 0, s[6:7]
	s_barrier
	ds_read_b128 v[170:173], v153 offset:49152
	ds_read_b128 v[182:185], v153 offset:50176
	ds_read_b128 v[190:193], v153 offset:51200
	ds_read_b128 v[194:197], v153 offset:52224
	ds_read_b128 v[198:201], v153 offset:53248
	ds_read_b128 v[202:205], v153 offset:54272
	ds_read_b128 v[206:209], v153 offset:55296
	ds_read_b128 v[210:213], v153 offset:56320
	global_load_lds_dwordx4 v[174:175], off
	v_lshl_add_u64 v[174:175], v[232:233], 0, s[6:7]
	s_mov_b32 m0, s38
	s_nop 0
	global_load_lds_dwordx4 v[174:175], off
	s_barrier
; #define PG8_STAGE(bufoff, gbase, voff) do { _Pragma("unroll") for (int _i = 0; _i < 2; ++_i) \
;         __builtin_amdgcn_global_load_lds((const unsigned*)((const char*)(gbase) + (voff)[_i]), (PG8_LAS unsigned*)(lds + (bufoff) + ldsw + _i * 8192), 16, 0, 0); } while (0)
; #define PG8_MMA(ai, bj, At, Bt) do { __builtin_amdgcn_s_setprio(1); _Pragma("unroll") for (int m = 0; m < 4; ++m) _Pragma("unroll") for (int n = 0; n < 2; ++n) _Pragma("unroll") for (int k = 0; k < 2; ++k) \
;         acc[ai][bj][m][n] = __builtin_amdgcn_mfma_f32_16x16x32_bf16(Bt[n][k], At[m][k], acc[ai][bj][m][n], 0, 0, 0); __builtin_amdgcn_s_setprio(0); } while (0)
; #define PG8_WAIT_V(n) asm volatile("s_waitcnt vmcnt(" #n ")" ::: "memory")
; #define PG8_WAIT_L(n) asm volatile("s_waitcnt lgkmcnt(" #n ")" ::: "memory")
; #define PG8_BAR __builtin_amdgcn_s_barrier()
; #define PG8_SCHED __builtin_amdgcn_sched_barrier(0)
; __device__ __forceinline__ f32x4 sigmoid4(f32x4 x) {
;     f32x4 d;
; #pragma unroll
;     for (int j = 0; j < 4; ++j) d[j] = 1.0f + __expf(-fmaxf(x[j], -20.0f));
;     const float p01 = d[0] * d[1], p23 = d[2] * d[3], r = __builtin_amdgcn_rcpf(p01 * p23), r01 = r * p23, r23 = r * p01;
;     return (f32x4){r01 * d[1], r01 * d[0], r23 * d[3], r23 * d[2]};
; }
;     __device__ __forceinline__ void operator()(const f32x4 (&acc)[2][2][4][2], const Unit& u, int wr, int wc, int fr, int fq) const {
;     ...
;         else if (mode == 2) { if (u.pn >= 6) act = 2; }
;     ...
;                 for (int bj = 0; bj < 2; ++bj) { f32x4 v0 = acc[ai][bj][m][0] + bv[bj][0], v1 = acc[ai][bj][m][1] + bv[bj][1];
;                     if (act == 1) {
; #pragma unroll
;                         for (int j = 0; j < 1; ++j) { v0 = v0 * sigmoid4(v0); v1 = v1 * sigmoid4(v1); } }
;                     else if (act == 2) {
; #pragma unroll
;                         for (int j = 0; j < 1; ++j) { v0 = sigmoid4(v0); v1 = sigmoid4(v1); } }
; template <class Epi, class Sched>
; __device__ __forceinline__ void gemm_phase(PG8_LAS unsigned char* lds, const Gemm g, const Sched& S, const Epi& E) {
;     ...
;             PG8_BAR; PG8_WAIT_L(0); PG8_MMA(1, 0, At, B0); PG8_BAR; PG8_SCHED;
;             PG8_STAGE(PG8_SB(1, 1), b3 + hstep, voffB);
;             PG8_WAIT_V(6); PG8_BAR; PG8_MMA(1, 1, At, B1); PG8_BAR;
	s_waitcnt lgkmcnt(0)
	v_mfma_f32_16x16x32_bf16 v[60:63], v[144:147], v[170:173], v[60:63]
	v_mfma_f32_16x16x32_bf16 v[56:59], v[160:163], v[170:173], v[56:59]
	v_mfma_f32_16x16x32_bf16 v[44:47], v[144:147], v[190:193], v[44:47]
	v_mfma_f32_16x16x32_bf16 v[40:43], v[160:163], v[190:193], v[40:43]
	v_mfma_f32_16x16x32_bf16 v[28:31], v[144:147], v[198:201], v[28:31]
	v_mfma_f32_16x16x32_bf16 v[24:27], v[160:163], v[198:201], v[24:27]
	v_mfma_f32_16x16x32_bf16 v[12:15], v[144:147], v[206:209], v[12:15]
	v_mfma_f32_16x16x32_bf16 v[8:11], v[160:163], v[206:209], v[8:11]
	v_mfma_f32_16x16x32_bf16 v[60:63], v[156:159], v[182:185], v[60:63]
	v_mfma_f32_16x16x32_bf16 v[56:59], v[166:169], v[182:185], v[56:59]
	v_mfma_f32_16x16x32_bf16 v[44:47], v[156:159], v[194:197], v[44:47]
	v_mfma_f32_16x16x32_bf16 v[40:43], v[166:169], v[194:197], v[40:43]
	v_mfma_f32_16x16x32_bf16 v[28:31], v[156:159], v[202:205], v[28:31]
	v_mfma_f32_16x16x32_bf16 v[24:27], v[166:169], v[202:205], v[24:27]
	v_mfma_f32_16x16x32_bf16 v[12:15], v[156:159], v[210:213], v[12:15]
	v_mfma_f32_16x16x32_bf16 v[8:11], v[166:169], v[210:213], v[8:11]
	s_barrier
	s_add_u32 s20, s20, 0x40080
	s_addc_u32 s21, s21, 0
	s_add_i32 s22, s22, s30
	v_lshl_add_u64 v[144:145], s[20:21], 0, v[130:131]
	s_mov_b32 m0, s22
	s_nop 0
	global_load_lds_dwordx4 v[144:145], off
	v_lshl_add_u64 v[144:145], s[20:21], 0, v[134:135]
	s_add_i32 m0, s22, 0x2000
	s_nop 0
	global_load_lds_dwordx4 v[144:145], off
	s_waitcnt vmcnt(6)
	s_barrier
	v_mfma_f32_16x16x32_bf16 v[52:55], v[214:217], v[170:173], v[52:55]
	v_mfma_f32_16x16x32_bf16 v[48:51], v[222:225], v[170:173], v[48:51]
	v_mfma_f32_16x16x32_bf16 v[36:39], v[214:217], v[190:193], v[36:39]
	v_mfma_f32_16x16x32_bf16 v[32:35], v[222:225], v[190:193], v[32:35]
	v_mfma_f32_16x16x32_bf16 v[20:23], v[214:217], v[198:201], v[20:23]
	v_mfma_f32_16x16x32_bf16 v[16:19], v[222:225], v[198:201], v[16:19]
	v_mfma_f32_16x16x32_bf16 v[4:7], v[214:217], v[206:209], v[4:7]
	v_mfma_f32_16x16x32_bf16 v[0:3], v[222:225], v[206:209], v[0:3]
	v_mfma_f32_16x16x32_bf16 v[52:55], v[218:221], v[182:185], v[52:55]
	v_mfma_f32_16x16x32_bf16 v[48:51], v[226:229], v[182:185], v[48:51]
	v_mfma_f32_16x16x32_bf16 v[36:39], v[218:221], v[194:197], v[36:39]
	v_mfma_f32_16x16x32_bf16 v[32:35], v[226:229], v[194:197], v[32:35]
	v_mfma_f32_16x16x32_bf16 v[20:23], v[218:221], v[202:205], v[20:23]
	v_mfma_f32_16x16x32_bf16 v[16:19], v[226:229], v[202:205], v[16:19]
	v_mfma_f32_16x16x32_bf16 v[4:7], v[218:221], v[210:213], v[4:7]
	v_mfma_f32_16x16x32_bf16 v[0:3], v[226:229], v[210:213], v[0:3]
	s_add_i32 s48, s48, 2
	s_add_u32 s18, s18, 0x100
	s_addc_u32 s19, s19, 0
	s_add_u32 s46, s46, 0x100
	s_addc_u32 s47, s47, 0
	s_cmp_gt_u32 s48, 13
	s_barrier
	s_cbranch_scc0 .LBB0_724
	s_cmp_gt_i32 s4, 5
	s_cselect_b64 s[18:19], -1, 0
	s_cmp_lt_i32 s4, 6
	v_pk_add_f32 v[144:145], v[126:127], 0 op_sel_hi:[1,0]
	v_pk_add_f32 v[146:147], v[124:125], 0 op_sel_hi:[1,0]
	v_pk_add_f32 v[124:125], v[122:123], 0 op_sel_hi:[1,0]
	v_pk_add_f32 v[126:127], v[120:121], 0 op_sel_hi:[1,0]
	s_cbranch_scc1 .LBB0_727
	v_max_f32_e32 v122, v144, v144
	v_max_f32_e32 v122, 0xc1a00000, v122
	v_mul_f32_e32 v122, 0xbfb8aa3b, v122
	v_max_f32_e32 v120, v146, v146
	v_max_f32_e32 v121, v147, v147
	v_exp_f32_e32 v123, v122
	v_max_f32_e32 v122, v145, v145
	v_max_f32_e32 v120, 0xc1a00000, v120
	v_max_f32_e32 v121, 0xc1a00000, v121
	v_max_f32_e32 v122, 0xc1a00000, v122
	v_mul_f32_e32 v120, 0xbfb8aa3b, v120
	v_mul_f32_e32 v121, 0xbfb8aa3b, v121
	v_mul_f32_e32 v122, 0xbfb8aa3b, v122
	v_exp_f32_e32 v120, v120
	v_exp_f32_e32 v121, v121
	v_exp_f32_e32 v122, v122
	v_max_f32_e32 v124, v124, v124
	v_max_f32_e32 v124, 0xc1a00000, v124
	v_pk_add_f32 v[120:121], v[120:121], 1.0 op_sel_hi:[1,0]
	v_pk_add_f32 v[122:123], v[122:123], 1.0 op_sel_hi:[1,0]
	v_mov_b32_e32 v144, v120
	v_mov_b32_e32 v145, v123
	v_pk_mov_b32 v[146:147], v[120:121], v[122:123] op_sel:[1,0]
	v_mul_f32_e32 v124, 0xbfb8aa3b, v124
	v_pk_mul_f32 v[144:145], v[144:145], v[146:147]
	v_max_f32_e32 v126, v126, v126
	v_max_f32_e32 v127, v127, v127
	v_exp_f32_e32 v147, v124
	v_max_f32_e32 v124, v125, v125
	v_max_f32_e32 v126, 0xc1a00000, v126
	v_max_f32_e32 v127, 0xc1a00000, v127
	v_max_f32_e32 v124, 0xc1a00000, v124
	v_mul_f32_e32 v146, v144, v145
	v_mul_f32_e32 v126, 0xbfb8aa3b, v126
	v_mul_f32_e32 v127, 0xbfb8aa3b, v127
	v_mul_f32_e32 v124, 0xbfb8aa3b, v124
	v_rcp_f32_e32 v155, v146
	v_exp_f32_e32 v126, v126
	v_exp_f32_e32 v127, v127
	v_exp_f32_e32 v146, v124
	v_mul_f32_e32 v124, v145, v155
	v_mul_f32_e32 v144, v144, v155
	v_pk_add_f32 v[126:127], v[126:127], 1.0 op_sel_hi:[1,0]
	v_pk_add_f32 v[156:157], v[146:147], 1.0 op_sel_hi:[1,0]
	v_mov_b32_e32 v146, v126
	v_mov_b32_e32 v147, v157
	v_pk_mov_b32 v[158:159], v[126:127], v[156:157] op_sel:[1,0]
	v_pk_mul_f32 v[144:145], v[122:123], v[144:145] op_sel_hi:[1,0]
	v_pk_mul_f32 v[158:159], v[146:147], v[158:159]
	s_nop 0
	v_mul_f32_e32 v125, v158, v159
	v_rcp_f32_e32 v125, v125
	s_nop 0
	v_pk_mul_f32 v[146:147], v[120:121], v[124:125] op_sel:[1,0] op_sel_hi:[0,0]
	v_mul_f32_e32 v120, v159, v125
	v_mul_f32_e32 v122, v158, v125
	v_pk_mul_f32 v[124:125], v[156:157], v[122:123] op_sel_hi:[1,0]
	v_pk_mul_f32 v[126:127], v[126:127], v[120:121] op_sel:[1,0] op_sel_hi:[0,0]

; #define PG8_STAGE(bufoff, gbase, voff) do { _Pragma("unroll") for (int _i = 0; _i < 2; ++_i) \
;         __builtin_amdgcn_global_load_lds((const unsigned*)((const char*)(gbase) + (voff)[_i]), (PG8_LAS unsigned*)(lds + (bufoff) + ldsw + _i * 8192), 16, 0, 0); } while (0)
; #define PG8_LDA(dst, b, h) do { _Pragma("unroll") for (int m = 0; m < 4; ++m) _Pragma("unroll") for (int k = 0; k < 2; ++k) dst[m][k] = *(const PG8_LAS bf16x8*)(lds + PG8_SA(b, h) + aoff + m * 2048 + k * 1024); } while (0)
; #define PG8_LDB(dst, b, h) do { _Pragma("unroll") for (int n = 0; n < 2; ++n) _Pragma("unroll") for (int k = 0; k < 2; ++k) dst[n][k] = *(const PG8_LAS bf16x8*)(lds + PG8_SB(b, h) + boff + n * 2048 + k * 1024); } while (0)
; #define PG8_MMA(ai, bj, At, Bt) do { __builtin_amdgcn_s_setprio(1); _Pragma("unroll") for (int m = 0; m < 4; ++m) _Pragma("unroll") for (int n = 0; n < 2; ++n) _Pragma("unroll") for (int k = 0; k < 2; ++k) \
;         acc[ai][bj][m][n] = __builtin_amdgcn_mfma_f32_16x16x32_bf16(Bt[n][k], At[m][k], acc[ai][bj][m][n], 0, 0, 0); __builtin_amdgcn_s_setprio(0); } while (0)
; #define PG8_WAIT_L(n) asm volatile("s_waitcnt lgkmcnt(" #n ")" ::: "memory")
; #define PG8_BAR __builtin_amdgcn_s_barrier()
; #define PG8_SCHED __builtin_amdgcn_sched_barrier(0)
; template <class Epi, class Sched>
; __device__ __forceinline__ void gemm_phase(PG8_LAS unsigned char* lds, const Gemm g, const Sched& S, const Epi& E) {
;     ...
;             PG8_LDB(B0, 0, 0); PG8_SCHED; PG8_LDA(At, 0, 0); PG8_STAGE(PG8_SA(1, 1), a1 + hstep, voffA);
;             PG8_WAIT_L(8); PG8_BAR; PG8_WAIT_L(0); PG8_MMA(0, 0, At, B0); PG8_BAR; PG8_SCHED;
;             PG8_LDB(B1, 0, 1); PG8_STAGE(PG8_SB(0, 0), b2, voffB);
;             PG8_BAR; PG8_WAIT_L(0); PG8_MMA(0, 1, At, B1); PG8_BAR;
;             PG8_LDA(At, 0, 1); PG8_STAGE(PG8_SA(0, 0), a2, voffA);
;             PG8_BAR; PG8_WAIT_L(0); PG8_MMA(1, 0, At, B0); PG8_BAR; PG8_SCHED;
.LBB0_991:
	ds_read_b128 v[144:147], v153
	ds_read_b128 v[156:159], v153 offset:1024
	ds_read_b128 v[160:163], v153 offset:2048
	ds_read_b128 v[164:167], v153 offset:3072
	ds_read_b128 v[168:171], v154
	ds_read_b128 v[172:175], v154 offset:1024
	ds_read_b128 v[182:185], v154 offset:2048
	ds_read_b128 v[190:193], v154 offset:3072
	ds_read_b128 v[194:197], v154 offset:4096
	ds_read_b128 v[198:201], v154 offset:5120
	ds_read_b128 v[202:205], v154 offset:6144
	ds_read_b128 v[206:209], v154 offset:7168
	s_add_u32 s20, s18, 0xfffc0080
	s_addc_u32 s21, s19, -1
	s_cmp_eq_u32 s47, 12
	s_cselect_b32 s23, s11, s21
	s_cselect_b32 s22, s43, s20
	s_cselect_b32 s21, s9, s46
	s_cselect_b32 s20, s44, s45
	v_lshl_add_u64 v[148:149], s[18:19], 0, v[136:137]
	s_add_i32 m0, s17, 0xc000
	s_nop 0
	global_load_lds_dwordx4 v[148:149], off
	v_lshl_add_u64 v[148:149], s[18:19], 0, v[138:139]
	s_add_i32 m0, s17, 0xe000
	s_nop 0
	global_load_lds_dwordx4 v[148:149], off
	s_waitcnt lgkmcnt(8)
	s_barrier
	s_waitcnt lgkmcnt(0)
	v_mfma_f32_16x16x32_bf16 v[124:127], v[144:147], v[168:171], v[124:127]
	v_mfma_f32_16x16x32_bf16 v[120:123], v[160:163], v[168:171], v[120:123]
	v_mfma_f32_16x16x32_bf16 v[112:115], v[144:147], v[182:185], v[112:115]
	v_mfma_f32_16x16x32_bf16 v[104:107], v[160:163], v[182:185], v[104:107]
	v_mfma_f32_16x16x32_bf16 v[96:99], v[144:147], v[194:197], v[96:99]
	v_mfma_f32_16x16x32_bf16 v[88:91], v[160:163], v[194:197], v[88:91]
	v_mfma_f32_16x16x32_bf16 v[80:83], v[144:147], v[202:205], v[80:83]
	v_mfma_f32_16x16x32_bf16 v[72:75], v[160:163], v[202:205], v[72:75]
	v_mfma_f32_16x16x32_bf16 v[124:127], v[156:159], v[172:175], v[124:127]
	v_mfma_f32_16x16x32_bf16 v[120:123], v[164:167], v[172:175], v[120:123]
	v_mfma_f32_16x16x32_bf16 v[112:115], v[156:159], v[190:193], v[112:115]
	v_mfma_f32_16x16x32_bf16 v[104:107], v[164:167], v[190:193], v[104:107]
	v_mfma_f32_16x16x32_bf16 v[96:99], v[156:159], v[198:201], v[96:99]
	v_mfma_f32_16x16x32_bf16 v[88:91], v[164:167], v[198:201], v[88:91]
	v_mfma_f32_16x16x32_bf16 v[80:83], v[156:159], v[206:209], v[80:83]
	v_mfma_f32_16x16x32_bf16 v[72:75], v[164:167], v[206:209], v[72:75]
	s_barrier
	ds_read_b128 v[210:213], v155
	ds_read_b128 v[214:217], v155 offset:1024
	ds_read_b128 v[218:221], v155 offset:2048
	ds_read_b128 v[222:225], v155 offset:3072
	s_add_i32 s48, s39, s29
	v_lshl_add_u64 v[148:149], s[20:21], 0, v[130:131]
	s_mov_b32 m0, s48
	s_nop 0
	global_load_lds_dwordx4 v[148:149], off
	v_lshl_add_u64 v[186:187], s[20:21], 0, v[134:135]
	s_add_i32 m0, s48, 0x2000
	s_nop 0
	global_load_lds_dwordx4 v[186:187], off
	s_barrier
	s_waitcnt lgkmcnt(0)
	v_mfma_f32_16x16x32_bf16 v[116:119], v[210:213], v[168:171], v[116:119]
	v_mfma_f32_16x16x32_bf16 v[108:111], v[218:221], v[168:171], v[108:111]
	v_mfma_f32_16x16x32_bf16 v[100:103], v[210:213], v[182:185], v[100:103]
	v_mfma_f32_16x16x32_bf16 v[92:95], v[218:221], v[182:185], v[92:95]
	v_mfma_f32_16x16x32_bf16 v[84:87], v[210:213], v[194:197], v[84:87]
	v_mfma_f32_16x16x32_bf16 v[76:79], v[218:221], v[194:197], v[76:79]
	v_mfma_f32_16x16x32_bf16 v[68:71], v[210:213], v[202:205], v[68:71]
	v_mfma_f32_16x16x32_bf16 v[64:67], v[218:221], v[202:205], v[64:67]
	v_mfma_f32_16x16x32_bf16 v[116:119], v[214:217], v[172:175], v[116:119]
	v_mfma_f32_16x16x32_bf16 v[108:111], v[222:225], v[172:175], v[108:111]
	v_mfma_f32_16x16x32_bf16 v[100:103], v[214:217], v[190:193], v[100:103]
	v_mfma_f32_16x16x32_bf16 v[92:95], v[222:225], v[190:193], v[92:95]
	v_mfma_f32_16x16x32_bf16 v[84:87], v[214:217], v[198:201], v[84:87]
	v_mfma_f32_16x16x32_bf16 v[76:79], v[222:225], v[198:201], v[76:79]
	v_mfma_f32_16x16x32_bf16 v[68:71], v[214:217], v[206:209], v[68:71]
	v_mfma_f32_16x16x32_bf16 v[64:67], v[222:225], v[206:209], v[64:67]
	s_mov_b32 m0, s17
	v_lshl_add_u64 v[226:227], s[22:23], 0, v[128:129]
	s_barrier
	ds_read_b128 v[168:171], v154 offset:16384
	ds_read_b128 v[172:175], v154 offset:17408
	ds_read_b128 v[182:185], v154 offset:18432
	ds_read_b128 v[190:193], v154 offset:19456
	ds_read_b128 v[194:197], v154 offset:20480
	ds_read_b128 v[198:201], v154 offset:21504
	ds_read_b128 v[202:205], v154 offset:22528
	ds_read_b128 v[206:209], v154 offset:23552
	global_load_lds_dwordx4 v[226:227], off
	v_lshl_add_u64 v[228:229], s[22:23], 0, v[132:133]
	s_mov_b32 m0, s30
	s_nop 0
	global_load_lds_dwordx4 v[228:229], off
	s_barrier
	s_waitcnt lgkmcnt(0)
	v_mfma_f32_16x16x32_bf16 v[60:63], v[144:147], v[168:171], v[60:63]
	v_mfma_f32_16x16x32_bf16 v[56:59], v[160:163], v[168:171], v[56:59]
	v_mfma_f32_16x16x32_bf16 v[48:51], v[144:147], v[182:185], v[48:51]
	v_mfma_f32_16x16x32_bf16 v[40:43], v[160:163], v[182:185], v[40:43]
	v_mfma_f32_16x16x32_bf16 v[32:35], v[144:147], v[194:197], v[32:35]
	v_mfma_f32_16x16x32_bf16 v[24:27], v[160:163], v[194:197], v[24:27]
	v_mfma_f32_16x16x32_bf16 v[16:19], v[144:147], v[202:205], v[16:19]
	v_mfma_f32_16x16x32_bf16 v[8:11], v[160:163], v[202:205], v[8:11]
	v_mfma_f32_16x16x32_bf16 v[60:63], v[156:159], v[172:175], v[60:63]
	v_mfma_f32_16x16x32_bf16 v[56:59], v[164:167], v[172:175], v[56:59]
	v_mfma_f32_16x16x32_bf16 v[48:51], v[156:159], v[190:193], v[48:51]
	v_mfma_f32_16x16x32_bf16 v[40:43], v[164:167], v[190:193], v[40:43]
	v_mfma_f32_16x16x32_bf16 v[32:35], v[156:159], v[198:201], v[32:35]
	v_mfma_f32_16x16x32_bf16 v[24:27], v[164:167], v[198:201], v[24:27]
	v_mfma_f32_16x16x32_bf16 v[16:19], v[156:159], v[206:209], v[16:19]
	v_mfma_f32_16x16x32_bf16 v[8:11], v[164:167], v[206:209], v[8:11]
	s_barrier
; #define PG8_STAGE(bufoff, gbase, voff) do { _Pragma("unroll") for (int _i = 0; _i < 2; ++_i) \
;         __builtin_amdgcn_global_load_lds((const unsigned*)((const char*)(gbase) + (voff)[_i]), (PG8_LAS unsigned*)(lds + (bufoff) + ldsw + _i * 8192), 16, 0, 0); } while (0)
; #define PG8_LDA(dst, b, h) do { _Pragma("unroll") for (int m = 0; m < 4; ++m) _Pragma("unroll") for (int k = 0; k < 2; ++k) dst[m][k] = *(const PG8_LAS bf16x8*)(lds + PG8_SA(b, h) + aoff + m * 2048 + k * 1024); } while (0)
; #define PG8_LDB(dst, b, h) do { _Pragma("unroll") for (int n = 0; n < 2; ++n) _Pragma("unroll") for (int k = 0; k < 2; ++k) dst[n][k] = *(const PG8_LAS bf16x8*)(lds + PG8_SB(b, h) + boff + n * 2048 + k * 1024); } while (0)
; #define PG8_MMA(ai, bj, At, Bt) do { __builtin_amdgcn_s_setprio(1); _Pragma("unroll") for (int m = 0; m < 4; ++m) _Pragma("unroll") for (int n = 0; n < 2; ++n) _Pragma("unroll") for (int k = 0; k < 2; ++k) \
;         acc[ai][bj][m][n] = __builtin_amdgcn_mfma_f32_16x16x32_bf16(Bt[n][k], At[m][k], acc[ai][bj][m][n], 0, 0, 0); __builtin_amdgcn_s_setprio(0); } while (0)
; #define PG8_WAIT_V(n) asm volatile("s_waitcnt vmcnt(" #n ")" ::: "memory")
; #define PG8_WAIT_L(n) asm volatile("s_waitcnt lgkmcnt(" #n ")" ::: "memory")
; #define PG8_BAR __builtin_amdgcn_s_barrier()
; #define PG8_SCHED __builtin_amdgcn_sched_barrier(0)
; template <class Epi, class Sched>
; __device__ __forceinline__ void gemm_phase(PG8_LAS unsigned char* lds, const Gemm g, const Sched& S, const Epi& E) {
;     ...
;             PG8_STAGE(PG8_SB(0, 1), b2 + hstep, voffB);
;             PG8_WAIT_V(6); PG8_BAR; PG8_MMA(1, 1, At, B1); PG8_BAR;
;             PG8_LDB(B0, 1, 0); PG8_SCHED; PG8_LDA(At, 1, 0); PG8_STAGE(PG8_SA(0, 1), a2 + hstep, voffA);
;             PG8_WAIT_L(8); PG8_BAR; PG8_WAIT_L(0); PG8_MMA(0, 0, At, B0); PG8_BAR; PG8_SCHED;
;             PG8_LDB(B1, 1, 1); PG8_STAGE(PG8_SB(1, 0), b3, voffB);
;             PG8_BAR; PG8_WAIT_L(0); PG8_MMA(0, 1, At, B1); PG8_BAR;
;             PG8_LDA(At, 1, 1); PG8_STAGE(PG8_SA(1, 0), a3, voffA);
	s_add_u32 s48, s20, 0x40000
	s_addc_u32 s49, s21, 0
	s_add_i32 s50, s40, s29
	v_lshl_add_u64 v[144:145], s[48:49], 0, v[130:131]
	s_mov_b32 m0, s50
	s_nop 0
	global_load_lds_dwordx4 v[144:145], off
	v_lshl_add_u64 v[144:145], s[48:49], 0, v[134:135]
	s_add_i32 m0, s50, 0x2000
	s_nop 0
	global_load_lds_dwordx4 v[144:145], off
	s_waitcnt vmcnt(6)
	s_barrier
	v_mfma_f32_16x16x32_bf16 v[52:55], v[210:213], v[168:171], v[52:55]
	v_mfma_f32_16x16x32_bf16 v[44:47], v[218:221], v[168:171], v[44:47]
	v_mfma_f32_16x16x32_bf16 v[36:39], v[210:213], v[182:185], v[36:39]
	v_mfma_f32_16x16x32_bf16 v[28:31], v[218:221], v[182:185], v[28:31]
	v_mfma_f32_16x16x32_bf16 v[20:23], v[210:213], v[194:197], v[20:23]
	v_mfma_f32_16x16x32_bf16 v[12:15], v[218:221], v[194:197], v[12:15]
	v_mfma_f32_16x16x32_bf16 v[4:7], v[210:213], v[202:205], v[4:7]
	v_mfma_f32_16x16x32_bf16 v[0:3], v[218:221], v[202:205], v[0:3]
	v_mfma_f32_16x16x32_bf16 v[52:55], v[214:217], v[172:175], v[52:55]
	v_mfma_f32_16x16x32_bf16 v[44:47], v[222:225], v[172:175], v[44:47]
	v_mfma_f32_16x16x32_bf16 v[36:39], v[214:217], v[190:193], v[36:39]
	v_mfma_f32_16x16x32_bf16 v[28:31], v[222:225], v[190:193], v[28:31]
	v_mfma_f32_16x16x32_bf16 v[20:23], v[214:217], v[198:201], v[20:23]
	v_mfma_f32_16x16x32_bf16 v[12:15], v[222:225], v[198:201], v[12:15]
	v_mfma_f32_16x16x32_bf16 v[4:7], v[214:217], v[206:209], v[4:7]
	v_mfma_f32_16x16x32_bf16 v[0:3], v[222:225], v[206:209], v[0:3]
	s_add_i32 s48, 0, 0x18000
	v_add_u32_e32 v164, s48, v151
	s_barrier
	ds_read_b128 v[144:147], v164
	ds_read_b128 v[156:159], v164 offset:1024
	ds_read_b128 v[160:163], v164 offset:2048
	ds_read_b128 v[164:167], v164 offset:3072
	ds_read_b128 v[168:171], v154 offset:32768
	ds_read_b128 v[172:175], v154 offset:33792
	ds_read_b128 v[182:185], v154 offset:34816
	ds_read_b128 v[190:193], v154 offset:35840
	ds_read_b128 v[194:197], v154 offset:36864
	ds_read_b128 v[198:201], v154 offset:37888
	ds_read_b128 v[202:205], v154 offset:38912
	ds_read_b128 v[206:209], v154 offset:39936
	s_add_u32 s22, s22, 0x40000
	s_addc_u32 s23, s23, 0
	s_mov_b32 m0, s31
	v_lshl_add_u64 v[210:211], s[22:23], 0, v[128:129]
	global_load_lds_dwordx4 v[210:211], off
	v_lshl_add_u64 v[210:211], s[22:23], 0, v[132:133]
	s_mov_b32 m0, s34
	s_nop 0
	global_load_lds_dwordx4 v[210:211], off
	s_waitcnt lgkmcnt(8)
	s_barrier
	s_waitcnt lgkmcnt(0)
	v_mfma_f32_16x16x32_bf16 v[124:127], v[144:147], v[168:171], v[124:127]
	v_mfma_f32_16x16x32_bf16 v[120:123], v[160:163], v[168:171], v[120:123]
	v_mfma_f32_16x16x32_bf16 v[112:115], v[144:147], v[182:185], v[112:115]
	v_mfma_f32_16x16x32_bf16 v[104:107], v[160:163], v[182:185], v[104:107]
	v_mfma_f32_16x16x32_bf16 v[96:99], v[144:147], v[194:197], v[96:99]
	v_mfma_f32_16x16x32_bf16 v[88:91], v[160:163], v[194:197], v[88:91]
	v_mfma_f32_16x16x32_bf16 v[80:83], v[144:147], v[202:205], v[80:83]
	v_mfma_f32_16x16x32_bf16 v[72:75], v[160:163], v[202:205], v[72:75]
	v_mfma_f32_16x16x32_bf16 v[124:127], v[156:159], v[172:175], v[124:127]
	v_mfma_f32_16x16x32_bf16 v[120:123], v[164:167], v[172:175], v[120:123]
	v_mfma_f32_16x16x32_bf16 v[112:115], v[156:159], v[190:193], v[112:115]
	v_mfma_f32_16x16x32_bf16 v[104:107], v[164:167], v[190:193], v[104:107]
	v_mfma_f32_16x16x32_bf16 v[96:99], v[156:159], v[198:201], v[96:99]
	v_mfma_f32_16x16x32_bf16 v[88:91], v[164:167], v[198:201], v[88:91]
	v_mfma_f32_16x16x32_bf16 v[80:83], v[156:159], v[206:209], v[80:83]
	v_mfma_f32_16x16x32_bf16 v[72:75], v[164:167], v[206:209], v[72:75]
	s_barrier
	s_add_i32 s22, 0, 0x1c000
	v_add_u32_e32 v179, s22, v151
	ds_read_b128 v[210:213], v179
	ds_read_b128 v[214:217], v179 offset:1024
	ds_read_b128 v[218:221], v179 offset:2048
	ds_read_b128 v[222:225], v179 offset:3072
	s_add_i32 s23, s48, s29
	v_lshl_add_u64 v[148:149], v[148:149], 0, s[6:7]
	s_mov_b32 m0, s23
	s_nop 0
	global_load_lds_dwordx4 v[148:149], off
	v_lshl_add_u64 v[148:149], v[186:187], 0, s[6:7]
	s_add_i32 m0, s23, 0x2000
	s_nop 0
	global_load_lds_dwordx4 v[148:149], off
	s_barrier
	s_waitcnt lgkmcnt(0)
	v_mfma_f32_16x16x32_bf16 v[116:119], v[210:213], v[168:171], v[116:119]
	v_mfma_f32_16x16x32_bf16 v[108:111], v[218:221], v[168:171], v[108:111]
	v_mfma_f32_16x16x32_bf16 v[100:103], v[210:213], v[182:185], v[100:103]
	v_mfma_f32_16x16x32_bf16 v[92:95], v[218:221], v[182:185], v[92:95]
	v_mfma_f32_16x16x32_bf16 v[84:87], v[210:213], v[194:197], v[84:87]
	v_mfma_f32_16x16x32_bf16 v[76:79], v[218:221], v[194:197], v[76:79]
	v_mfma_f32_16x16x32_bf16 v[68:71], v[210:213], v[202:205], v[68:71]
	v_mfma_f32_16x16x32_bf16 v[64:67], v[218:221], v[202:205], v[64:67]
	v_mfma_f32_16x16x32_bf16 v[116:119], v[214:217], v[172:175], v[116:119]
	v_mfma_f32_16x16x32_bf16 v[108:111], v[222:225], v[172:175], v[108:111]
	v_mfma_f32_16x16x32_bf16 v[100:103], v[214:217], v[190:193], v[100:103]
	v_mfma_f32_16x16x32_bf16 v[92:95], v[222:225], v[190:193], v[92:95]
	v_mfma_f32_16x16x32_bf16 v[84:87], v[214:217], v[198:201], v[84:87]
	v_mfma_f32_16x16x32_bf16 v[76:79], v[222:225], v[198:201], v[76:79]
	v_mfma_f32_16x16x32_bf16 v[68:71], v[214:217], v[206:209], v[68:71]
	v_mfma_f32_16x16x32_bf16 v[64:67], v[222:225], v[206:209], v[64:67]
	s_mov_b32 m0, s36
	v_lshl_add_u64 v[148:149], v[226:227], 0, s[6:7]
	s_barrier
	ds_read_b128 v[168:171], v154 offset:49152
	ds_read_b128 v[172:175], v154 offset:50176
	ds_read_b128 v[182:185], v154 offset:51200
	ds_read_b128 v[190:193], v154 offset:52224
	ds_read_b128 v[194:197], v154 offset:53248
	ds_read_b128 v[198:201], v154 offset:54272
	ds_read_b128 v[202:205], v154 offset:55296
	ds_read_b128 v[206:209], v154 offset:56320
	global_load_lds_dwordx4 v[148:149], off
	v_lshl_add_u64 v[148:149], v[228:229], 0, s[6:7]
	s_mov_b32 m0, s37
	s_nop 0
	global_load_lds_dwordx4 v[148:149], off
	s_barrier
; __device__ __forceinline__ unsigned cvt_pk_bf16(float lo, float hi) { unsigned r; asm volatile("v_cvt_pk_bf16_f32 %0, %1, %2" : "=v"(r) : "v"(lo), "v"(hi)); return r; }
; __device__ __forceinline__ float bf_lo(unsigned u) { return __uint_as_float(u << 16); }
; __device__ __forceinline__ float bf_hi(unsigned u) { return __uint_as_float(u & 0xffff0000u); }
; #define PG8_WAIT_V(n) asm volatile("s_waitcnt vmcnt(" #n ")" ::: "memory")
; #define PG8_WAIT_L(n) asm volatile("s_waitcnt lgkmcnt(" #n ")" ::: "memory")
; #define PG8_BAR __builtin_amdgcn_s_barrier()
;     __device__ __forceinline__ void operator()(const f32x4 (&acc)[2][2][4][2], const Unit& u, int wr, int wc, int fr, int fq) const {
;         const int row0 = u.pm * BM + wr * 64 + fr, col0 = u.pn * BM + wc * 32 + 8 * fq;
; #pragma unroll
;         for (int ai = 0; ai < 2; ++ai)
; #pragma unroll
;             for (int m = 0; m < 4; ++m) { const size_t r = (size_t)(row0 + ai * HALF + m * 16); bf16_t* rowp = O + r * ldc + col0; const bf16_t* gp = G + r * ldg + col0;
; #pragma unroll
;                 for (int bj = 0; bj < 2; ++bj) { const u32x4 gw = *(const u32x4*)(gp + bj * HALF);
;                     f32x4 v0 = acc[ai][bj][m][0], v1 = acc[ai][bj][m][1];
;                     v0[0] *= bf_lo(gw.x); v0[1] *= bf_hi(gw.x); v0[2] *= bf_lo(gw.y); v0[3] *= bf_hi(gw.y);
;                     v1[0] *= bf_lo(gw.z); v1[1] *= bf_hi(gw.z); v1[2] *= bf_lo(gw.w); v1[3] *= bf_hi(gw.w);
;                     if (ACCUM) { const u32x4 pw = *(const u32x4*)(rowp + bj * HALF);
;                         v0[0] += bf_lo(pw.x); v0[1] += bf_hi(pw.x); v0[2] += bf_lo(pw.y); v0[3] += bf_hi(pw.y);
;                         v1[0] += bf_lo(pw.z); v1[1] += bf_hi(pw.z); v1[2] += bf_lo(pw.w); v1[3] += bf_hi(pw.w); }
;                     u32x4 w; w.x = cvt_pk_bf16(v0[0], v0[1]); w.y = cvt_pk_bf16(v0[2], v0[3]); w.z = cvt_pk_bf16(v1[0], v1[1]); w.w = cvt_pk_bf16(v1[2], v1[3]);
;                     *(u32x4*)(rowp + bj * HALF) = w; } }
; template <class Epi, class Sched>
; __device__ __forceinline__ void gemm_phase(PG8_LAS unsigned char* lds, const Gemm g, const Sched& S, const Epi& E) {
;     ...
;             PG8_BAR; PG8_WAIT_L(0); PG8_MMA(1, 0, At, B0); PG8_BAR; PG8_SCHED;
;             PG8_STAGE(PG8_SB(1, 1), b3 + hstep, voffB);
;             PG8_WAIT_V(6); PG8_BAR; PG8_MMA(1, 1, At, B1); PG8_BAR;
	s_waitcnt lgkmcnt(0)
	v_mfma_f32_16x16x32_bf16 v[60:63], v[144:147], v[168:171], v[60:63]
	v_mfma_f32_16x16x32_bf16 v[56:59], v[160:163], v[168:171], v[56:59]
	v_mfma_f32_16x16x32_bf16 v[48:51], v[144:147], v[182:185], v[48:51]
	v_mfma_f32_16x16x32_bf16 v[40:43], v[160:163], v[182:185], v[40:43]
	v_mfma_f32_16x16x32_bf16 v[32:35], v[144:147], v[194:197], v[32:35]
	v_mfma_f32_16x16x32_bf16 v[24:27], v[160:163], v[194:197], v[24:27]
	v_mfma_f32_16x16x32_bf16 v[16:19], v[144:147], v[202:205], v[16:19]
	v_mfma_f32_16x16x32_bf16 v[8:11], v[160:163], v[202:205], v[8:11]
	v_mfma_f32_16x16x32_bf16 v[60:63], v[156:159], v[172:175], v[60:63]
	v_mfma_f32_16x16x32_bf16 v[56:59], v[164:167], v[172:175], v[56:59]
	v_mfma_f32_16x16x32_bf16 v[48:51], v[156:159], v[190:193], v[48:51]
	v_mfma_f32_16x16x32_bf16 v[40:43], v[164:167], v[190:193], v[40:43]
	v_mfma_f32_16x16x32_bf16 v[32:35], v[156:159], v[198:201], v[32:35]
	v_mfma_f32_16x16x32_bf16 v[24:27], v[164:167], v[198:201], v[24:27]
	v_mfma_f32_16x16x32_bf16 v[16:19], v[156:159], v[206:209], v[16:19]
	v_mfma_f32_16x16x32_bf16 v[8:11], v[164:167], v[206:209], v[8:11]
	s_barrier
	s_add_u32 s20, s20, 0x40080
	s_addc_u32 s21, s21, 0
	s_add_i32 s22, s22, s29
	v_lshl_add_u64 v[144:145], s[20:21], 0, v[130:131]
	s_mov_b32 m0, s22
	s_nop 0
	global_load_lds_dwordx4 v[144:145], off
	v_lshl_add_u64 v[144:145], s[20:21], 0, v[134:135]
	s_add_i32 m0, s22, 0x2000
	s_nop 0
	global_load_lds_dwordx4 v[144:145], off
	s_waitcnt vmcnt(6)
	s_barrier
	v_mfma_f32_16x16x32_bf16 v[52:55], v[210:213], v[168:171], v[52:55]
	v_mfma_f32_16x16x32_bf16 v[44:47], v[218:221], v[168:171], v[44:47]
	v_mfma_f32_16x16x32_bf16 v[36:39], v[210:213], v[182:185], v[36:39]
	v_mfma_f32_16x16x32_bf16 v[28:31], v[218:221], v[182:185], v[28:31]
	v_mfma_f32_16x16x32_bf16 v[20:23], v[210:213], v[194:197], v[20:23]
	v_mfma_f32_16x16x32_bf16 v[12:15], v[218:221], v[194:197], v[12:15]
	v_mfma_f32_16x16x32_bf16 v[4:7], v[210:213], v[202:205], v[4:7]
	v_mfma_f32_16x16x32_bf16 v[0:3], v[218:221], v[202:205], v[0:3]
	v_mfma_f32_16x16x32_bf16 v[52:55], v[214:217], v[172:175], v[52:55]
	v_mfma_f32_16x16x32_bf16 v[44:47], v[222:225], v[172:175], v[44:47]
	v_mfma_f32_16x16x32_bf16 v[36:39], v[214:217], v[190:193], v[36:39]
	v_mfma_f32_16x16x32_bf16 v[28:31], v[222:225], v[190:193], v[28:31]
	v_mfma_f32_16x16x32_bf16 v[20:23], v[214:217], v[198:201], v[20:23]
	v_mfma_f32_16x16x32_bf16 v[12:15], v[222:225], v[198:201], v[12:15]
	v_mfma_f32_16x16x32_bf16 v[4:7], v[214:217], v[206:209], v[4:7]
	v_mfma_f32_16x16x32_bf16 v[0:3], v[222:225], v[206:209], v[0:3]
	s_add_i32 s47, s47, 2
	s_add_u32 s18, s18, 0x100
	s_addc_u32 s19, s19, 0
	s_add_u32 s45, s45, 0x100
	s_addc_u32 s46, s46, 0
	s_cmp_gt_u32 s47, 13
	s_barrier
	s_cbranch_scc0 .LBB0_991
	v_lshl_or_b32 v144, s42, 8, v152
	v_lshl_add_u32 v146, s16, 8, v150
	v_ashrrev_i32_e32 v145, 31, v144
	v_mov_b64_e32 v[148:149], s[4:5]
	v_lshlrev_b64 v[144:145], 1, v[144:145]
	v_mad_i64_i32 v[156:157], s[18:19], v146, s41, v[148:149]
	v_lshl_add_u64 v[160:161], v[156:157], 0, v[144:145]
	global_load_dwordx4 v[156:159], v[160:161], off offset:3072
	s_and_b64 vcc, exec, s[2:3]
	s_mov_b32 s42, s8
	s_mov_b32 s16, s10
	s_mov_b64 s[20:21], s[14:15]
	s_waitcnt vmcnt(0)
	v_lshlrev_b32_e32 v147, 16, v156
	v_and_b32_e32 v156, 0xffff0000, v156
	v_lshlrev_b32_e32 v162, 16, v157
	v_and_b32_e32 v157, 0xffff0000, v157
	v_lshlrev_b32_e32 v164, 16, v159
	v_and_b32_e32 v159, 0xffff0000, v159
	v_lshlrev_b32_e32 v163, 16, v158
	v_and_b32_e32 v158, 0xffff0000, v158
	v_mul_f32_e32 v124, v124, v147
	v_mul_f32_e32 v125, v125, v156
	v_mul_f32_e32 v126, v126, v162
	v_mul_f32_e32 v127, v127, v157
	v_mul_f32_e32 v123, v123, v159
	v_mul_f32_e32 v147, v120, v163
	v_mul_f32_e32 v156, v121, v158
	v_mul_f32_e32 v157, v122, v164
	v_cvt_pk_bf16_f32 v120, v124, v125
	v_cvt_pk_bf16_f32 v121, v126, v127
	v_cvt_pk_bf16_f32 v122, v147, v156
	v_cvt_pk_bf16_f32 v123, v157, v123
	global_load_dwordx4 v[124:127], v[160:161], off offset:3328
	v_ashrrev_i32_e32 v147, 31, v146
	v_lshlrev_b64 v[158:159], 11, v[146:147]
	v_lshl_add_u64 v[158:159], s[0:1], 0, v[158:159]
	v_or_b32_e32 v156, 16, v146
	v_lshl_add_u64 v[158:159], v[158:159], 0, v[144:145]
	v_mad_i64_i32 v[160:161], s[18:19], v156, s41, v[148:149]
	global_store_dwordx4 v[158:159], v[120:123], off
	v_lshl_add_u64 v[160:161], v[160:161], 0, v[144:145]
	v_ashrrev_i32_e32 v157, 31, v156
	s_waitcnt vmcnt(0)
	v_lshlrev_b32_e32 v120, 16, v124
	v_and_b32_e32 v121, 0xffff0000, v124
	v_lshlrev_b32_e32 v122, 16, v125
	v_and_b32_e32 v123, 0xffff0000, v125
	v_lshlrev_b32_e32 v124, 16, v126
	v_and_b32_e32 v125, 0xffff0000, v126
	v_lshlrev_b32_e32 v126, 16, v127
	v_and_b32_e32 v127, 0xffff0000, v127
	v_mul_f32_e32 v116, v116, v120
	v_mul_f32_e32 v117, v117, v121
	v_mul_f32_e32 v118, v118, v122
	v_mul_f32_e32 v119, v119, v123
	v_mul_f32_e32 v111, v111, v127
	v_mul_f32_e32 v120, v108, v124
	v_mul_f32_e32 v121, v109, v125
	v_mul_f32_e32 v122, v110, v126
	v_cvt_pk_bf16_f32 v108, v116, v117
	v_cvt_pk_bf16_f32 v109, v118, v119
	v_cvt_pk_bf16_f32 v110, v120, v121
	v_cvt_pk_bf16_f32 v111, v122, v111
	global_load_dwordx4 v[116:119], v[160:161], off offset:3072
	s_nop 0
	global_store_dwordx4 v[158:159], v[108:111], off offset:256
	s_waitcnt vmcnt(0)
; __device__ __forceinline__ unsigned cvt_pk_bf16(float lo, float hi) { unsigned r; asm volatile("v_cvt_pk_bf16_f32 %0, %1, %2" : "=v"(r) : "v"(lo), "v"(hi)); return r; }
; __device__ __forceinline__ float bf_lo(unsigned u) { return __uint_as_float(u << 16); }
; __device__ __forceinline__ float bf_hi(unsigned u) { return __uint_as_float(u & 0xffff0000u); }
;     __device__ __forceinline__ void operator()(const f32x4 (&acc)[2][2][4][2], const Unit& u, int wr, int wc, int fr, int fq) const {
;     ...
;             for (int m = 0; m < 4; ++m) { const size_t r = (size_t)(row0 + ai * HALF + m * 16); bf16_t* rowp = O + r * ldc + col0; const bf16_t* gp = G + r * ldg + col0;
; #pragma unroll
;                 for (int bj = 0; bj < 2; ++bj) { const u32x4 gw = *(const u32x4*)(gp + bj * HALF);
;                     f32x4 v0 = acc[ai][bj][m][0], v1 = acc[ai][bj][m][1];
;                     v0[0] *= bf_lo(gw.x); v0[1] *= bf_hi(gw.x); v0[2] *= bf_lo(gw.y); v0[3] *= bf_hi(gw.y);
;                     v1[0] *= bf_lo(gw.z); v1[1] *= bf_hi(gw.z); v1[2] *= bf_lo(gw.w); v1[3] *= bf_hi(gw.w);
;                     if (ACCUM) { const u32x4 pw = *(const u32x4*)(rowp + bj * HALF);
;                         v0[0] += bf_lo(pw.x); v0[1] += bf_hi(pw.x); v0[2] += bf_lo(pw.y); v0[3] += bf_hi(pw.y);
;                         v1[0] += bf_lo(pw.z); v1[1] += bf_hi(pw.z); v1[2] += bf_lo(pw.w); v1[3] += bf_hi(pw.w); }
;                     u32x4 w; w.x = cvt_pk_bf16(v0[0], v0[1]); w.y = cvt_pk_bf16(v0[2], v0[3]); w.z = cvt_pk_bf16(v1[0], v1[1]); w.w = cvt_pk_bf16(v1[2], v1[3]);
;                     *(u32x4*)(rowp + bj * HALF) = w; } }
	s_nop 0
	v_lshlrev_b32_e32 v108, 16, v116
	v_and_b32_e32 v109, 0xffff0000, v116
	v_lshlrev_b32_e32 v110, 16, v117
	v_and_b32_e32 v111, 0xffff0000, v117
	v_lshlrev_b32_e32 v116, 16, v118
	v_and_b32_e32 v117, 0xffff0000, v118
	v_lshlrev_b32_e32 v118, 16, v119
	v_and_b32_e32 v119, 0xffff0000, v119
	v_mul_f32_e32 v108, v112, v108
	v_mul_f32_e32 v109, v113, v109
	v_mul_f32_e32 v110, v114, v110
	v_mul_f32_e32 v111, v115, v111
	v_mul_f32_e32 v107, v107, v119
	v_mul_f32_e32 v112, v104, v116
	v_mul_f32_e32 v113, v105, v117
	v_mul_f32_e32 v114, v106, v118
	v_cvt_pk_bf16_f32 v104, v108, v109
	v_cvt_pk_bf16_f32 v105, v110, v111
	v_cvt_pk_bf16_f32 v106, v112, v113
	v_cvt_pk_bf16_f32 v107, v114, v107
	global_load_dwordx4 v[108:111], v[160:161], off offset:3328
	v_lshlrev_b64 v[116:117], 11, v[156:157]
	v_lshl_add_u64 v[116:117], s[0:1], 0, v[116:117]
	v_or_b32_e32 v112, 32, v146
	v_lshl_add_u64 v[116:117], v[116:117], 0, v[144:145]
	v_mad_i64_i32 v[114:115], s[18:19], v112, s41, v[148:149]
	global_store_dwordx4 v[116:117], v[104:107], off
	v_lshl_add_u64 v[114:115], v[114:115], 0, v[144:145]
	v_ashrrev_i32_e32 v113, 31, v112
	s_waitcnt vmcnt(0)
	v_lshlrev_b32_e32 v104, 16, v108
	v_and_b32_e32 v105, 0xffff0000, v108
	v_lshlrev_b32_e32 v106, 16, v109
	v_and_b32_e32 v107, 0xffff0000, v109
	v_lshlrev_b32_e32 v108, 16, v110
	v_and_b32_e32 v109, 0xffff0000, v110
	v_lshlrev_b32_e32 v110, 16, v111
	v_and_b32_e32 v111, 0xffff0000, v111
	v_mul_f32_e32 v100, v100, v104
	v_mul_f32_e32 v101, v101, v105
	v_mul_f32_e32 v102, v102, v106
	v_mul_f32_e32 v103, v103, v107
	v_mul_f32_e32 v95, v95, v111
	v_mul_f32_e32 v104, v92, v108
	v_mul_f32_e32 v105, v93, v109
	v_mul_f32_e32 v106, v94, v110
	v_cvt_pk_bf16_f32 v92, v100, v101
	v_cvt_pk_bf16_f32 v93, v102, v103
	v_cvt_pk_bf16_f32 v94, v104, v105
	v_cvt_pk_bf16_f32 v95, v106, v95
	global_load_dwordx4 v[100:103], v[114:115], off offset:3072
	s_nop 0
	global_store_dwordx4 v[116:117], v[92:95], off offset:256
	s_waitcnt vmcnt(0)
	s_nop 0
	v_lshlrev_b32_e32 v92, 16, v100
	v_and_b32_e32 v93, 0xffff0000, v100
	v_lshlrev_b32_e32 v94, 16, v101
	v_and_b32_e32 v95, 0xffff0000, v101
	v_lshlrev_b32_e32 v100, 16, v102
	v_and_b32_e32 v101, 0xffff0000, v102
	v_lshlrev_b32_e32 v102, 16, v103
	v_and_b32_e32 v103, 0xffff0000, v103
	v_mul_f32_e32 v92, v96, v92
	v_mul_f32_e32 v93, v97, v93
	v_mul_f32_e32 v94, v98, v94
	v_mul_f32_e32 v95, v99, v95
	v_mul_f32_e32 v91, v91, v103
	v_mul_f32_e32 v96, v88, v100
	v_mul_f32_e32 v97, v89, v101
	v_mul_f32_e32 v98, v90, v102
	v_cvt_pk_bf16_f32 v88, v92, v93
	v_cvt_pk_bf16_f32 v89, v94, v95
	v_cvt_pk_bf16_f32 v90, v96, v97
	v_cvt_pk_bf16_f32 v91, v98, v91
	global_load_dwordx4 v[92:95], v[114:115], off offset:3328
	v_lshlrev_b64 v[100:101], 11, v[112:113]
	v_lshl_add_u64 v[100:101], s[0:1], 0, v[100:101]
	v_or_b32_e32 v96, 48, v146
	v_lshl_add_u64 v[100:101], v[100:101], 0, v[144:145]
	v_mad_i64_i32 v[98:99], s[18:19], v96, s41, v[148:149]
	global_store_dwordx4 v[100:101], v[88:91], off
	v_lshl_add_u64 v[98:99], v[98:99], 0, v[144:145]
	v_ashrrev_i32_e32 v97, 31, v96
	s_waitcnt vmcnt(0)
	v_lshlrev_b32_e32 v88, 16, v92
	v_and_b32_e32 v89, 0xffff0000, v92
	v_lshlrev_b32_e32 v90, 16, v93
	v_and_b32_e32 v91, 0xffff0000, v93
	v_lshlrev_b32_e32 v92, 16, v94
	v_and_b32_e32 v93, 0xffff0000, v94
	v_lshlrev_b32_e32 v94, 16, v95
	v_and_b32_e32 v95, 0xffff0000, v95
	v_mul_f32_e32 v84, v84, v88
	v_mul_f32_e32 v85, v85, v89
	v_mul_f32_e32 v86, v86, v90
	v_mul_f32_e32 v87, v87, v91
	v_mul_f32_e32 v79, v79, v95
	v_mul_f32_e32 v88, v76, v92
	v_mul_f32_e32 v89, v77, v93
	v_mul_f32_e32 v90, v78, v94
	v_cvt_pk_bf16_f32 v76, v84, v85
	v_cvt_pk_bf16_f32 v77, v86, v87
	v_cvt_pk_bf16_f32 v78, v88, v89
	v_cvt_pk_bf16_f32 v79, v90, v79
	global_load_dwordx4 v[84:87], v[98:99], off offset:3072
	s_nop 0
	global_store_dwordx4 v[100:101], v[76:79], off offset:256
	s_waitcnt vmcnt(0)
	s_nop 0
	v_lshlrev_b32_e32 v76, 16, v84
	v_and_b32_e32 v77, 0xffff0000, v84
	v_lshlrev_b32_e32 v78, 16, v85
	v_and_b32_e32 v79, 0xffff0000, v85
	v_lshlrev_b32_e32 v84, 16, v86
	v_and_b32_e32 v85, 0xffff0000, v86
	v_lshlrev_b32_e32 v86, 16, v87
	v_and_b32_e32 v87, 0xffff0000, v87
	v_mul_f32_e32 v76, v80, v76
	v_mul_f32_e32 v77, v81, v77
	v_mul_f32_e32 v78, v82, v78
	v_mul_f32_e32 v79, v83, v79
	v_mul_f32_e32 v75, v75, v87
	v_mul_f32_e32 v80, v72, v84
	v_mul_f32_e32 v81, v73, v85
	v_mul_f32_e32 v82, v74, v86
	v_cvt_pk_bf16_f32 v72, v76, v77
	v_cvt_pk_bf16_f32 v73, v78, v79
	v_cvt_pk_bf16_f32 v74, v80, v81
	v_cvt_pk_bf16_f32 v75, v82, v75
	global_load_dwordx4 v[76:79], v[98:99], off offset:3328
	v_lshlrev_b64 v[84:85], 11, v[96:97]
	v_lshl_add_u64 v[84:85], s[0:1], 0, v[84:85]
	v_add_u32_e32 v80, 0x80, v146
	v_lshl_add_u64 v[84:85], v[84:85], 0, v[144:145]
	v_mad_i64_i32 v[82:83], s[18:19], v80, s41, v[148:149]
	global_store_dwordx4 v[84:85], v[72:75], off
	v_lshl_add_u64 v[82:83], v[82:83], 0, v[144:145]
	v_ashrrev_i32_e32 v81, 31, v80
	s_waitcnt vmcnt(0)
	v_lshlrev_b32_e32 v72, 16, v76
	v_and_b32_e32 v73, 0xffff0000, v76
	v_lshlrev_b32_e32 v74, 16, v77
	v_and_b32_e32 v75, 0xffff0000, v77
	v_lshlrev_b32_e32 v76, 16, v78
	v_and_b32_e32 v77, 0xffff0000, v78
	v_lshlrev_b32_e32 v78, 16, v79
	v_and_b32_e32 v79, 0xffff0000, v79
	v_mul_f32_e32 v68, v68, v72
	v_mul_f32_e32 v69, v69, v73
	v_mul_f32_e32 v70, v70, v74
	v_mul_f32_e32 v71, v71, v75
	v_mul_f32_e32 v67, v67, v79
	v_mul_f32_e32 v72, v64, v76
	v_mul_f32_e32 v73, v65, v77
	v_mul_f32_e32 v74, v66, v78
	v_cvt_pk_bf16_f32 v64, v68, v69
	v_cvt_pk_bf16_f32 v65, v70, v71
	v_cvt_pk_bf16_f32 v66, v72, v73
	v_cvt_pk_bf16_f32 v67, v74, v67
	global_load_dwordx4 v[68:71], v[82:83], off offset:3072
	s_nop 0
	global_store_dwordx4 v[84:85], v[64:67], off offset:256
	s_waitcnt vmcnt(0)
; __device__ __forceinline__ unsigned cvt_pk_bf16(float lo, float hi) { unsigned r; asm volatile("v_cvt_pk_bf16_f32 %0, %1, %2" : "=v"(r) : "v"(lo), "v"(hi)); return r; }
; __device__ __forceinline__ float bf_lo(unsigned u) { return __uint_as_float(u << 16); }
; __device__ __forceinline__ float bf_hi(unsigned u) { return __uint_as_float(u & 0xffff0000u); }
;     __device__ __forceinline__ void operator()(const f32x4 (&acc)[2][2][4][2], const Unit& u, int wr, int wc, int fr, int fq) const {
;     ...
;             for (int m = 0; m < 4; ++m) { const size_t r = (size_t)(row0 + ai * HALF + m * 16); bf16_t* rowp = O + r * ldc + col0; const bf16_t* gp = G + r * ldg + col0;
; #pragma unroll
;                 for (int bj = 0; bj < 2; ++bj) { const u32x4 gw = *(const u32x4*)(gp + bj * HALF);
;                     f32x4 v0 = acc[ai][bj][m][0], v1 = acc[ai][bj][m][1];
;                     v0[0] *= bf_lo(gw.x); v0[1] *= bf_hi(gw.x); v0[2] *= bf_lo(gw.y); v0[3] *= bf_hi(gw.y);
;                     v1[0] *= bf_lo(gw.z); v1[1] *= bf_hi(gw.z); v1[2] *= bf_lo(gw.w); v1[3] *= bf_hi(gw.w);
;                     if (ACCUM) { const u32x4 pw = *(const u32x4*)(rowp + bj * HALF);
;                         v0[0] += bf_lo(pw.x); v0[1] += bf_hi(pw.x); v0[2] += bf_lo(pw.y); v0[3] += bf_hi(pw.y);
;                         v1[0] += bf_lo(pw.z); v1[1] += bf_hi(pw.z); v1[2] += bf_lo(pw.w); v1[3] += bf_hi(pw.w); }
;                     u32x4 w; w.x = cvt_pk_bf16(v0[0], v0[1]); w.y = cvt_pk_bf16(v0[2], v0[3]); w.z = cvt_pk_bf16(v1[0], v1[1]); w.w = cvt_pk_bf16(v1[2], v1[3]);
;                     *(u32x4*)(rowp + bj * HALF) = w; } }
	s_nop 0
	v_lshlrev_b32_e32 v64, 16, v68
	v_and_b32_e32 v65, 0xffff0000, v68
	v_lshlrev_b32_e32 v66, 16, v69
	v_and_b32_e32 v67, 0xffff0000, v69
	v_lshlrev_b32_e32 v68, 16, v70
	v_and_b32_e32 v69, 0xffff0000, v70
	v_lshlrev_b32_e32 v70, 16, v71
	v_and_b32_e32 v71, 0xffff0000, v71
	v_mul_f32_e32 v60, v60, v64
	v_mul_f32_e32 v61, v61, v65
	v_mul_f32_e32 v62, v62, v66
	v_mul_f32_e32 v63, v63, v67
	v_mul_f32_e32 v59, v59, v71
	v_mul_f32_e32 v64, v56, v68
	v_mul_f32_e32 v65, v57, v69
	v_mul_f32_e32 v66, v58, v70
	v_cvt_pk_bf16_f32 v56, v60, v61
	v_cvt_pk_bf16_f32 v57, v62, v63
	v_cvt_pk_bf16_f32 v58, v64, v65
	v_cvt_pk_bf16_f32 v59, v66, v59
	global_load_dwordx4 v[60:63], v[82:83], off offset:3328
	v_lshlrev_b64 v[68:69], 11, v[80:81]
	v_lshl_add_u64 v[68:69], s[0:1], 0, v[68:69]
	v_add_u32_e32 v64, 0x90, v146
	v_lshl_add_u64 v[68:69], v[68:69], 0, v[144:145]
	v_mad_i64_i32 v[66:67], s[18:19], v64, s41, v[148:149]
	global_store_dwordx4 v[68:69], v[56:59], off
	v_lshl_add_u64 v[66:67], v[66:67], 0, v[144:145]
	v_ashrrev_i32_e32 v65, 31, v64
	s_waitcnt vmcnt(0)
	v_lshlrev_b32_e32 v56, 16, v60
	v_and_b32_e32 v57, 0xffff0000, v60
	v_lshlrev_b32_e32 v58, 16, v61
	v_and_b32_e32 v59, 0xffff0000, v61
	v_lshlrev_b32_e32 v60, 16, v62
	v_and_b32_e32 v61, 0xffff0000, v62
	v_lshlrev_b32_e32 v62, 16, v63
	v_and_b32_e32 v63, 0xffff0000, v63
	v_mul_f32_e32 v52, v52, v56
	v_mul_f32_e32 v53, v53, v57
	v_mul_f32_e32 v54, v54, v58
	v_mul_f32_e32 v55, v55, v59
	v_mul_f32_e32 v47, v47, v63
	v_mul_f32_e32 v56, v44, v60
	v_mul_f32_e32 v57, v45, v61
	v_mul_f32_e32 v58, v46, v62
	v_cvt_pk_bf16_f32 v44, v52, v53
	v_cvt_pk_bf16_f32 v45, v54, v55
	v_cvt_pk_bf16_f32 v46, v56, v57
	v_cvt_pk_bf16_f32 v47, v58, v47
	global_load_dwordx4 v[52:55], v[66:67], off offset:3072
	s_nop 0
	global_store_dwordx4 v[68:69], v[44:47], off offset:256
	s_waitcnt vmcnt(0)
	s_nop 0
	v_lshlrev_b32_e32 v44, 16, v52
	v_and_b32_e32 v45, 0xffff0000, v52
	v_lshlrev_b32_e32 v46, 16, v53
	v_and_b32_e32 v47, 0xffff0000, v53
	v_lshlrev_b32_e32 v52, 16, v54
	v_and_b32_e32 v53, 0xffff0000, v54
	v_lshlrev_b32_e32 v54, 16, v55
	v_and_b32_e32 v55, 0xffff0000, v55
	v_mul_f32_e32 v44, v48, v44
	v_mul_f32_e32 v45, v49, v45
	v_mul_f32_e32 v46, v50, v46
	v_mul_f32_e32 v47, v51, v47
	v_mul_f32_e32 v43, v43, v55
	v_mul_f32_e32 v48, v40, v52
	v_mul_f32_e32 v49, v41, v53
	v_mul_f32_e32 v50, v42, v54
	v_cvt_pk_bf16_f32 v40, v44, v45
	v_cvt_pk_bf16_f32 v41, v46, v47
	v_cvt_pk_bf16_f32 v42, v48, v49
	v_cvt_pk_bf16_f32 v43, v50, v43
	global_load_dwordx4 v[44:47], v[66:67], off offset:3328
	v_lshlrev_b64 v[52:53], 11, v[64:65]
	v_lshl_add_u64 v[52:53], s[0:1], 0, v[52:53]
	v_add_u32_e32 v48, 0xa0, v146
	v_lshl_add_u64 v[52:53], v[52:53], 0, v[144:145]
	v_mad_i64_i32 v[50:51], s[18:19], v48, s41, v[148:149]
	global_store_dwordx4 v[52:53], v[40:43], off
	v_lshl_add_u64 v[50:51], v[50:51], 0, v[144:145]
	v_ashrrev_i32_e32 v49, 31, v48
	s_waitcnt vmcnt(0)
	v_lshlrev_b32_e32 v40, 16, v44
	v_and_b32_e32 v41, 0xffff0000, v44
	v_lshlrev_b32_e32 v42, 16, v45
	v_and_b32_e32 v43, 0xffff0000, v45
	v_lshlrev_b32_e32 v44, 16, v46
	v_and_b32_e32 v45, 0xffff0000, v46
	v_lshlrev_b32_e32 v46, 16, v47
	v_and_b32_e32 v47, 0xffff0000, v47
	v_mul_f32_e32 v36, v36, v40
	v_mul_f32_e32 v37, v37, v41
	v_mul_f32_e32 v38, v38, v42
	v_mul_f32_e32 v39, v39, v43
	v_mul_f32_e32 v31, v31, v47
	v_mul_f32_e32 v40, v28, v44
	v_mul_f32_e32 v41, v29, v45
	v_mul_f32_e32 v42, v30, v46
	v_cvt_pk_bf16_f32 v28, v36, v37
	v_cvt_pk_bf16_f32 v29, v38, v39
	v_cvt_pk_bf16_f32 v30, v40, v41
	v_cvt_pk_bf16_f32 v31, v42, v31
	global_load_dwordx4 v[36:39], v[50:51], off offset:3072
	s_nop 0
	global_store_dwordx4 v[52:53], v[28:31], off offset:256
	s_waitcnt vmcnt(0)
; __device__ __forceinline__ unsigned cvt_pk_bf16(float lo, float hi) { unsigned r; asm volatile("v_cvt_pk_bf16_f32 %0, %1, %2" : "=v"(r) : "v"(lo), "v"(hi)); return r; }
; __device__ __forceinline__ float bf_lo(unsigned u) { return __uint_as_float(u << 16); }
; __device__ __forceinline__ float bf_hi(unsigned u) { return __uint_as_float(u & 0xffff0000u); }
; #define PG8_WAIT_V(n) asm volatile("s_waitcnt vmcnt(" #n ")" ::: "memory")
; #define PG8_BAR __builtin_amdgcn_s_barrier()
;     __device__ __forceinline__ void operator()(const f32x4 (&acc)[2][2][4][2], const Unit& u, int wr, int wc, int fr, int fq) const {
;     ...
;             for (int m = 0; m < 4; ++m) { const size_t r = (size_t)(row0 + ai * HALF + m * 16); bf16_t* rowp = O + r * ldc + col0; const bf16_t* gp = G + r * ldg + col0;
; #pragma unroll
;                 for (int bj = 0; bj < 2; ++bj) { const u32x4 gw = *(const u32x4*)(gp + bj * HALF);
;                     f32x4 v0 = acc[ai][bj][m][0], v1 = acc[ai][bj][m][1];
;                     v0[0] *= bf_lo(gw.x); v0[1] *= bf_hi(gw.x); v0[2] *= bf_lo(gw.y); v0[3] *= bf_hi(gw.y);
;                     v1[0] *= bf_lo(gw.z); v1[1] *= bf_hi(gw.z); v1[2] *= bf_lo(gw.w); v1[3] *= bf_hi(gw.w);
;                     if (ACCUM) { const u32x4 pw = *(const u32x4*)(rowp + bj * HALF);
;                         v0[0] += bf_lo(pw.x); v0[1] += bf_hi(pw.x); v0[2] += bf_lo(pw.y); v0[3] += bf_hi(pw.y);
;                         v1[0] += bf_lo(pw.z); v1[1] += bf_hi(pw.z); v1[2] += bf_lo(pw.w); v1[3] += bf_hi(pw.w); }
;                     u32x4 w; w.x = cvt_pk_bf16(v0[0], v0[1]); w.y = cvt_pk_bf16(v0[2], v0[3]); w.z = cvt_pk_bf16(v1[0], v1[1]); w.w = cvt_pk_bf16(v1[2], v1[3]);
;                     *(u32x4*)(rowp + bj * HALF) = w; } }
; template <class Epi, class Sched>
; __device__ __forceinline__ void gemm_phase(PG8_LAS unsigned char* lds, const Gemm g, const Sched& S, const Epi& E) {
;     ...
;         if (!has_next) break;
;     ...
;     PG8_WAIT_V(0);
;     if (wr == 0) PG8_BAR;
;     PG8_BAR;
	s_nop 0
	v_lshlrev_b32_e32 v28, 16, v36
	v_and_b32_e32 v29, 0xffff0000, v36
	v_lshlrev_b32_e32 v30, 16, v37
	v_and_b32_e32 v31, 0xffff0000, v37
	v_lshlrev_b32_e32 v36, 16, v38
	v_and_b32_e32 v37, 0xffff0000, v38
	v_lshlrev_b32_e32 v38, 16, v39
	v_and_b32_e32 v39, 0xffff0000, v39
	v_mul_f32_e32 v28, v32, v28
	v_mul_f32_e32 v29, v33, v29
	v_mul_f32_e32 v30, v34, v30
	v_mul_f32_e32 v31, v35, v31
	v_mul_f32_e32 v27, v27, v39
	v_mul_f32_e32 v32, v24, v36
	v_mul_f32_e32 v33, v25, v37
	v_mul_f32_e32 v34, v26, v38
	v_cvt_pk_bf16_f32 v24, v28, v29
	v_cvt_pk_bf16_f32 v25, v30, v31
	v_cvt_pk_bf16_f32 v26, v32, v33
	v_cvt_pk_bf16_f32 v27, v34, v27
	global_load_dwordx4 v[28:31], v[50:51], off offset:3328
	v_lshlrev_b64 v[36:37], 11, v[48:49]
	v_lshl_add_u64 v[36:37], s[0:1], 0, v[36:37]
	v_add_u32_e32 v32, 0xb0, v146
	v_lshl_add_u64 v[36:37], v[36:37], 0, v[144:145]
	v_mad_i64_i32 v[34:35], s[18:19], v32, s41, v[148:149]
	global_store_dwordx4 v[36:37], v[24:27], off
	v_lshl_add_u64 v[34:35], v[34:35], 0, v[144:145]
	v_ashrrev_i32_e32 v33, 31, v32
	s_mov_b64 s[18:19], s[12:13]
	s_waitcnt vmcnt(0)
	v_lshlrev_b32_e32 v24, 16, v28
	v_and_b32_e32 v25, 0xffff0000, v28
	v_lshlrev_b32_e32 v26, 16, v29
	v_and_b32_e32 v27, 0xffff0000, v29
	v_lshlrev_b32_e32 v28, 16, v30
	v_and_b32_e32 v29, 0xffff0000, v30
	v_lshlrev_b32_e32 v30, 16, v31
	v_and_b32_e32 v31, 0xffff0000, v31
	v_mul_f32_e32 v20, v20, v24
	v_mul_f32_e32 v21, v21, v25
	v_mul_f32_e32 v22, v22, v26
	v_mul_f32_e32 v23, v23, v27
	v_mul_f32_e32 v15, v15, v31
	v_mul_f32_e32 v24, v12, v28
	v_mul_f32_e32 v25, v13, v29
	v_mul_f32_e32 v26, v14, v30
	v_cvt_pk_bf16_f32 v12, v20, v21
	v_cvt_pk_bf16_f32 v13, v22, v23
	v_cvt_pk_bf16_f32 v14, v24, v25
	v_cvt_pk_bf16_f32 v15, v26, v15
	global_load_dwordx4 v[20:23], v[34:35], off offset:3072
	s_nop 0
	global_store_dwordx4 v[36:37], v[12:15], off offset:256
	s_waitcnt vmcnt(0)
	s_nop 0
	v_lshlrev_b32_e32 v12, 16, v20
	v_and_b32_e32 v13, 0xffff0000, v20
	v_lshlrev_b32_e32 v14, 16, v21
	v_and_b32_e32 v15, 0xffff0000, v21
	v_lshlrev_b32_e32 v20, 16, v22
	v_and_b32_e32 v21, 0xffff0000, v22
	v_lshlrev_b32_e32 v22, 16, v23
	v_and_b32_e32 v23, 0xffff0000, v23
	v_mul_f32_e32 v12, v16, v12
	v_mul_f32_e32 v13, v17, v13
	v_mul_f32_e32 v14, v18, v14
	v_mul_f32_e32 v15, v19, v15
	v_mul_f32_e32 v11, v11, v23
	v_mul_f32_e32 v16, v8, v20
	v_mul_f32_e32 v17, v9, v21
	v_mul_f32_e32 v18, v10, v22
	v_cvt_pk_bf16_f32 v8, v12, v13
	v_cvt_pk_bf16_f32 v9, v14, v15
	v_cvt_pk_bf16_f32 v10, v16, v17
	v_cvt_pk_bf16_f32 v11, v18, v11
	global_load_dwordx4 v[12:15], v[34:35], off offset:3328
	v_lshlrev_b64 v[16:17], 11, v[32:33]
	v_lshl_add_u64 v[16:17], s[0:1], 0, v[16:17]
	v_lshl_add_u64 v[16:17], v[16:17], 0, v[144:145]
	global_store_dwordx4 v[16:17], v[8:11], off
	s_waitcnt vmcnt(0)
	s_nop 0
	v_lshlrev_b32_e32 v8, 16, v12
	v_and_b32_e32 v9, 0xffff0000, v12
	v_lshlrev_b32_e32 v10, 16, v13
	v_and_b32_e32 v11, 0xffff0000, v13
	v_lshlrev_b32_e32 v12, 16, v14
	v_and_b32_e32 v13, 0xffff0000, v14
	v_lshlrev_b32_e32 v14, 16, v15
	v_and_b32_e32 v15, 0xffff0000, v15
	v_mul_f32_e32 v3, v3, v15
	v_mul_f32_e32 v4, v4, v8
	v_mul_f32_e32 v5, v5, v9
	v_mul_f32_e32 v6, v6, v10
	v_mul_f32_e32 v7, v7, v11
	v_mul_f32_e32 v8, v0, v12
	v_mul_f32_e32 v9, v1, v13
	v_mul_f32_e32 v10, v2, v14
	v_cvt_pk_bf16_f32 v0, v4, v5
	v_cvt_pk_bf16_f32 v1, v6, v7
	v_cvt_pk_bf16_f32 v2, v8, v9
	v_cvt_pk_bf16_f32 v3, v10, v3
	global_store_dwordx4 v[16:17], v[0:3], off offset:256
	s_cbranch_vccz .LBB0_984
	s_waitcnt vmcnt(0)
	s_cmpk_gt_u32 s25, 0xff
	s_cbranch_scc1 .LBB0_995
	s_barrier

; #define PG8_STAGE(bufoff, gbase, voff) do { _Pragma("unroll") for (int _i = 0; _i < 2; ++_i) \
;         __builtin_amdgcn_global_load_lds((const unsigned*)((const char*)(gbase) + (voff)[_i]), (PG8_LAS unsigned*)(lds + (bufoff) + ldsw + _i * 8192), 16, 0, 0); } while (0)
; #define PG8_LDA(dst, b, h) do { _Pragma("unroll") for (int m = 0; m < 4; ++m) _Pragma("unroll") for (int k = 0; k < 2; ++k) dst[m][k] = *(const PG8_LAS bf16x8*)(lds + PG8_SA(b, h) + aoff + m * 2048 + k * 1024); } while (0)
; #define PG8_LDB(dst, b, h) do { _Pragma("unroll") for (int n = 0; n < 2; ++n) _Pragma("unroll") for (int k = 0; k < 2; ++k) dst[n][k] = *(const PG8_LAS bf16x8*)(lds + PG8_SB(b, h) + boff + n * 2048 + k * 1024); } while (0)
; #define PG8_MMA(ai, bj, At, Bt) do { __builtin_amdgcn_s_setprio(1); _Pragma("unroll") for (int m = 0; m < 4; ++m) _Pragma("unroll") for (int n = 0; n < 2; ++n) _Pragma("unroll") for (int k = 0; k < 2; ++k) \
;         acc[ai][bj][m][n] = __builtin_amdgcn_mfma_f32_16x16x32_bf16(Bt[n][k], At[m][k], acc[ai][bj][m][n], 0, 0, 0); __builtin_amdgcn_s_setprio(0); } while (0)
; #define PG8_WAIT_L(n) asm volatile("s_waitcnt lgkmcnt(" #n ")" ::: "memory")
; #define PG8_BAR __builtin_amdgcn_s_barrier()
; #define PG8_SCHED __builtin_amdgcn_sched_barrier(0)
; template <class Epi, class Sched>
; __device__ __forceinline__ void gemm_phase(PG8_LAS unsigned char* lds, const Gemm g, const Sched& S, const Epi& E) {
;     ...
;             PG8_LDB(B0, 0, 0); PG8_SCHED; PG8_LDA(At, 0, 0); PG8_STAGE(PG8_SA(1, 1), a1 + hstep, voffA);
;             PG8_WAIT_L(8); PG8_BAR; PG8_WAIT_L(0); PG8_MMA(0, 0, At, B0); PG8_BAR; PG8_SCHED;
;             PG8_LDB(B1, 0, 1); PG8_STAGE(PG8_SB(0, 0), b2, voffB);
;             PG8_BAR; PG8_WAIT_L(0); PG8_MMA(0, 1, At, B1); PG8_BAR;
;             PG8_LDA(At, 0, 1); PG8_STAGE(PG8_SA(0, 0), a2, voffA);
;             PG8_BAR; PG8_WAIT_L(0); PG8_MMA(1, 0, At, B0); PG8_BAR; PG8_SCHED;
.LBB0_1011:
	ds_read_b128 v[144:147], v153
	ds_read_b128 v[156:159], v153 offset:1024
	ds_read_b128 v[160:163], v153 offset:2048
	ds_read_b128 v[164:167], v153 offset:3072
	ds_read_b128 v[168:171], v154
	ds_read_b128 v[172:175], v154 offset:1024
	ds_read_b128 v[182:185], v154 offset:2048
	ds_read_b128 v[190:193], v154 offset:3072
	ds_read_b128 v[194:197], v154 offset:4096
	ds_read_b128 v[198:201], v154 offset:5120
	ds_read_b128 v[202:205], v154 offset:6144
	ds_read_b128 v[206:209], v154 offset:7168
	s_add_u32 s20, s18, 0xfffc0080
	s_addc_u32 s21, s19, -1
	s_cmp_eq_u32 s47, 12
	s_cselect_b32 s23, s11, s21
	s_cselect_b32 s22, s43, s20
	s_cselect_b32 s21, s9, s46
	s_cselect_b32 s20, s44, s45
	v_lshl_add_u64 v[148:149], s[18:19], 0, v[136:137]
	s_add_i32 m0, s17, 0xc000
	s_nop 0
	global_load_lds_dwordx4 v[148:149], off
	v_lshl_add_u64 v[148:149], s[18:19], 0, v[138:139]
	s_add_i32 m0, s17, 0xe000
	s_nop 0
	global_load_lds_dwordx4 v[148:149], off
	s_waitcnt lgkmcnt(8)
	s_barrier
	s_waitcnt lgkmcnt(0)
	v_mfma_f32_16x16x32_bf16 v[124:127], v[144:147], v[168:171], v[124:127]
	v_mfma_f32_16x16x32_bf16 v[120:123], v[160:163], v[168:171], v[120:123]
	v_mfma_f32_16x16x32_bf16 v[108:111], v[144:147], v[182:185], v[108:111]
	v_mfma_f32_16x16x32_bf16 v[104:107], v[160:163], v[182:185], v[104:107]
	v_mfma_f32_16x16x32_bf16 v[92:95], v[144:147], v[194:197], v[92:95]
	v_mfma_f32_16x16x32_bf16 v[88:91], v[160:163], v[194:197], v[88:91]
	v_mfma_f32_16x16x32_bf16 v[76:79], v[144:147], v[202:205], v[76:79]
	v_mfma_f32_16x16x32_bf16 v[72:75], v[160:163], v[202:205], v[72:75]
	v_mfma_f32_16x16x32_bf16 v[124:127], v[156:159], v[172:175], v[124:127]
	v_mfma_f32_16x16x32_bf16 v[120:123], v[164:167], v[172:175], v[120:123]
	v_mfma_f32_16x16x32_bf16 v[108:111], v[156:159], v[190:193], v[108:111]
	v_mfma_f32_16x16x32_bf16 v[104:107], v[164:167], v[190:193], v[104:107]
	v_mfma_f32_16x16x32_bf16 v[92:95], v[156:159], v[198:201], v[92:95]
	v_mfma_f32_16x16x32_bf16 v[88:91], v[164:167], v[198:201], v[88:91]
	v_mfma_f32_16x16x32_bf16 v[76:79], v[156:159], v[206:209], v[76:79]
	v_mfma_f32_16x16x32_bf16 v[72:75], v[164:167], v[206:209], v[72:75]
	s_barrier
	ds_read_b128 v[210:213], v155
	ds_read_b128 v[214:217], v155 offset:1024
	ds_read_b128 v[218:221], v155 offset:2048
	ds_read_b128 v[222:225], v155 offset:3072
	s_add_i32 s48, s39, s29
	v_lshl_add_u64 v[148:149], s[20:21], 0, v[130:131]
	s_mov_b32 m0, s48
	s_nop 0
	global_load_lds_dwordx4 v[148:149], off
	v_lshl_add_u64 v[186:187], s[20:21], 0, v[134:135]
	s_add_i32 m0, s48, 0x2000
	s_nop 0
	global_load_lds_dwordx4 v[186:187], off
	s_barrier
	s_waitcnt lgkmcnt(0)
	v_mfma_f32_16x16x32_bf16 v[116:119], v[210:213], v[168:171], v[116:119]
	v_mfma_f32_16x16x32_bf16 v[112:115], v[218:221], v[168:171], v[112:115]
	v_mfma_f32_16x16x32_bf16 v[100:103], v[210:213], v[182:185], v[100:103]
	v_mfma_f32_16x16x32_bf16 v[96:99], v[218:221], v[182:185], v[96:99]
	v_mfma_f32_16x16x32_bf16 v[84:87], v[210:213], v[194:197], v[84:87]
	v_mfma_f32_16x16x32_bf16 v[80:83], v[218:221], v[194:197], v[80:83]
	v_mfma_f32_16x16x32_bf16 v[68:71], v[210:213], v[202:205], v[68:71]
	v_mfma_f32_16x16x32_bf16 v[64:67], v[218:221], v[202:205], v[64:67]
	v_mfma_f32_16x16x32_bf16 v[116:119], v[214:217], v[172:175], v[116:119]
	v_mfma_f32_16x16x32_bf16 v[112:115], v[222:225], v[172:175], v[112:115]
	v_mfma_f32_16x16x32_bf16 v[100:103], v[214:217], v[190:193], v[100:103]
	v_mfma_f32_16x16x32_bf16 v[96:99], v[222:225], v[190:193], v[96:99]
	v_mfma_f32_16x16x32_bf16 v[84:87], v[214:217], v[198:201], v[84:87]
	v_mfma_f32_16x16x32_bf16 v[80:83], v[222:225], v[198:201], v[80:83]
	v_mfma_f32_16x16x32_bf16 v[68:71], v[214:217], v[206:209], v[68:71]
	v_mfma_f32_16x16x32_bf16 v[64:67], v[222:225], v[206:209], v[64:67]
	s_mov_b32 m0, s17
	v_lshl_add_u64 v[226:227], s[22:23], 0, v[128:129]
	s_barrier
	ds_read_b128 v[168:171], v154 offset:16384
	ds_read_b128 v[172:175], v154 offset:17408
	ds_read_b128 v[182:185], v154 offset:18432
	ds_read_b128 v[190:193], v154 offset:19456
	ds_read_b128 v[194:197], v154 offset:20480
	ds_read_b128 v[198:201], v154 offset:21504
	ds_read_b128 v[202:205], v154 offset:22528
	ds_read_b128 v[206:209], v154 offset:23552
	global_load_lds_dwordx4 v[226:227], off
	v_lshl_add_u64 v[228:229], s[22:23], 0, v[132:133]
	s_mov_b32 m0, s30
	s_nop 0
	global_load_lds_dwordx4 v[228:229], off
	s_barrier
	s_waitcnt lgkmcnt(0)
	v_mfma_f32_16x16x32_bf16 v[60:63], v[144:147], v[168:171], v[60:63]
	v_mfma_f32_16x16x32_bf16 v[56:59], v[160:163], v[168:171], v[56:59]
	v_mfma_f32_16x16x32_bf16 v[44:47], v[144:147], v[182:185], v[44:47]
	v_mfma_f32_16x16x32_bf16 v[40:43], v[160:163], v[182:185], v[40:43]
	v_mfma_f32_16x16x32_bf16 v[28:31], v[144:147], v[194:197], v[28:31]
	v_mfma_f32_16x16x32_bf16 v[24:27], v[160:163], v[194:197], v[24:27]
	v_mfma_f32_16x16x32_bf16 v[12:15], v[144:147], v[202:205], v[12:15]
	v_mfma_f32_16x16x32_bf16 v[8:11], v[160:163], v[202:205], v[8:11]
	v_mfma_f32_16x16x32_bf16 v[60:63], v[156:159], v[172:175], v[60:63]
	v_mfma_f32_16x16x32_bf16 v[56:59], v[164:167], v[172:175], v[56:59]
	v_mfma_f32_16x16x32_bf16 v[44:47], v[156:159], v[190:193], v[44:47]
	v_mfma_f32_16x16x32_bf16 v[40:43], v[164:167], v[190:193], v[40:43]
	v_mfma_f32_16x16x32_bf16 v[28:31], v[156:159], v[198:201], v[28:31]
	v_mfma_f32_16x16x32_bf16 v[24:27], v[164:167], v[198:201], v[24:27]
	v_mfma_f32_16x16x32_bf16 v[12:15], v[156:159], v[206:209], v[12:15]
	v_mfma_f32_16x16x32_bf16 v[8:11], v[164:167], v[206:209], v[8:11]
	s_barrier
; #define PG8_STAGE(bufoff, gbase, voff) do { _Pragma("unroll") for (int _i = 0; _i < 2; ++_i) \
;         __builtin_amdgcn_global_load_lds((const unsigned*)((const char*)(gbase) + (voff)[_i]), (PG8_LAS unsigned*)(lds + (bufoff) + ldsw + _i * 8192), 16, 0, 0); } while (0)
; #define PG8_LDA(dst, b, h) do { _Pragma("unroll") for (int m = 0; m < 4; ++m) _Pragma("unroll") for (int k = 0; k < 2; ++k) dst[m][k] = *(const PG8_LAS bf16x8*)(lds + PG8_SA(b, h) + aoff + m * 2048 + k * 1024); } while (0)
; #define PG8_LDB(dst, b, h) do { _Pragma("unroll") for (int n = 0; n < 2; ++n) _Pragma("unroll") for (int k = 0; k < 2; ++k) dst[n][k] = *(const PG8_LAS bf16x8*)(lds + PG8_SB(b, h) + boff + n * 2048 + k * 1024); } while (0)
; #define PG8_MMA(ai, bj, At, Bt) do { __builtin_amdgcn_s_setprio(1); _Pragma("unroll") for (int m = 0; m < 4; ++m) _Pragma("unroll") for (int n = 0; n < 2; ++n) _Pragma("unroll") for (int k = 0; k < 2; ++k) \
;         acc[ai][bj][m][n] = __builtin_amdgcn_mfma_f32_16x16x32_bf16(Bt[n][k], At[m][k], acc[ai][bj][m][n], 0, 0, 0); __builtin_amdgcn_s_setprio(0); } while (0)
; #define PG8_WAIT_V(n) asm volatile("s_waitcnt vmcnt(" #n ")" ::: "memory")
; #define PG8_WAIT_L(n) asm volatile("s_waitcnt lgkmcnt(" #n ")" ::: "memory")
; #define PG8_BAR __builtin_amdgcn_s_barrier()
; #define PG8_SCHED __builtin_amdgcn_sched_barrier(0)
; template <class Epi, class Sched>
; __device__ __forceinline__ void gemm_phase(PG8_LAS unsigned char* lds, const Gemm g, const Sched& S, const Epi& E) {
;     ...
;             PG8_STAGE(PG8_SB(0, 1), b2 + hstep, voffB);
;             PG8_WAIT_V(6); PG8_BAR; PG8_MMA(1, 1, At, B1); PG8_BAR;
;             PG8_LDB(B0, 1, 0); PG8_SCHED; PG8_LDA(At, 1, 0); PG8_STAGE(PG8_SA(0, 1), a2 + hstep, voffA);
;             PG8_WAIT_L(8); PG8_BAR; PG8_WAIT_L(0); PG8_MMA(0, 0, At, B0); PG8_BAR; PG8_SCHED;
;             PG8_LDB(B1, 1, 1); PG8_STAGE(PG8_SB(1, 0), b3, voffB);
;             PG8_BAR; PG8_WAIT_L(0); PG8_MMA(0, 1, At, B1); PG8_BAR;
;             PG8_LDA(At, 1, 1); PG8_STAGE(PG8_SA(1, 0), a3, voffA);
	s_add_u32 s48, s20, 0x40000
	s_addc_u32 s49, s21, 0
	s_add_i32 s50, s40, s29
	v_lshl_add_u64 v[144:145], s[48:49], 0, v[130:131]
	s_mov_b32 m0, s50
	s_nop 0
	global_load_lds_dwordx4 v[144:145], off
	v_lshl_add_u64 v[144:145], s[48:49], 0, v[134:135]
	s_add_i32 m0, s50, 0x2000
	s_nop 0
	global_load_lds_dwordx4 v[144:145], off
	s_waitcnt vmcnt(6)
	s_barrier
	v_mfma_f32_16x16x32_bf16 v[52:55], v[210:213], v[168:171], v[52:55]
	v_mfma_f32_16x16x32_bf16 v[48:51], v[218:221], v[168:171], v[48:51]
	v_mfma_f32_16x16x32_bf16 v[36:39], v[210:213], v[182:185], v[36:39]
	v_mfma_f32_16x16x32_bf16 v[32:35], v[218:221], v[182:185], v[32:35]
	v_mfma_f32_16x16x32_bf16 v[20:23], v[210:213], v[194:197], v[20:23]
	v_mfma_f32_16x16x32_bf16 v[16:19], v[218:221], v[194:197], v[16:19]
	v_mfma_f32_16x16x32_bf16 v[4:7], v[210:213], v[202:205], v[4:7]
	v_mfma_f32_16x16x32_bf16 v[0:3], v[218:221], v[202:205], v[0:3]
	v_mfma_f32_16x16x32_bf16 v[52:55], v[214:217], v[172:175], v[52:55]
	v_mfma_f32_16x16x32_bf16 v[48:51], v[222:225], v[172:175], v[48:51]
	v_mfma_f32_16x16x32_bf16 v[36:39], v[214:217], v[190:193], v[36:39]
	v_mfma_f32_16x16x32_bf16 v[32:35], v[222:225], v[190:193], v[32:35]
	v_mfma_f32_16x16x32_bf16 v[20:23], v[214:217], v[198:201], v[20:23]
	v_mfma_f32_16x16x32_bf16 v[16:19], v[222:225], v[198:201], v[16:19]
	v_mfma_f32_16x16x32_bf16 v[4:7], v[214:217], v[206:209], v[4:7]
	v_mfma_f32_16x16x32_bf16 v[0:3], v[222:225], v[206:209], v[0:3]
	s_add_i32 s48, 0, 0x18000
	v_add_u32_e32 v164, s48, v151
	s_barrier
	ds_read_b128 v[144:147], v164
	ds_read_b128 v[156:159], v164 offset:1024
	ds_read_b128 v[160:163], v164 offset:2048
	ds_read_b128 v[164:167], v164 offset:3072
	ds_read_b128 v[168:171], v154 offset:32768
	ds_read_b128 v[172:175], v154 offset:33792
	ds_read_b128 v[182:185], v154 offset:34816
	ds_read_b128 v[190:193], v154 offset:35840
	ds_read_b128 v[194:197], v154 offset:36864
	ds_read_b128 v[198:201], v154 offset:37888
	ds_read_b128 v[202:205], v154 offset:38912
	ds_read_b128 v[206:209], v154 offset:39936
	s_add_u32 s22, s22, 0x40000
	s_addc_u32 s23, s23, 0
	s_mov_b32 m0, s31
	v_lshl_add_u64 v[210:211], s[22:23], 0, v[128:129]
	global_load_lds_dwordx4 v[210:211], off
	v_lshl_add_u64 v[210:211], s[22:23], 0, v[132:133]
	s_mov_b32 m0, s34
	s_nop 0
	global_load_lds_dwordx4 v[210:211], off
	s_waitcnt lgkmcnt(8)
	s_barrier
	s_waitcnt lgkmcnt(0)
	v_mfma_f32_16x16x32_bf16 v[124:127], v[144:147], v[168:171], v[124:127]
	v_mfma_f32_16x16x32_bf16 v[120:123], v[160:163], v[168:171], v[120:123]
	v_mfma_f32_16x16x32_bf16 v[108:111], v[144:147], v[182:185], v[108:111]
	v_mfma_f32_16x16x32_bf16 v[104:107], v[160:163], v[182:185], v[104:107]
	v_mfma_f32_16x16x32_bf16 v[92:95], v[144:147], v[194:197], v[92:95]
	v_mfma_f32_16x16x32_bf16 v[88:91], v[160:163], v[194:197], v[88:91]
	v_mfma_f32_16x16x32_bf16 v[76:79], v[144:147], v[202:205], v[76:79]
	v_mfma_f32_16x16x32_bf16 v[72:75], v[160:163], v[202:205], v[72:75]
	v_mfma_f32_16x16x32_bf16 v[124:127], v[156:159], v[172:175], v[124:127]
	v_mfma_f32_16x16x32_bf16 v[120:123], v[164:167], v[172:175], v[120:123]
	v_mfma_f32_16x16x32_bf16 v[108:111], v[156:159], v[190:193], v[108:111]
	v_mfma_f32_16x16x32_bf16 v[104:107], v[164:167], v[190:193], v[104:107]
	v_mfma_f32_16x16x32_bf16 v[92:95], v[156:159], v[198:201], v[92:95]
	v_mfma_f32_16x16x32_bf16 v[88:91], v[164:167], v[198:201], v[88:91]
	v_mfma_f32_16x16x32_bf16 v[76:79], v[156:159], v[206:209], v[76:79]
	v_mfma_f32_16x16x32_bf16 v[72:75], v[164:167], v[206:209], v[72:75]
	s_barrier
	s_add_i32 s22, 0, 0x1c000
	v_add_u32_e32 v179, s22, v151
	ds_read_b128 v[210:213], v179
	ds_read_b128 v[214:217], v179 offset:1024
	ds_read_b128 v[218:221], v179 offset:2048
	ds_read_b128 v[222:225], v179 offset:3072
	s_add_i32 s23, s48, s29
	v_lshl_add_u64 v[148:149], v[148:149], 0, s[6:7]
	s_mov_b32 m0, s23
	s_nop 0
	global_load_lds_dwordx4 v[148:149], off
	v_lshl_add_u64 v[148:149], v[186:187], 0, s[6:7]
	s_add_i32 m0, s23, 0x2000
	s_nop 0
	global_load_lds_dwordx4 v[148:149], off
	s_barrier
	s_waitcnt lgkmcnt(0)
	v_mfma_f32_16x16x32_bf16 v[116:119], v[210:213], v[168:171], v[116:119]
	v_mfma_f32_16x16x32_bf16 v[112:115], v[218:221], v[168:171], v[112:115]
	v_mfma_f32_16x16x32_bf16 v[100:103], v[210:213], v[182:185], v[100:103]
	v_mfma_f32_16x16x32_bf16 v[96:99], v[218:221], v[182:185], v[96:99]
	v_mfma_f32_16x16x32_bf16 v[84:87], v[210:213], v[194:197], v[84:87]
	v_mfma_f32_16x16x32_bf16 v[80:83], v[218:221], v[194:197], v[80:83]
	v_mfma_f32_16x16x32_bf16 v[68:71], v[210:213], v[202:205], v[68:71]
	v_mfma_f32_16x16x32_bf16 v[64:67], v[218:221], v[202:205], v[64:67]
	v_mfma_f32_16x16x32_bf16 v[116:119], v[214:217], v[172:175], v[116:119]
	v_mfma_f32_16x16x32_bf16 v[112:115], v[222:225], v[172:175], v[112:115]
	v_mfma_f32_16x16x32_bf16 v[100:103], v[214:217], v[190:193], v[100:103]
	v_mfma_f32_16x16x32_bf16 v[96:99], v[222:225], v[190:193], v[96:99]
	v_mfma_f32_16x16x32_bf16 v[84:87], v[214:217], v[198:201], v[84:87]
	v_mfma_f32_16x16x32_bf16 v[80:83], v[222:225], v[198:201], v[80:83]
	v_mfma_f32_16x16x32_bf16 v[68:71], v[214:217], v[206:209], v[68:71]
	v_mfma_f32_16x16x32_bf16 v[64:67], v[222:225], v[206:209], v[64:67]
	s_mov_b32 m0, s36
	v_lshl_add_u64 v[148:149], v[226:227], 0, s[6:7]
	s_barrier
	ds_read_b128 v[168:171], v154 offset:49152
	ds_read_b128 v[172:175], v154 offset:50176
	ds_read_b128 v[182:185], v154 offset:51200
	ds_read_b128 v[190:193], v154 offset:52224
	ds_read_b128 v[194:197], v154 offset:53248
	ds_read_b128 v[198:201], v154 offset:54272
	ds_read_b128 v[202:205], v154 offset:55296
	ds_read_b128 v[206:209], v154 offset:56320
	global_load_lds_dwordx4 v[148:149], off
	v_lshl_add_u64 v[148:149], v[228:229], 0, s[6:7]
	s_mov_b32 m0, s37
	s_nop 0
	global_load_lds_dwordx4 v[148:149], off
	s_barrier
; __device__ __forceinline__ unsigned cvt_pk_bf16(float lo, float hi) { unsigned r; asm volatile("v_cvt_pk_bf16_f32 %0, %1, %2" : "=v"(r) : "v"(lo), "v"(hi)); return r; }
; __device__ __forceinline__ float bf_lo(unsigned u) { return __uint_as_float(u << 16); }
; __device__ __forceinline__ float bf_hi(unsigned u) { return __uint_as_float(u & 0xffff0000u); }
; #define PG8_STAGE(bufoff, gbase, voff) do { _Pragma("unroll") for (int _i = 0; _i < 2; ++_i) \
;         __builtin_amdgcn_global_load_lds((const unsigned*)((const char*)(gbase) + (voff)[_i]), (PG8_LAS unsigned*)(lds + (bufoff) + ldsw + _i * 8192), 16, 0, 0); } while (0)
; #define PG8_WAIT_V(n) asm volatile("s_waitcnt vmcnt(" #n ")" ::: "memory")
; #define PG8_BAR __builtin_amdgcn_s_barrier()
;     __device__ __forceinline__ void operator()(const f32x4 (&acc)[2][2][4][2], const Unit& u, int wr, int wc, int fr, int fq) const {
;     ...
;             for (int m = 0; m < 4; ++m) { const size_t r = (size_t)(row0 + ai * HALF + m * 16); bf16_t* rowp = O + r * ldc + col0; const bf16_t* gp = G + r * ldg + col0;
; #pragma unroll
;                 for (int bj = 0; bj < 2; ++bj) { const u32x4 gw = *(const u32x4*)(gp + bj * HALF);
;                     f32x4 v0 = acc[ai][bj][m][0], v1 = acc[ai][bj][m][1];
;                     v0[0] *= bf_lo(gw.x); v0[1] *= bf_hi(gw.x); v0[2] *= bf_lo(gw.y); v0[3] *= bf_hi(gw.y);
;                     v1[0] *= bf_lo(gw.z); v1[1] *= bf_hi(gw.z); v1[2] *= bf_lo(gw.w); v1[3] *= bf_hi(gw.w);
;                     if (ACCUM) { const u32x4 pw = *(const u32x4*)(rowp + bj * HALF);
;                         v0[0] += bf_lo(pw.x); v0[1] += bf_hi(pw.x); v0[2] += bf_lo(pw.y); v0[3] += bf_hi(pw.y);
;                         v1[0] += bf_lo(pw.z); v1[1] += bf_hi(pw.z); v1[2] += bf_lo(pw.w); v1[3] += bf_hi(pw.w); }
;                     u32x4 w; w.x = cvt_pk_bf16(v0[0], v0[1]); w.y = cvt_pk_bf16(v0[2], v0[3]); w.z = cvt_pk_bf16(v1[0], v1[1]); w.w = cvt_pk_bf16(v1[2], v1[3]);
;                     *(u32x4*)(rowp + bj * HALF) = w; } }
; template <class Epi, class Sched>
; __device__ __forceinline__ void gemm_phase(PG8_LAS unsigned char* lds, const Gemm g, const Sched& S, const Epi& E) {
;     ...
;             PG8_BAR; PG8_WAIT_L(0); PG8_MMA(1, 0, At, B0); PG8_BAR; PG8_SCHED;
;             PG8_STAGE(PG8_SB(1, 1), b3 + hstep, voffB);
;             PG8_WAIT_V(6); PG8_BAR; PG8_MMA(1, 1, At, B1); PG8_BAR;
	s_waitcnt lgkmcnt(0)
	v_mfma_f32_16x16x32_bf16 v[60:63], v[144:147], v[168:171], v[60:63]
	v_mfma_f32_16x16x32_bf16 v[56:59], v[160:163], v[168:171], v[56:59]
	v_mfma_f32_16x16x32_bf16 v[44:47], v[144:147], v[182:185], v[44:47]
	v_mfma_f32_16x16x32_bf16 v[40:43], v[160:163], v[182:185], v[40:43]
	v_mfma_f32_16x16x32_bf16 v[28:31], v[144:147], v[194:197], v[28:31]
	v_mfma_f32_16x16x32_bf16 v[24:27], v[160:163], v[194:197], v[24:27]
	v_mfma_f32_16x16x32_bf16 v[12:15], v[144:147], v[202:205], v[12:15]
	v_mfma_f32_16x16x32_bf16 v[8:11], v[160:163], v[202:205], v[8:11]
	v_mfma_f32_16x16x32_bf16 v[60:63], v[156:159], v[172:175], v[60:63]
	v_mfma_f32_16x16x32_bf16 v[56:59], v[164:167], v[172:175], v[56:59]
	v_mfma_f32_16x16x32_bf16 v[44:47], v[156:159], v[190:193], v[44:47]
	v_mfma_f32_16x16x32_bf16 v[40:43], v[164:167], v[190:193], v[40:43]
	v_mfma_f32_16x16x32_bf16 v[28:31], v[156:159], v[198:201], v[28:31]
	v_mfma_f32_16x16x32_bf16 v[24:27], v[164:167], v[198:201], v[24:27]
	v_mfma_f32_16x16x32_bf16 v[12:15], v[156:159], v[206:209], v[12:15]
	v_mfma_f32_16x16x32_bf16 v[8:11], v[164:167], v[206:209], v[8:11]
	s_barrier
	s_add_u32 s20, s20, 0x40080
	s_addc_u32 s21, s21, 0
	s_add_i32 s22, s22, s29
	v_lshl_add_u64 v[144:145], s[20:21], 0, v[130:131]
	s_mov_b32 m0, s22
	s_nop 0
	global_load_lds_dwordx4 v[144:145], off
	v_lshl_add_u64 v[144:145], s[20:21], 0, v[134:135]
	s_add_i32 m0, s22, 0x2000
	s_nop 0
	global_load_lds_dwordx4 v[144:145], off
	s_waitcnt vmcnt(6)
	s_barrier
	v_mfma_f32_16x16x32_bf16 v[52:55], v[210:213], v[168:171], v[52:55]
	v_mfma_f32_16x16x32_bf16 v[48:51], v[218:221], v[168:171], v[48:51]
	v_mfma_f32_16x16x32_bf16 v[36:39], v[210:213], v[182:185], v[36:39]
	v_mfma_f32_16x16x32_bf16 v[32:35], v[218:221], v[182:185], v[32:35]
	v_mfma_f32_16x16x32_bf16 v[20:23], v[210:213], v[194:197], v[20:23]
	v_mfma_f32_16x16x32_bf16 v[16:19], v[218:221], v[194:197], v[16:19]
	v_mfma_f32_16x16x32_bf16 v[4:7], v[210:213], v[202:205], v[4:7]
	v_mfma_f32_16x16x32_bf16 v[0:3], v[218:221], v[202:205], v[0:3]
	v_mfma_f32_16x16x32_bf16 v[52:55], v[214:217], v[172:175], v[52:55]
	v_mfma_f32_16x16x32_bf16 v[48:51], v[222:225], v[172:175], v[48:51]
	v_mfma_f32_16x16x32_bf16 v[36:39], v[214:217], v[190:193], v[36:39]
	v_mfma_f32_16x16x32_bf16 v[32:35], v[222:225], v[190:193], v[32:35]
	v_mfma_f32_16x16x32_bf16 v[20:23], v[214:217], v[198:201], v[20:23]
	v_mfma_f32_16x16x32_bf16 v[16:19], v[222:225], v[198:201], v[16:19]
	v_mfma_f32_16x16x32_bf16 v[4:7], v[214:217], v[206:209], v[4:7]
	v_mfma_f32_16x16x32_bf16 v[0:3], v[222:225], v[206:209], v[0:3]
	s_add_i32 s47, s47, 2
	s_add_u32 s18, s18, 0x100
	s_addc_u32 s19, s19, 0
	s_add_u32 s45, s45, 0x100
	s_addc_u32 s46, s46, 0
	s_cmp_gt_u32 s47, 13
	s_barrier
	s_cbranch_scc0 .LBB0_1011
	v_lshl_add_u32 v146, s16, 8, v150
	v_lshl_or_b32 v144, s42, 8, v152
	v_ashrrev_i32_e32 v147, 31, v146
	v_ashrrev_i32_e32 v145, 31, v144
	v_mov_b64_e32 v[148:149], s[4:5]
	v_lshlrev_b64 v[160:161], 11, v[146:147]
	v_lshlrev_b64 v[144:145], 1, v[144:145]
	v_mad_i64_i32 v[156:157], s[18:19], v146, s41, v[148:149]
	v_lshl_add_u64 v[160:161], s[0:1], 0, v[160:161]
	v_lshl_add_u64 v[164:165], v[156:157], 0, v[144:145]
	v_lshl_add_u64 v[166:167], v[160:161], 0, v[144:145]
	global_load_dwordx4 v[156:159], v[164:165], off
	global_load_dwordx4 v[160:163], v[166:167], off
	s_and_b64 vcc, exec, s[2:3]
	s_mov_b32 s42, s8
	s_mov_b32 s16, s10
	s_mov_b64 s[20:21], s[14:15]
	s_waitcnt vmcnt(0)
	v_lshlrev_b32_e32 v147, 16, v156
	v_and_b32_e32 v156, 0xffff0000, v156
	v_lshlrev_b32_e32 v168, 16, v157
	v_and_b32_e32 v157, 0xffff0000, v157
	v_lshlrev_b32_e32 v169, 16, v158
	v_and_b32_e32 v158, 0xffff0000, v158
	v_lshlrev_b32_e32 v170, 16, v159
	v_and_b32_e32 v159, 0xffff0000, v159
	v_lshlrev_b32_e32 v171, 16, v160
	v_and_b32_e32 v160, 0xffff0000, v160
	v_lshlrev_b32_e32 v172, 16, v161
	v_and_b32_e32 v161, 0xffff0000, v161
	v_lshlrev_b32_e32 v173, 16, v162
	v_and_b32_e32 v162, 0xffff0000, v162
	v_lshlrev_b32_e32 v174, 16, v163
	v_and_b32_e32 v163, 0xffff0000, v163
	v_fmac_f32_e32 v171, v124, v147
	v_fmac_f32_e32 v160, v125, v156
	v_fmac_f32_e32 v172, v126, v168
	v_fmac_f32_e32 v161, v127, v157
	v_fmac_f32_e32 v173, v120, v169
	v_fmac_f32_e32 v162, v121, v158
	v_fmac_f32_e32 v174, v122, v170
	v_fmac_f32_e32 v163, v123, v159
	v_cvt_pk_bf16_f32 v120, v171, v160
	v_cvt_pk_bf16_f32 v121, v172, v161
	v_cvt_pk_bf16_f32 v122, v173, v162
	v_cvt_pk_bf16_f32 v123, v174, v163
	global_load_dwordx4 v[124:127], v[164:165], off offset:256
	global_load_dwordx4 v[156:159], v[166:167], off offset:256
	v_or_b32_e32 v160, 16, v146
	global_store_dwordx4 v[166:167], v[120:123], off
	v_mad_i64_i32 v[162:163], s[18:19], v160, s41, v[148:149]
	v_lshl_add_u64 v[162:163], v[162:163], 0, v[144:145]
	s_waitcnt vmcnt(0)
	v_lshlrev_b32_e32 v122, 16, v125
	v_lshlrev_b32_e32 v161, 16, v157
	v_lshlrev_b32_e32 v120, 16, v124
	v_and_b32_e32 v121, 0xffff0000, v124
	v_and_b32_e32 v123, 0xffff0000, v125
	v_lshlrev_b32_e32 v124, 16, v126
	v_and_b32_e32 v125, 0xffff0000, v126
	v_lshlrev_b32_e32 v147, 16, v156
	v_and_b32_e32 v156, 0xffff0000, v156
	v_and_b32_e32 v157, 0xffff0000, v157
	v_lshlrev_b32_e32 v164, 16, v158
	v_and_b32_e32 v158, 0xffff0000, v158
	v_fmac_f32_e32 v161, v118, v122
	v_fmac_f32_e32 v147, v116, v120
	v_fmac_f32_e32 v156, v117, v121
	v_fmac_f32_e32 v157, v119, v123
	v_fmac_f32_e32 v164, v112, v124
	v_fmac_f32_e32 v158, v113, v125
	v_cvt_pk_bf16_f32 v112, v147, v156
	v_cvt_pk_bf16_f32 v113, v161, v157
	v_ashrrev_i32_e32 v161, 31, v160
	v_lshlrev_b64 v[120:121], 11, v[160:161]
	v_lshl_add_u64 v[120:121], s[0:1], 0, v[120:121]
	v_lshlrev_b32_e32 v126, 16, v127
	v_and_b32_e32 v127, 0xffff0000, v127
	v_lshlrev_b32_e32 v165, 16, v159
	v_and_b32_e32 v159, 0xffff0000, v159
	v_lshl_add_u64 v[124:125], v[120:121], 0, v[144:145]
	v_fmac_f32_e32 v165, v114, v126
	v_fmac_f32_e32 v159, v115, v127
	v_cvt_pk_bf16_f32 v114, v164, v158
	v_cvt_pk_bf16_f32 v115, v165, v159
	global_load_dwordx4 v[116:119], v[162:163], off
	global_load_dwordx4 v[120:123], v[124:125], off
	s_waitcnt vmcnt(0)
; __device__ __forceinline__ unsigned cvt_pk_bf16(float lo, float hi) { unsigned r; asm volatile("v_cvt_pk_bf16_f32 %0, %1, %2" : "=v"(r) : "v"(lo), "v"(hi)); return r; }
; __device__ __forceinline__ float bf_lo(unsigned u) { return __uint_as_float(u << 16); }
; __device__ __forceinline__ float bf_hi(unsigned u) { return __uint_as_float(u & 0xffff0000u); }
;     __device__ __forceinline__ void operator()(const f32x4 (&acc)[2][2][4][2], const Unit& u, int wr, int wc, int fr, int fq) const {
;     ...
;             for (int m = 0; m < 4; ++m) { const size_t r = (size_t)(row0 + ai * HALF + m * 16); bf16_t* rowp = O + r * ldc + col0; const bf16_t* gp = G + r * ldg + col0;
; #pragma unroll
;                 for (int bj = 0; bj < 2; ++bj) { const u32x4 gw = *(const u32x4*)(gp + bj * HALF);
;                     f32x4 v0 = acc[ai][bj][m][0], v1 = acc[ai][bj][m][1];
;                     v0[0] *= bf_lo(gw.x); v0[1] *= bf_hi(gw.x); v0[2] *= bf_lo(gw.y); v0[3] *= bf_hi(gw.y);
;                     v1[0] *= bf_lo(gw.z); v1[1] *= bf_hi(gw.z); v1[2] *= bf_lo(gw.w); v1[3] *= bf_hi(gw.w);
;                     if (ACCUM) { const u32x4 pw = *(const u32x4*)(rowp + bj * HALF);
;                         v0[0] += bf_lo(pw.x); v0[1] += bf_hi(pw.x); v0[2] += bf_lo(pw.y); v0[3] += bf_hi(pw.y);
;                         v1[0] += bf_lo(pw.z); v1[1] += bf_hi(pw.z); v1[2] += bf_lo(pw.w); v1[3] += bf_hi(pw.w); }
;                     u32x4 w; w.x = cvt_pk_bf16(v0[0], v0[1]); w.y = cvt_pk_bf16(v0[2], v0[3]); w.z = cvt_pk_bf16(v1[0], v1[1]); w.w = cvt_pk_bf16(v1[2], v1[3]);
;                     *(u32x4*)(rowp + bj * HALF) = w; } }
	v_lshlrev_b32_e32 v126, 16, v120
	global_store_dwordx4 v[166:167], v[112:115], off offset:256
	v_and_b32_e32 v120, 0xffff0000, v120
	v_lshlrev_b32_e32 v127, 16, v121
	v_lshlrev_b32_e32 v112, 16, v116
	v_and_b32_e32 v113, 0xffff0000, v116
	v_lshlrev_b32_e32 v114, 16, v117
	v_and_b32_e32 v115, 0xffff0000, v117
	v_lshlrev_b32_e32 v116, 16, v118
	v_and_b32_e32 v117, 0xffff0000, v118
	v_lshlrev_b32_e32 v118, 16, v119
	v_and_b32_e32 v119, 0xffff0000, v119
	v_and_b32_e32 v121, 0xffff0000, v121
	v_lshlrev_b32_e32 v147, 16, v122
	v_and_b32_e32 v122, 0xffff0000, v122
	v_lshlrev_b32_e32 v156, 16, v123
	v_and_b32_e32 v123, 0xffff0000, v123
	v_fmac_f32_e32 v126, v108, v112
	v_fmac_f32_e32 v120, v109, v113
	v_fmac_f32_e32 v127, v110, v114
	v_fmac_f32_e32 v121, v111, v115
	v_fmac_f32_e32 v147, v104, v116
	v_fmac_f32_e32 v122, v105, v117
	v_fmac_f32_e32 v156, v106, v118
	v_fmac_f32_e32 v123, v107, v119
	v_cvt_pk_bf16_f32 v104, v126, v120
	v_cvt_pk_bf16_f32 v105, v127, v121
	v_cvt_pk_bf16_f32 v106, v147, v122
	v_cvt_pk_bf16_f32 v107, v156, v123
	global_load_dwordx4 v[108:111], v[162:163], off offset:256
	global_load_dwordx4 v[112:115], v[124:125], off offset:256
	v_or_b32_e32 v116, 32, v146
	global_store_dwordx4 v[124:125], v[104:107], off
	v_mad_i64_i32 v[118:119], s[18:19], v116, s41, v[148:149]
	v_lshl_add_u64 v[118:119], v[118:119], 0, v[144:145]
	s_waitcnt vmcnt(0)
	v_lshlrev_b32_e32 v104, 16, v108
	v_lshlrev_b32_e32 v117, 16, v112
	v_and_b32_e32 v105, 0xffff0000, v108
	v_lshlrev_b32_e32 v108, 16, v110
	v_and_b32_e32 v112, 0xffff0000, v112
	v_lshlrev_b32_e32 v121, 16, v114
	v_fmac_f32_e32 v117, v100, v104
	v_fmac_f32_e32 v112, v101, v105
	v_fmac_f32_e32 v121, v96, v108
	v_cvt_pk_bf16_f32 v96, v117, v112
	v_ashrrev_i32_e32 v117, 31, v116
	v_lshlrev_b64 v[104:105], 11, v[116:117]
	v_lshlrev_b32_e32 v106, 16, v109
	v_and_b32_e32 v107, 0xffff0000, v109
	v_and_b32_e32 v109, 0xffff0000, v110
	v_and_b32_e32 v114, 0xffff0000, v114
	v_lshl_add_u64 v[104:105], s[0:1], 0, v[104:105]
	v_lshlrev_b32_e32 v110, 16, v111
	v_and_b32_e32 v111, 0xffff0000, v111
	v_lshlrev_b32_e32 v120, 16, v113
	v_and_b32_e32 v113, 0xffff0000, v113
	v_lshlrev_b32_e32 v122, 16, v115
	v_and_b32_e32 v115, 0xffff0000, v115
	v_fmac_f32_e32 v114, v97, v109
	v_lshl_add_u64 v[108:109], v[104:105], 0, v[144:145]
	v_fmac_f32_e32 v120, v102, v106
	v_fmac_f32_e32 v113, v103, v107
	v_fmac_f32_e32 v122, v98, v110
	v_fmac_f32_e32 v115, v99, v111
	v_cvt_pk_bf16_f32 v97, v120, v113
	v_cvt_pk_bf16_f32 v98, v121, v114
	v_cvt_pk_bf16_f32 v99, v122, v115
	global_load_dwordx4 v[100:103], v[118:119], off
	global_load_dwordx4 v[104:107], v[108:109], off
	s_waitcnt vmcnt(0)
	v_lshlrev_b32_e32 v110, 16, v104
	global_store_dwordx4 v[124:125], v[96:99], off offset:256
	v_and_b32_e32 v104, 0xffff0000, v104
	v_lshlrev_b32_e32 v111, 16, v105
	v_lshlrev_b32_e32 v96, 16, v100
	v_and_b32_e32 v97, 0xffff0000, v100
	v_lshlrev_b32_e32 v98, 16, v101
	v_and_b32_e32 v99, 0xffff0000, v101
	v_lshlrev_b32_e32 v100, 16, v102
	v_and_b32_e32 v101, 0xffff0000, v102
	v_lshlrev_b32_e32 v102, 16, v103
	v_and_b32_e32 v103, 0xffff0000, v103
	v_and_b32_e32 v105, 0xffff0000, v105
	v_lshlrev_b32_e32 v112, 16, v106
	v_and_b32_e32 v106, 0xffff0000, v106
	v_lshlrev_b32_e32 v113, 16, v107
	v_and_b32_e32 v107, 0xffff0000, v107
	v_fmac_f32_e32 v110, v92, v96
	v_fmac_f32_e32 v104, v93, v97
	v_fmac_f32_e32 v111, v94, v98
	v_fmac_f32_e32 v105, v95, v99
	v_fmac_f32_e32 v112, v88, v100
	v_fmac_f32_e32 v106, v89, v101
	v_fmac_f32_e32 v113, v90, v102
	v_fmac_f32_e32 v107, v91, v103
	v_cvt_pk_bf16_f32 v88, v110, v104
	v_cvt_pk_bf16_f32 v89, v111, v105
	v_cvt_pk_bf16_f32 v90, v112, v106
	v_cvt_pk_bf16_f32 v91, v113, v107
	global_load_dwordx4 v[92:95], v[118:119], off offset:256
	global_load_dwordx4 v[96:99], v[108:109], off offset:256
	v_or_b32_e32 v100, 48, v146
	global_store_dwordx4 v[108:109], v[88:91], off
	v_mad_i64_i32 v[102:103], s[18:19], v100, s41, v[148:149]
	v_lshl_add_u64 v[102:103], v[102:103], 0, v[144:145]
	s_waitcnt vmcnt(0)
	v_lshlrev_b32_e32 v88, 16, v92
	v_lshlrev_b32_e32 v101, 16, v96
	v_and_b32_e32 v89, 0xffff0000, v92
	v_lshlrev_b32_e32 v92, 16, v94
	v_and_b32_e32 v96, 0xffff0000, v96
	v_lshlrev_b32_e32 v105, 16, v98
	v_fmac_f32_e32 v101, v84, v88
	v_fmac_f32_e32 v96, v85, v89
	v_fmac_f32_e32 v105, v80, v92
	v_cvt_pk_bf16_f32 v80, v101, v96
	v_ashrrev_i32_e32 v101, 31, v100
	v_lshlrev_b64 v[88:89], 11, v[100:101]
	v_lshlrev_b32_e32 v90, 16, v93
	v_and_b32_e32 v91, 0xffff0000, v93
	v_and_b32_e32 v93, 0xffff0000, v94
	v_and_b32_e32 v98, 0xffff0000, v98
	v_lshl_add_u64 v[88:89], s[0:1], 0, v[88:89]
	v_lshlrev_b32_e32 v94, 16, v95
	v_and_b32_e32 v95, 0xffff0000, v95
	v_lshlrev_b32_e32 v104, 16, v97
	v_and_b32_e32 v97, 0xffff0000, v97
	v_lshlrev_b32_e32 v106, 16, v99
	v_and_b32_e32 v99, 0xffff0000, v99
	v_fmac_f32_e32 v98, v81, v93
	v_lshl_add_u64 v[92:93], v[88:89], 0, v[144:145]
	v_fmac_f32_e32 v104, v86, v90
	v_fmac_f32_e32 v97, v87, v91
	v_fmac_f32_e32 v106, v82, v94
	v_fmac_f32_e32 v99, v83, v95
	v_cvt_pk_bf16_f32 v81, v104, v97
	v_cvt_pk_bf16_f32 v82, v105, v98
	v_cvt_pk_bf16_f32 v83, v106, v99
	global_load_dwordx4 v[84:87], v[102:103], off
	global_load_dwordx4 v[88:91], v[92:93], off
	s_waitcnt vmcnt(0)
; __device__ __forceinline__ unsigned cvt_pk_bf16(float lo, float hi) { unsigned r; asm volatile("v_cvt_pk_bf16_f32 %0, %1, %2" : "=v"(r) : "v"(lo), "v"(hi)); return r; }
; __device__ __forceinline__ float bf_lo(unsigned u) { return __uint_as_float(u << 16); }
; __device__ __forceinline__ float bf_hi(unsigned u) { return __uint_as_float(u & 0xffff0000u); }
;     __device__ __forceinline__ void operator()(const f32x4 (&acc)[2][2][4][2], const Unit& u, int wr, int wc, int fr, int fq) const {
;     ...
;             for (int m = 0; m < 4; ++m) { const size_t r = (size_t)(row0 + ai * HALF + m * 16); bf16_t* rowp = O + r * ldc + col0; const bf16_t* gp = G + r * ldg + col0;
; #pragma unroll
;                 for (int bj = 0; bj < 2; ++bj) { const u32x4 gw = *(const u32x4*)(gp + bj * HALF);
;                     f32x4 v0 = acc[ai][bj][m][0], v1 = acc[ai][bj][m][1];
;                     v0[0] *= bf_lo(gw.x); v0[1] *= bf_hi(gw.x); v0[2] *= bf_lo(gw.y); v0[3] *= bf_hi(gw.y);
;                     v1[0] *= bf_lo(gw.z); v1[1] *= bf_hi(gw.z); v1[2] *= bf_lo(gw.w); v1[3] *= bf_hi(gw.w);
;                     if (ACCUM) { const u32x4 pw = *(const u32x4*)(rowp + bj * HALF);
;                         v0[0] += bf_lo(pw.x); v0[1] += bf_hi(pw.x); v0[2] += bf_lo(pw.y); v0[3] += bf_hi(pw.y);
;                         v1[0] += bf_lo(pw.z); v1[1] += bf_hi(pw.z); v1[2] += bf_lo(pw.w); v1[3] += bf_hi(pw.w); }
;                     u32x4 w; w.x = cvt_pk_bf16(v0[0], v0[1]); w.y = cvt_pk_bf16(v0[2], v0[3]); w.z = cvt_pk_bf16(v1[0], v1[1]); w.w = cvt_pk_bf16(v1[2], v1[3]);
;                     *(u32x4*)(rowp + bj * HALF) = w; } }
	v_lshlrev_b32_e32 v94, 16, v88
	global_store_dwordx4 v[108:109], v[80:83], off offset:256
	v_and_b32_e32 v88, 0xffff0000, v88
	v_lshlrev_b32_e32 v95, 16, v89
	v_lshlrev_b32_e32 v80, 16, v84
	v_and_b32_e32 v81, 0xffff0000, v84
	v_lshlrev_b32_e32 v82, 16, v85
	v_and_b32_e32 v83, 0xffff0000, v85
	v_lshlrev_b32_e32 v84, 16, v86
	v_and_b32_e32 v85, 0xffff0000, v86
	v_lshlrev_b32_e32 v86, 16, v87
	v_and_b32_e32 v87, 0xffff0000, v87
	v_and_b32_e32 v89, 0xffff0000, v89
	v_lshlrev_b32_e32 v96, 16, v90
	v_and_b32_e32 v90, 0xffff0000, v90
	v_lshlrev_b32_e32 v97, 16, v91
	v_and_b32_e32 v91, 0xffff0000, v91
	v_fmac_f32_e32 v94, v76, v80
	v_fmac_f32_e32 v88, v77, v81
	v_fmac_f32_e32 v95, v78, v82
	v_fmac_f32_e32 v89, v79, v83
	v_fmac_f32_e32 v96, v72, v84
	v_fmac_f32_e32 v90, v73, v85
	v_fmac_f32_e32 v97, v74, v86
	v_fmac_f32_e32 v91, v75, v87
	v_cvt_pk_bf16_f32 v72, v94, v88
	v_cvt_pk_bf16_f32 v73, v95, v89
	v_cvt_pk_bf16_f32 v74, v96, v90
	v_cvt_pk_bf16_f32 v75, v97, v91
	global_load_dwordx4 v[76:79], v[102:103], off offset:256
	global_load_dwordx4 v[80:83], v[92:93], off offset:256
	v_add_u32_e32 v84, 0x80, v146
	global_store_dwordx4 v[92:93], v[72:75], off
	v_mad_i64_i32 v[86:87], s[18:19], v84, s41, v[148:149]
	v_lshl_add_u64 v[86:87], v[86:87], 0, v[144:145]
	s_waitcnt vmcnt(0)
	v_lshlrev_b32_e32 v72, 16, v76
	v_lshlrev_b32_e32 v85, 16, v80
	v_and_b32_e32 v73, 0xffff0000, v76
	v_lshlrev_b32_e32 v76, 16, v78
	v_and_b32_e32 v80, 0xffff0000, v80
	v_lshlrev_b32_e32 v89, 16, v82
	v_fmac_f32_e32 v85, v68, v72
	v_fmac_f32_e32 v80, v69, v73
	v_fmac_f32_e32 v89, v64, v76
	v_cvt_pk_bf16_f32 v64, v85, v80
	v_ashrrev_i32_e32 v85, 31, v84
	v_lshlrev_b64 v[72:73], 11, v[84:85]
	v_lshlrev_b32_e32 v74, 16, v77
	v_and_b32_e32 v75, 0xffff0000, v77
	v_and_b32_e32 v77, 0xffff0000, v78
	v_and_b32_e32 v82, 0xffff0000, v82
	v_lshl_add_u64 v[72:73], s[0:1], 0, v[72:73]
	v_lshlrev_b32_e32 v78, 16, v79
	v_and_b32_e32 v79, 0xffff0000, v79
	v_lshlrev_b32_e32 v88, 16, v81
	v_and_b32_e32 v81, 0xffff0000, v81
	v_lshlrev_b32_e32 v90, 16, v83
	v_and_b32_e32 v83, 0xffff0000, v83
	v_fmac_f32_e32 v82, v65, v77
	v_lshl_add_u64 v[76:77], v[72:73], 0, v[144:145]
	v_fmac_f32_e32 v88, v70, v74
	v_fmac_f32_e32 v81, v71, v75
	v_fmac_f32_e32 v90, v66, v78
	v_fmac_f32_e32 v83, v67, v79
	v_cvt_pk_bf16_f32 v65, v88, v81
	v_cvt_pk_bf16_f32 v66, v89, v82
	v_cvt_pk_bf16_f32 v67, v90, v83
	global_load_dwordx4 v[68:71], v[86:87], off
	global_load_dwordx4 v[72:75], v[76:77], off
	s_waitcnt vmcnt(0)
	v_lshlrev_b32_e32 v78, 16, v72
	global_store_dwordx4 v[92:93], v[64:67], off offset:256
	v_and_b32_e32 v72, 0xffff0000, v72
	v_lshlrev_b32_e32 v79, 16, v73
	v_lshlrev_b32_e32 v64, 16, v68
	v_and_b32_e32 v65, 0xffff0000, v68
	v_lshlrev_b32_e32 v66, 16, v69
	v_and_b32_e32 v67, 0xffff0000, v69
	v_lshlrev_b32_e32 v68, 16, v70
	v_and_b32_e32 v69, 0xffff0000, v70
	v_lshlrev_b32_e32 v70, 16, v71
	v_and_b32_e32 v71, 0xffff0000, v71
	v_and_b32_e32 v73, 0xffff0000, v73
	v_lshlrev_b32_e32 v80, 16, v74
	v_and_b32_e32 v74, 0xffff0000, v74
	v_lshlrev_b32_e32 v81, 16, v75
	v_and_b32_e32 v75, 0xffff0000, v75
	v_fmac_f32_e32 v78, v60, v64
	v_fmac_f32_e32 v72, v61, v65
	v_fmac_f32_e32 v79, v62, v66
	v_fmac_f32_e32 v73, v63, v67
	v_fmac_f32_e32 v80, v56, v68
	v_fmac_f32_e32 v74, v57, v69
	v_fmac_f32_e32 v81, v58, v70
	v_fmac_f32_e32 v75, v59, v71
	v_cvt_pk_bf16_f32 v56, v78, v72
	v_cvt_pk_bf16_f32 v57, v79, v73
	v_cvt_pk_bf16_f32 v58, v80, v74
	v_cvt_pk_bf16_f32 v59, v81, v75
	global_load_dwordx4 v[60:63], v[86:87], off offset:256
	global_load_dwordx4 v[64:67], v[76:77], off offset:256
	v_add_u32_e32 v68, 0x90, v146
	global_store_dwordx4 v[76:77], v[56:59], off
	v_mad_i64_i32 v[70:71], s[18:19], v68, s41, v[148:149]
	v_lshl_add_u64 v[70:71], v[70:71], 0, v[144:145]
	s_waitcnt vmcnt(0)
	v_lshlrev_b32_e32 v56, 16, v60
	v_lshlrev_b32_e32 v69, 16, v64
	v_and_b32_e32 v57, 0xffff0000, v60
	v_lshlrev_b32_e32 v60, 16, v62
	v_and_b32_e32 v64, 0xffff0000, v64
	v_lshlrev_b32_e32 v73, 16, v66
	v_fmac_f32_e32 v69, v52, v56
	v_fmac_f32_e32 v64, v53, v57
	v_fmac_f32_e32 v73, v48, v60
	v_cvt_pk_bf16_f32 v48, v69, v64
	v_ashrrev_i32_e32 v69, 31, v68
	v_lshlrev_b64 v[56:57], 11, v[68:69]
	v_lshlrev_b32_e32 v58, 16, v61
	v_and_b32_e32 v59, 0xffff0000, v61
	v_and_b32_e32 v61, 0xffff0000, v62
	v_and_b32_e32 v66, 0xffff0000, v66
	v_lshl_add_u64 v[56:57], s[0:1], 0, v[56:57]
	v_lshlrev_b32_e32 v62, 16, v63
	v_and_b32_e32 v63, 0xffff0000, v63
	v_lshlrev_b32_e32 v72, 16, v65
	v_and_b32_e32 v65, 0xffff0000, v65
	v_lshlrev_b32_e32 v74, 16, v67
	v_and_b32_e32 v67, 0xffff0000, v67
	v_fmac_f32_e32 v66, v49, v61
	v_lshl_add_u64 v[60:61], v[56:57], 0, v[144:145]
	v_fmac_f32_e32 v72, v54, v58
	v_fmac_f32_e32 v65, v55, v59
	v_fmac_f32_e32 v74, v50, v62
	v_fmac_f32_e32 v67, v51, v63
	v_cvt_pk_bf16_f32 v49, v72, v65
	v_cvt_pk_bf16_f32 v50, v73, v66
	v_cvt_pk_bf16_f32 v51, v74, v67
	global_load_dwordx4 v[52:55], v[70:71], off
	global_load_dwordx4 v[56:59], v[60:61], off
	s_waitcnt vmcnt(0)
	v_lshlrev_b32_e32 v62, 16, v56
	global_store_dwordx4 v[76:77], v[48:51], off offset:256
	v_and_b32_e32 v56, 0xffff0000, v56
	v_lshlrev_b32_e32 v63, 16, v57
	v_lshlrev_b32_e32 v48, 16, v52
	v_and_b32_e32 v49, 0xffff0000, v52
	v_lshlrev_b32_e32 v50, 16, v53
	v_and_b32_e32 v51, 0xffff0000, v53
	v_lshlrev_b32_e32 v52, 16, v54
	v_and_b32_e32 v53, 0xffff0000, v54
	v_lshlrev_b32_e32 v54, 16, v55
	v_and_b32_e32 v55, 0xffff0000, v55
	v_and_b32_e32 v57, 0xffff0000, v57
	v_lshlrev_b32_e32 v64, 16, v58
	v_and_b32_e32 v58, 0xffff0000, v58
	v_lshlrev_b32_e32 v65, 16, v59
	v_and_b32_e32 v59, 0xffff0000, v59
	v_fmac_f32_e32 v62, v44, v48
	v_fmac_f32_e32 v56, v45, v49
	v_fmac_f32_e32 v63, v46, v50
	v_fmac_f32_e32 v57, v47, v51
	v_fmac_f32_e32 v64, v40, v52
	v_fmac_f32_e32 v58, v41, v53
	v_fmac_f32_e32 v65, v42, v54
	v_fmac_f32_e32 v59, v43, v55
	v_cvt_pk_bf16_f32 v40, v62, v56
	v_cvt_pk_bf16_f32 v41, v63, v57
	v_cvt_pk_bf16_f32 v42, v64, v58
	v_cvt_pk_bf16_f32 v43, v65, v59
	global_load_dwordx4 v[44:47], v[70:71], off offset:256
	global_load_dwordx4 v[48:51], v[60:61], off offset:256
	v_add_u32_e32 v52, 0xa0, v146
	global_store_dwordx4 v[60:61], v[40:43], off
	v_mad_i64_i32 v[54:55], s[18:19], v52, s41, v[148:149]
	v_lshl_add_u64 v[54:55], v[54:55], 0, v[144:145]
	s_waitcnt vmcnt(0)
; __device__ __forceinline__ unsigned cvt_pk_bf16(float lo, float hi) { unsigned r; asm volatile("v_cvt_pk_bf16_f32 %0, %1, %2" : "=v"(r) : "v"(lo), "v"(hi)); return r; }
; __device__ __forceinline__ float bf_lo(unsigned u) { return __uint_as_float(u << 16); }
; __device__ __forceinline__ float bf_hi(unsigned u) { return __uint_as_float(u & 0xffff0000u); }
; #define PG8_WAIT_V(n) asm volatile("s_waitcnt vmcnt(" #n ")" ::: "memory")
; #define PG8_BAR __builtin_amdgcn_s_barrier()
;     __device__ __forceinline__ void operator()(const f32x4 (&acc)[2][2][4][2], const Unit& u, int wr, int wc, int fr, int fq) const {
;     ...
;             for (int m = 0; m < 4; ++m) { const size_t r = (size_t)(row0 + ai * HALF + m * 16); bf16_t* rowp = O + r * ldc + col0; const bf16_t* gp = G + r * ldg + col0;
; #pragma unroll
;                 for (int bj = 0; bj < 2; ++bj) { const u32x4 gw = *(const u32x4*)(gp + bj * HALF);
;                     f32x4 v0 = acc[ai][bj][m][0], v1 = acc[ai][bj][m][1];
;                     v0[0] *= bf_lo(gw.x); v0[1] *= bf_hi(gw.x); v0[2] *= bf_lo(gw.y); v0[3] *= bf_hi(gw.y);
;                     v1[0] *= bf_lo(gw.z); v1[1] *= bf_hi(gw.z); v1[2] *= bf_lo(gw.w); v1[3] *= bf_hi(gw.w);
;                     if (ACCUM) { const u32x4 pw = *(const u32x4*)(rowp + bj * HALF);
;                         v0[0] += bf_lo(pw.x); v0[1] += bf_hi(pw.x); v0[2] += bf_lo(pw.y); v0[3] += bf_hi(pw.y);
;                         v1[0] += bf_lo(pw.z); v1[1] += bf_hi(pw.z); v1[2] += bf_lo(pw.w); v1[3] += bf_hi(pw.w); }
;                     u32x4 w; w.x = cvt_pk_bf16(v0[0], v0[1]); w.y = cvt_pk_bf16(v0[2], v0[3]); w.z = cvt_pk_bf16(v1[0], v1[1]); w.w = cvt_pk_bf16(v1[2], v1[3]);
;                     *(u32x4*)(rowp + bj * HALF) = w; } }
; template <class Epi, class Sched>
; __device__ __forceinline__ void gemm_phase(PG8_LAS unsigned char* lds, const Gemm g, const Sched& S, const Epi& E) {
;     ...
;         if (!has_next) break;
;     ...
;     PG8_WAIT_V(0);
;     if (wr == 0) PG8_BAR;
;     PG8_BAR;
	v_lshlrev_b32_e32 v40, 16, v44
	v_lshlrev_b32_e32 v53, 16, v48
	v_and_b32_e32 v41, 0xffff0000, v44
	v_lshlrev_b32_e32 v44, 16, v46
	v_and_b32_e32 v48, 0xffff0000, v48
	v_lshlrev_b32_e32 v57, 16, v50
	v_fmac_f32_e32 v53, v36, v40
	v_fmac_f32_e32 v48, v37, v41
	v_fmac_f32_e32 v57, v32, v44
	v_cvt_pk_bf16_f32 v32, v53, v48
	v_ashrrev_i32_e32 v53, 31, v52
	v_lshlrev_b64 v[40:41], 11, v[52:53]
	v_lshlrev_b32_e32 v42, 16, v45
	v_and_b32_e32 v43, 0xffff0000, v45
	v_and_b32_e32 v45, 0xffff0000, v46
	v_and_b32_e32 v50, 0xffff0000, v50
	v_lshl_add_u64 v[40:41], s[0:1], 0, v[40:41]
	v_lshlrev_b32_e32 v46, 16, v47
	v_and_b32_e32 v47, 0xffff0000, v47
	v_lshlrev_b32_e32 v56, 16, v49
	v_and_b32_e32 v49, 0xffff0000, v49
	v_lshlrev_b32_e32 v58, 16, v51
	v_and_b32_e32 v51, 0xffff0000, v51
	v_fmac_f32_e32 v50, v33, v45
	v_lshl_add_u64 v[44:45], v[40:41], 0, v[144:145]
	v_fmac_f32_e32 v56, v38, v42
	v_fmac_f32_e32 v49, v39, v43
	v_fmac_f32_e32 v58, v34, v46
	v_fmac_f32_e32 v51, v35, v47
	v_cvt_pk_bf16_f32 v33, v56, v49
	v_cvt_pk_bf16_f32 v34, v57, v50
	v_cvt_pk_bf16_f32 v35, v58, v51
	global_load_dwordx4 v[36:39], v[54:55], off
	global_load_dwordx4 v[40:43], v[44:45], off
	s_waitcnt vmcnt(0)
	v_lshlrev_b32_e32 v46, 16, v40
	global_store_dwordx4 v[60:61], v[32:35], off offset:256
	v_and_b32_e32 v40, 0xffff0000, v40
	v_lshlrev_b32_e32 v47, 16, v41
	v_lshlrev_b32_e32 v32, 16, v36
	v_and_b32_e32 v33, 0xffff0000, v36
	v_lshlrev_b32_e32 v34, 16, v37
	v_and_b32_e32 v35, 0xffff0000, v37
	v_lshlrev_b32_e32 v36, 16, v38
	v_and_b32_e32 v37, 0xffff0000, v38
	v_lshlrev_b32_e32 v38, 16, v39
	v_and_b32_e32 v39, 0xffff0000, v39
	v_and_b32_e32 v41, 0xffff0000, v41
	v_lshlrev_b32_e32 v48, 16, v42
	v_and_b32_e32 v42, 0xffff0000, v42
	v_lshlrev_b32_e32 v49, 16, v43
	v_and_b32_e32 v43, 0xffff0000, v43
	v_fmac_f32_e32 v46, v28, v32
	v_fmac_f32_e32 v40, v29, v33
	v_fmac_f32_e32 v47, v30, v34
	v_fmac_f32_e32 v41, v31, v35
	v_fmac_f32_e32 v48, v24, v36
	v_fmac_f32_e32 v42, v25, v37
	v_fmac_f32_e32 v49, v26, v38
	v_fmac_f32_e32 v43, v27, v39
	v_cvt_pk_bf16_f32 v24, v46, v40
	v_cvt_pk_bf16_f32 v25, v47, v41
	v_cvt_pk_bf16_f32 v26, v48, v42
	v_cvt_pk_bf16_f32 v27, v49, v43
	global_load_dwordx4 v[28:31], v[54:55], off offset:256
	global_load_dwordx4 v[32:35], v[44:45], off offset:256
	v_add_u32_e32 v36, 0xb0, v146
	global_store_dwordx4 v[44:45], v[24:27], off
	v_mad_i64_i32 v[38:39], s[18:19], v36, s41, v[148:149]
	v_lshl_add_u64 v[38:39], v[38:39], 0, v[144:145]
	s_mov_b64 s[18:19], s[12:13]
	s_waitcnt vmcnt(0)
	v_lshlrev_b32_e32 v24, 16, v28
	v_lshlrev_b32_e32 v37, 16, v32
	v_and_b32_e32 v25, 0xffff0000, v28
	v_lshlrev_b32_e32 v28, 16, v30
	v_and_b32_e32 v32, 0xffff0000, v32
	v_lshlrev_b32_e32 v41, 16, v34
	v_fmac_f32_e32 v37, v20, v24
	v_fmac_f32_e32 v32, v21, v25
	v_fmac_f32_e32 v41, v16, v28
	v_cvt_pk_bf16_f32 v16, v37, v32
	v_ashrrev_i32_e32 v37, 31, v36
	v_lshlrev_b64 v[24:25], 11, v[36:37]
	v_lshlrev_b32_e32 v26, 16, v29
	v_and_b32_e32 v27, 0xffff0000, v29
	v_and_b32_e32 v29, 0xffff0000, v30
	v_and_b32_e32 v34, 0xffff0000, v34
	v_lshl_add_u64 v[24:25], s[0:1], 0, v[24:25]
	v_lshlrev_b32_e32 v30, 16, v31
	v_and_b32_e32 v31, 0xffff0000, v31
	v_lshlrev_b32_e32 v40, 16, v33
	v_and_b32_e32 v33, 0xffff0000, v33
	v_lshlrev_b32_e32 v42, 16, v35
	v_and_b32_e32 v35, 0xffff0000, v35
	v_fmac_f32_e32 v34, v17, v29
	v_lshl_add_u64 v[28:29], v[24:25], 0, v[144:145]
	v_fmac_f32_e32 v40, v22, v26
	v_fmac_f32_e32 v33, v23, v27
	v_fmac_f32_e32 v42, v18, v30
	v_fmac_f32_e32 v35, v19, v31
	v_cvt_pk_bf16_f32 v17, v40, v33
	v_cvt_pk_bf16_f32 v18, v41, v34
	v_cvt_pk_bf16_f32 v19, v42, v35
	global_load_dwordx4 v[20:23], v[38:39], off
	global_load_dwordx4 v[24:27], v[28:29], off
	s_waitcnt vmcnt(0)
	v_lshlrev_b32_e32 v30, 16, v24
	global_store_dwordx4 v[44:45], v[16:19], off offset:256
	v_and_b32_e32 v24, 0xffff0000, v24
	v_lshlrev_b32_e32 v31, 16, v25
	v_lshlrev_b32_e32 v16, 16, v20
	v_and_b32_e32 v17, 0xffff0000, v20
	v_lshlrev_b32_e32 v18, 16, v21
	v_and_b32_e32 v19, 0xffff0000, v21
	v_lshlrev_b32_e32 v20, 16, v22
	v_and_b32_e32 v21, 0xffff0000, v22
	v_lshlrev_b32_e32 v22, 16, v23
	v_and_b32_e32 v23, 0xffff0000, v23
	v_and_b32_e32 v25, 0xffff0000, v25
	v_lshlrev_b32_e32 v32, 16, v26
	v_and_b32_e32 v26, 0xffff0000, v26
	v_lshlrev_b32_e32 v33, 16, v27
	v_and_b32_e32 v27, 0xffff0000, v27
	v_fmac_f32_e32 v30, v12, v16
	v_fmac_f32_e32 v24, v13, v17
	v_fmac_f32_e32 v31, v14, v18
	v_fmac_f32_e32 v25, v15, v19
	v_fmac_f32_e32 v32, v8, v20
	v_fmac_f32_e32 v26, v9, v21
	v_fmac_f32_e32 v33, v10, v22
	v_fmac_f32_e32 v27, v11, v23
	v_cvt_pk_bf16_f32 v8, v30, v24
	v_cvt_pk_bf16_f32 v9, v31, v25
	v_cvt_pk_bf16_f32 v10, v32, v26
	v_cvt_pk_bf16_f32 v11, v33, v27
	global_load_dwordx4 v[12:15], v[38:39], off offset:256
	global_load_dwordx4 v[16:19], v[28:29], off offset:256
	s_waitcnt vmcnt(0)
	v_lshlrev_b32_e32 v20, 16, v16
	global_store_dwordx4 v[28:29], v[8:11], off
	v_and_b32_e32 v16, 0xffff0000, v16
	v_lshlrev_b32_e32 v21, 16, v17
	v_lshlrev_b32_e32 v8, 16, v12
	v_and_b32_e32 v9, 0xffff0000, v12
	v_lshlrev_b32_e32 v10, 16, v13
	v_and_b32_e32 v11, 0xffff0000, v13
	v_lshlrev_b32_e32 v12, 16, v14
	v_and_b32_e32 v13, 0xffff0000, v14
	v_lshlrev_b32_e32 v14, 16, v15
	v_and_b32_e32 v15, 0xffff0000, v15
	v_and_b32_e32 v17, 0xffff0000, v17
	v_lshlrev_b32_e32 v22, 16, v18
	v_and_b32_e32 v18, 0xffff0000, v18
	v_lshlrev_b32_e32 v23, 16, v19
	v_and_b32_e32 v19, 0xffff0000, v19
	v_fmac_f32_e32 v20, v4, v8
	v_fmac_f32_e32 v16, v5, v9
	v_fmac_f32_e32 v21, v6, v10
	v_fmac_f32_e32 v17, v7, v11
	v_fmac_f32_e32 v22, v0, v12
	v_fmac_f32_e32 v18, v1, v13
	v_fmac_f32_e32 v23, v2, v14
	v_fmac_f32_e32 v19, v3, v15
	v_cvt_pk_bf16_f32 v0, v20, v16
	v_cvt_pk_bf16_f32 v1, v21, v17
	v_cvt_pk_bf16_f32 v2, v22, v18
	v_cvt_pk_bf16_f32 v3, v23, v19
	global_store_dwordx4 v[28:29], v[0:3], off offset:256
	s_cbranch_vccz .LBB0_1004
	s_waitcnt vmcnt(0)
	s_cmpk_gt_u32 s25, 0xff
	s_cbranch_scc1 .LBB0_1015
	s_barrier

; #define PG8_STAGE(bufoff, gbase, voff) do { _Pragma("unroll") for (int _i = 0; _i < 2; ++_i) \
;         __builtin_amdgcn_global_load_lds((const unsigned*)((const char*)(gbase) + (voff)[_i]), (PG8_LAS unsigned*)(lds + (bufoff) + ldsw + _i * 8192), 16, 0, 0); } while (0)
; #define PG8_LDA(dst, b, h) do { _Pragma("unroll") for (int m = 0; m < 4; ++m) _Pragma("unroll") for (int k = 0; k < 2; ++k) dst[m][k] = *(const PG8_LAS bf16x8*)(lds + PG8_SA(b, h) + aoff + m * 2048 + k * 1024); } while (0)
; #define PG8_LDB(dst, b, h) do { _Pragma("unroll") for (int n = 0; n < 2; ++n) _Pragma("unroll") for (int k = 0; k < 2; ++k) dst[n][k] = *(const PG8_LAS bf16x8*)(lds + PG8_SB(b, h) + boff + n * 2048 + k * 1024); } while (0)
; #define PG8_MMA(ai, bj, At, Bt) do { __builtin_amdgcn_s_setprio(1); _Pragma("unroll") for (int m = 0; m < 4; ++m) _Pragma("unroll") for (int n = 0; n < 2; ++n) _Pragma("unroll") for (int k = 0; k < 2; ++k) \
;         acc[ai][bj][m][n] = __builtin_amdgcn_mfma_f32_16x16x32_bf16(Bt[n][k], At[m][k], acc[ai][bj][m][n], 0, 0, 0); __builtin_amdgcn_s_setprio(0); } while (0)
; #define PG8_WAIT_L(n) asm volatile("s_waitcnt lgkmcnt(" #n ")" ::: "memory")
; #define PG8_BAR __builtin_amdgcn_s_barrier()
; #define PG8_SCHED __builtin_amdgcn_sched_barrier(0)
; template <class Epi, class Sched>
; __device__ __forceinline__ void gemm_phase(PG8_LAS unsigned char* lds, const Gemm g, const Sched& S, const Epi& E) {
;     ...
;             PG8_LDB(B0, 0, 0); PG8_SCHED; PG8_LDA(At, 0, 0); PG8_STAGE(PG8_SA(1, 1), a1 + hstep, voffA);
;             PG8_WAIT_L(8); PG8_BAR; PG8_WAIT_L(0); PG8_MMA(0, 0, At, B0); PG8_BAR; PG8_SCHED;
;             PG8_LDB(B1, 0, 1); PG8_STAGE(PG8_SB(0, 0), b2, voffB);
;             PG8_BAR; PG8_WAIT_L(0); PG8_MMA(0, 1, At, B1); PG8_BAR;
;             PG8_LDA(At, 0, 1); PG8_STAGE(PG8_SA(0, 0), a2, voffA);
;             PG8_BAR; PG8_WAIT_L(0); PG8_MMA(1, 0, At, B0); PG8_BAR; PG8_SCHED;
.LBB0_1083:
	ds_read_b128 v[152:155], v149
	ds_read_b128 v[156:159], v149 offset:1024
	ds_read_b128 v[160:163], v149 offset:2048
	ds_read_b128 v[164:167], v149 offset:3072
	ds_read_b128 v[168:171], v150
	ds_read_b128 v[172:175], v150 offset:1024
	ds_read_b128 v[182:185], v150 offset:2048
	ds_read_b128 v[190:193], v150 offset:3072
	ds_read_b128 v[194:197], v150 offset:4096
	ds_read_b128 v[198:201], v150 offset:5120
	ds_read_b128 v[202:205], v150 offset:6144
	ds_read_b128 v[206:209], v150 offset:7168
	s_add_u32 s26, s24, 0xfffc0080
	s_addc_u32 s27, s25, -1
	s_cmp_eq_u32 s56, 12
	s_cselect_b32 s29, s17, s27
	s_cselect_b32 s28, s52, s26
	s_cselect_b32 s27, s15, s55
	s_cselect_b32 s26, s53, s54
	v_lshl_add_u64 v[144:145], s[24:25], 0, v[136:137]
	s_add_i32 m0, s23, 0xc000
	s_nop 0
	global_load_lds_dwordx4 v[144:145], off
	v_lshl_add_u64 v[144:145], s[24:25], 0, v[138:139]
	s_add_i32 m0, s23, 0xe000
	s_nop 0
	global_load_lds_dwordx4 v[144:145], off
	s_waitcnt lgkmcnt(8)
	s_barrier
	s_waitcnt lgkmcnt(0)
	v_mfma_f32_16x16x32_bf16 v[124:127], v[152:155], v[168:171], v[124:127]
	v_mfma_f32_16x16x32_bf16 v[120:123], v[160:163], v[168:171], v[120:123]
	v_mfma_f32_16x16x32_bf16 v[108:111], v[152:155], v[182:185], v[108:111]
	v_mfma_f32_16x16x32_bf16 v[104:107], v[160:163], v[182:185], v[104:107]
	v_mfma_f32_16x16x32_bf16 v[92:95], v[152:155], v[194:197], v[92:95]
	v_mfma_f32_16x16x32_bf16 v[88:91], v[160:163], v[194:197], v[88:91]
	v_mfma_f32_16x16x32_bf16 v[76:79], v[152:155], v[202:205], v[76:79]
	v_mfma_f32_16x16x32_bf16 v[72:75], v[160:163], v[202:205], v[72:75]
	v_mfma_f32_16x16x32_bf16 v[124:127], v[156:159], v[172:175], v[124:127]
	v_mfma_f32_16x16x32_bf16 v[120:123], v[164:167], v[172:175], v[120:123]
	v_mfma_f32_16x16x32_bf16 v[108:111], v[156:159], v[190:193], v[108:111]
	v_mfma_f32_16x16x32_bf16 v[104:107], v[164:167], v[190:193], v[104:107]
	v_mfma_f32_16x16x32_bf16 v[92:95], v[156:159], v[198:201], v[92:95]
	v_mfma_f32_16x16x32_bf16 v[88:91], v[164:167], v[198:201], v[88:91]
	v_mfma_f32_16x16x32_bf16 v[76:79], v[156:159], v[206:209], v[76:79]
	v_mfma_f32_16x16x32_bf16 v[72:75], v[164:167], v[206:209], v[72:75]
	s_barrier
	ds_read_b128 v[210:213], v151
	ds_read_b128 v[214:217], v151 offset:1024
	ds_read_b128 v[218:221], v151 offset:2048
	ds_read_b128 v[222:225], v151 offset:3072
	s_add_i32 s57, s45, s37
	v_lshl_add_u64 v[144:145], s[26:27], 0, v[130:131]
	s_mov_b32 m0, s57
	s_nop 0
	global_load_lds_dwordx4 v[144:145], off
	v_lshl_add_u64 v[186:187], s[26:27], 0, v[134:135]
	s_add_i32 m0, s57, 0x2000
	s_nop 0
	global_load_lds_dwordx4 v[186:187], off
	s_barrier
	s_waitcnt lgkmcnt(0)
	v_mfma_f32_16x16x32_bf16 v[116:119], v[210:213], v[168:171], v[116:119]
	v_mfma_f32_16x16x32_bf16 v[112:115], v[218:221], v[168:171], v[112:115]
	v_mfma_f32_16x16x32_bf16 v[100:103], v[210:213], v[182:185], v[100:103]
	v_mfma_f32_16x16x32_bf16 v[96:99], v[218:221], v[182:185], v[96:99]
	v_mfma_f32_16x16x32_bf16 v[84:87], v[210:213], v[194:197], v[84:87]
	v_mfma_f32_16x16x32_bf16 v[80:83], v[218:221], v[194:197], v[80:83]
	v_mfma_f32_16x16x32_bf16 v[68:71], v[210:213], v[202:205], v[68:71]
	v_mfma_f32_16x16x32_bf16 v[64:67], v[218:221], v[202:205], v[64:67]
	v_mfma_f32_16x16x32_bf16 v[116:119], v[214:217], v[172:175], v[116:119]
	v_mfma_f32_16x16x32_bf16 v[112:115], v[222:225], v[172:175], v[112:115]
	v_mfma_f32_16x16x32_bf16 v[100:103], v[214:217], v[190:193], v[100:103]
	v_mfma_f32_16x16x32_bf16 v[96:99], v[222:225], v[190:193], v[96:99]
	v_mfma_f32_16x16x32_bf16 v[84:87], v[214:217], v[198:201], v[84:87]
	v_mfma_f32_16x16x32_bf16 v[80:83], v[222:225], v[198:201], v[80:83]
	v_mfma_f32_16x16x32_bf16 v[68:71], v[214:217], v[206:209], v[68:71]
	v_mfma_f32_16x16x32_bf16 v[64:67], v[222:225], v[206:209], v[64:67]
	s_mov_b32 m0, s23
	v_lshl_add_u64 v[226:227], s[28:29], 0, v[128:129]
	s_barrier
	ds_read_b128 v[168:171], v150 offset:16384
	ds_read_b128 v[172:175], v150 offset:17408
	ds_read_b128 v[182:185], v150 offset:18432
	ds_read_b128 v[190:193], v150 offset:19456
	ds_read_b128 v[194:197], v150 offset:20480
	ds_read_b128 v[198:201], v150 offset:21504
	ds_read_b128 v[202:205], v150 offset:22528
	ds_read_b128 v[206:209], v150 offset:23552
	global_load_lds_dwordx4 v[226:227], off
	v_lshl_add_u64 v[228:229], s[28:29], 0, v[132:133]
	s_mov_b32 m0, s38
	s_nop 0
	global_load_lds_dwordx4 v[228:229], off
	s_barrier
	s_waitcnt lgkmcnt(0)
	v_mfma_f32_16x16x32_bf16 v[60:63], v[152:155], v[168:171], v[60:63]
	v_mfma_f32_16x16x32_bf16 v[56:59], v[160:163], v[168:171], v[56:59]
	v_mfma_f32_16x16x32_bf16 v[48:51], v[152:155], v[182:185], v[48:51]
	v_mfma_f32_16x16x32_bf16 v[40:43], v[160:163], v[182:185], v[40:43]
	v_mfma_f32_16x16x32_bf16 v[32:35], v[152:155], v[194:197], v[32:35]
	v_mfma_f32_16x16x32_bf16 v[24:27], v[160:163], v[194:197], v[24:27]
	v_mfma_f32_16x16x32_bf16 v[16:19], v[152:155], v[202:205], v[16:19]
	v_mfma_f32_16x16x32_bf16 v[8:11], v[160:163], v[202:205], v[8:11]
	v_mfma_f32_16x16x32_bf16 v[60:63], v[156:159], v[172:175], v[60:63]
	v_mfma_f32_16x16x32_bf16 v[56:59], v[164:167], v[172:175], v[56:59]
	v_mfma_f32_16x16x32_bf16 v[48:51], v[156:159], v[190:193], v[48:51]
	v_mfma_f32_16x16x32_bf16 v[40:43], v[164:167], v[190:193], v[40:43]
	v_mfma_f32_16x16x32_bf16 v[32:35], v[156:159], v[198:201], v[32:35]
	v_mfma_f32_16x16x32_bf16 v[24:27], v[164:167], v[198:201], v[24:27]
	v_mfma_f32_16x16x32_bf16 v[16:19], v[156:159], v[206:209], v[16:19]
	v_mfma_f32_16x16x32_bf16 v[8:11], v[164:167], v[206:209], v[8:11]
	s_barrier
; #define PG8_STAGE(bufoff, gbase, voff) do { _Pragma("unroll") for (int _i = 0; _i < 2; ++_i) \
;         __builtin_amdgcn_global_load_lds((const unsigned*)((const char*)(gbase) + (voff)[_i]), (PG8_LAS unsigned*)(lds + (bufoff) + ldsw + _i * 8192), 16, 0, 0); } while (0)
; #define PG8_LDA(dst, b, h) do { _Pragma("unroll") for (int m = 0; m < 4; ++m) _Pragma("unroll") for (int k = 0; k < 2; ++k) dst[m][k] = *(const PG8_LAS bf16x8*)(lds + PG8_SA(b, h) + aoff + m * 2048 + k * 1024); } while (0)
; #define PG8_LDB(dst, b, h) do { _Pragma("unroll") for (int n = 0; n < 2; ++n) _Pragma("unroll") for (int k = 0; k < 2; ++k) dst[n][k] = *(const PG8_LAS bf16x8*)(lds + PG8_SB(b, h) + boff + n * 2048 + k * 1024); } while (0)
; #define PG8_MMA(ai, bj, At, Bt) do { __builtin_amdgcn_s_setprio(1); _Pragma("unroll") for (int m = 0; m < 4; ++m) _Pragma("unroll") for (int n = 0; n < 2; ++n) _Pragma("unroll") for (int k = 0; k < 2; ++k) \
;         acc[ai][bj][m][n] = __builtin_amdgcn_mfma_f32_16x16x32_bf16(Bt[n][k], At[m][k], acc[ai][bj][m][n], 0, 0, 0); __builtin_amdgcn_s_setprio(0); } while (0)
; #define PG8_WAIT_V(n) asm volatile("s_waitcnt vmcnt(" #n ")" ::: "memory")
; #define PG8_WAIT_L(n) asm volatile("s_waitcnt lgkmcnt(" #n ")" ::: "memory")
; #define PG8_BAR __builtin_amdgcn_s_barrier()
; #define PG8_SCHED __builtin_amdgcn_sched_barrier(0)
; template <class Epi, class Sched>
; __device__ __forceinline__ void gemm_phase(PG8_LAS unsigned char* lds, const Gemm g, const Sched& S, const Epi& E) {
;     ...
;             PG8_STAGE(PG8_SB(0, 1), b2 + hstep, voffB);
;             PG8_WAIT_V(6); PG8_BAR; PG8_MMA(1, 1, At, B1); PG8_BAR;
;             PG8_LDB(B0, 1, 0); PG8_SCHED; PG8_LDA(At, 1, 0); PG8_STAGE(PG8_SA(0, 1), a2 + hstep, voffA);
;             PG8_WAIT_L(8); PG8_BAR; PG8_WAIT_L(0); PG8_MMA(0, 0, At, B0); PG8_BAR; PG8_SCHED;
;             PG8_LDB(B1, 1, 1); PG8_STAGE(PG8_SB(1, 0), b3, voffB);
;             PG8_BAR; PG8_WAIT_L(0); PG8_MMA(0, 1, At, B1); PG8_BAR;
;             PG8_LDA(At, 1, 1); PG8_STAGE(PG8_SA(1, 0), a3, voffA);
;             PG8_BAR; PG8_WAIT_L(0); PG8_MMA(1, 0, At, B0); PG8_BAR; PG8_SCHED;
	s_add_u32 s58, s26, 0x40000
	s_addc_u32 s59, s27, 0
	s_add_i32 s57, s46, s37
	v_lshl_add_u64 v[152:153], s[58:59], 0, v[130:131]
	s_mov_b32 m0, s57
	s_nop 0
	global_load_lds_dwordx4 v[152:153], off
	v_lshl_add_u64 v[152:153], s[58:59], 0, v[134:135]
	s_add_i32 m0, s57, 0x2000
	s_nop 0
	global_load_lds_dwordx4 v[152:153], off
	s_waitcnt vmcnt(6)
	s_barrier
	v_mfma_f32_16x16x32_bf16 v[52:55], v[210:213], v[168:171], v[52:55]
	v_mfma_f32_16x16x32_bf16 v[44:47], v[218:221], v[168:171], v[44:47]
	v_mfma_f32_16x16x32_bf16 v[36:39], v[210:213], v[182:185], v[36:39]
	v_mfma_f32_16x16x32_bf16 v[28:31], v[218:221], v[182:185], v[28:31]
	v_mfma_f32_16x16x32_bf16 v[20:23], v[210:213], v[194:197], v[20:23]
	v_mfma_f32_16x16x32_bf16 v[12:15], v[218:221], v[194:197], v[12:15]
	v_mfma_f32_16x16x32_bf16 v[4:7], v[210:213], v[202:205], v[4:7]
	v_mfma_f32_16x16x32_bf16 v[0:3], v[218:221], v[202:205], v[0:3]
	v_mfma_f32_16x16x32_bf16 v[52:55], v[214:217], v[172:175], v[52:55]
	v_mfma_f32_16x16x32_bf16 v[44:47], v[222:225], v[172:175], v[44:47]
	v_mfma_f32_16x16x32_bf16 v[36:39], v[214:217], v[190:193], v[36:39]
	v_mfma_f32_16x16x32_bf16 v[28:31], v[222:225], v[190:193], v[28:31]
	v_mfma_f32_16x16x32_bf16 v[20:23], v[214:217], v[198:201], v[20:23]
	v_mfma_f32_16x16x32_bf16 v[12:15], v[222:225], v[198:201], v[12:15]
	v_mfma_f32_16x16x32_bf16 v[4:7], v[214:217], v[206:209], v[4:7]
	v_mfma_f32_16x16x32_bf16 v[0:3], v[222:225], v[206:209], v[0:3]
	s_add_i32 s57, 0, 0x18000
	v_add_u32_e32 v164, s57, v147
	s_barrier
	ds_read_b128 v[152:155], v164
	ds_read_b128 v[156:159], v164 offset:1024
	ds_read_b128 v[160:163], v164 offset:2048
	ds_read_b128 v[164:167], v164 offset:3072
	ds_read_b128 v[168:171], v150 offset:32768
	ds_read_b128 v[172:175], v150 offset:33792
	ds_read_b128 v[182:185], v150 offset:34816
	ds_read_b128 v[190:193], v150 offset:35840
	ds_read_b128 v[194:197], v150 offset:36864
	ds_read_b128 v[198:201], v150 offset:37888
	ds_read_b128 v[202:205], v150 offset:38912
	ds_read_b128 v[206:209], v150 offset:39936
	s_add_u32 s28, s28, 0x40000
	s_addc_u32 s29, s29, 0
	s_mov_b32 m0, s39
	v_lshl_add_u64 v[210:211], s[28:29], 0, v[128:129]
	global_load_lds_dwordx4 v[210:211], off
	v_lshl_add_u64 v[210:211], s[28:29], 0, v[132:133]
	s_mov_b32 m0, s40
	s_nop 0
	global_load_lds_dwordx4 v[210:211], off
	s_waitcnt lgkmcnt(8)
	s_barrier
	s_waitcnt lgkmcnt(0)
	v_mfma_f32_16x16x32_bf16 v[124:127], v[152:155], v[168:171], v[124:127]
	v_mfma_f32_16x16x32_bf16 v[120:123], v[160:163], v[168:171], v[120:123]
	v_mfma_f32_16x16x32_bf16 v[108:111], v[152:155], v[182:185], v[108:111]
	v_mfma_f32_16x16x32_bf16 v[104:107], v[160:163], v[182:185], v[104:107]
	v_mfma_f32_16x16x32_bf16 v[92:95], v[152:155], v[194:197], v[92:95]
	v_mfma_f32_16x16x32_bf16 v[88:91], v[160:163], v[194:197], v[88:91]
	v_mfma_f32_16x16x32_bf16 v[76:79], v[152:155], v[202:205], v[76:79]
	v_mfma_f32_16x16x32_bf16 v[72:75], v[160:163], v[202:205], v[72:75]
	v_mfma_f32_16x16x32_bf16 v[124:127], v[156:159], v[172:175], v[124:127]
	v_mfma_f32_16x16x32_bf16 v[120:123], v[164:167], v[172:175], v[120:123]
	v_mfma_f32_16x16x32_bf16 v[108:111], v[156:159], v[190:193], v[108:111]
	v_mfma_f32_16x16x32_bf16 v[104:107], v[164:167], v[190:193], v[104:107]
	v_mfma_f32_16x16x32_bf16 v[92:95], v[156:159], v[198:201], v[92:95]
	v_mfma_f32_16x16x32_bf16 v[88:91], v[164:167], v[198:201], v[88:91]
	v_mfma_f32_16x16x32_bf16 v[76:79], v[156:159], v[206:209], v[76:79]
	v_mfma_f32_16x16x32_bf16 v[72:75], v[164:167], v[206:209], v[72:75]
	s_barrier
	s_add_i32 s28, 0, 0x1c000
	v_add_u32_e32 v179, s28, v147
	ds_read_b128 v[210:213], v179
	ds_read_b128 v[214:217], v179 offset:1024
	ds_read_b128 v[218:221], v179 offset:2048
	ds_read_b128 v[222:225], v179 offset:3072
	s_add_i32 s29, s57, s37
	v_lshl_add_u64 v[144:145], v[144:145], 0, s[6:7]
	s_mov_b32 m0, s29
	s_nop 0
	global_load_lds_dwordx4 v[144:145], off
	v_lshl_add_u64 v[144:145], v[186:187], 0, s[6:7]
	s_add_i32 m0, s29, 0x2000
	s_nop 0
	global_load_lds_dwordx4 v[144:145], off
	s_barrier
	s_waitcnt lgkmcnt(0)
	v_mfma_f32_16x16x32_bf16 v[116:119], v[210:213], v[168:171], v[116:119]
	v_mfma_f32_16x16x32_bf16 v[112:115], v[218:221], v[168:171], v[112:115]
	v_mfma_f32_16x16x32_bf16 v[100:103], v[210:213], v[182:185], v[100:103]
	v_mfma_f32_16x16x32_bf16 v[96:99], v[218:221], v[182:185], v[96:99]
	v_mfma_f32_16x16x32_bf16 v[84:87], v[210:213], v[194:197], v[84:87]
	v_mfma_f32_16x16x32_bf16 v[80:83], v[218:221], v[194:197], v[80:83]
	v_mfma_f32_16x16x32_bf16 v[68:71], v[210:213], v[202:205], v[68:71]
	v_mfma_f32_16x16x32_bf16 v[64:67], v[218:221], v[202:205], v[64:67]
	v_mfma_f32_16x16x32_bf16 v[116:119], v[214:217], v[172:175], v[116:119]
	v_mfma_f32_16x16x32_bf16 v[112:115], v[222:225], v[172:175], v[112:115]
	v_mfma_f32_16x16x32_bf16 v[100:103], v[214:217], v[190:193], v[100:103]
	v_mfma_f32_16x16x32_bf16 v[96:99], v[222:225], v[190:193], v[96:99]
	v_mfma_f32_16x16x32_bf16 v[84:87], v[214:217], v[198:201], v[84:87]
	v_mfma_f32_16x16x32_bf16 v[80:83], v[222:225], v[198:201], v[80:83]
	v_mfma_f32_16x16x32_bf16 v[68:71], v[214:217], v[206:209], v[68:71]
	v_mfma_f32_16x16x32_bf16 v[64:67], v[222:225], v[206:209], v[64:67]
	s_mov_b32 m0, s42
	v_lshl_add_u64 v[144:145], v[226:227], 0, s[6:7]
	s_barrier
	ds_read_b128 v[168:171], v150 offset:49152
	ds_read_b128 v[172:175], v150 offset:50176
	ds_read_b128 v[182:185], v150 offset:51200
	ds_read_b128 v[190:193], v150 offset:52224
	ds_read_b128 v[194:197], v150 offset:53248
	ds_read_b128 v[198:201], v150 offset:54272
	ds_read_b128 v[202:205], v150 offset:55296
	ds_read_b128 v[206:209], v150 offset:56320
	global_load_lds_dwordx4 v[144:145], off
	v_lshl_add_u64 v[144:145], v[228:229], 0, s[6:7]
	s_mov_b32 m0, s43
	s_nop 0
	global_load_lds_dwordx4 v[144:145], off
	s_barrier
; __device__ __forceinline__ unsigned cvt_pk_bf16(float lo, float hi) { unsigned r; asm volatile("v_cvt_pk_bf16_f32 %0, %1, %2" : "=v"(r) : "v"(lo), "v"(hi)); return r; }
; __device__ __forceinline__ float flogsig16(float x) { return (fminf(x, 0.f) - __logf(1.0f + __expf(-fabsf(x)))) * 0.0625f; }
; #define PG8_STAGE(bufoff, gbase, voff) do { _Pragma("unroll") for (int _i = 0; _i < 2; ++_i) \
;         __builtin_amdgcn_global_load_lds((const unsigned*)((const char*)(gbase) + (voff)[_i]), (PG8_LAS unsigned*)(lds + (bufoff) + ldsw + _i * 8192), 16, 0, 0); } while (0)
; #define PG8_WAIT_V(n) asm volatile("s_waitcnt vmcnt(" #n ")" ::: "memory")
; #define PG8_WAIT_L(n) asm volatile("s_waitcnt lgkmcnt(" #n ")" ::: "memory")
; #define PG8_BAR __builtin_amdgcn_s_barrier()
; #define PG8_SCHED __builtin_amdgcn_sched_barrier(0)
;     __device__ __forceinline__ void operator()(const f32x4 (&acc)[2][2][4][2], const Unit& u, int wr, int wc, int fr, int fq) const {
;     ...
;             for (int m = 0; m < 4; ++m) { bf16_t* rowp = O + (size_t)(row0 + ai * HALF + m * 16) * ldc + col0;
; #pragma unroll
;                 for (int bj = 0; bj < 2; ++bj) { f32x4 v0 = acc[ai][bj][m][0] + bv[bj][0], v1 = acc[ai][bj][m][1] + bv[bj][1];
;                     if (act == 1) {
; #pragma unroll
;                         for (int j = 0; j < 1; ++j) { v0 = v0 * sigmoid4(v0); v1 = v1 * sigmoid4(v1); } }
;                     else if (act == 2) {
; #pragma unroll
;                         for (int j = 0; j < 1; ++j) { v0 = sigmoid4(v0); v1 = sigmoid4(v1); } }
;                     else if (act == 3) {
; #pragma unroll
;                         for (int j = 0; j < 4; ++j) { v0[j] = flogsig16(v0[j]); v1[j] = flogsig16(v1[j]); } }
;                     u32x4 w; w.x = cvt_pk_bf16(v0[0], v0[1]); w.y = cvt_pk_bf16(v0[2], v0[3]); w.z = cvt_pk_bf16(v1[0], v1[1]); w.w = cvt_pk_bf16(v1[2], v1[3]);
;                     *(u32x4*)(rowp + bj * HALF) = w; } }
; template <class Epi, class Sched>
; __device__ __forceinline__ void gemm_phase(PG8_LAS unsigned char* lds, const Gemm g, const Sched& S, const Epi& E) {
;     ...
;             PG8_BAR; PG8_WAIT_L(0); PG8_MMA(1, 0, At, B0); PG8_BAR; PG8_SCHED;
;             PG8_STAGE(PG8_SB(1, 1), b3 + hstep, voffB);
;             PG8_WAIT_V(6); PG8_BAR; PG8_MMA(1, 1, At, B1); PG8_BAR;
;         }
	s_waitcnt lgkmcnt(0)
	v_mfma_f32_16x16x32_bf16 v[60:63], v[152:155], v[168:171], v[60:63]
	v_mfma_f32_16x16x32_bf16 v[56:59], v[160:163], v[168:171], v[56:59]
	v_mfma_f32_16x16x32_bf16 v[48:51], v[152:155], v[182:185], v[48:51]
	v_mfma_f32_16x16x32_bf16 v[40:43], v[160:163], v[182:185], v[40:43]
	v_mfma_f32_16x16x32_bf16 v[32:35], v[152:155], v[194:197], v[32:35]
	v_mfma_f32_16x16x32_bf16 v[24:27], v[160:163], v[194:197], v[24:27]
	v_mfma_f32_16x16x32_bf16 v[16:19], v[152:155], v[202:205], v[16:19]
	v_mfma_f32_16x16x32_bf16 v[8:11], v[160:163], v[202:205], v[8:11]
	v_mfma_f32_16x16x32_bf16 v[60:63], v[156:159], v[172:175], v[60:63]
	v_mfma_f32_16x16x32_bf16 v[56:59], v[164:167], v[172:175], v[56:59]
	v_mfma_f32_16x16x32_bf16 v[48:51], v[156:159], v[190:193], v[48:51]
	v_mfma_f32_16x16x32_bf16 v[40:43], v[164:167], v[190:193], v[40:43]
	v_mfma_f32_16x16x32_bf16 v[32:35], v[156:159], v[198:201], v[32:35]
	v_mfma_f32_16x16x32_bf16 v[24:27], v[164:167], v[198:201], v[24:27]
	v_mfma_f32_16x16x32_bf16 v[16:19], v[156:159], v[206:209], v[16:19]
	v_mfma_f32_16x16x32_bf16 v[8:11], v[164:167], v[206:209], v[8:11]
	s_barrier
	s_add_u32 s26, s26, 0x40080
	s_addc_u32 s27, s27, 0
	s_add_i32 s28, s28, s37
	v_lshl_add_u64 v[144:145], s[26:27], 0, v[130:131]
	s_mov_b32 m0, s28
	s_nop 0
	global_load_lds_dwordx4 v[144:145], off
	v_lshl_add_u64 v[144:145], s[26:27], 0, v[134:135]
	s_add_i32 m0, s28, 0x2000
	s_nop 0
	global_load_lds_dwordx4 v[144:145], off
	s_waitcnt vmcnt(6)
	s_barrier
	v_mfma_f32_16x16x32_bf16 v[52:55], v[210:213], v[168:171], v[52:55]
	v_mfma_f32_16x16x32_bf16 v[44:47], v[218:221], v[168:171], v[44:47]
	v_mfma_f32_16x16x32_bf16 v[36:39], v[210:213], v[182:185], v[36:39]
	v_mfma_f32_16x16x32_bf16 v[28:31], v[218:221], v[182:185], v[28:31]
	v_mfma_f32_16x16x32_bf16 v[20:23], v[210:213], v[194:197], v[20:23]
	v_mfma_f32_16x16x32_bf16 v[12:15], v[218:221], v[194:197], v[12:15]
	v_mfma_f32_16x16x32_bf16 v[4:7], v[210:213], v[202:205], v[4:7]
	v_mfma_f32_16x16x32_bf16 v[0:3], v[218:221], v[202:205], v[0:3]
	v_mfma_f32_16x16x32_bf16 v[52:55], v[214:217], v[172:175], v[52:55]
	v_mfma_f32_16x16x32_bf16 v[44:47], v[222:225], v[172:175], v[44:47]
	v_mfma_f32_16x16x32_bf16 v[36:39], v[214:217], v[190:193], v[36:39]
	v_mfma_f32_16x16x32_bf16 v[28:31], v[222:225], v[190:193], v[28:31]
	v_mfma_f32_16x16x32_bf16 v[20:23], v[214:217], v[198:201], v[20:23]
	v_mfma_f32_16x16x32_bf16 v[12:15], v[222:225], v[198:201], v[12:15]
	v_mfma_f32_16x16x32_bf16 v[4:7], v[214:217], v[206:209], v[4:7]
	v_mfma_f32_16x16x32_bf16 v[0:3], v[222:225], v[206:209], v[0:3]
	s_add_i32 s56, s56, 2
	s_add_u32 s24, s24, 0x100
	s_addc_u32 s25, s25, 0
	s_add_u32 s54, s54, 0x100
	s_addc_u32 s55, s55, 0
	s_cmp_gt_u32 s56, 13
	s_barrier
	s_cbranch_scc0 .LBB0_1083
	v_lshl_add_u32 v152, s22, 8, v146
	v_lshl_or_b32 v144, s51, 8, v148
	v_ashrrev_i32_e32 v153, 31, v152
	v_ashrrev_i32_e32 v145, 31, v144
	v_lshlrev_b64 v[154:155], 11, v[152:153]
	v_lshl_add_u64 v[154:155], s[4:5], 0, v[154:155]
	v_lshlrev_b64 v[156:157], 1, v[144:145]
	v_lshl_add_u64 v[144:145], v[154:155], 0, v[156:157]
	v_pk_add_f32 v[126:127], v[126:127], 0 op_sel_hi:[1,0]
	v_pk_add_f32 v[124:125], v[124:125], 0 op_sel_hi:[1,0]
	v_pk_add_f32 v[154:155], v[122:123], 0 op_sel_hi:[1,0]
	v_pk_add_f32 v[122:123], v[120:121], 0 op_sel_hi:[1,0]
	v_cvt_pk_bf16_f32 v120, v124, v125
	v_cvt_pk_bf16_f32 v121, v126, v127
	v_pk_add_f32 v[116:117], v[116:117], 0 op_sel_hi:[1,0]
	v_cvt_pk_bf16_f32 v122, v122, v123
	v_cvt_pk_bf16_f32 v123, v154, v155
	global_store_dwordx4 v[144:145], v[120:123], off
	v_pk_add_f32 v[118:119], v[118:119], 0 op_sel_hi:[1,0]
	v_pk_add_f32 v[110:111], v[110:111], 0 op_sel_hi:[1,0]
	v_pk_add_f32 v[120:121], v[114:115], 0 op_sel_hi:[1,0]
	v_pk_add_f32 v[114:115], v[112:113], 0 op_sel_hi:[1,0]
	v_cvt_pk_bf16_f32 v112, v116, v117
	v_cvt_pk_bf16_f32 v113, v118, v119
	v_pk_add_f32 v[108:109], v[108:109], 0 op_sel_hi:[1,0]
	v_cvt_pk_bf16_f32 v114, v114, v115
	v_cvt_pk_bf16_f32 v115, v120, v121
	global_store_dwordx4 v[144:145], v[112:115], off offset:256
	v_pk_add_f32 v[100:101], v[100:101], 0 op_sel_hi:[1,0]
	v_pk_add_f32 v[102:103], v[102:103], 0 op_sel_hi:[1,0]
	v_or_b32_e32 v112, 16, v152
	v_ashrrev_i32_e32 v113, 31, v112
	v_lshlrev_b64 v[112:113], 11, v[112:113]
	v_lshl_add_u64 v[112:113], s[4:5], 0, v[112:113]
	v_lshl_add_u64 v[112:113], v[112:113], 0, v[156:157]
	v_pk_add_f32 v[114:115], v[106:107], 0 op_sel_hi:[1,0]
	v_pk_add_f32 v[106:107], v[104:105], 0 op_sel_hi:[1,0]
	v_cvt_pk_bf16_f32 v104, v108, v109
	v_cvt_pk_bf16_f32 v105, v110, v111
	v_pk_add_f32 v[94:95], v[94:95], 0 op_sel_hi:[1,0]
	v_cvt_pk_bf16_f32 v106, v106, v107
	v_cvt_pk_bf16_f32 v107, v114, v115
	global_store_dwordx4 v[112:113], v[104:107], off
	v_pk_add_f32 v[92:93], v[92:93], 0 op_sel_hi:[1,0]
	v_pk_add_f32 v[84:85], v[84:85], 0 op_sel_hi:[1,0]
	v_pk_add_f32 v[104:105], v[98:99], 0 op_sel_hi:[1,0]
	v_pk_add_f32 v[98:99], v[96:97], 0 op_sel_hi:[1,0]
	v_cvt_pk_bf16_f32 v96, v100, v101
	v_cvt_pk_bf16_f32 v97, v102, v103
	v_pk_add_f32 v[86:87], v[86:87], 0 op_sel_hi:[1,0]
	v_cvt_pk_bf16_f32 v98, v98, v99
	v_cvt_pk_bf16_f32 v99, v104, v105
	global_store_dwordx4 v[112:113], v[96:99], off offset:256
	v_pk_add_f32 v[78:79], v[78:79], 0 op_sel_hi:[1,0]
	v_pk_add_f32 v[76:77], v[76:77], 0 op_sel_hi:[1,0]
	v_or_b32_e32 v96, 32, v152
	v_ashrrev_i32_e32 v97, 31, v96
	v_lshlrev_b64 v[96:97], 11, v[96:97]
	v_lshl_add_u64 v[96:97], s[4:5], 0, v[96:97]
; __device__ __forceinline__ unsigned cvt_pk_bf16(float lo, float hi) { unsigned r; asm volatile("v_cvt_pk_bf16_f32 %0, %1, %2" : "=v"(r) : "v"(lo), "v"(hi)); return r; }
; __device__ __forceinline__ float flogsig16(float x) { return (fminf(x, 0.f) - __logf(1.0f + __expf(-fabsf(x)))) * 0.0625f; }
; #define PG8_WAIT_V(n) asm volatile("s_waitcnt vmcnt(" #n ")" ::: "memory")
; #define PG8_BAR __builtin_amdgcn_s_barrier()
;     __device__ __forceinline__ void operator()(const f32x4 (&acc)[2][2][4][2], const Unit& u, int wr, int wc, int fr, int fq) const {
;     ...
;             for (int m = 0; m < 4; ++m) { bf16_t* rowp = O + (size_t)(row0 + ai * HALF + m * 16) * ldc + col0;
; #pragma unroll
;                 for (int bj = 0; bj < 2; ++bj) { f32x4 v0 = acc[ai][bj][m][0] + bv[bj][0], v1 = acc[ai][bj][m][1] + bv[bj][1];
;                     if (act == 1) {
; #pragma unroll
;                         for (int j = 0; j < 1; ++j) { v0 = v0 * sigmoid4(v0); v1 = v1 * sigmoid4(v1); } }
;                     else if (act == 2) {
; #pragma unroll
;                         for (int j = 0; j < 1; ++j) { v0 = sigmoid4(v0); v1 = sigmoid4(v1); } }
;                     else if (act == 3) {
; #pragma unroll
;                         for (int j = 0; j < 4; ++j) { v0[j] = flogsig16(v0[j]); v1[j] = flogsig16(v1[j]); } }
;                     u32x4 w; w.x = cvt_pk_bf16(v0[0], v0[1]); w.y = cvt_pk_bf16(v0[2], v0[3]); w.z = cvt_pk_bf16(v1[0], v1[1]); w.w = cvt_pk_bf16(v1[2], v1[3]);
;                     *(u32x4*)(rowp + bj * HALF) = w; } }
; template <class Epi, class Sched>
; __device__ __forceinline__ void gemm_phase(PG8_LAS unsigned char* lds, const Gemm g, const Sched& S, const Epi& E) {
;     ...
;         if (!has_next) break;
; #pragma unroll
;         for (int a = 0; a < 2; ++a)
; #pragma unroll
;             for (int b = 0; b < 2; ++b)
; #pragma unroll
;                 for (int m = 0; m < 4; ++m)
; #pragma unroll
;                     for (int n = 0; n < 2; ++n) acc[a][b][m][n] = (f32x4){0.f, 0.f, 0.f, 0.f};
;         cur = nxt; cA = nA; cB = nB; ++ui;
;     }
;     PG8_WAIT_V(0);
;     if (wr == 0) PG8_BAR;
;     PG8_BAR;
	v_lshl_add_u64 v[96:97], v[96:97], 0, v[156:157]
	v_pk_add_f32 v[98:99], v[90:91], 0 op_sel_hi:[1,0]
	v_pk_add_f32 v[90:91], v[88:89], 0 op_sel_hi:[1,0]
	v_cvt_pk_bf16_f32 v88, v92, v93
	v_cvt_pk_bf16_f32 v89, v94, v95
	v_pk_add_f32 v[70:71], v[70:71], 0 op_sel_hi:[1,0]
	v_cvt_pk_bf16_f32 v90, v90, v91
	v_cvt_pk_bf16_f32 v91, v98, v99
	global_store_dwordx4 v[96:97], v[88:91], off
	v_pk_add_f32 v[68:69], v[68:69], 0 op_sel_hi:[1,0]
	v_pk_add_f32 v[60:61], v[60:61], 0 op_sel_hi:[1,0]
	v_pk_add_f32 v[88:89], v[82:83], 0 op_sel_hi:[1,0]
	v_pk_add_f32 v[82:83], v[80:81], 0 op_sel_hi:[1,0]
	v_cvt_pk_bf16_f32 v80, v84, v85
	v_cvt_pk_bf16_f32 v81, v86, v87
	v_pk_add_f32 v[62:63], v[62:63], 0 op_sel_hi:[1,0]
	v_cvt_pk_bf16_f32 v82, v82, v83
	v_cvt_pk_bf16_f32 v83, v88, v89
	global_store_dwordx4 v[96:97], v[80:83], off offset:256
	v_pk_add_f32 v[54:55], v[54:55], 0 op_sel_hi:[1,0]
	v_pk_add_f32 v[52:53], v[52:53], 0 op_sel_hi:[1,0]
	v_or_b32_e32 v80, 48, v152
	v_ashrrev_i32_e32 v81, 31, v80
	v_lshlrev_b64 v[80:81], 11, v[80:81]
	v_lshl_add_u64 v[80:81], s[4:5], 0, v[80:81]
	v_lshl_add_u64 v[80:81], v[80:81], 0, v[156:157]
	v_pk_add_f32 v[82:83], v[74:75], 0 op_sel_hi:[1,0]
	v_pk_add_f32 v[74:75], v[72:73], 0 op_sel_hi:[1,0]
	v_cvt_pk_bf16_f32 v72, v76, v77
	v_cvt_pk_bf16_f32 v73, v78, v79
	v_pk_add_f32 v[48:49], v[48:49], 0 op_sel_hi:[1,0]
	v_cvt_pk_bf16_f32 v74, v74, v75
	v_cvt_pk_bf16_f32 v75, v82, v83
	global_store_dwordx4 v[80:81], v[72:75], off
	v_pk_add_f32 v[38:39], v[38:39], 0 op_sel_hi:[1,0]
	v_pk_add_f32 v[36:37], v[36:37], 0 op_sel_hi:[1,0]
	v_pk_add_f32 v[72:73], v[66:67], 0 op_sel_hi:[1,0]
	v_pk_add_f32 v[66:67], v[64:65], 0 op_sel_hi:[1,0]
	v_cvt_pk_bf16_f32 v64, v68, v69
	v_cvt_pk_bf16_f32 v65, v70, v71
	v_pk_add_f32 v[32:33], v[32:33], 0 op_sel_hi:[1,0]
	v_cvt_pk_bf16_f32 v66, v66, v67
	v_cvt_pk_bf16_f32 v67, v72, v73
	global_store_dwordx4 v[80:81], v[64:67], off offset:256
	v_pk_add_f32 v[22:23], v[22:23], 0 op_sel_hi:[1,0]
	v_pk_add_f32 v[20:21], v[20:21], 0 op_sel_hi:[1,0]
	v_pk_add_f32 v[66:67], v[58:59], 0 op_sel_hi:[1,0]
	v_pk_add_f32 v[58:59], v[56:57], 0 op_sel_hi:[1,0]
	v_cvt_pk_bf16_f32 v56, v60, v61
	v_add_co_u32_e32 v60, vcc, s47, v144
	v_cvt_pk_bf16_f32 v57, v62, v63
	v_cvt_pk_bf16_f32 v58, v58, v59
	v_cvt_pk_bf16_f32 v59, v66, v67
	v_lshl_add_u64 v[64:65], v[144:145], 0, s[0:1]
	s_nop 0
	v_addc_co_u32_e32 v61, vcc, 0, v145, vcc
	global_store_dwordx4 v[60:61], v[56:59], off
	v_pk_add_f32 v[16:17], v[16:17], 0 op_sel_hi:[1,0]
	s_mov_b32 s51, s14
	v_pk_add_f32 v[56:57], v[46:47], 0 op_sel_hi:[1,0]
	v_pk_add_f32 v[46:47], v[44:45], 0 op_sel_hi:[1,0]
	v_cvt_pk_bf16_f32 v44, v52, v53
	v_cvt_pk_bf16_f32 v45, v54, v55
	s_mov_b32 s22, s16
	v_cvt_pk_bf16_f32 v46, v46, v47
	v_cvt_pk_bf16_f32 v47, v56, v57
	global_store_dwordx4 v[64:65], v[44:47], off offset:256
	s_mov_b64 s[26:27], s[20:21]
	s_mov_b64 s[24:25], s[18:19]
	v_pk_add_f32 v[46:47], v[50:51], 0 op_sel_hi:[1,0]
	v_pk_add_f32 v[50:51], v[42:43], 0 op_sel_hi:[1,0]
	v_pk_add_f32 v[42:43], v[40:41], 0 op_sel_hi:[1,0]
	v_cvt_pk_bf16_f32 v40, v48, v49
	v_cvt_pk_bf16_f32 v41, v46, v47
	v_add_co_u32_e32 v46, vcc, s48, v144
	v_cvt_pk_bf16_f32 v42, v42, v43
	v_cvt_pk_bf16_f32 v43, v50, v51
	v_lshl_add_u64 v[44:45], v[144:145], 0, s[8:9]
	s_nop 0
	v_addc_co_u32_e32 v47, vcc, 0, v145, vcc
	global_store_dwordx4 v[46:47], v[40:43], off
	v_pk_add_f32 v[6:7], v[6:7], 0 op_sel_hi:[1,0]
	v_pk_add_f32 v[4:5], v[4:5], 0 op_sel_hi:[1,0]
	v_pk_add_f32 v[40:41], v[30:31], 0 op_sel_hi:[1,0]
	v_pk_add_f32 v[30:31], v[28:29], 0 op_sel_hi:[1,0]
	v_cvt_pk_bf16_f32 v28, v36, v37
	v_cvt_pk_bf16_f32 v29, v38, v39
	s_nop 0
	v_cvt_pk_bf16_f32 v30, v30, v31
	v_cvt_pk_bf16_f32 v31, v40, v41
	global_store_dwordx4 v[44:45], v[28:31], off offset:256
	s_nop 1
	v_pk_add_f32 v[30:31], v[34:35], 0 op_sel_hi:[1,0]
	v_pk_add_f32 v[34:35], v[26:27], 0 op_sel_hi:[1,0]
	v_pk_add_f32 v[26:27], v[24:25], 0 op_sel_hi:[1,0]
	v_cvt_pk_bf16_f32 v24, v32, v33
	v_cvt_pk_bf16_f32 v25, v30, v31
	v_add_co_u32_e32 v30, vcc, s49, v144
	v_cvt_pk_bf16_f32 v26, v26, v27
	v_cvt_pk_bf16_f32 v27, v34, v35
	v_lshl_add_u64 v[28:29], v[144:145], 0, s[10:11]
	s_nop 0
	v_addc_co_u32_e32 v31, vcc, 0, v145, vcc
	global_store_dwordx4 v[30:31], v[24:27], off
	s_nop 1
	v_pk_add_f32 v[24:25], v[14:15], 0 op_sel_hi:[1,0]
	v_pk_add_f32 v[14:15], v[12:13], 0 op_sel_hi:[1,0]
	v_cvt_pk_bf16_f32 v12, v20, v21
	v_cvt_pk_bf16_f32 v13, v22, v23
	s_nop 0
	v_cvt_pk_bf16_f32 v14, v14, v15
	v_cvt_pk_bf16_f32 v15, v24, v25
	global_store_dwordx4 v[28:29], v[12:15], off offset:256
	s_nop 1
	v_pk_add_f32 v[14:15], v[18:19], 0 op_sel_hi:[1,0]
	v_pk_add_f32 v[18:19], v[10:11], 0 op_sel_hi:[1,0]
	v_pk_add_f32 v[10:11], v[8:9], 0 op_sel_hi:[1,0]
	v_cvt_pk_bf16_f32 v8, v16, v17
	v_cvt_pk_bf16_f32 v9, v14, v15
	v_add_co_u32_e32 v14, vcc, s50, v144
	v_lshl_add_u64 v[12:13], v[144:145], 0, s[12:13]
	s_nop 0
	v_addc_co_u32_e32 v15, vcc, 0, v145, vcc
	v_cvt_pk_bf16_f32 v10, v10, v11
	v_cvt_pk_bf16_f32 v11, v18, v19
	global_store_dwordx4 v[14:15], v[8:11], off
	s_and_b64 vcc, exec, s[2:3]
	s_nop 0
	v_pk_add_f32 v[8:9], v[2:3], 0 op_sel_hi:[1,0]
	v_pk_add_f32 v[2:3], v[0:1], 0 op_sel_hi:[1,0]
	v_cvt_pk_bf16_f32 v0, v4, v5
	v_cvt_pk_bf16_f32 v1, v6, v7
	s_nop 0
	v_cvt_pk_bf16_f32 v2, v2, v3
	v_cvt_pk_bf16_f32 v3, v8, v9
	global_store_dwordx4 v[12:13], v[0:3], off offset:256
	s_cbranch_vccz .LBB0_1076
	s_waitcnt vmcnt(0)
	s_cmpk_gt_u32 s31, 0xff
	s_cbranch_scc1 .LBB0_1087
	s_barrier

; #define PG8_STAGE(bufoff, gbase, voff) do { _Pragma("unroll") for (int _i = 0; _i < 2; ++_i) \
;         __builtin_amdgcn_global_load_lds((const unsigned*)((const char*)(gbase) + (voff)[_i]), (PG8_LAS unsigned*)(lds + (bufoff) + ldsw + _i * 8192), 16, 0, 0); } while (0)
; #define PG8_LDA(dst, b, h) do { _Pragma("unroll") for (int m = 0; m < 4; ++m) _Pragma("unroll") for (int k = 0; k < 2; ++k) dst[m][k] = *(const PG8_LAS bf16x8*)(lds + PG8_SA(b, h) + aoff + m * 2048 + k * 1024); } while (0)
; #define PG8_LDB(dst, b, h) do { _Pragma("unroll") for (int n = 0; n < 2; ++n) _Pragma("unroll") for (int k = 0; k < 2; ++k) dst[n][k] = *(const PG8_LAS bf16x8*)(lds + PG8_SB(b, h) + boff + n * 2048 + k * 1024); } while (0)
; #define PG8_MMA(ai, bj, At, Bt) do { __builtin_amdgcn_s_setprio(1); _Pragma("unroll") for (int m = 0; m < 4; ++m) _Pragma("unroll") for (int n = 0; n < 2; ++n) _Pragma("unroll") for (int k = 0; k < 2; ++k) \
;         acc[ai][bj][m][n] = __builtin_amdgcn_mfma_f32_16x16x32_bf16(Bt[n][k], At[m][k], acc[ai][bj][m][n], 0, 0, 0); __builtin_amdgcn_s_setprio(0); } while (0)
; #define PG8_WAIT_L(n) asm volatile("s_waitcnt lgkmcnt(" #n ")" ::: "memory")
; #define PG8_BAR __builtin_amdgcn_s_barrier()
; #define PG8_SCHED __builtin_amdgcn_sched_barrier(0)
; template <class Epi, class Sched>
; __device__ __forceinline__ void gemm_phase(PG8_LAS unsigned char* lds, const Gemm g, const Sched& S, const Epi& E) {
;     ...
;             PG8_LDB(B0, 0, 0); PG8_SCHED; PG8_LDA(At, 0, 0); PG8_STAGE(PG8_SA(1, 1), a1 + hstep, voffA);
;             PG8_WAIT_L(8); PG8_BAR; PG8_WAIT_L(0); PG8_MMA(0, 0, At, B0); PG8_BAR; PG8_SCHED;
;             PG8_LDB(B1, 0, 1); PG8_STAGE(PG8_SB(0, 0), b2, voffB);
;             PG8_BAR; PG8_WAIT_L(0); PG8_MMA(0, 1, At, B1); PG8_BAR;
;             PG8_LDA(At, 0, 1); PG8_STAGE(PG8_SA(0, 0), a2, voffA);
;             PG8_BAR; PG8_WAIT_L(0); PG8_MMA(1, 0, At, B0); PG8_BAR; PG8_SCHED;
.LBB0_1202:
	ds_read_b128 v[144:147], v151
	ds_read_b128 v[154:157], v151 offset:1024
	ds_read_b128 v[158:161], v151 offset:2048
	ds_read_b128 v[162:165], v151 offset:3072
	ds_read_b128 v[166:169], v152
	ds_read_b128 v[170:173], v152 offset:1024
	ds_read_b128 v[182:185], v152 offset:2048
	ds_read_b128 v[190:193], v152 offset:3072
	ds_read_b128 v[194:197], v152 offset:4096
	ds_read_b128 v[198:201], v152 offset:5120
	ds_read_b128 v[202:205], v152 offset:6144
	ds_read_b128 v[206:209], v152 offset:7168
	s_add_u32 s18, s16, 0xfffc0080
	s_addc_u32 s19, s17, -1
	s_cmp_eq_u32 s46, 12
	s_cselect_b32 s21, s9, s19
	s_cselect_b32 s20, s42, s18
	s_cselect_b32 s19, s7, s45
	s_cselect_b32 s18, s43, s44
	v_lshl_add_u64 v[174:175], s[16:17], 0, v[136:137]
	s_add_i32 m0, s15, 0xc000
	s_nop 0
	global_load_lds_dwordx4 v[174:175], off
	v_lshl_add_u64 v[174:175], s[16:17], 0, v[138:139]
	s_add_i32 m0, s15, 0xe000
	s_nop 0
	global_load_lds_dwordx4 v[174:175], off
	s_waitcnt lgkmcnt(8)
	s_barrier
	s_waitcnt lgkmcnt(0)
	v_mfma_f32_16x16x32_bf16 v[124:127], v[144:147], v[166:169], v[124:127]
	v_mfma_f32_16x16x32_bf16 v[120:123], v[158:161], v[166:169], v[120:123]
	v_mfma_f32_16x16x32_bf16 v[108:111], v[144:147], v[182:185], v[108:111]
	v_mfma_f32_16x16x32_bf16 v[104:107], v[158:161], v[182:185], v[104:107]
	v_mfma_f32_16x16x32_bf16 v[92:95], v[144:147], v[194:197], v[92:95]
	v_mfma_f32_16x16x32_bf16 v[88:91], v[158:161], v[194:197], v[88:91]
	v_mfma_f32_16x16x32_bf16 v[76:79], v[144:147], v[202:205], v[76:79]
	v_mfma_f32_16x16x32_bf16 v[72:75], v[158:161], v[202:205], v[72:75]
	v_mfma_f32_16x16x32_bf16 v[124:127], v[154:157], v[170:173], v[124:127]
	v_mfma_f32_16x16x32_bf16 v[120:123], v[162:165], v[170:173], v[120:123]
	v_mfma_f32_16x16x32_bf16 v[108:111], v[154:157], v[190:193], v[108:111]
	v_mfma_f32_16x16x32_bf16 v[104:107], v[162:165], v[190:193], v[104:107]
	v_mfma_f32_16x16x32_bf16 v[92:95], v[154:157], v[198:201], v[92:95]
	v_mfma_f32_16x16x32_bf16 v[88:91], v[162:165], v[198:201], v[88:91]
	v_mfma_f32_16x16x32_bf16 v[76:79], v[154:157], v[206:209], v[76:79]
	v_mfma_f32_16x16x32_bf16 v[72:75], v[162:165], v[206:209], v[72:75]
	s_barrier
	ds_read_b128 v[210:213], v153
	ds_read_b128 v[214:217], v153 offset:1024
	ds_read_b128 v[218:221], v153 offset:2048
	ds_read_b128 v[222:225], v153 offset:3072
	s_add_i32 s47, s38, s26
	v_lshl_add_u64 v[174:175], s[18:19], 0, v[132:133]
	s_mov_b32 m0, s47
	s_nop 0
	global_load_lds_dwordx4 v[174:175], off
	v_lshl_add_u64 v[186:187], s[18:19], 0, v[128:129]
	s_add_i32 m0, s47, 0x2000
	s_nop 0
	global_load_lds_dwordx4 v[186:187], off
	s_barrier
	s_waitcnt lgkmcnt(0)
	v_mfma_f32_16x16x32_bf16 v[116:119], v[210:213], v[166:169], v[116:119]
	v_mfma_f32_16x16x32_bf16 v[112:115], v[218:221], v[166:169], v[112:115]
	v_mfma_f32_16x16x32_bf16 v[100:103], v[210:213], v[182:185], v[100:103]
	v_mfma_f32_16x16x32_bf16 v[96:99], v[218:221], v[182:185], v[96:99]
	v_mfma_f32_16x16x32_bf16 v[84:87], v[210:213], v[194:197], v[84:87]
	v_mfma_f32_16x16x32_bf16 v[80:83], v[218:221], v[194:197], v[80:83]
	v_mfma_f32_16x16x32_bf16 v[68:71], v[210:213], v[202:205], v[68:71]
	v_mfma_f32_16x16x32_bf16 v[64:67], v[218:221], v[202:205], v[64:67]
	v_mfma_f32_16x16x32_bf16 v[116:119], v[214:217], v[170:173], v[116:119]
	v_mfma_f32_16x16x32_bf16 v[112:115], v[222:225], v[170:173], v[112:115]
	v_mfma_f32_16x16x32_bf16 v[100:103], v[214:217], v[190:193], v[100:103]
	v_mfma_f32_16x16x32_bf16 v[96:99], v[222:225], v[190:193], v[96:99]
	v_mfma_f32_16x16x32_bf16 v[84:87], v[214:217], v[198:201], v[84:87]
	v_mfma_f32_16x16x32_bf16 v[80:83], v[222:225], v[198:201], v[80:83]
	v_mfma_f32_16x16x32_bf16 v[68:71], v[214:217], v[206:209], v[68:71]
	v_mfma_f32_16x16x32_bf16 v[64:67], v[222:225], v[206:209], v[64:67]
	s_mov_b32 m0, s15
	v_lshl_add_u64 v[226:227], s[20:21], 0, v[134:135]
	s_barrier
	ds_read_b128 v[166:169], v152 offset:16384
	ds_read_b128 v[170:173], v152 offset:17408
	ds_read_b128 v[182:185], v152 offset:18432
	ds_read_b128 v[190:193], v152 offset:19456
	ds_read_b128 v[194:197], v152 offset:20480
	ds_read_b128 v[198:201], v152 offset:21504
	ds_read_b128 v[202:205], v152 offset:22528
	ds_read_b128 v[206:209], v152 offset:23552
	global_load_lds_dwordx4 v[226:227], off
	v_lshl_add_u64 v[228:229], s[20:21], 0, v[130:131]
	s_mov_b32 m0, s29
	s_nop 0
	global_load_lds_dwordx4 v[228:229], off
	s_barrier
	s_waitcnt lgkmcnt(0)
	v_mfma_f32_16x16x32_bf16 v[60:63], v[144:147], v[166:169], v[60:63]
	v_mfma_f32_16x16x32_bf16 v[56:59], v[158:161], v[166:169], v[56:59]
	v_mfma_f32_16x16x32_bf16 v[44:47], v[144:147], v[182:185], v[44:47]
	v_mfma_f32_16x16x32_bf16 v[40:43], v[158:161], v[182:185], v[40:43]
	v_mfma_f32_16x16x32_bf16 v[28:31], v[144:147], v[194:197], v[28:31]
	v_mfma_f32_16x16x32_bf16 v[24:27], v[158:161], v[194:197], v[24:27]
	v_mfma_f32_16x16x32_bf16 v[12:15], v[144:147], v[202:205], v[12:15]
	v_mfma_f32_16x16x32_bf16 v[8:11], v[158:161], v[202:205], v[8:11]
	v_mfma_f32_16x16x32_bf16 v[60:63], v[154:157], v[170:173], v[60:63]
	v_mfma_f32_16x16x32_bf16 v[56:59], v[162:165], v[170:173], v[56:59]
	v_mfma_f32_16x16x32_bf16 v[44:47], v[154:157], v[190:193], v[44:47]
	v_mfma_f32_16x16x32_bf16 v[40:43], v[162:165], v[190:193], v[40:43]
	v_mfma_f32_16x16x32_bf16 v[28:31], v[154:157], v[198:201], v[28:31]
	v_mfma_f32_16x16x32_bf16 v[24:27], v[162:165], v[198:201], v[24:27]
	v_mfma_f32_16x16x32_bf16 v[12:15], v[154:157], v[206:209], v[12:15]
	v_mfma_f32_16x16x32_bf16 v[8:11], v[162:165], v[206:209], v[8:11]
	s_barrier
; #define PG8_STAGE(bufoff, gbase, voff) do { _Pragma("unroll") for (int _i = 0; _i < 2; ++_i) \
;         __builtin_amdgcn_global_load_lds((const unsigned*)((const char*)(gbase) + (voff)[_i]), (PG8_LAS unsigned*)(lds + (bufoff) + ldsw + _i * 8192), 16, 0, 0); } while (0)
; #define PG8_LDA(dst, b, h) do { _Pragma("unroll") for (int m = 0; m < 4; ++m) _Pragma("unroll") for (int k = 0; k < 2; ++k) dst[m][k] = *(const PG8_LAS bf16x8*)(lds + PG8_SA(b, h) + aoff + m * 2048 + k * 1024); } while (0)
; #define PG8_LDB(dst, b, h) do { _Pragma("unroll") for (int n = 0; n < 2; ++n) _Pragma("unroll") for (int k = 0; k < 2; ++k) dst[n][k] = *(const PG8_LAS bf16x8*)(lds + PG8_SB(b, h) + boff + n * 2048 + k * 1024); } while (0)
; #define PG8_MMA(ai, bj, At, Bt) do { __builtin_amdgcn_s_setprio(1); _Pragma("unroll") for (int m = 0; m < 4; ++m) _Pragma("unroll") for (int n = 0; n < 2; ++n) _Pragma("unroll") for (int k = 0; k < 2; ++k) \
;         acc[ai][bj][m][n] = __builtin_amdgcn_mfma_f32_16x16x32_bf16(Bt[n][k], At[m][k], acc[ai][bj][m][n], 0, 0, 0); __builtin_amdgcn_s_setprio(0); } while (0)
; #define PG8_WAIT_V(n) asm volatile("s_waitcnt vmcnt(" #n ")" ::: "memory")
; #define PG8_WAIT_L(n) asm volatile("s_waitcnt lgkmcnt(" #n ")" ::: "memory")
; #define PG8_BAR __builtin_amdgcn_s_barrier()
; #define PG8_SCHED __builtin_amdgcn_sched_barrier(0)
; template <class Epi, class Sched>
; __device__ __forceinline__ void gemm_phase(PG8_LAS unsigned char* lds, const Gemm g, const Sched& S, const Epi& E) {
;     ...
;             PG8_STAGE(PG8_SB(0, 1), b2 + hstep, voffB);
;             PG8_WAIT_V(6); PG8_BAR; PG8_MMA(1, 1, At, B1); PG8_BAR;
;             PG8_LDB(B0, 1, 0); PG8_SCHED; PG8_LDA(At, 1, 0); PG8_STAGE(PG8_SA(0, 1), a2 + hstep, voffA);
;             PG8_WAIT_L(8); PG8_BAR; PG8_WAIT_L(0); PG8_MMA(0, 0, At, B0); PG8_BAR; PG8_SCHED;
;             PG8_LDB(B1, 1, 1); PG8_STAGE(PG8_SB(1, 0), b3, voffB);
;             PG8_BAR; PG8_WAIT_L(0); PG8_MMA(0, 1, At, B1); PG8_BAR;
;             PG8_LDA(At, 1, 1); PG8_STAGE(PG8_SA(1, 0), a3, voffA);
;             PG8_BAR; PG8_WAIT_L(0); PG8_MMA(1, 0, At, B0); PG8_BAR; PG8_SCHED;
	s_add_u32 s48, s18, 0x40000
	s_addc_u32 s49, s19, 0
	s_add_i32 s47, s39, s26
	v_lshl_add_u64 v[144:145], s[48:49], 0, v[132:133]
	s_mov_b32 m0, s47
	s_nop 0
	global_load_lds_dwordx4 v[144:145], off
	v_lshl_add_u64 v[144:145], s[48:49], 0, v[128:129]
	s_add_i32 m0, s47, 0x2000
	s_nop 0
	global_load_lds_dwordx4 v[144:145], off
	s_waitcnt vmcnt(6)
	s_barrier
	v_mfma_f32_16x16x32_bf16 v[52:55], v[210:213], v[166:169], v[52:55]
	v_mfma_f32_16x16x32_bf16 v[48:51], v[218:221], v[166:169], v[48:51]
	v_mfma_f32_16x16x32_bf16 v[36:39], v[210:213], v[182:185], v[36:39]
	v_mfma_f32_16x16x32_bf16 v[32:35], v[218:221], v[182:185], v[32:35]
	v_mfma_f32_16x16x32_bf16 v[20:23], v[210:213], v[194:197], v[20:23]
	v_mfma_f32_16x16x32_bf16 v[16:19], v[218:221], v[194:197], v[16:19]
	v_mfma_f32_16x16x32_bf16 v[4:7], v[210:213], v[202:205], v[4:7]
	v_mfma_f32_16x16x32_bf16 v[0:3], v[218:221], v[202:205], v[0:3]
	v_mfma_f32_16x16x32_bf16 v[52:55], v[214:217], v[170:173], v[52:55]
	v_mfma_f32_16x16x32_bf16 v[48:51], v[222:225], v[170:173], v[48:51]
	v_mfma_f32_16x16x32_bf16 v[36:39], v[214:217], v[190:193], v[36:39]
	v_mfma_f32_16x16x32_bf16 v[32:35], v[222:225], v[190:193], v[32:35]
	v_mfma_f32_16x16x32_bf16 v[20:23], v[214:217], v[198:201], v[20:23]
	v_mfma_f32_16x16x32_bf16 v[16:19], v[222:225], v[198:201], v[16:19]
	v_mfma_f32_16x16x32_bf16 v[4:7], v[214:217], v[206:209], v[4:7]
	v_mfma_f32_16x16x32_bf16 v[0:3], v[222:225], v[206:209], v[0:3]
	s_add_i32 s47, 0, 0x18000
	v_add_u32_e32 v162, s47, v149
	s_barrier
	ds_read_b128 v[144:147], v162
	ds_read_b128 v[154:157], v162 offset:1024
	ds_read_b128 v[158:161], v162 offset:2048
	ds_read_b128 v[162:165], v162 offset:3072
	ds_read_b128 v[166:169], v152 offset:32768
	ds_read_b128 v[170:173], v152 offset:33792
	ds_read_b128 v[182:185], v152 offset:34816
	ds_read_b128 v[190:193], v152 offset:35840
	ds_read_b128 v[194:197], v152 offset:36864
	ds_read_b128 v[198:201], v152 offset:37888
	ds_read_b128 v[202:205], v152 offset:38912
	ds_read_b128 v[206:209], v152 offset:39936
	s_add_u32 s20, s20, 0x40000
	s_addc_u32 s21, s21, 0
	s_mov_b32 m0, s30
	v_lshl_add_u64 v[210:211], s[20:21], 0, v[134:135]
	global_load_lds_dwordx4 v[210:211], off
	v_lshl_add_u64 v[210:211], s[20:21], 0, v[130:131]
	s_mov_b32 m0, s31
	s_nop 0
	global_load_lds_dwordx4 v[210:211], off
	s_waitcnt lgkmcnt(8)
	s_barrier
	s_waitcnt lgkmcnt(0)
	v_mfma_f32_16x16x32_bf16 v[124:127], v[144:147], v[166:169], v[124:127]
	v_mfma_f32_16x16x32_bf16 v[120:123], v[158:161], v[166:169], v[120:123]
	v_mfma_f32_16x16x32_bf16 v[108:111], v[144:147], v[182:185], v[108:111]
	v_mfma_f32_16x16x32_bf16 v[104:107], v[158:161], v[182:185], v[104:107]
	v_mfma_f32_16x16x32_bf16 v[92:95], v[144:147], v[194:197], v[92:95]
	v_mfma_f32_16x16x32_bf16 v[88:91], v[158:161], v[194:197], v[88:91]
	v_mfma_f32_16x16x32_bf16 v[76:79], v[144:147], v[202:205], v[76:79]
	v_mfma_f32_16x16x32_bf16 v[72:75], v[158:161], v[202:205], v[72:75]
	v_mfma_f32_16x16x32_bf16 v[124:127], v[154:157], v[170:173], v[124:127]
	v_mfma_f32_16x16x32_bf16 v[120:123], v[162:165], v[170:173], v[120:123]
	v_mfma_f32_16x16x32_bf16 v[108:111], v[154:157], v[190:193], v[108:111]
	v_mfma_f32_16x16x32_bf16 v[104:107], v[162:165], v[190:193], v[104:107]
	v_mfma_f32_16x16x32_bf16 v[92:95], v[154:157], v[198:201], v[92:95]
	v_mfma_f32_16x16x32_bf16 v[88:91], v[162:165], v[198:201], v[88:91]
	v_mfma_f32_16x16x32_bf16 v[76:79], v[154:157], v[206:209], v[76:79]
	v_mfma_f32_16x16x32_bf16 v[72:75], v[162:165], v[206:209], v[72:75]
	s_barrier
	s_add_i32 s20, 0, 0x1c000
	v_add_u32_e32 v179, s20, v149
	ds_read_b128 v[210:213], v179
	ds_read_b128 v[214:217], v179 offset:1024
	ds_read_b128 v[218:221], v179 offset:2048
	ds_read_b128 v[222:225], v179 offset:3072
	s_add_i32 s21, s47, s26
	v_lshl_add_u64 v[174:175], v[174:175], 0, s[4:5]
	s_mov_b32 m0, s21
	s_nop 0
	global_load_lds_dwordx4 v[174:175], off
	v_lshl_add_u64 v[174:175], v[186:187], 0, s[4:5]
	s_add_i32 m0, s21, 0x2000
	s_nop 0
	global_load_lds_dwordx4 v[174:175], off
	s_barrier
	s_waitcnt lgkmcnt(0)
	v_mfma_f32_16x16x32_bf16 v[116:119], v[210:213], v[166:169], v[116:119]
	v_mfma_f32_16x16x32_bf16 v[112:115], v[218:221], v[166:169], v[112:115]
	v_mfma_f32_16x16x32_bf16 v[100:103], v[210:213], v[182:185], v[100:103]
	v_mfma_f32_16x16x32_bf16 v[96:99], v[218:221], v[182:185], v[96:99]
	v_mfma_f32_16x16x32_bf16 v[84:87], v[210:213], v[194:197], v[84:87]
	v_mfma_f32_16x16x32_bf16 v[80:83], v[218:221], v[194:197], v[80:83]
	v_mfma_f32_16x16x32_bf16 v[68:71], v[210:213], v[202:205], v[68:71]
	v_mfma_f32_16x16x32_bf16 v[64:67], v[218:221], v[202:205], v[64:67]
	v_mfma_f32_16x16x32_bf16 v[116:119], v[214:217], v[170:173], v[116:119]
	v_mfma_f32_16x16x32_bf16 v[112:115], v[222:225], v[170:173], v[112:115]
	v_mfma_f32_16x16x32_bf16 v[100:103], v[214:217], v[190:193], v[100:103]
	v_mfma_f32_16x16x32_bf16 v[96:99], v[222:225], v[190:193], v[96:99]
	v_mfma_f32_16x16x32_bf16 v[84:87], v[214:217], v[198:201], v[84:87]
	v_mfma_f32_16x16x32_bf16 v[80:83], v[222:225], v[198:201], v[80:83]
	v_mfma_f32_16x16x32_bf16 v[68:71], v[214:217], v[206:209], v[68:71]
	v_mfma_f32_16x16x32_bf16 v[64:67], v[222:225], v[206:209], v[64:67]
	s_mov_b32 m0, s35
	v_lshl_add_u64 v[174:175], v[226:227], 0, s[4:5]
	s_barrier
	ds_read_b128 v[166:169], v152 offset:49152
	ds_read_b128 v[170:173], v152 offset:50176
	ds_read_b128 v[182:185], v152 offset:51200
	ds_read_b128 v[190:193], v152 offset:52224
	ds_read_b128 v[194:197], v152 offset:53248
	ds_read_b128 v[198:201], v152 offset:54272
	ds_read_b128 v[202:205], v152 offset:55296
	ds_read_b128 v[206:209], v152 offset:56320
	global_load_lds_dwordx4 v[174:175], off
	v_lshl_add_u64 v[174:175], v[228:229], 0, s[4:5]
	s_mov_b32 m0, s36
	s_nop 0
	global_load_lds_dwordx4 v[174:175], off
	s_barrier
; __device__ __forceinline__ unsigned cvt_pk_bf16(float lo, float hi) { unsigned r; asm volatile("v_cvt_pk_bf16_f32 %0, %1, %2" : "=v"(r) : "v"(lo), "v"(hi)); return r; }
; #define PG8_STAGE(bufoff, gbase, voff) do { _Pragma("unroll") for (int _i = 0; _i < 2; ++_i) \
;         __builtin_amdgcn_global_load_lds((const unsigned*)((const char*)(gbase) + (voff)[_i]), (PG8_LAS unsigned*)(lds + (bufoff) + ldsw + _i * 8192), 16, 0, 0); } while (0)
; #define PG8_MMA(ai, bj, At, Bt) do { __builtin_amdgcn_s_setprio(1); _Pragma("unroll") for (int m = 0; m < 4; ++m) _Pragma("unroll") for (int n = 0; n < 2; ++n) _Pragma("unroll") for (int k = 0; k < 2; ++k) \
;         acc[ai][bj][m][n] = __builtin_amdgcn_mfma_f32_16x16x32_bf16(Bt[n][k], At[m][k], acc[ai][bj][m][n], 0, 0, 0); __builtin_amdgcn_s_setprio(0); } while (0)
; #define PG8_WAIT_V(n) asm volatile("s_waitcnt vmcnt(" #n ")" ::: "memory")
; #define PG8_WAIT_L(n) asm volatile("s_waitcnt lgkmcnt(" #n ")" ::: "memory")
; #define PG8_BAR __builtin_amdgcn_s_barrier()
; #define PG8_SCHED __builtin_amdgcn_sched_barrier(0)
;     __device__ __forceinline__ void operator()(const f32x4 (&acc)[2][2][4][2], const Unit& u, int wr, int wc, int fr, int fq) const {
;     ...
;         for (int ai = 0; ai < 2; ++ai)
; #pragma unroll
;             for (int m = 0; m < 4; ++m) { bf16_t* rowp = O + (size_t)(row0 + ai * HALF + m * 16) * ldc + col0;
;                 f32x4 v0, v1;
; #pragma unroll
;                 for (int j = 0; j < 1; ++j) { v0 = acc[ai][0][m][0] * sigmoid4(acc[ai][0][m][0]) * acc[ai][1][m][0]; v1 = acc[ai][0][m][1] * sigmoid4(acc[ai][0][m][1]) * acc[ai][1][m][1]; }
;                 u32x4 w; w.x = cvt_pk_bf16(v0[0], v0[1]); w.y = cvt_pk_bf16(v0[2], v0[3]); w.z = cvt_pk_bf16(v1[0], v1[1]); w.w = cvt_pk_bf16(v1[2], v1[3]);
;                 *(u32x4*)rowp = w; }
; template <class Epi, class Sched>
; __device__ __forceinline__ void gemm_phase(PG8_LAS unsigned char* lds, const Gemm g, const Sched& S, const Epi& E) {
;     ...
;             PG8_BAR; PG8_WAIT_L(0); PG8_MMA(1, 0, At, B0); PG8_BAR; PG8_SCHED;
;             PG8_STAGE(PG8_SB(1, 1), b3 + hstep, voffB);
;             PG8_WAIT_V(6); PG8_BAR; PG8_MMA(1, 1, At, B1); PG8_BAR;
;         }
	s_waitcnt lgkmcnt(0)
	v_mfma_f32_16x16x32_bf16 v[60:63], v[144:147], v[166:169], v[60:63]
	v_mfma_f32_16x16x32_bf16 v[56:59], v[158:161], v[166:169], v[56:59]
	v_mfma_f32_16x16x32_bf16 v[44:47], v[144:147], v[182:185], v[44:47]
	v_mfma_f32_16x16x32_bf16 v[40:43], v[158:161], v[182:185], v[40:43]
	v_mfma_f32_16x16x32_bf16 v[28:31], v[144:147], v[194:197], v[28:31]
	v_mfma_f32_16x16x32_bf16 v[24:27], v[158:161], v[194:197], v[24:27]
	v_mfma_f32_16x16x32_bf16 v[12:15], v[144:147], v[202:205], v[12:15]
	v_mfma_f32_16x16x32_bf16 v[8:11], v[158:161], v[202:205], v[8:11]
	v_mfma_f32_16x16x32_bf16 v[60:63], v[154:157], v[170:173], v[60:63]
	v_mfma_f32_16x16x32_bf16 v[56:59], v[162:165], v[170:173], v[56:59]
	v_mfma_f32_16x16x32_bf16 v[44:47], v[154:157], v[190:193], v[44:47]
	v_mfma_f32_16x16x32_bf16 v[40:43], v[162:165], v[190:193], v[40:43]
	v_mfma_f32_16x16x32_bf16 v[28:31], v[154:157], v[198:201], v[28:31]
	v_mfma_f32_16x16x32_bf16 v[24:27], v[162:165], v[198:201], v[24:27]
	v_mfma_f32_16x16x32_bf16 v[12:15], v[154:157], v[206:209], v[12:15]
	v_mfma_f32_16x16x32_bf16 v[8:11], v[162:165], v[206:209], v[8:11]
	s_barrier
	s_add_u32 s18, s18, 0x40080
	s_addc_u32 s19, s19, 0
	s_add_i32 s20, s20, s26
	v_lshl_add_u64 v[144:145], s[18:19], 0, v[132:133]
	s_mov_b32 m0, s20
	s_nop 0
	global_load_lds_dwordx4 v[144:145], off
	v_lshl_add_u64 v[144:145], s[18:19], 0, v[128:129]
	s_add_i32 m0, s20, 0x2000
	s_nop 0
	global_load_lds_dwordx4 v[144:145], off
	s_waitcnt vmcnt(6)
	s_barrier
	v_mfma_f32_16x16x32_bf16 v[52:55], v[210:213], v[166:169], v[52:55]
	v_mfma_f32_16x16x32_bf16 v[48:51], v[218:221], v[166:169], v[48:51]
	v_mfma_f32_16x16x32_bf16 v[36:39], v[210:213], v[182:185], v[36:39]
	v_mfma_f32_16x16x32_bf16 v[32:35], v[218:221], v[182:185], v[32:35]
	v_mfma_f32_16x16x32_bf16 v[20:23], v[210:213], v[194:197], v[20:23]
	v_mfma_f32_16x16x32_bf16 v[16:19], v[218:221], v[194:197], v[16:19]
	v_mfma_f32_16x16x32_bf16 v[4:7], v[210:213], v[202:205], v[4:7]
	v_mfma_f32_16x16x32_bf16 v[0:3], v[218:221], v[202:205], v[0:3]
	v_mfma_f32_16x16x32_bf16 v[52:55], v[214:217], v[170:173], v[52:55]
	v_mfma_f32_16x16x32_bf16 v[48:51], v[222:225], v[170:173], v[48:51]
	v_mfma_f32_16x16x32_bf16 v[36:39], v[214:217], v[190:193], v[36:39]
	v_mfma_f32_16x16x32_bf16 v[32:35], v[222:225], v[190:193], v[32:35]
	v_mfma_f32_16x16x32_bf16 v[20:23], v[214:217], v[198:201], v[20:23]
	v_mfma_f32_16x16x32_bf16 v[16:19], v[222:225], v[198:201], v[16:19]
	v_mfma_f32_16x16x32_bf16 v[4:7], v[214:217], v[206:209], v[4:7]
	v_mfma_f32_16x16x32_bf16 v[0:3], v[222:225], v[206:209], v[0:3]
	s_add_i32 s46, s46, 2
	s_add_u32 s16, s16, 0x100
	s_addc_u32 s17, s17, 0
	s_add_u32 s44, s44, 0x100
	s_addc_u32 s45, s45, 0
	s_cmp_gt_u32 s46, 13
	s_barrier
	s_cbranch_scc0 .LBB0_1202
	v_max_f32_e32 v144, v124, v124
	v_max_f32_e32 v144, 0xc1a00000, v144
	v_mul_f32_e32 v144, 0xbfb8aa3b, v144
	v_exp_f32_e32 v157, v144
	v_max_f32_e32 v144, v125, v125
	v_max_f32_e32 v144, 0xc1a00000, v144
	v_mul_f32_e32 v144, 0xbfb8aa3b, v144
	v_exp_f32_e32 v156, v144
	v_max_f32_e32 v144, v126, v126
	v_max_f32_e32 v144, 0xc1a00000, v144
	v_mul_f32_e32 v144, 0xbfb8aa3b, v144
	v_exp_f32_e32 v159, v144
	v_max_f32_e32 v144, v127, v127
	v_max_f32_e32 v144, 0xc1a00000, v144
	v_mul_f32_e32 v144, 0xbfb8aa3b, v144
	v_exp_f32_e32 v158, v144
	v_pk_add_f32 v[156:157], v[156:157], 1.0 op_sel_hi:[1,0]
	v_lshl_or_b32 v146, s41, 7, v150
	v_mov_b32_e32 v160, v157
	v_pk_add_f32 v[158:159], v[158:159], 1.0 op_sel_hi:[1,0]
	v_mov_b32_e32 v162, v156
	v_mov_b32_e32 v161, v159
	v_mov_b32_e32 v163, v158
	v_pk_mul_f32 v[160:161], v[160:161], v[162:163]
	v_lshl_add_u32 v154, s14, 8, v148
	v_mul_f32_e32 v155, v160, v161
	v_rcp_f32_e32 v155, v155
	v_ashrrev_i32_e32 v147, 31, v146
	v_mov_b64_e32 v[144:145], s[0:1]
	v_mad_i64_i32 v[162:163], s[16:17], v154, s40, v[144:145]
	v_mul_f32_e32 v164, v161, v155
	v_mul_f32_e32 v160, v160, v155
	v_max_f32_e32 v155, v120, v120
	v_max_f32_e32 v155, 0xc1a00000, v155
	v_mul_f32_e32 v155, 0xbfb8aa3b, v155
	v_pk_mul_f32 v[158:159], v[158:159], v[160:161] op_sel_hi:[1,0]
	v_exp_f32_e32 v161, v155
	v_max_f32_e32 v155, v121, v121
	v_max_f32_e32 v155, 0xc1a00000, v155
	v_mul_f32_e32 v155, 0xbfb8aa3b, v155
	v_exp_f32_e32 v160, v155
	v_max_f32_e32 v155, v122, v122
	v_max_f32_e32 v155, 0xc1a00000, v155
	v_mul_f32_e32 v155, 0xbfb8aa3b, v155
	v_exp_f32_e32 v167, v155
	v_max_f32_e32 v155, v123, v123
	v_max_f32_e32 v155, 0xc1a00000, v155
	v_mul_f32_e32 v155, 0xbfb8aa3b, v155
	v_exp_f32_e32 v166, v155
	v_pk_mul_f32 v[156:157], v[156:157], v[164:165] op_sel_hi:[1,0]
	v_pk_mul_f32 v[126:127], v[126:127], v[158:159]
	v_pk_mul_f32 v[124:125], v[124:125], v[156:157]
	v_pk_add_f32 v[156:157], v[160:161], 1.0 op_sel_hi:[1,0]
	v_pk_add_f32 v[160:161], v[166:167], 1.0 op_sel_hi:[1,0]
	v_mov_b32_e32 v164, v157
	v_mov_b32_e32 v165, v161
	v_mov_b32_e32 v166, v156
	v_mov_b32_e32 v167, v160
	v_pk_mul_f32 v[164:165], v[164:165], v[166:167]
	v_pk_mul_f32 v[118:119], v[126:127], v[118:119]
	v_mul_f32_e32 v155, v164, v165
	v_rcp_f32_e32 v155, v155
	v_pk_mul_f32 v[116:117], v[124:125], v[116:117]
	v_lshlrev_b64 v[146:147], 1, v[146:147]
	v_lshl_add_u64 v[162:163], v[162:163], 0, v[146:147]
	v_mul_f32_e32 v124, v165, v155
	v_mul_f32_e32 v126, v164, v155
	v_pk_mul_f32 v[126:127], v[160:161], v[126:127] op_sel_hi:[1,0]
	v_pk_mul_f32 v[124:125], v[156:157], v[124:125] op_sel_hi:[1,0]
	v_pk_mul_f32 v[122:123], v[122:123], v[126:127]
	v_pk_mul_f32 v[120:121], v[120:121], v[124:125]
	v_pk_mul_f32 v[122:123], v[122:123], v[114:115]
	v_pk_mul_f32 v[114:115], v[120:121], v[112:113]
	v_cvt_pk_bf16_f32 v112, v116, v117
	v_cvt_pk_bf16_f32 v113, v118, v119
; __device__ __forceinline__ unsigned cvt_pk_bf16(float lo, float hi) { unsigned r; asm volatile("v_cvt_pk_bf16_f32 %0, %1, %2" : "=v"(r) : "v"(lo), "v"(hi)); return r; }
; __device__ __forceinline__ f32x4 sigmoid4(f32x4 x) {
;     f32x4 d;
; #pragma unroll
;     for (int j = 0; j < 4; ++j) d[j] = 1.0f + __expf(-fmaxf(x[j], -20.0f));
;     const float p01 = d[0] * d[1], p23 = d[2] * d[3], r = __builtin_amdgcn_rcpf(p01 * p23), r01 = r * p23, r23 = r * p01;
;     return (f32x4){r01 * d[1], r01 * d[0], r23 * d[3], r23 * d[2]};
; }
;     __device__ __forceinline__ void operator()(const f32x4 (&acc)[2][2][4][2], const Unit& u, int wr, int wc, int fr, int fq) const {
;     ...
;         for (int ai = 0; ai < 2; ++ai)
; #pragma unroll
;             for (int m = 0; m < 4; ++m) { bf16_t* rowp = O + (size_t)(row0 + ai * HALF + m * 16) * ldc + col0;
;                 f32x4 v0, v1;
; #pragma unroll
;                 for (int j = 0; j < 1; ++j) { v0 = acc[ai][0][m][0] * sigmoid4(acc[ai][0][m][0]) * acc[ai][1][m][0]; v1 = acc[ai][0][m][1] * sigmoid4(acc[ai][0][m][1]) * acc[ai][1][m][1]; }
;                 u32x4 w; w.x = cvt_pk_bf16(v0[0], v0[1]); w.y = cvt_pk_bf16(v0[2], v0[3]); w.z = cvt_pk_bf16(v1[0], v1[1]); w.w = cvt_pk_bf16(v1[2], v1[3]);
;                 *(u32x4*)rowp = w; }
	v_max_f32_e32 v116, v108, v108
	v_max_f32_e32 v118, v110, v110
	v_max_f32_e32 v116, 0xc1a00000, v116
	v_max_f32_e32 v118, 0xc1a00000, v118
	v_mul_f32_e32 v116, 0xbfb8aa3b, v116
	v_mul_f32_e32 v118, 0xbfb8aa3b, v118
	v_exp_f32_e32 v117, v116
	v_max_f32_e32 v116, v109, v109
	v_exp_f32_e32 v119, v118
	v_max_f32_e32 v118, v111, v111
	v_max_f32_e32 v116, 0xc1a00000, v116
	v_max_f32_e32 v118, 0xc1a00000, v118
	v_mul_f32_e32 v116, 0xbfb8aa3b, v116
	v_mul_f32_e32 v118, 0xbfb8aa3b, v118
	v_exp_f32_e32 v116, v116
	v_exp_f32_e32 v118, v118
	v_cvt_pk_bf16_f32 v114, v114, v115
	v_cvt_pk_bf16_f32 v115, v122, v123
	global_store_dwordx4 v[162:163], v[112:115], off
	v_or_b32_e32 v120, 16, v154
	s_and_b64 vcc, exec, s[2:3]
	v_pk_add_f32 v[112:113], v[116:117], 1.0 op_sel_hi:[1,0]
	v_pk_add_f32 v[114:115], v[118:119], 1.0 op_sel_hi:[1,0]
	v_mov_b32_e32 v116, v113
	v_mov_b32_e32 v117, v115
	v_mov_b32_e32 v118, v112
	v_mov_b32_e32 v119, v114
	v_pk_mul_f32 v[116:117], v[116:117], v[118:119]
	s_mov_b32 s41, s6
	v_mul_f32_e32 v118, v116, v117
	v_rcp_f32_e32 v121, v118
	v_mad_i64_i32 v[118:119], s[16:17], v120, s40, v[144:145]
	v_lshl_add_u64 v[118:119], v[118:119], 0, v[146:147]
	v_mul_f32_e32 v116, v116, v121
	v_mul_f32_e32 v120, v117, v121
	v_pk_mul_f32 v[114:115], v[114:115], v[116:117] op_sel_hi:[1,0]
	v_max_f32_e32 v116, v104, v104
	v_max_f32_e32 v121, v106, v106
	v_max_f32_e32 v116, 0xc1a00000, v116
	v_max_f32_e32 v121, 0xc1a00000, v121
	v_mul_f32_e32 v116, 0xbfb8aa3b, v116
	v_mul_f32_e32 v121, 0xbfb8aa3b, v121
	v_exp_f32_e32 v117, v116
	v_max_f32_e32 v116, v105, v105
	v_exp_f32_e32 v123, v121
	v_max_f32_e32 v121, v107, v107
	v_max_f32_e32 v116, 0xc1a00000, v116
	v_max_f32_e32 v121, 0xc1a00000, v121
	v_mul_f32_e32 v116, 0xbfb8aa3b, v116
	v_mul_f32_e32 v121, 0xbfb8aa3b, v121
	v_exp_f32_e32 v116, v116
	v_exp_f32_e32 v122, v121
	v_pk_mul_f32 v[112:113], v[112:113], v[120:121] op_sel_hi:[1,0]
	v_pk_mul_f32 v[110:111], v[110:111], v[114:115]
	v_pk_mul_f32 v[108:109], v[108:109], v[112:113]
	v_pk_add_f32 v[112:113], v[116:117], 1.0 op_sel_hi:[1,0]
	v_pk_add_f32 v[116:117], v[122:123], 1.0 op_sel_hi:[1,0]
	v_mov_b32_e32 v120, v113
	v_mov_b32_e32 v121, v117
	v_mov_b32_e32 v122, v112
	v_mov_b32_e32 v123, v116
	v_pk_mul_f32 v[120:121], v[120:121], v[122:123]
	v_pk_mul_f32 v[102:103], v[110:111], v[102:103]
	v_mul_f32_e32 v122, v120, v121
	v_rcp_f32_e32 v122, v122
	v_pk_mul_f32 v[100:101], v[108:109], v[100:101]
	s_mov_b32 s14, s8
	s_mov_b64 s[18:19], s[12:13]
	v_mul_f32_e32 v108, v121, v122
	v_mul_f32_e32 v110, v120, v122
	v_pk_mul_f32 v[110:111], v[116:117], v[110:111] op_sel_hi:[1,0]
	v_pk_mul_f32 v[108:109], v[112:113], v[108:109] op_sel_hi:[1,0]
	v_pk_mul_f32 v[106:107], v[106:107], v[110:111]
	v_pk_mul_f32 v[104:105], v[104:105], v[108:109]
	v_pk_mul_f32 v[106:107], v[106:107], v[98:99]
	v_pk_mul_f32 v[98:99], v[104:105], v[96:97]
	v_cvt_pk_bf16_f32 v96, v100, v101
	v_cvt_pk_bf16_f32 v97, v102, v103
	v_max_f32_e32 v100, v92, v92
	v_max_f32_e32 v102, v94, v94
	v_max_f32_e32 v100, 0xc1a00000, v100
	v_max_f32_e32 v102, 0xc1a00000, v102
	v_mul_f32_e32 v100, 0xbfb8aa3b, v100
	v_mul_f32_e32 v102, 0xbfb8aa3b, v102
	v_exp_f32_e32 v101, v100
	v_max_f32_e32 v100, v93, v93
	v_exp_f32_e32 v103, v102
	v_max_f32_e32 v102, v95, v95
	v_max_f32_e32 v100, 0xc1a00000, v100
	v_max_f32_e32 v102, 0xc1a00000, v102
	v_mul_f32_e32 v100, 0xbfb8aa3b, v100
	v_mul_f32_e32 v102, 0xbfb8aa3b, v102
	v_exp_f32_e32 v100, v100
	v_exp_f32_e32 v102, v102
	v_cvt_pk_bf16_f32 v98, v98, v99
	v_cvt_pk_bf16_f32 v99, v106, v107
	global_store_dwordx4 v[118:119], v[96:99], off
	v_or_b32_e32 v104, 32, v154
	s_nop 0
	v_pk_add_f32 v[96:97], v[100:101], 1.0 op_sel_hi:[1,0]
	v_pk_add_f32 v[98:99], v[102:103], 1.0 op_sel_hi:[1,0]
	v_mov_b32_e32 v100, v97
	v_mov_b32_e32 v101, v99
	v_mov_b32_e32 v102, v96
	v_mov_b32_e32 v103, v98
	v_pk_mul_f32 v[100:101], v[100:101], v[102:103]
	s_nop 0
	v_mul_f32_e32 v102, v100, v101
	v_rcp_f32_e32 v105, v102
	v_mad_i64_i32 v[102:103], s[16:17], v104, s40, v[144:145]
	v_lshl_add_u64 v[102:103], v[102:103], 0, v[146:147]
	v_mul_f32_e32 v100, v100, v105
	v_mul_f32_e32 v104, v101, v105
	v_pk_mul_f32 v[98:99], v[98:99], v[100:101] op_sel_hi:[1,0]
	v_max_f32_e32 v100, v88, v88
	v_max_f32_e32 v105, v90, v90
	v_max_f32_e32 v100, 0xc1a00000, v100
	v_max_f32_e32 v105, 0xc1a00000, v105
	v_mul_f32_e32 v100, 0xbfb8aa3b, v100
	v_mul_f32_e32 v105, 0xbfb8aa3b, v105
	v_exp_f32_e32 v101, v100
	v_max_f32_e32 v100, v89, v89
	v_exp_f32_e32 v107, v105
	v_max_f32_e32 v105, v91, v91
	v_max_f32_e32 v100, 0xc1a00000, v100
	v_max_f32_e32 v105, 0xc1a00000, v105
	v_mul_f32_e32 v100, 0xbfb8aa3b, v100
	v_mul_f32_e32 v105, 0xbfb8aa3b, v105
	v_exp_f32_e32 v100, v100
	v_exp_f32_e32 v106, v105
	v_pk_mul_f32 v[96:97], v[96:97], v[104:105] op_sel_hi:[1,0]
	v_pk_mul_f32 v[94:95], v[94:95], v[98:99]
	v_pk_mul_f32 v[92:93], v[92:93], v[96:97]
	v_pk_add_f32 v[96:97], v[100:101], 1.0 op_sel_hi:[1,0]
	v_pk_add_f32 v[100:101], v[106:107], 1.0 op_sel_hi:[1,0]
	v_mov_b32_e32 v104, v97
	v_mov_b32_e32 v105, v101
	v_mov_b32_e32 v106, v96
	v_mov_b32_e32 v107, v100
	v_pk_mul_f32 v[104:105], v[104:105], v[106:107]
	v_pk_mul_f32 v[86:87], v[94:95], v[86:87]
	v_mul_f32_e32 v106, v104, v105
	v_rcp_f32_e32 v106, v106
	v_pk_mul_f32 v[84:85], v[92:93], v[84:85]
	v_mul_f32_e32 v92, v105, v106
	v_mul_f32_e32 v94, v104, v106
	v_pk_mul_f32 v[94:95], v[100:101], v[94:95] op_sel_hi:[1,0]
	v_pk_mul_f32 v[92:93], v[96:97], v[92:93] op_sel_hi:[1,0]
	v_pk_mul_f32 v[90:91], v[90:91], v[94:95]
	v_pk_mul_f32 v[88:89], v[88:89], v[92:93]
	v_pk_mul_f32 v[90:91], v[90:91], v[82:83]
	v_pk_mul_f32 v[82:83], v[88:89], v[80:81]
	v_cvt_pk_bf16_f32 v80, v84, v85
; __device__ __forceinline__ unsigned cvt_pk_bf16(float lo, float hi) { unsigned r; asm volatile("v_cvt_pk_bf16_f32 %0, %1, %2" : "=v"(r) : "v"(lo), "v"(hi)); return r; }
; __device__ __forceinline__ f32x4 sigmoid4(f32x4 x) {
;     f32x4 d;
; #pragma unroll
;     for (int j = 0; j < 4; ++j) d[j] = 1.0f + __expf(-fmaxf(x[j], -20.0f));
;     const float p01 = d[0] * d[1], p23 = d[2] * d[3], r = __builtin_amdgcn_rcpf(p01 * p23), r01 = r * p23, r23 = r * p01;
;     return (f32x4){r01 * d[1], r01 * d[0], r23 * d[3], r23 * d[2]};
; }
;     __device__ __forceinline__ void operator()(const f32x4 (&acc)[2][2][4][2], const Unit& u, int wr, int wc, int fr, int fq) const {
;     ...
;         for (int ai = 0; ai < 2; ++ai)
; #pragma unroll
;             for (int m = 0; m < 4; ++m) { bf16_t* rowp = O + (size_t)(row0 + ai * HALF + m * 16) * ldc + col0;
;                 f32x4 v0, v1;
; #pragma unroll
;                 for (int j = 0; j < 1; ++j) { v0 = acc[ai][0][m][0] * sigmoid4(acc[ai][0][m][0]) * acc[ai][1][m][0]; v1 = acc[ai][0][m][1] * sigmoid4(acc[ai][0][m][1]) * acc[ai][1][m][1]; }
;                 u32x4 w; w.x = cvt_pk_bf16(v0[0], v0[1]); w.y = cvt_pk_bf16(v0[2], v0[3]); w.z = cvt_pk_bf16(v1[0], v1[1]); w.w = cvt_pk_bf16(v1[2], v1[3]);
;                 *(u32x4*)rowp = w; }
	v_cvt_pk_bf16_f32 v81, v86, v87
	v_max_f32_e32 v84, v76, v76
	v_max_f32_e32 v86, v78, v78
	v_max_f32_e32 v84, 0xc1a00000, v84
	v_max_f32_e32 v86, 0xc1a00000, v86
	v_mul_f32_e32 v84, 0xbfb8aa3b, v84
	v_mul_f32_e32 v86, 0xbfb8aa3b, v86
	v_exp_f32_e32 v85, v84
	v_max_f32_e32 v84, v77, v77
	v_exp_f32_e32 v87, v86
	v_max_f32_e32 v86, v79, v79
	v_max_f32_e32 v84, 0xc1a00000, v84
	v_max_f32_e32 v86, 0xc1a00000, v86
	v_mul_f32_e32 v84, 0xbfb8aa3b, v84
	v_mul_f32_e32 v86, 0xbfb8aa3b, v86
	v_exp_f32_e32 v84, v84
	v_exp_f32_e32 v86, v86
	v_cvt_pk_bf16_f32 v82, v82, v83
	v_cvt_pk_bf16_f32 v83, v90, v91
	global_store_dwordx4 v[102:103], v[80:83], off
	v_or_b32_e32 v88, 48, v154
	s_nop 0
	v_pk_add_f32 v[80:81], v[84:85], 1.0 op_sel_hi:[1,0]
	v_pk_add_f32 v[82:83], v[86:87], 1.0 op_sel_hi:[1,0]
	v_mov_b32_e32 v84, v81
	v_mov_b32_e32 v85, v83
	v_mov_b32_e32 v86, v80
	v_mov_b32_e32 v87, v82
	v_pk_mul_f32 v[84:85], v[84:85], v[86:87]
	s_nop 0
	v_mul_f32_e32 v86, v84, v85
	v_rcp_f32_e32 v89, v86
	v_mad_i64_i32 v[86:87], s[16:17], v88, s40, v[144:145]
	v_lshl_add_u64 v[86:87], v[86:87], 0, v[146:147]
	v_mul_f32_e32 v84, v84, v89
	v_mul_f32_e32 v88, v85, v89
	v_pk_mul_f32 v[82:83], v[82:83], v[84:85] op_sel_hi:[1,0]
	v_max_f32_e32 v84, v72, v72
	v_max_f32_e32 v89, v74, v74
	v_max_f32_e32 v84, 0xc1a00000, v84
	v_max_f32_e32 v89, 0xc1a00000, v89
	v_mul_f32_e32 v84, 0xbfb8aa3b, v84
	v_mul_f32_e32 v89, 0xbfb8aa3b, v89
	v_exp_f32_e32 v85, v84
	v_max_f32_e32 v84, v73, v73
	v_exp_f32_e32 v91, v89
	v_max_f32_e32 v89, v75, v75
	v_max_f32_e32 v84, 0xc1a00000, v84
	v_max_f32_e32 v89, 0xc1a00000, v89
	v_mul_f32_e32 v84, 0xbfb8aa3b, v84
	v_mul_f32_e32 v89, 0xbfb8aa3b, v89
	v_exp_f32_e32 v84, v84
	v_exp_f32_e32 v90, v89
	v_pk_mul_f32 v[80:81], v[80:81], v[88:89] op_sel_hi:[1,0]
	v_pk_mul_f32 v[78:79], v[78:79], v[82:83]
	v_pk_mul_f32 v[76:77], v[76:77], v[80:81]
	v_pk_add_f32 v[80:81], v[84:85], 1.0 op_sel_hi:[1,0]
	v_pk_add_f32 v[84:85], v[90:91], 1.0 op_sel_hi:[1,0]
	v_mov_b32_e32 v88, v81
	v_mov_b32_e32 v89, v85
	v_mov_b32_e32 v90, v80
	v_mov_b32_e32 v91, v84
	v_pk_mul_f32 v[88:89], v[88:89], v[90:91]
	v_pk_mul_f32 v[70:71], v[78:79], v[70:71]
	v_mul_f32_e32 v90, v88, v89
	v_rcp_f32_e32 v90, v90
	v_pk_mul_f32 v[68:69], v[76:77], v[68:69]
	v_mul_f32_e32 v76, v89, v90
	v_mul_f32_e32 v78, v88, v90
	v_pk_mul_f32 v[78:79], v[84:85], v[78:79] op_sel_hi:[1,0]
	v_pk_mul_f32 v[76:77], v[80:81], v[76:77] op_sel_hi:[1,0]
	v_pk_mul_f32 v[74:75], v[74:75], v[78:79]
	v_pk_mul_f32 v[72:73], v[72:73], v[76:77]
	v_pk_mul_f32 v[74:75], v[74:75], v[66:67]
	v_pk_mul_f32 v[66:67], v[72:73], v[64:65]
	v_cvt_pk_bf16_f32 v64, v68, v69
	v_cvt_pk_bf16_f32 v65, v70, v71
	v_max_f32_e32 v68, v60, v60
	v_max_f32_e32 v70, v62, v62
	v_max_f32_e32 v68, 0xc1a00000, v68
	v_max_f32_e32 v70, 0xc1a00000, v70
	v_mul_f32_e32 v68, 0xbfb8aa3b, v68
	v_mul_f32_e32 v70, 0xbfb8aa3b, v70
	v_exp_f32_e32 v69, v68
	v_max_f32_e32 v68, v61, v61
	v_exp_f32_e32 v71, v70
	v_max_f32_e32 v70, v63, v63
	v_max_f32_e32 v68, 0xc1a00000, v68
	v_max_f32_e32 v70, 0xc1a00000, v70
	v_mul_f32_e32 v68, 0xbfb8aa3b, v68
	v_mul_f32_e32 v70, 0xbfb8aa3b, v70
	v_exp_f32_e32 v68, v68
	v_exp_f32_e32 v70, v70
	v_cvt_pk_bf16_f32 v66, v66, v67
	v_cvt_pk_bf16_f32 v67, v74, v75
	global_store_dwordx4 v[86:87], v[64:67], off
	v_add_u32_e32 v72, 0x80, v154
	s_nop 0
	v_pk_add_f32 v[64:65], v[68:69], 1.0 op_sel_hi:[1,0]
	v_pk_add_f32 v[66:67], v[70:71], 1.0 op_sel_hi:[1,0]
	v_mov_b32_e32 v68, v65
	v_mov_b32_e32 v69, v67
	v_mov_b32_e32 v70, v64
	v_mov_b32_e32 v71, v66
	v_pk_mul_f32 v[68:69], v[68:69], v[70:71]
	s_nop 0
	v_mul_f32_e32 v70, v68, v69
	v_rcp_f32_e32 v73, v70
	v_mad_i64_i32 v[70:71], s[16:17], v72, s40, v[144:145]
	v_lshl_add_u64 v[70:71], v[70:71], 0, v[146:147]
	v_mul_f32_e32 v68, v68, v73
	v_mul_f32_e32 v72, v69, v73
	v_pk_mul_f32 v[66:67], v[66:67], v[68:69] op_sel_hi:[1,0]
	v_max_f32_e32 v68, v56, v56
	v_max_f32_e32 v73, v58, v58
	v_max_f32_e32 v68, 0xc1a00000, v68
	v_max_f32_e32 v73, 0xc1a00000, v73
	v_mul_f32_e32 v68, 0xbfb8aa3b, v68
	v_mul_f32_e32 v73, 0xbfb8aa3b, v73
	v_exp_f32_e32 v69, v68
	v_max_f32_e32 v68, v57, v57
	v_exp_f32_e32 v75, v73
	v_max_f32_e32 v73, v59, v59
	v_max_f32_e32 v68, 0xc1a00000, v68
	v_max_f32_e32 v73, 0xc1a00000, v73
	v_mul_f32_e32 v68, 0xbfb8aa3b, v68
	v_mul_f32_e32 v73, 0xbfb8aa3b, v73
	v_exp_f32_e32 v68, v68
	v_exp_f32_e32 v74, v73
	v_pk_mul_f32 v[64:65], v[64:65], v[72:73] op_sel_hi:[1,0]
	v_pk_mul_f32 v[62:63], v[62:63], v[66:67]
	v_pk_mul_f32 v[60:61], v[60:61], v[64:65]
	v_pk_add_f32 v[64:65], v[68:69], 1.0 op_sel_hi:[1,0]
	v_pk_add_f32 v[68:69], v[74:75], 1.0 op_sel_hi:[1,0]
	v_mov_b32_e32 v72, v65
	v_mov_b32_e32 v73, v69
	v_mov_b32_e32 v74, v64
	v_mov_b32_e32 v75, v68
	v_pk_mul_f32 v[72:73], v[72:73], v[74:75]
	v_pk_mul_f32 v[54:55], v[62:63], v[54:55]
	v_mul_f32_e32 v74, v72, v73
	v_rcp_f32_e32 v74, v74
	v_pk_mul_f32 v[52:53], v[60:61], v[52:53]
	v_mul_f32_e32 v60, v73, v74
	v_mul_f32_e32 v62, v72, v74
	v_pk_mul_f32 v[62:63], v[68:69], v[62:63] op_sel_hi:[1,0]
	v_pk_mul_f32 v[60:61], v[64:65], v[60:61] op_sel_hi:[1,0]
	v_pk_mul_f32 v[58:59], v[58:59], v[62:63]
	v_pk_mul_f32 v[56:57], v[56:57], v[60:61]
	v_pk_mul_f32 v[58:59], v[58:59], v[50:51]
	v_pk_mul_f32 v[50:51], v[56:57], v[48:49]
	v_cvt_pk_bf16_f32 v48, v52, v53
	v_cvt_pk_bf16_f32 v49, v54, v55
	v_max_f32_e32 v52, v44, v44
	v_max_f32_e32 v54, v46, v46
	v_max_f32_e32 v52, 0xc1a00000, v52
	v_max_f32_e32 v54, 0xc1a00000, v54
	v_mul_f32_e32 v52, 0xbfb8aa3b, v52
	v_mul_f32_e32 v54, 0xbfb8aa3b, v54
	v_exp_f32_e32 v53, v52
	v_max_f32_e32 v52, v45, v45
	v_exp_f32_e32 v55, v54
	v_max_f32_e32 v54, v47, v47
	v_max_f32_e32 v52, 0xc1a00000, v52
; __device__ __forceinline__ unsigned cvt_pk_bf16(float lo, float hi) { unsigned r; asm volatile("v_cvt_pk_bf16_f32 %0, %1, %2" : "=v"(r) : "v"(lo), "v"(hi)); return r; }
; __device__ __forceinline__ f32x4 sigmoid4(f32x4 x) {
;     f32x4 d;
; #pragma unroll
;     for (int j = 0; j < 4; ++j) d[j] = 1.0f + __expf(-fmaxf(x[j], -20.0f));
;     const float p01 = d[0] * d[1], p23 = d[2] * d[3], r = __builtin_amdgcn_rcpf(p01 * p23), r01 = r * p23, r23 = r * p01;
;     return (f32x4){r01 * d[1], r01 * d[0], r23 * d[3], r23 * d[2]};
; }
;     __device__ __forceinline__ void operator()(const f32x4 (&acc)[2][2][4][2], const Unit& u, int wr, int wc, int fr, int fq) const {
;     ...
;         for (int ai = 0; ai < 2; ++ai)
; #pragma unroll
;             for (int m = 0; m < 4; ++m) { bf16_t* rowp = O + (size_t)(row0 + ai * HALF + m * 16) * ldc + col0;
;                 f32x4 v0, v1;
; #pragma unroll
;                 for (int j = 0; j < 1; ++j) { v0 = acc[ai][0][m][0] * sigmoid4(acc[ai][0][m][0]) * acc[ai][1][m][0]; v1 = acc[ai][0][m][1] * sigmoid4(acc[ai][0][m][1]) * acc[ai][1][m][1]; }
;                 u32x4 w; w.x = cvt_pk_bf16(v0[0], v0[1]); w.y = cvt_pk_bf16(v0[2], v0[3]); w.z = cvt_pk_bf16(v1[0], v1[1]); w.w = cvt_pk_bf16(v1[2], v1[3]);
;                 *(u32x4*)rowp = w; }
	v_max_f32_e32 v54, 0xc1a00000, v54
	v_mul_f32_e32 v52, 0xbfb8aa3b, v52
	v_mul_f32_e32 v54, 0xbfb8aa3b, v54
	v_exp_f32_e32 v52, v52
	v_exp_f32_e32 v54, v54
	v_cvt_pk_bf16_f32 v50, v50, v51
	v_cvt_pk_bf16_f32 v51, v58, v59
	global_store_dwordx4 v[70:71], v[48:51], off
	v_add_u32_e32 v56, 0x90, v154
	s_nop 0
	v_pk_add_f32 v[48:49], v[52:53], 1.0 op_sel_hi:[1,0]
	v_pk_add_f32 v[50:51], v[54:55], 1.0 op_sel_hi:[1,0]
	v_mov_b32_e32 v52, v49
	v_mov_b32_e32 v53, v51
	v_mov_b32_e32 v54, v48
	v_mov_b32_e32 v55, v50
	v_pk_mul_f32 v[52:53], v[52:53], v[54:55]
	s_nop 0
	v_mul_f32_e32 v54, v52, v53
	v_rcp_f32_e32 v57, v54
	v_mad_i64_i32 v[54:55], s[16:17], v56, s40, v[144:145]
	v_lshl_add_u64 v[54:55], v[54:55], 0, v[146:147]
	v_mul_f32_e32 v52, v52, v57
	v_mul_f32_e32 v56, v53, v57
	v_pk_mul_f32 v[50:51], v[50:51], v[52:53] op_sel_hi:[1,0]
	v_max_f32_e32 v52, v40, v40
	v_max_f32_e32 v57, v42, v42
	v_max_f32_e32 v52, 0xc1a00000, v52
	v_max_f32_e32 v57, 0xc1a00000, v57
	v_mul_f32_e32 v52, 0xbfb8aa3b, v52
	v_mul_f32_e32 v57, 0xbfb8aa3b, v57
	v_exp_f32_e32 v53, v52
	v_max_f32_e32 v52, v41, v41
	v_exp_f32_e32 v59, v57
	v_max_f32_e32 v57, v43, v43
	v_max_f32_e32 v52, 0xc1a00000, v52
	v_max_f32_e32 v57, 0xc1a00000, v57
	v_mul_f32_e32 v52, 0xbfb8aa3b, v52
	v_mul_f32_e32 v57, 0xbfb8aa3b, v57
	v_exp_f32_e32 v52, v52
	v_exp_f32_e32 v58, v57
	v_pk_mul_f32 v[48:49], v[48:49], v[56:57] op_sel_hi:[1,0]
	v_pk_mul_f32 v[46:47], v[46:47], v[50:51]
	v_pk_mul_f32 v[44:45], v[44:45], v[48:49]
	v_pk_add_f32 v[48:49], v[52:53], 1.0 op_sel_hi:[1,0]
	v_pk_add_f32 v[52:53], v[58:59], 1.0 op_sel_hi:[1,0]
	v_mov_b32_e32 v56, v49
	v_mov_b32_e32 v57, v53
	v_mov_b32_e32 v58, v48
	v_mov_b32_e32 v59, v52
	v_pk_mul_f32 v[56:57], v[56:57], v[58:59]
	v_pk_mul_f32 v[38:39], v[46:47], v[38:39]
	v_mul_f32_e32 v58, v56, v57
	v_rcp_f32_e32 v58, v58
	v_pk_mul_f32 v[36:37], v[44:45], v[36:37]
	v_mul_f32_e32 v44, v57, v58
	v_mul_f32_e32 v46, v56, v58
	v_pk_mul_f32 v[46:47], v[52:53], v[46:47] op_sel_hi:[1,0]
	v_pk_mul_f32 v[44:45], v[48:49], v[44:45] op_sel_hi:[1,0]
	v_pk_mul_f32 v[42:43], v[42:43], v[46:47]
	v_pk_mul_f32 v[40:41], v[40:41], v[44:45]
	v_pk_mul_f32 v[42:43], v[42:43], v[34:35]
	v_pk_mul_f32 v[34:35], v[40:41], v[32:33]
	v_cvt_pk_bf16_f32 v32, v36, v37
	v_cvt_pk_bf16_f32 v33, v38, v39
	v_max_f32_e32 v36, v28, v28
	v_max_f32_e32 v38, v30, v30
	v_max_f32_e32 v36, 0xc1a00000, v36
	v_max_f32_e32 v38, 0xc1a00000, v38
	v_mul_f32_e32 v36, 0xbfb8aa3b, v36
	v_mul_f32_e32 v38, 0xbfb8aa3b, v38
	v_exp_f32_e32 v37, v36
	v_max_f32_e32 v36, v29, v29
	v_exp_f32_e32 v39, v38
	v_max_f32_e32 v38, v31, v31
	v_max_f32_e32 v36, 0xc1a00000, v36
	v_max_f32_e32 v38, 0xc1a00000, v38
	v_mul_f32_e32 v36, 0xbfb8aa3b, v36
	v_mul_f32_e32 v38, 0xbfb8aa3b, v38
	v_exp_f32_e32 v36, v36
	v_exp_f32_e32 v38, v38
	v_cvt_pk_bf16_f32 v34, v34, v35
	v_cvt_pk_bf16_f32 v35, v42, v43
	global_store_dwordx4 v[54:55], v[32:35], off
	v_add_u32_e32 v40, 0xa0, v154
	s_nop 0
	v_pk_add_f32 v[32:33], v[36:37], 1.0 op_sel_hi:[1,0]
	v_pk_add_f32 v[34:35], v[38:39], 1.0 op_sel_hi:[1,0]
	v_mov_b32_e32 v36, v33
	v_mov_b32_e32 v37, v35
	v_mov_b32_e32 v38, v32
	v_mov_b32_e32 v39, v34
	v_pk_mul_f32 v[36:37], v[36:37], v[38:39]
	s_nop 0
	v_mul_f32_e32 v38, v36, v37
	v_rcp_f32_e32 v41, v38
	v_mad_i64_i32 v[38:39], s[16:17], v40, s40, v[144:145]
	v_lshl_add_u64 v[38:39], v[38:39], 0, v[146:147]
	v_mul_f32_e32 v36, v36, v41
	v_mul_f32_e32 v40, v37, v41
	v_pk_mul_f32 v[34:35], v[34:35], v[36:37] op_sel_hi:[1,0]
	v_max_f32_e32 v36, v24, v24
	v_max_f32_e32 v41, v26, v26
	v_max_f32_e32 v36, 0xc1a00000, v36
	v_max_f32_e32 v41, 0xc1a00000, v41
	v_mul_f32_e32 v36, 0xbfb8aa3b, v36
	v_mul_f32_e32 v41, 0xbfb8aa3b, v41
	v_exp_f32_e32 v37, v36
	v_max_f32_e32 v36, v25, v25
	v_exp_f32_e32 v43, v41
	v_max_f32_e32 v41, v27, v27
	v_max_f32_e32 v36, 0xc1a00000, v36
	v_max_f32_e32 v41, 0xc1a00000, v41
	v_mul_f32_e32 v36, 0xbfb8aa3b, v36
; __device__ __forceinline__ unsigned cvt_pk_bf16(float lo, float hi) { unsigned r; asm volatile("v_cvt_pk_bf16_f32 %0, %1, %2" : "=v"(r) : "v"(lo), "v"(hi)); return r; }
; __device__ __forceinline__ f32x4 sigmoid4(f32x4 x) {
;     f32x4 d;
; #pragma unroll
;     for (int j = 0; j < 4; ++j) d[j] = 1.0f + __expf(-fmaxf(x[j], -20.0f));
;     const float p01 = d[0] * d[1], p23 = d[2] * d[3], r = __builtin_amdgcn_rcpf(p01 * p23), r01 = r * p23, r23 = r * p01;
;     return (f32x4){r01 * d[1], r01 * d[0], r23 * d[3], r23 * d[2]};
; }
;     __device__ __forceinline__ void operator()(const f32x4 (&acc)[2][2][4][2], const Unit& u, int wr, int wc, int fr, int fq) const {
;     ...
;         for (int ai = 0; ai < 2; ++ai)
; #pragma unroll
;             for (int m = 0; m < 4; ++m) { bf16_t* rowp = O + (size_t)(row0 + ai * HALF + m * 16) * ldc + col0;
;                 f32x4 v0, v1;
; #pragma unroll
;                 for (int j = 0; j < 1; ++j) { v0 = acc[ai][0][m][0] * sigmoid4(acc[ai][0][m][0]) * acc[ai][1][m][0]; v1 = acc[ai][0][m][1] * sigmoid4(acc[ai][0][m][1]) * acc[ai][1][m][1]; }
;                 u32x4 w; w.x = cvt_pk_bf16(v0[0], v0[1]); w.y = cvt_pk_bf16(v0[2], v0[3]); w.z = cvt_pk_bf16(v1[0], v1[1]); w.w = cvt_pk_bf16(v1[2], v1[3]);
;                 *(u32x4*)rowp = w; }
	v_mul_f32_e32 v41, 0xbfb8aa3b, v41
	v_exp_f32_e32 v36, v36
	v_exp_f32_e32 v42, v41
	v_pk_mul_f32 v[32:33], v[32:33], v[40:41] op_sel_hi:[1,0]
	v_pk_mul_f32 v[30:31], v[30:31], v[34:35]
	v_pk_mul_f32 v[28:29], v[28:29], v[32:33]
	v_pk_add_f32 v[32:33], v[36:37], 1.0 op_sel_hi:[1,0]
	v_pk_add_f32 v[36:37], v[42:43], 1.0 op_sel_hi:[1,0]
	v_mov_b32_e32 v40, v33
	v_mov_b32_e32 v41, v37
	v_mov_b32_e32 v42, v32
	v_mov_b32_e32 v43, v36
	v_pk_mul_f32 v[40:41], v[40:41], v[42:43]
	v_pk_mul_f32 v[22:23], v[30:31], v[22:23]
	v_mul_f32_e32 v42, v40, v41
	v_rcp_f32_e32 v42, v42
	v_pk_mul_f32 v[20:21], v[28:29], v[20:21]
	v_mul_f32_e32 v28, v41, v42
	v_mul_f32_e32 v30, v40, v42
	v_pk_mul_f32 v[30:31], v[36:37], v[30:31] op_sel_hi:[1,0]
	v_pk_mul_f32 v[28:29], v[32:33], v[28:29] op_sel_hi:[1,0]
	v_pk_mul_f32 v[26:27], v[26:27], v[30:31]
	v_pk_mul_f32 v[24:25], v[24:25], v[28:29]
	v_pk_mul_f32 v[26:27], v[26:27], v[18:19]
	v_pk_mul_f32 v[18:19], v[24:25], v[16:17]
	v_cvt_pk_bf16_f32 v16, v20, v21
	v_cvt_pk_bf16_f32 v17, v22, v23
	v_max_f32_e32 v20, v12, v12
	v_max_f32_e32 v22, v14, v14
	v_max_f32_e32 v20, 0xc1a00000, v20
	v_max_f32_e32 v22, 0xc1a00000, v22
	v_mul_f32_e32 v20, 0xbfb8aa3b, v20
	v_mul_f32_e32 v22, 0xbfb8aa3b, v22
	v_exp_f32_e32 v21, v20
	v_max_f32_e32 v20, v13, v13
	v_exp_f32_e32 v23, v22
	v_max_f32_e32 v22, v15, v15
	v_max_f32_e32 v20, 0xc1a00000, v20
	v_max_f32_e32 v22, 0xc1a00000, v22
	v_mul_f32_e32 v20, 0xbfb8aa3b, v20
	v_mul_f32_e32 v22, 0xbfb8aa3b, v22
	v_exp_f32_e32 v20, v20
	v_exp_f32_e32 v22, v22
	v_cvt_pk_bf16_f32 v18, v18, v19
	v_cvt_pk_bf16_f32 v19, v26, v27
	global_store_dwordx4 v[38:39], v[16:19], off
	v_add_u32_e32 v24, 0xb0, v154
	s_nop 0
	v_pk_add_f32 v[16:17], v[20:21], 1.0 op_sel_hi:[1,0]
	v_pk_add_f32 v[18:19], v[22:23], 1.0 op_sel_hi:[1,0]
	v_mov_b32_e32 v20, v17
	v_mov_b32_e32 v21, v19
	v_mov_b32_e32 v22, v16
	v_mov_b32_e32 v23, v18
	v_pk_mul_f32 v[20:21], v[20:21], v[22:23]
	s_nop 0
	v_mul_f32_e32 v22, v20, v21
	v_rcp_f32_e32 v25, v22
	v_mad_i64_i32 v[22:23], s[16:17], v24, s40, v[144:145]
	v_lshl_add_u64 v[22:23], v[22:23], 0, v[146:147]
	v_mul_f32_e32 v20, v20, v25
	v_mul_f32_e32 v24, v21, v25
	v_pk_mul_f32 v[18:19], v[18:19], v[20:21] op_sel_hi:[1,0]
	v_max_f32_e32 v20, v8, v8
	v_max_f32_e32 v25, v10, v10
	v_max_f32_e32 v20, 0xc1a00000, v20
	v_max_f32_e32 v25, 0xc1a00000, v25
	v_mul_f32_e32 v20, 0xbfb8aa3b, v20
	v_mul_f32_e32 v25, 0xbfb8aa3b, v25
	v_exp_f32_e32 v21, v20
	v_max_f32_e32 v20, v9, v9
	v_exp_f32_e32 v27, v25
	v_max_f32_e32 v25, v11, v11
	v_max_f32_e32 v20, 0xc1a00000, v20
	v_max_f32_e32 v25, 0xc1a00000, v25
	v_mul_f32_e32 v20, 0xbfb8aa3b, v20
	v_mul_f32_e32 v25, 0xbfb8aa3b, v25
	v_exp_f32_e32 v20, v20
	v_exp_f32_e32 v26, v25
	v_pk_mul_f32 v[16:17], v[16:17], v[24:25] op_sel_hi:[1,0]
	v_pk_mul_f32 v[14:15], v[14:15], v[18:19]
	v_pk_mul_f32 v[12:13], v[12:13], v[16:17]
	v_pk_add_f32 v[16:17], v[20:21], 1.0 op_sel_hi:[1,0]
	v_pk_add_f32 v[20:21], v[26:27], 1.0 op_sel_hi:[1,0]
	v_mov_b32_e32 v24, v17
	v_mov_b32_e32 v25, v21
	v_mov_b32_e32 v26, v16
	v_mov_b32_e32 v27, v20
	v_pk_mul_f32 v[24:25], v[24:25], v[26:27]
	v_pk_mul_f32 v[6:7], v[14:15], v[6:7]
	v_mul_f32_e32 v26, v24, v25
	v_rcp_f32_e32 v26, v26
	v_pk_mul_f32 v[4:5], v[12:13], v[4:5]
	s_mov_b64 s[16:17], s[10:11]
	v_mul_f32_e32 v12, v25, v26
	v_mul_f32_e32 v14, v24, v26
	v_pk_mul_f32 v[14:15], v[20:21], v[14:15] op_sel_hi:[1,0]
	v_pk_mul_f32 v[12:13], v[16:17], v[12:13] op_sel_hi:[1,0]
	v_pk_mul_f32 v[10:11], v[10:11], v[14:15]
	v_pk_mul_f32 v[8:9], v[8:9], v[12:13]
	v_pk_mul_f32 v[10:11], v[10:11], v[2:3]
	v_pk_mul_f32 v[2:3], v[8:9], v[0:1]
	v_cvt_pk_bf16_f32 v0, v4, v5
	v_cvt_pk_bf16_f32 v1, v6, v7
	s_nop 0
	v_cvt_pk_bf16_f32 v2, v2, v3
	v_cvt_pk_bf16_f32 v3, v10, v11
	global_store_dwordx4 v[22:23], v[0:3], off
	s_cbranch_vccz .LBB0_1199
	s_waitcnt vmcnt(0)
	s_cmpk_gt_u32 s23, 0xff
	s_cbranch_scc1 .LBB0_1206
	s_barrier

; #define PG8_STAGE(bufoff, gbase, voff) do { _Pragma("unroll") for (int _i = 0; _i < 2; ++_i) \
;         __builtin_amdgcn_global_load_lds((const unsigned*)((const char*)(gbase) + (voff)[_i]), (PG8_LAS unsigned*)(lds + (bufoff) + ldsw + _i * 8192), 16, 0, 0); } while (0)
; #define PG8_LDA(dst, b, h) do { _Pragma("unroll") for (int m = 0; m < 4; ++m) _Pragma("unroll") for (int k = 0; k < 2; ++k) dst[m][k] = *(const PG8_LAS bf16x8*)(lds + PG8_SA(b, h) + aoff + m * 2048 + k * 1024); } while (0)
; #define PG8_LDB(dst, b, h) do { _Pragma("unroll") for (int n = 0; n < 2; ++n) _Pragma("unroll") for (int k = 0; k < 2; ++k) dst[n][k] = *(const PG8_LAS bf16x8*)(lds + PG8_SB(b, h) + boff + n * 2048 + k * 1024); } while (0)
; #define PG8_MMA(ai, bj, At, Bt) do { __builtin_amdgcn_s_setprio(1); _Pragma("unroll") for (int m = 0; m < 4; ++m) _Pragma("unroll") for (int n = 0; n < 2; ++n) _Pragma("unroll") for (int k = 0; k < 2; ++k) \
;         acc[ai][bj][m][n] = __builtin_amdgcn_mfma_f32_16x16x32_bf16(Bt[n][k], At[m][k], acc[ai][bj][m][n], 0, 0, 0); __builtin_amdgcn_s_setprio(0); } while (0)
; #define PG8_WAIT_L(n) asm volatile("s_waitcnt lgkmcnt(" #n ")" ::: "memory")
; #define PG8_BAR __builtin_amdgcn_s_barrier()
; #define PG8_SCHED __builtin_amdgcn_sched_barrier(0)
; template <class Epi, class Sched>
; __device__ __forceinline__ void gemm_phase(PG8_LAS unsigned char* lds, const Gemm g, const Sched& S, const Epi& E) {
;     ...
;             PG8_LDB(B0, 0, 0); PG8_SCHED; PG8_LDA(At, 0, 0); PG8_STAGE(PG8_SA(1, 1), a1 + hstep, voffA);
;             PG8_WAIT_L(8); PG8_BAR; PG8_WAIT_L(0); PG8_MMA(0, 0, At, B0); PG8_BAR; PG8_SCHED;
;             PG8_LDB(B1, 0, 1); PG8_STAGE(PG8_SB(0, 0), b2, voffB);
;             PG8_BAR; PG8_WAIT_L(0); PG8_MMA(0, 1, At, B1); PG8_BAR;
;             PG8_LDA(At, 0, 1); PG8_STAGE(PG8_SA(0, 0), a2, voffA);
;             PG8_BAR; PG8_WAIT_L(0); PG8_MMA(1, 0, At, B0); PG8_BAR; PG8_SCHED;
.LBB0_1278:
	ds_read_b128 v[152:155], v149
	ds_read_b128 v[156:159], v149 offset:1024
	ds_read_b128 v[160:163], v149 offset:2048
	ds_read_b128 v[164:167], v149 offset:3072
	ds_read_b128 v[168:171], v150
	ds_read_b128 v[172:175], v150 offset:1024
	ds_read_b128 v[182:185], v150 offset:2048
	ds_read_b128 v[190:193], v150 offset:3072
	ds_read_b128 v[194:197], v150 offset:4096
	ds_read_b128 v[198:201], v150 offset:5120
	ds_read_b128 v[202:205], v150 offset:6144
	ds_read_b128 v[206:209], v150 offset:7168
	s_add_u32 s20, s18, 0x100
	s_addc_u32 s21, s19, 0
	s_cmp_eq_u32 s54, 40
	s_cselect_b32 s25, s1, s21
	s_cselect_b32 s24, s0, s20
	s_cselect_b32 s23, s5, s53
	s_cselect_b32 s22, s4, s52
	v_lshl_add_u64 v[144:145], s[18:19], 0, v[136:137]
	s_add_i32 m0, s34, 0xc000
	s_nop 0
	global_load_lds_dwordx4 v[144:145], off
	v_lshl_add_u64 v[144:145], s[18:19], 0, v[138:139]
	s_add_i32 m0, s34, 0xe000
	s_nop 0
	global_load_lds_dwordx4 v[144:145], off
	s_waitcnt lgkmcnt(8)
	s_barrier
	s_waitcnt lgkmcnt(0)
	v_mfma_f32_16x16x32_bf16 v[124:127], v[152:155], v[168:171], v[124:127]
	v_mfma_f32_16x16x32_bf16 v[120:123], v[160:163], v[168:171], v[120:123]
	v_mfma_f32_16x16x32_bf16 v[108:111], v[152:155], v[182:185], v[108:111]
	v_mfma_f32_16x16x32_bf16 v[104:107], v[160:163], v[182:185], v[104:107]
	v_mfma_f32_16x16x32_bf16 v[92:95], v[152:155], v[194:197], v[92:95]
	v_mfma_f32_16x16x32_bf16 v[88:91], v[160:163], v[194:197], v[88:91]
	v_mfma_f32_16x16x32_bf16 v[76:79], v[152:155], v[202:205], v[76:79]
	v_mfma_f32_16x16x32_bf16 v[72:75], v[160:163], v[202:205], v[72:75]
	v_mfma_f32_16x16x32_bf16 v[124:127], v[156:159], v[172:175], v[124:127]
	v_mfma_f32_16x16x32_bf16 v[120:123], v[164:167], v[172:175], v[120:123]
	v_mfma_f32_16x16x32_bf16 v[108:111], v[156:159], v[190:193], v[108:111]
	v_mfma_f32_16x16x32_bf16 v[104:107], v[164:167], v[190:193], v[104:107]
	v_mfma_f32_16x16x32_bf16 v[92:95], v[156:159], v[198:201], v[92:95]
	v_mfma_f32_16x16x32_bf16 v[88:91], v[164:167], v[198:201], v[88:91]
	v_mfma_f32_16x16x32_bf16 v[76:79], v[156:159], v[206:209], v[76:79]
	v_mfma_f32_16x16x32_bf16 v[72:75], v[164:167], v[206:209], v[72:75]
	s_barrier
	ds_read_b128 v[210:213], v151
	ds_read_b128 v[214:217], v151 offset:1024
	ds_read_b128 v[218:221], v151 offset:2048
	ds_read_b128 v[222:225], v151 offset:3072
	s_add_i32 s18, s42, s31
	v_lshl_add_u64 v[144:145], s[22:23], 0, v[130:131]
	s_mov_b32 m0, s18
	s_nop 0
	global_load_lds_dwordx4 v[144:145], off
	v_lshl_add_u64 v[186:187], s[22:23], 0, v[134:135]
	s_add_i32 m0, s18, 0x2000
	s_nop 0
	global_load_lds_dwordx4 v[186:187], off
	s_barrier
	s_waitcnt lgkmcnt(0)
	v_mfma_f32_16x16x32_bf16 v[116:119], v[210:213], v[168:171], v[116:119]
	v_mfma_f32_16x16x32_bf16 v[112:115], v[218:221], v[168:171], v[112:115]
	v_mfma_f32_16x16x32_bf16 v[100:103], v[210:213], v[182:185], v[100:103]
	v_mfma_f32_16x16x32_bf16 v[96:99], v[218:221], v[182:185], v[96:99]
	v_mfma_f32_16x16x32_bf16 v[84:87], v[210:213], v[194:197], v[84:87]
	v_mfma_f32_16x16x32_bf16 v[80:83], v[218:221], v[194:197], v[80:83]
	v_mfma_f32_16x16x32_bf16 v[68:71], v[210:213], v[202:205], v[68:71]
	v_mfma_f32_16x16x32_bf16 v[64:67], v[218:221], v[202:205], v[64:67]
	v_mfma_f32_16x16x32_bf16 v[116:119], v[214:217], v[172:175], v[116:119]
	v_mfma_f32_16x16x32_bf16 v[112:115], v[222:225], v[172:175], v[112:115]
	v_mfma_f32_16x16x32_bf16 v[100:103], v[214:217], v[190:193], v[100:103]
	v_mfma_f32_16x16x32_bf16 v[96:99], v[222:225], v[190:193], v[96:99]
	v_mfma_f32_16x16x32_bf16 v[84:87], v[214:217], v[198:201], v[84:87]
	v_mfma_f32_16x16x32_bf16 v[80:83], v[222:225], v[198:201], v[80:83]
	v_mfma_f32_16x16x32_bf16 v[68:71], v[214:217], v[206:209], v[68:71]
	v_mfma_f32_16x16x32_bf16 v[64:67], v[222:225], v[206:209], v[64:67]
	s_mov_b32 m0, s34
	v_lshl_add_u64 v[226:227], s[24:25], 0, v[128:129]
	s_barrier
	ds_read_b128 v[168:171], v150 offset:16384
	ds_read_b128 v[172:175], v150 offset:17408
	ds_read_b128 v[182:185], v150 offset:18432
	ds_read_b128 v[190:193], v150 offset:19456
	ds_read_b128 v[194:197], v150 offset:20480
	ds_read_b128 v[198:201], v150 offset:21504
	ds_read_b128 v[202:205], v150 offset:22528
	ds_read_b128 v[206:209], v150 offset:23552
	global_load_lds_dwordx4 v[226:227], off
	v_lshl_add_u64 v[228:229], s[24:25], 0, v[132:133]
	s_mov_b32 m0, s35
	s_nop 0
	global_load_lds_dwordx4 v[228:229], off
	s_barrier
	s_waitcnt lgkmcnt(0)
	v_mfma_f32_16x16x32_bf16 v[60:63], v[152:155], v[168:171], v[60:63]
	v_mfma_f32_16x16x32_bf16 v[56:59], v[160:163], v[168:171], v[56:59]
	v_mfma_f32_16x16x32_bf16 v[48:51], v[152:155], v[182:185], v[48:51]
	v_mfma_f32_16x16x32_bf16 v[40:43], v[160:163], v[182:185], v[40:43]
	v_mfma_f32_16x16x32_bf16 v[32:35], v[152:155], v[194:197], v[32:35]
	v_mfma_f32_16x16x32_bf16 v[24:27], v[160:163], v[194:197], v[24:27]
	v_mfma_f32_16x16x32_bf16 v[16:19], v[152:155], v[202:205], v[16:19]
	v_mfma_f32_16x16x32_bf16 v[8:11], v[160:163], v[202:205], v[8:11]
	v_mfma_f32_16x16x32_bf16 v[60:63], v[156:159], v[172:175], v[60:63]
	v_mfma_f32_16x16x32_bf16 v[56:59], v[164:167], v[172:175], v[56:59]
	v_mfma_f32_16x16x32_bf16 v[48:51], v[156:159], v[190:193], v[48:51]
	v_mfma_f32_16x16x32_bf16 v[40:43], v[164:167], v[190:193], v[40:43]
	v_mfma_f32_16x16x32_bf16 v[32:35], v[156:159], v[198:201], v[32:35]
	v_mfma_f32_16x16x32_bf16 v[24:27], v[164:167], v[198:201], v[24:27]
	v_mfma_f32_16x16x32_bf16 v[16:19], v[156:159], v[206:209], v[16:19]
	v_mfma_f32_16x16x32_bf16 v[8:11], v[164:167], v[206:209], v[8:11]
	s_barrier
; #define PG8_STAGE(bufoff, gbase, voff) do { _Pragma("unroll") for (int _i = 0; _i < 2; ++_i) \
;         __builtin_amdgcn_global_load_lds((const unsigned*)((const char*)(gbase) + (voff)[_i]), (PG8_LAS unsigned*)(lds + (bufoff) + ldsw + _i * 8192), 16, 0, 0); } while (0)
; #define PG8_LDA(dst, b, h) do { _Pragma("unroll") for (int m = 0; m < 4; ++m) _Pragma("unroll") for (int k = 0; k < 2; ++k) dst[m][k] = *(const PG8_LAS bf16x8*)(lds + PG8_SA(b, h) + aoff + m * 2048 + k * 1024); } while (0)
; #define PG8_LDB(dst, b, h) do { _Pragma("unroll") for (int n = 0; n < 2; ++n) _Pragma("unroll") for (int k = 0; k < 2; ++k) dst[n][k] = *(const PG8_LAS bf16x8*)(lds + PG8_SB(b, h) + boff + n * 2048 + k * 1024); } while (0)
; #define PG8_MMA(ai, bj, At, Bt) do { __builtin_amdgcn_s_setprio(1); _Pragma("unroll") for (int m = 0; m < 4; ++m) _Pragma("unroll") for (int n = 0; n < 2; ++n) _Pragma("unroll") for (int k = 0; k < 2; ++k) \
;         acc[ai][bj][m][n] = __builtin_amdgcn_mfma_f32_16x16x32_bf16(Bt[n][k], At[m][k], acc[ai][bj][m][n], 0, 0, 0); __builtin_amdgcn_s_setprio(0); } while (0)
; #define PG8_WAIT_V(n) asm volatile("s_waitcnt vmcnt(" #n ")" ::: "memory")
; #define PG8_WAIT_L(n) asm volatile("s_waitcnt lgkmcnt(" #n ")" ::: "memory")
; #define PG8_BAR __builtin_amdgcn_s_barrier()
; #define PG8_SCHED __builtin_amdgcn_sched_barrier(0)
; template <class Epi, class Sched>
; __device__ __forceinline__ void gemm_phase(PG8_LAS unsigned char* lds, const Gemm g, const Sched& S, const Epi& E) {
;     ...
;             PG8_STAGE(PG8_SB(0, 1), b2 + hstep, voffB);
;             PG8_WAIT_V(6); PG8_BAR; PG8_MMA(1, 1, At, B1); PG8_BAR;
;             PG8_LDB(B0, 1, 0); PG8_SCHED; PG8_LDA(At, 1, 0); PG8_STAGE(PG8_SA(0, 1), a2 + hstep, voffA);
;             PG8_WAIT_L(8); PG8_BAR; PG8_WAIT_L(0); PG8_MMA(0, 0, At, B0); PG8_BAR; PG8_SCHED;
;             PG8_LDB(B1, 1, 1); PG8_STAGE(PG8_SB(1, 0), b3, voffB);
;             PG8_BAR; PG8_WAIT_L(0); PG8_MMA(0, 1, At, B1); PG8_BAR;
;             PG8_LDA(At, 1, 1); PG8_STAGE(PG8_SA(1, 0), a3, voffA);
;             PG8_BAR; PG8_WAIT_L(0); PG8_MMA(1, 0, At, B0); PG8_BAR; PG8_SCHED;
	s_add_u32 s18, s22, 0xb0000
	s_addc_u32 s19, s23, 0
	s_add_i32 s55, s43, s31
	v_lshl_add_u64 v[152:153], s[18:19], 0, v[130:131]
	s_mov_b32 m0, s55
	s_nop 0
	global_load_lds_dwordx4 v[152:153], off
	v_lshl_add_u64 v[152:153], s[18:19], 0, v[134:135]
	s_add_i32 m0, s55, 0x2000
	s_nop 0
	global_load_lds_dwordx4 v[152:153], off
	s_waitcnt vmcnt(6)
	s_barrier
	v_mfma_f32_16x16x32_bf16 v[52:55], v[210:213], v[168:171], v[52:55]
	v_mfma_f32_16x16x32_bf16 v[44:47], v[218:221], v[168:171], v[44:47]
	v_mfma_f32_16x16x32_bf16 v[36:39], v[210:213], v[182:185], v[36:39]
	v_mfma_f32_16x16x32_bf16 v[28:31], v[218:221], v[182:185], v[28:31]
	v_mfma_f32_16x16x32_bf16 v[20:23], v[210:213], v[194:197], v[20:23]
	v_mfma_f32_16x16x32_bf16 v[12:15], v[218:221], v[194:197], v[12:15]
	v_mfma_f32_16x16x32_bf16 v[4:7], v[210:213], v[202:205], v[4:7]
	v_mfma_f32_16x16x32_bf16 v[0:3], v[218:221], v[202:205], v[0:3]
	v_mfma_f32_16x16x32_bf16 v[52:55], v[214:217], v[172:175], v[52:55]
	v_mfma_f32_16x16x32_bf16 v[44:47], v[222:225], v[172:175], v[44:47]
	v_mfma_f32_16x16x32_bf16 v[36:39], v[214:217], v[190:193], v[36:39]
	v_mfma_f32_16x16x32_bf16 v[28:31], v[222:225], v[190:193], v[28:31]
	v_mfma_f32_16x16x32_bf16 v[20:23], v[214:217], v[198:201], v[20:23]
	v_mfma_f32_16x16x32_bf16 v[12:15], v[222:225], v[198:201], v[12:15]
	v_mfma_f32_16x16x32_bf16 v[4:7], v[214:217], v[206:209], v[4:7]
	v_mfma_f32_16x16x32_bf16 v[0:3], v[222:225], v[206:209], v[0:3]
	s_add_i32 s55, 0, 0x18000
	v_add_u32_e32 v164, s55, v147
	s_barrier
	ds_read_b128 v[152:155], v164
	ds_read_b128 v[156:159], v164 offset:1024
	ds_read_b128 v[160:163], v164 offset:2048
	ds_read_b128 v[164:167], v164 offset:3072
	ds_read_b128 v[168:171], v150 offset:32768
	ds_read_b128 v[172:175], v150 offset:33792
	ds_read_b128 v[182:185], v150 offset:34816
	ds_read_b128 v[190:193], v150 offset:35840
	ds_read_b128 v[194:197], v150 offset:36864
	ds_read_b128 v[198:201], v150 offset:37888
	ds_read_b128 v[202:205], v150 offset:38912
	ds_read_b128 v[206:209], v150 offset:39936
	s_add_u32 s18, s24, 0xb0000
	s_addc_u32 s19, s25, 0
	s_mov_b32 m0, s36
	v_lshl_add_u64 v[210:211], s[18:19], 0, v[128:129]
	global_load_lds_dwordx4 v[210:211], off
	v_lshl_add_u64 v[210:211], s[18:19], 0, v[132:133]
	s_mov_b32 m0, s37
	s_nop 0
	global_load_lds_dwordx4 v[210:211], off
	s_waitcnt lgkmcnt(8)
	s_barrier
	s_waitcnt lgkmcnt(0)
	v_mfma_f32_16x16x32_bf16 v[124:127], v[152:155], v[168:171], v[124:127]
	v_mfma_f32_16x16x32_bf16 v[120:123], v[160:163], v[168:171], v[120:123]
	v_mfma_f32_16x16x32_bf16 v[108:111], v[152:155], v[182:185], v[108:111]
	v_mfma_f32_16x16x32_bf16 v[104:107], v[160:163], v[182:185], v[104:107]
	v_mfma_f32_16x16x32_bf16 v[92:95], v[152:155], v[194:197], v[92:95]
	v_mfma_f32_16x16x32_bf16 v[88:91], v[160:163], v[194:197], v[88:91]
	v_mfma_f32_16x16x32_bf16 v[76:79], v[152:155], v[202:205], v[76:79]
	v_mfma_f32_16x16x32_bf16 v[72:75], v[160:163], v[202:205], v[72:75]
	v_mfma_f32_16x16x32_bf16 v[124:127], v[156:159], v[172:175], v[124:127]
	v_mfma_f32_16x16x32_bf16 v[120:123], v[164:167], v[172:175], v[120:123]
	v_mfma_f32_16x16x32_bf16 v[108:111], v[156:159], v[190:193], v[108:111]
	v_mfma_f32_16x16x32_bf16 v[104:107], v[164:167], v[190:193], v[104:107]
	v_mfma_f32_16x16x32_bf16 v[92:95], v[156:159], v[198:201], v[92:95]
	v_mfma_f32_16x16x32_bf16 v[88:91], v[164:167], v[198:201], v[88:91]
	v_mfma_f32_16x16x32_bf16 v[76:79], v[156:159], v[206:209], v[76:79]
	v_mfma_f32_16x16x32_bf16 v[72:75], v[164:167], v[206:209], v[72:75]
	s_barrier
	s_add_i32 s24, 0, 0x1c000
	v_add_u32_e32 v179, s24, v147
	ds_read_b128 v[210:213], v179
	ds_read_b128 v[214:217], v179 offset:1024
	ds_read_b128 v[218:221], v179 offset:2048
	ds_read_b128 v[222:225], v179 offset:3072
	s_add_i32 s18, s55, s31
	v_lshl_add_u64 v[144:145], v[144:145], 0, s[8:9]
	s_mov_b32 m0, s18
	s_nop 0
	global_load_lds_dwordx4 v[144:145], off
	v_lshl_add_u64 v[144:145], v[186:187], 0, s[8:9]
	s_add_i32 m0, s18, 0x2000
	s_nop 0
	global_load_lds_dwordx4 v[144:145], off
	s_barrier
	s_waitcnt lgkmcnt(0)
	v_mfma_f32_16x16x32_bf16 v[116:119], v[210:213], v[168:171], v[116:119]
	v_mfma_f32_16x16x32_bf16 v[112:115], v[218:221], v[168:171], v[112:115]
	v_mfma_f32_16x16x32_bf16 v[100:103], v[210:213], v[182:185], v[100:103]
	v_mfma_f32_16x16x32_bf16 v[96:99], v[218:221], v[182:185], v[96:99]
	v_mfma_f32_16x16x32_bf16 v[84:87], v[210:213], v[194:197], v[84:87]
	v_mfma_f32_16x16x32_bf16 v[80:83], v[218:221], v[194:197], v[80:83]
	v_mfma_f32_16x16x32_bf16 v[68:71], v[210:213], v[202:205], v[68:71]
	v_mfma_f32_16x16x32_bf16 v[64:67], v[218:221], v[202:205], v[64:67]
	v_mfma_f32_16x16x32_bf16 v[116:119], v[214:217], v[172:175], v[116:119]
	v_mfma_f32_16x16x32_bf16 v[112:115], v[222:225], v[172:175], v[112:115]
	v_mfma_f32_16x16x32_bf16 v[100:103], v[214:217], v[190:193], v[100:103]
	v_mfma_f32_16x16x32_bf16 v[96:99], v[222:225], v[190:193], v[96:99]
	v_mfma_f32_16x16x32_bf16 v[84:87], v[214:217], v[198:201], v[84:87]
	v_mfma_f32_16x16x32_bf16 v[80:83], v[222:225], v[198:201], v[80:83]
	v_mfma_f32_16x16x32_bf16 v[68:71], v[214:217], v[206:209], v[68:71]
	v_mfma_f32_16x16x32_bf16 v[64:67], v[222:225], v[206:209], v[64:67]
	s_mov_b32 m0, s39
	v_lshl_add_u64 v[144:145], v[226:227], 0, s[8:9]
	s_barrier
	ds_read_b128 v[168:171], v150 offset:49152
	ds_read_b128 v[172:175], v150 offset:50176
	ds_read_b128 v[182:185], v150 offset:51200
	ds_read_b128 v[190:193], v150 offset:52224
	ds_read_b128 v[194:197], v150 offset:53248
	ds_read_b128 v[198:201], v150 offset:54272
	ds_read_b128 v[202:205], v150 offset:55296
	ds_read_b128 v[206:209], v150 offset:56320
	global_load_lds_dwordx4 v[144:145], off
	v_lshl_add_u64 v[144:145], v[228:229], 0, s[8:9]
	s_mov_b32 m0, s40
	s_nop 0
	global_load_lds_dwordx4 v[144:145], off
	s_barrier
; __device__ __forceinline__ unsigned cvt_pk_bf16(float lo, float hi) { unsigned r; asm volatile("v_cvt_pk_bf16_f32 %0, %1, %2" : "=v"(r) : "v"(lo), "v"(hi)); return r; }
; __device__ __forceinline__ float flogsig16(float x) { return (fminf(x, 0.f) - __logf(1.0f + __expf(-fabsf(x)))) * 0.0625f; }
; #define PG8_STAGE(bufoff, gbase, voff) do { _Pragma("unroll") for (int _i = 0; _i < 2; ++_i) \
;         __builtin_amdgcn_global_load_lds((const unsigned*)((const char*)(gbase) + (voff)[_i]), (PG8_LAS unsigned*)(lds + (bufoff) + ldsw + _i * 8192), 16, 0, 0); } while (0)
; #define PG8_WAIT_V(n) asm volatile("s_waitcnt vmcnt(" #n ")" ::: "memory")
; #define PG8_WAIT_L(n) asm volatile("s_waitcnt lgkmcnt(" #n ")" ::: "memory")
; #define PG8_BAR __builtin_amdgcn_s_barrier()
; #define PG8_SCHED __builtin_amdgcn_sched_barrier(0)
;     __device__ __forceinline__ void operator()(const f32x4 (&acc)[2][2][4][2], const Unit& u, int wr, int wc, int fr, int fq) const {
;     ...
;             for (int m = 0; m < 4; ++m) { bf16_t* rowp = O + (size_t)(row0 + ai * HALF + m * 16) * ldc + col0;
; #pragma unroll
;                 for (int bj = 0; bj < 2; ++bj) { f32x4 v0 = acc[ai][bj][m][0] + bv[bj][0], v1 = acc[ai][bj][m][1] + bv[bj][1];
;                     if (act == 1) {
; #pragma unroll
;                         for (int j = 0; j < 1; ++j) { v0 = v0 * sigmoid4(v0); v1 = v1 * sigmoid4(v1); } }
;                     else if (act == 2) {
; #pragma unroll
;                         for (int j = 0; j < 1; ++j) { v0 = sigmoid4(v0); v1 = sigmoid4(v1); } }
;                     else if (act == 3) {
; #pragma unroll
;                         for (int j = 0; j < 4; ++j) { v0[j] = flogsig16(v0[j]); v1[j] = flogsig16(v1[j]); } }
;                     u32x4 w; w.x = cvt_pk_bf16(v0[0], v0[1]); w.y = cvt_pk_bf16(v0[2], v0[3]); w.z = cvt_pk_bf16(v1[0], v1[1]); w.w = cvt_pk_bf16(v1[2], v1[3]);
;                     *(u32x4*)(rowp + bj * HALF) = w; } }
; template <class Epi, class Sched>
; __device__ __forceinline__ void gemm_phase(PG8_LAS unsigned char* lds, const Gemm g, const Sched& S, const Epi& E) {
;     ...
;             PG8_BAR; PG8_WAIT_L(0); PG8_MMA(1, 0, At, B0); PG8_BAR; PG8_SCHED;
;             PG8_STAGE(PG8_SB(1, 1), b3 + hstep, voffB);
;             PG8_WAIT_V(6); PG8_BAR; PG8_MMA(1, 1, At, B1); PG8_BAR;
;         }
	s_waitcnt lgkmcnt(0)
	v_mfma_f32_16x16x32_bf16 v[60:63], v[152:155], v[168:171], v[60:63]
	v_mfma_f32_16x16x32_bf16 v[56:59], v[160:163], v[168:171], v[56:59]
	v_mfma_f32_16x16x32_bf16 v[48:51], v[152:155], v[182:185], v[48:51]
	v_mfma_f32_16x16x32_bf16 v[40:43], v[160:163], v[182:185], v[40:43]
	v_mfma_f32_16x16x32_bf16 v[32:35], v[152:155], v[194:197], v[32:35]
	v_mfma_f32_16x16x32_bf16 v[24:27], v[160:163], v[194:197], v[24:27]
	v_mfma_f32_16x16x32_bf16 v[16:19], v[152:155], v[202:205], v[16:19]
	v_mfma_f32_16x16x32_bf16 v[8:11], v[160:163], v[202:205], v[8:11]
	v_mfma_f32_16x16x32_bf16 v[60:63], v[156:159], v[172:175], v[60:63]
	v_mfma_f32_16x16x32_bf16 v[56:59], v[164:167], v[172:175], v[56:59]
	v_mfma_f32_16x16x32_bf16 v[48:51], v[156:159], v[190:193], v[48:51]
	v_mfma_f32_16x16x32_bf16 v[40:43], v[164:167], v[190:193], v[40:43]
	v_mfma_f32_16x16x32_bf16 v[32:35], v[156:159], v[198:201], v[32:35]
	v_mfma_f32_16x16x32_bf16 v[24:27], v[164:167], v[198:201], v[24:27]
	v_mfma_f32_16x16x32_bf16 v[16:19], v[156:159], v[206:209], v[16:19]
	v_mfma_f32_16x16x32_bf16 v[8:11], v[164:167], v[206:209], v[8:11]
	s_barrier
	s_add_u32 s18, s22, 0xb0080
	s_addc_u32 s19, s23, 0
	s_add_i32 s22, s24, s31
	v_lshl_add_u64 v[144:145], s[18:19], 0, v[130:131]
	s_mov_b32 m0, s22
	s_nop 0
	global_load_lds_dwordx4 v[144:145], off
	v_lshl_add_u64 v[144:145], s[18:19], 0, v[134:135]
	s_add_i32 m0, s22, 0x2000
	s_nop 0
	global_load_lds_dwordx4 v[144:145], off
	s_waitcnt vmcnt(6)
	s_barrier
	v_mfma_f32_16x16x32_bf16 v[52:55], v[210:213], v[168:171], v[52:55]
	v_mfma_f32_16x16x32_bf16 v[44:47], v[218:221], v[168:171], v[44:47]
	v_mfma_f32_16x16x32_bf16 v[36:39], v[210:213], v[182:185], v[36:39]
	v_mfma_f32_16x16x32_bf16 v[28:31], v[218:221], v[182:185], v[28:31]
	v_mfma_f32_16x16x32_bf16 v[20:23], v[210:213], v[194:197], v[20:23]
	v_mfma_f32_16x16x32_bf16 v[12:15], v[218:221], v[194:197], v[12:15]
	v_mfma_f32_16x16x32_bf16 v[4:7], v[210:213], v[202:205], v[4:7]
	v_mfma_f32_16x16x32_bf16 v[0:3], v[218:221], v[202:205], v[0:3]
	v_mfma_f32_16x16x32_bf16 v[52:55], v[214:217], v[172:175], v[52:55]
	v_mfma_f32_16x16x32_bf16 v[44:47], v[222:225], v[172:175], v[44:47]
	v_mfma_f32_16x16x32_bf16 v[36:39], v[214:217], v[190:193], v[36:39]
	v_mfma_f32_16x16x32_bf16 v[28:31], v[222:225], v[190:193], v[28:31]
	v_mfma_f32_16x16x32_bf16 v[20:23], v[214:217], v[198:201], v[20:23]
	v_mfma_f32_16x16x32_bf16 v[12:15], v[222:225], v[198:201], v[12:15]
	v_mfma_f32_16x16x32_bf16 v[4:7], v[214:217], v[206:209], v[4:7]
	v_mfma_f32_16x16x32_bf16 v[0:3], v[222:225], v[206:209], v[0:3]
	s_add_i32 s54, s54, 2
	s_add_u32 s52, s52, 0x100
	s_addc_u32 s53, s53, 0
	s_cmp_gt_u32 s54, 41
	s_mov_b64 s[18:19], s[20:21]
	s_barrier
	s_cbranch_scc0 .LBB0_1278
	v_lshl_add_u32 v152, s50, 8, v146
	v_lshl_or_b32 v144, s51, 8, v148
	v_ashrrev_i32_e32 v153, 31, v152
	v_ashrrev_i32_e32 v145, 31, v144
	v_lshlrev_b64 v[154:155], 11, v[152:153]
	v_lshl_add_u64 v[154:155], s[6:7], 0, v[154:155]
	v_lshlrev_b64 v[156:157], 1, v[144:145]
	v_lshl_add_u64 v[144:145], v[154:155], 0, v[156:157]
	v_pk_add_f32 v[126:127], v[126:127], 0 op_sel_hi:[1,0]
	v_pk_add_f32 v[124:125], v[124:125], 0 op_sel_hi:[1,0]
	v_pk_add_f32 v[154:155], v[122:123], 0 op_sel_hi:[1,0]
	v_pk_add_f32 v[122:123], v[120:121], 0 op_sel_hi:[1,0]
	v_cvt_pk_bf16_f32 v120, v124, v125
	v_cvt_pk_bf16_f32 v121, v126, v127
	v_pk_add_f32 v[116:117], v[116:117], 0 op_sel_hi:[1,0]
	v_cvt_pk_bf16_f32 v122, v122, v123
	v_cvt_pk_bf16_f32 v123, v154, v155
	global_store_dwordx4 v[144:145], v[120:123], off
	v_pk_add_f32 v[118:119], v[118:119], 0 op_sel_hi:[1,0]
	v_pk_add_f32 v[110:111], v[110:111], 0 op_sel_hi:[1,0]
	v_pk_add_f32 v[120:121], v[114:115], 0 op_sel_hi:[1,0]
	v_pk_add_f32 v[114:115], v[112:113], 0 op_sel_hi:[1,0]
	v_cvt_pk_bf16_f32 v112, v116, v117
	v_cvt_pk_bf16_f32 v113, v118, v119
	v_pk_add_f32 v[108:109], v[108:109], 0 op_sel_hi:[1,0]
	v_cvt_pk_bf16_f32 v114, v114, v115
	v_cvt_pk_bf16_f32 v115, v120, v121
	global_store_dwordx4 v[144:145], v[112:115], off offset:256
	v_pk_add_f32 v[100:101], v[100:101], 0 op_sel_hi:[1,0]
	v_pk_add_f32 v[102:103], v[102:103], 0 op_sel_hi:[1,0]
	v_or_b32_e32 v112, 16, v152
	v_ashrrev_i32_e32 v113, 31, v112
	v_lshlrev_b64 v[112:113], 11, v[112:113]
	v_lshl_add_u64 v[112:113], s[6:7], 0, v[112:113]
	v_lshl_add_u64 v[112:113], v[112:113], 0, v[156:157]
	v_pk_add_f32 v[114:115], v[106:107], 0 op_sel_hi:[1,0]
	v_pk_add_f32 v[106:107], v[104:105], 0 op_sel_hi:[1,0]
	v_cvt_pk_bf16_f32 v104, v108, v109
	v_cvt_pk_bf16_f32 v105, v110, v111
	v_pk_add_f32 v[94:95], v[94:95], 0 op_sel_hi:[1,0]
	v_cvt_pk_bf16_f32 v106, v106, v107
	v_cvt_pk_bf16_f32 v107, v114, v115
	global_store_dwordx4 v[112:113], v[104:107], off
	v_pk_add_f32 v[92:93], v[92:93], 0 op_sel_hi:[1,0]
	v_pk_add_f32 v[84:85], v[84:85], 0 op_sel_hi:[1,0]
	v_pk_add_f32 v[104:105], v[98:99], 0 op_sel_hi:[1,0]
	v_pk_add_f32 v[98:99], v[96:97], 0 op_sel_hi:[1,0]
	v_cvt_pk_bf16_f32 v96, v100, v101
	v_cvt_pk_bf16_f32 v97, v102, v103
	v_pk_add_f32 v[86:87], v[86:87], 0 op_sel_hi:[1,0]
	v_cvt_pk_bf16_f32 v98, v98, v99
	v_cvt_pk_bf16_f32 v99, v104, v105
	global_store_dwordx4 v[112:113], v[96:99], off offset:256
	v_pk_add_f32 v[78:79], v[78:79], 0 op_sel_hi:[1,0]
	v_pk_add_f32 v[76:77], v[76:77], 0 op_sel_hi:[1,0]
	v_or_b32_e32 v96, 32, v152
	v_ashrrev_i32_e32 v97, 31, v96
	v_lshlrev_b64 v[96:97], 11, v[96:97]
	v_lshl_add_u64 v[96:97], s[6:7], 0, v[96:97]
; __device__ __forceinline__ unsigned cvt_pk_bf16(float lo, float hi) { unsigned r; asm volatile("v_cvt_pk_bf16_f32 %0, %1, %2" : "=v"(r) : "v"(lo), "v"(hi)); return r; }
; __device__ __forceinline__ float flogsig16(float x) { return (fminf(x, 0.f) - __logf(1.0f + __expf(-fabsf(x)))) * 0.0625f; }
; #define PG8_WAIT_V(n) asm volatile("s_waitcnt vmcnt(" #n ")" ::: "memory")
; #define PG8_BAR __builtin_amdgcn_s_barrier()
;     __device__ __forceinline__ void operator()(const f32x4 (&acc)[2][2][4][2], const Unit& u, int wr, int wc, int fr, int fq) const {
;     ...
;             for (int m = 0; m < 4; ++m) { bf16_t* rowp = O + (size_t)(row0 + ai * HALF + m * 16) * ldc + col0;
; #pragma unroll
;                 for (int bj = 0; bj < 2; ++bj) { f32x4 v0 = acc[ai][bj][m][0] + bv[bj][0], v1 = acc[ai][bj][m][1] + bv[bj][1];
;                     if (act == 1) {
; #pragma unroll
;                         for (int j = 0; j < 1; ++j) { v0 = v0 * sigmoid4(v0); v1 = v1 * sigmoid4(v1); } }
;                     else if (act == 2) {
; #pragma unroll
;                         for (int j = 0; j < 1; ++j) { v0 = sigmoid4(v0); v1 = sigmoid4(v1); } }
;                     else if (act == 3) {
; #pragma unroll
;                         for (int j = 0; j < 4; ++j) { v0[j] = flogsig16(v0[j]); v1[j] = flogsig16(v1[j]); } }
;                     u32x4 w; w.x = cvt_pk_bf16(v0[0], v0[1]); w.y = cvt_pk_bf16(v0[2], v0[3]); w.z = cvt_pk_bf16(v1[0], v1[1]); w.w = cvt_pk_bf16(v1[2], v1[3]);
;                     *(u32x4*)(rowp + bj * HALF) = w; } }
; template <class Epi, class Sched>
; __device__ __forceinline__ void gemm_phase(PG8_LAS unsigned char* lds, const Gemm g, const Sched& S, const Epi& E) {
;     ...
;         if (!has_next) break;
; #pragma unroll
;         for (int a = 0; a < 2; ++a)
; #pragma unroll
;             for (int b = 0; b < 2; ++b)
; #pragma unroll
;                 for (int m = 0; m < 4; ++m)
; #pragma unroll
;                     for (int n = 0; n < 2; ++n) acc[a][b][m][n] = (f32x4){0.f, 0.f, 0.f, 0.f};
;         cur = nxt; cA = nA; cB = nB; ++ui;
;     }
;     PG8_WAIT_V(0);
;     if (wr == 0) PG8_BAR;
;     PG8_BAR;
	v_lshl_add_u64 v[96:97], v[96:97], 0, v[156:157]
	v_pk_add_f32 v[98:99], v[90:91], 0 op_sel_hi:[1,0]
	v_pk_add_f32 v[90:91], v[88:89], 0 op_sel_hi:[1,0]
	v_cvt_pk_bf16_f32 v88, v92, v93
	v_cvt_pk_bf16_f32 v89, v94, v95
	v_pk_add_f32 v[70:71], v[70:71], 0 op_sel_hi:[1,0]
	v_cvt_pk_bf16_f32 v90, v90, v91
	v_cvt_pk_bf16_f32 v91, v98, v99
	global_store_dwordx4 v[96:97], v[88:91], off
	v_pk_add_f32 v[68:69], v[68:69], 0 op_sel_hi:[1,0]
	v_pk_add_f32 v[60:61], v[60:61], 0 op_sel_hi:[1,0]
	v_pk_add_f32 v[88:89], v[82:83], 0 op_sel_hi:[1,0]
	v_pk_add_f32 v[82:83], v[80:81], 0 op_sel_hi:[1,0]
	v_cvt_pk_bf16_f32 v80, v84, v85
	v_cvt_pk_bf16_f32 v81, v86, v87
	v_pk_add_f32 v[62:63], v[62:63], 0 op_sel_hi:[1,0]
	v_cvt_pk_bf16_f32 v82, v82, v83
	v_cvt_pk_bf16_f32 v83, v88, v89
	global_store_dwordx4 v[96:97], v[80:83], off offset:256
	v_pk_add_f32 v[54:55], v[54:55], 0 op_sel_hi:[1,0]
	v_pk_add_f32 v[52:53], v[52:53], 0 op_sel_hi:[1,0]
	v_or_b32_e32 v80, 48, v152
	v_ashrrev_i32_e32 v81, 31, v80
	v_lshlrev_b64 v[80:81], 11, v[80:81]
	v_lshl_add_u64 v[80:81], s[6:7], 0, v[80:81]
	v_lshl_add_u64 v[80:81], v[80:81], 0, v[156:157]
	v_pk_add_f32 v[82:83], v[74:75], 0 op_sel_hi:[1,0]
	v_pk_add_f32 v[74:75], v[72:73], 0 op_sel_hi:[1,0]
	v_cvt_pk_bf16_f32 v72, v76, v77
	v_cvt_pk_bf16_f32 v73, v78, v79
	v_pk_add_f32 v[48:49], v[48:49], 0 op_sel_hi:[1,0]
	v_cvt_pk_bf16_f32 v74, v74, v75
	v_cvt_pk_bf16_f32 v75, v82, v83
	global_store_dwordx4 v[80:81], v[72:75], off
	v_pk_add_f32 v[38:39], v[38:39], 0 op_sel_hi:[1,0]
	v_pk_add_f32 v[36:37], v[36:37], 0 op_sel_hi:[1,0]
	v_pk_add_f32 v[72:73], v[66:67], 0 op_sel_hi:[1,0]
	v_pk_add_f32 v[66:67], v[64:65], 0 op_sel_hi:[1,0]
	v_cvt_pk_bf16_f32 v64, v68, v69
	v_cvt_pk_bf16_f32 v65, v70, v71
	v_pk_add_f32 v[32:33], v[32:33], 0 op_sel_hi:[1,0]
	v_cvt_pk_bf16_f32 v66, v66, v67
	v_cvt_pk_bf16_f32 v67, v72, v73
	global_store_dwordx4 v[80:81], v[64:67], off offset:256
	v_pk_add_f32 v[22:23], v[22:23], 0 op_sel_hi:[1,0]
	v_pk_add_f32 v[20:21], v[20:21], 0 op_sel_hi:[1,0]
	v_pk_add_f32 v[66:67], v[58:59], 0 op_sel_hi:[1,0]
	v_pk_add_f32 v[58:59], v[56:57], 0 op_sel_hi:[1,0]
	v_cvt_pk_bf16_f32 v56, v60, v61
	v_add_co_u32_e32 v60, vcc, s44, v144
	v_cvt_pk_bf16_f32 v57, v62, v63
	v_cvt_pk_bf16_f32 v58, v58, v59
	v_cvt_pk_bf16_f32 v59, v66, v67
	v_lshl_add_u64 v[64:65], v[144:145], 0, s[10:11]
	s_nop 0
	v_addc_co_u32_e32 v61, vcc, 0, v145, vcc
	global_store_dwordx4 v[60:61], v[56:59], off
	v_pk_add_f32 v[16:17], v[16:17], 0 op_sel_hi:[1,0]
	s_mov_b32 s51, s48
	v_pk_add_f32 v[56:57], v[46:47], 0 op_sel_hi:[1,0]
	v_pk_add_f32 v[46:47], v[44:45], 0 op_sel_hi:[1,0]
	v_cvt_pk_bf16_f32 v44, v52, v53
	v_cvt_pk_bf16_f32 v45, v54, v55
	s_mov_b32 s50, s49
	v_cvt_pk_bf16_f32 v46, v46, v47
	v_cvt_pk_bf16_f32 v47, v56, v57
	global_store_dwordx4 v[64:65], v[44:47], off offset:256
	s_mov_b64 s[20:21], s[4:5]
	s_mov_b64 s[18:19], s[0:1]
	v_pk_add_f32 v[46:47], v[50:51], 0 op_sel_hi:[1,0]
	v_pk_add_f32 v[50:51], v[42:43], 0 op_sel_hi:[1,0]
	v_pk_add_f32 v[42:43], v[40:41], 0 op_sel_hi:[1,0]
	v_cvt_pk_bf16_f32 v40, v48, v49
	v_cvt_pk_bf16_f32 v41, v46, v47
	v_add_co_u32_e32 v46, vcc, s45, v144
	v_cvt_pk_bf16_f32 v42, v42, v43
	v_cvt_pk_bf16_f32 v43, v50, v51
	v_lshl_add_u64 v[44:45], v[144:145], 0, s[12:13]
	s_nop 0
	v_addc_co_u32_e32 v47, vcc, 0, v145, vcc
	global_store_dwordx4 v[46:47], v[40:43], off
	v_pk_add_f32 v[6:7], v[6:7], 0 op_sel_hi:[1,0]
	v_pk_add_f32 v[4:5], v[4:5], 0 op_sel_hi:[1,0]
	v_pk_add_f32 v[40:41], v[30:31], 0 op_sel_hi:[1,0]
	v_pk_add_f32 v[30:31], v[28:29], 0 op_sel_hi:[1,0]
	v_cvt_pk_bf16_f32 v28, v36, v37
	v_cvt_pk_bf16_f32 v29, v38, v39
	s_nop 0
	v_cvt_pk_bf16_f32 v30, v30, v31
	v_cvt_pk_bf16_f32 v31, v40, v41
	global_store_dwordx4 v[44:45], v[28:31], off offset:256
	s_nop 1
	v_pk_add_f32 v[30:31], v[34:35], 0 op_sel_hi:[1,0]
	v_pk_add_f32 v[34:35], v[26:27], 0 op_sel_hi:[1,0]
	v_pk_add_f32 v[26:27], v[24:25], 0 op_sel_hi:[1,0]
	v_cvt_pk_bf16_f32 v24, v32, v33
	v_cvt_pk_bf16_f32 v25, v30, v31
	v_add_co_u32_e32 v30, vcc, s46, v144
	v_cvt_pk_bf16_f32 v26, v26, v27
	v_cvt_pk_bf16_f32 v27, v34, v35
	v_lshl_add_u64 v[28:29], v[144:145], 0, s[14:15]
	s_nop 0
	v_addc_co_u32_e32 v31, vcc, 0, v145, vcc
	global_store_dwordx4 v[30:31], v[24:27], off
	s_nop 1
	v_pk_add_f32 v[24:25], v[14:15], 0 op_sel_hi:[1,0]
	v_pk_add_f32 v[14:15], v[12:13], 0 op_sel_hi:[1,0]
	v_cvt_pk_bf16_f32 v12, v20, v21
	v_cvt_pk_bf16_f32 v13, v22, v23
	s_nop 0
	v_cvt_pk_bf16_f32 v14, v14, v15
	v_cvt_pk_bf16_f32 v15, v24, v25
	global_store_dwordx4 v[28:29], v[12:15], off offset:256
	s_nop 1
	v_pk_add_f32 v[14:15], v[18:19], 0 op_sel_hi:[1,0]
	v_pk_add_f32 v[18:19], v[10:11], 0 op_sel_hi:[1,0]
	v_pk_add_f32 v[10:11], v[8:9], 0 op_sel_hi:[1,0]
	v_cvt_pk_bf16_f32 v8, v16, v17
	v_cvt_pk_bf16_f32 v9, v14, v15
	v_add_co_u32_e32 v14, vcc, s47, v144
	v_lshl_add_u64 v[12:13], v[144:145], 0, s[16:17]
	s_nop 0
	v_addc_co_u32_e32 v15, vcc, 0, v145, vcc
	v_cvt_pk_bf16_f32 v10, v10, v11
	v_cvt_pk_bf16_f32 v11, v18, v19
	global_store_dwordx4 v[14:15], v[8:11], off
	s_and_b64 vcc, exec, s[2:3]
	s_nop 0
	v_pk_add_f32 v[8:9], v[2:3], 0 op_sel_hi:[1,0]
	v_pk_add_f32 v[2:3], v[0:1], 0 op_sel_hi:[1,0]
	v_cvt_pk_bf16_f32 v0, v4, v5
	v_cvt_pk_bf16_f32 v1, v6, v7
	s_nop 0
	v_cvt_pk_bf16_f32 v2, v2, v3
	v_cvt_pk_bf16_f32 v3, v8, v9
	global_store_dwordx4 v[12:13], v[0:3], off offset:256
	s_cbranch_vccz .LBB0_1267
	s_waitcnt vmcnt(0)
	s_cmpk_gt_u32 s27, 0xff
	s_cbranch_scc1 .LBB0_1282
	s_barrier
